# E23: SP2 load segments interleave m0 write / ds_read / LDS-DMA load (no s_nop pads, DMA issue starts first); on E20
# speedup vs baseline: 1.0314x; 1.0028x over previous
.LBB0_303:
	s_lshl_b32 s18, s91, 20
	s_and_b64 s[8:9], s[34:35], exec
	s_cselect_b32 s8, s18, s94
	s_lshl_b32 s19, s90, 20
	s_and_b64 s[42:43], s[34:35], exec
	s_cselect_b32 s9, s19, s95
	s_add_i32 s94, s94, 0x80080
	s_addk_i32 s95, 0x100
	s_mov_b32 vcc_lo, -2
	ds_read_b128 v[142:145], v136
	ds_read_b128 v[170:173], v136 offset:1024
	ds_read_b128 v[174:177], v136 offset:2048
	ds_read_b128 v[178:181], v136 offset:3072
	ds_read_b128 v[182:185], v137
	ds_read_b128 v[186:189], v137 offset:1024
	ds_read_b128 v[190:193], v137 offset:2048
	ds_read_b128 v[194:197], v137 offset:3072
	s_add_i32 s42, s94, 0xfff80080
	s_cmp_eq_u32 vcc_lo, 28
	s_cselect_b32 s97, s8, s42
	s_cselect_b32 s52, s9, s95
	s_or_b32 vcc_hi, s97, 0x80
	s_mov_b32 m0, s72
	ds_read_b128 v[198:201], v138
	ds_read_b128 v[202:205], v138 offset:1024
	ds_read_b128 v[228:231], v138 offset:2048
	ds_read_b128 v[232:235], v138 offset:3072
	ds_read_b128 v[236:239], v138 offset:4096
	ds_read_b128 v[240:243], v138 offset:5120
	ds_read_b128 v[244:247], v138 offset:6144
	ds_read_b128 v[248:251], v138 offset:7168
	buffer_load_dwordx4 v132, s[60:63], s94 offen lds
	s_mov_b32 m0, s47
	s_nop 0
	buffer_load_dwordx4 v134, s[60:63], s94 offen lds
	s_waitcnt vmcnt(8)
	s_waitcnt lgkmcnt(0)
	s_setprio 1
	s_barrier
	v_mfma_f32_16x16x32_bf16 v[114:117], v[142:145], v[198:201], 0
	v_mfma_f32_16x16x32_bf16 v[114:117], v[170:173], v[202:205], v[114:117]
	v_mfma_f32_16x16x32_bf16 v[110:113], v[174:177], v[198:201], 0
	v_mfma_f32_16x16x32_bf16 v[110:113], v[178:181], v[202:205], v[110:113]
	v_mfma_f32_16x16x32_bf16 v[122:125], v[190:193], v[198:201], 0
	v_mfma_f32_16x16x32_bf16 v[122:125], v[194:197], v[202:205], v[122:125]
	v_mfma_f32_16x16x32_bf16 v[126:129], v[182:185], v[198:201], 0
	v_mfma_f32_16x16x32_bf16 v[126:129], v[186:189], v[202:205], v[126:129]
	v_mfma_f32_16x16x32_bf16 v[118:121], v[182:185], v[228:231], 0
	v_mfma_f32_16x16x32_bf16 v[118:121], v[186:189], v[232:235], v[118:121]
	v_mfma_f32_16x16x32_bf16 v[98:101], v[190:193], v[228:231], 0
	v_mfma_f32_16x16x32_bf16 v[98:101], v[194:197], v[232:235], v[98:101]
	v_mfma_f32_16x16x32_bf16 v[102:105], v[174:177], v[228:231], 0
	v_mfma_f32_16x16x32_bf16 v[102:105], v[178:181], v[232:235], v[102:105]
	v_mfma_f32_16x16x32_bf16 v[106:109], v[142:145], v[228:231], 0
	v_mfma_f32_16x16x32_bf16 v[106:109], v[170:173], v[232:235], v[106:109]
	v_mfma_f32_16x16x32_bf16 v[94:97], v[142:145], v[236:239], 0
	v_mfma_f32_16x16x32_bf16 v[94:97], v[170:173], v[240:243], v[94:97]
	v_mfma_f32_16x16x32_bf16 v[86:89], v[174:177], v[236:239], 0
	v_mfma_f32_16x16x32_bf16 v[86:89], v[178:181], v[240:243], v[86:89]
	v_mfma_f32_16x16x32_bf16 v[82:85], v[190:193], v[236:239], 0
	v_mfma_f32_16x16x32_bf16 v[82:85], v[194:197], v[240:243], v[82:85]
	v_mfma_f32_16x16x32_bf16 v[90:93], v[182:185], v[236:239], 0
	v_mfma_f32_16x16x32_bf16 v[90:93], v[186:189], v[240:243], v[90:93]
	v_mfma_f32_16x16x32_bf16 v[74:77], v[182:185], v[244:247], 0
	v_mfma_f32_16x16x32_bf16 v[74:77], v[186:189], v[248:251], v[74:77]
	v_mfma_f32_16x16x32_bf16 v[66:69], v[190:193], v[244:247], 0
	v_mfma_f32_16x16x32_bf16 v[66:69], v[194:197], v[248:251], v[66:69]
	v_mfma_f32_16x16x32_bf16 v[70:73], v[174:177], v[244:247], 0
	v_mfma_f32_16x16x32_bf16 v[70:73], v[178:181], v[248:251], v[70:73]
	v_mfma_f32_16x16x32_bf16 v[78:81], v[142:145], v[244:247], 0
	v_mfma_f32_16x16x32_bf16 v[78:81], v[170:173], v[248:251], v[78:81]
	s_barrier
	s_setprio 0
	s_mov_b32 s42, s62
	s_mov_b32 s43, s63
	s_mov_b32 m0, s13
	ds_read_b128 v[198:201], v138 offset:16384
	buffer_load_dwordx4 v133, s[40:43], s52 offen lds
	s_add_i32 s96, s52, 0x80000
	s_mov_b32 m0, s14
	ds_read_b128 v[202:205], v138 offset:17408
	buffer_load_dwordx4 v135, s[40:43], s52 offen lds
	s_mov_b32 m0, s15
	ds_read_b128 v[228:231], v138 offset:18432
	buffer_load_dwordx4 v133, s[40:43], s96 offen lds
	s_mov_b32 m0, s16
	ds_read_b128 v[232:235], v138 offset:19456
	buffer_load_dwordx4 v135, s[40:43], s96 offen lds
	s_mov_b32 m0, s2
	ds_read_b128 v[236:239], v138 offset:20480
	buffer_load_dwordx4 v132, s[60:63], s97 offen lds
	s_mov_b32 m0, s21
	ds_read_b128 v[240:243], v138 offset:21504
	buffer_load_dwordx4 v134, s[60:63], s97 offen lds
	ds_read_b128 v[244:247], v138 offset:22528
	ds_read_b128 v[248:251], v138 offset:23552
	s_waitcnt vmcnt(8)
	s_waitcnt lgkmcnt(0)
	s_setprio 1
	s_barrier
	v_mfma_f32_16x16x32_bf16 v[62:65], v[142:145], v[198:201], 0
	v_mfma_f32_16x16x32_bf16 v[62:65], v[170:173], v[202:205], v[62:65]
	v_mfma_f32_16x16x32_bf16 v[54:57], v[174:177], v[198:201], 0
	v_mfma_f32_16x16x32_bf16 v[54:57], v[178:181], v[202:205], v[54:57]
	v_mfma_f32_16x16x32_bf16 v[50:53], v[190:193], v[198:201], 0
	v_mfma_f32_16x16x32_bf16 v[50:53], v[194:197], v[202:205], v[50:53]
	v_mfma_f32_16x16x32_bf16 v[58:61], v[182:185], v[198:201], 0
	v_mfma_f32_16x16x32_bf16 v[58:61], v[186:189], v[202:205], v[58:61]
	v_mfma_f32_16x16x32_bf16 v[42:45], v[182:185], v[228:231], 0
	v_mfma_f32_16x16x32_bf16 v[42:45], v[186:189], v[232:235], v[42:45]
	v_mfma_f32_16x16x32_bf16 v[34:37], v[190:193], v[228:231], 0
	v_mfma_f32_16x16x32_bf16 v[34:37], v[194:197], v[232:235], v[34:37]
	v_mfma_f32_16x16x32_bf16 v[38:41], v[174:177], v[228:231], 0
	v_mfma_f32_16x16x32_bf16 v[38:41], v[178:181], v[232:235], v[38:41]
	v_mfma_f32_16x16x32_bf16 v[46:49], v[142:145], v[228:231], 0
	v_mfma_f32_16x16x32_bf16 v[46:49], v[170:173], v[232:235], v[46:49]
	v_mfma_f32_16x16x32_bf16 v[30:33], v[142:145], v[236:239], 0
	v_mfma_f32_16x16x32_bf16 v[30:33], v[170:173], v[240:243], v[30:33]
	v_mfma_f32_16x16x32_bf16 v[22:25], v[174:177], v[236:239], 0
	v_mfma_f32_16x16x32_bf16 v[22:25], v[178:181], v[240:243], v[22:25]
	v_mfma_f32_16x16x32_bf16 v[18:21], v[190:193], v[236:239], 0
	v_mfma_f32_16x16x32_bf16 v[18:21], v[194:197], v[240:243], v[18:21]
	v_mfma_f32_16x16x32_bf16 v[26:29], v[182:185], v[236:239], 0
	v_mfma_f32_16x16x32_bf16 v[26:29], v[186:189], v[240:243], v[26:29]
	v_mfma_f32_16x16x32_bf16 v[10:13], v[182:185], v[244:247], 0
	v_mfma_f32_16x16x32_bf16 v[10:13], v[186:189], v[248:251], v[10:13]
	v_mfma_f32_16x16x32_bf16 v[2:5], v[190:193], v[244:247], 0
	v_mfma_f32_16x16x32_bf16 v[2:5], v[194:197], v[248:251], v[2:5]
	v_mfma_f32_16x16x32_bf16 v[6:9], v[174:177], v[244:247], 0
	v_mfma_f32_16x16x32_bf16 v[6:9], v[178:181], v[248:251], v[6:9]
	v_mfma_f32_16x16x32_bf16 v[14:17], v[142:145], v[244:247], 0
	v_mfma_f32_16x16x32_bf16 v[14:17], v[170:173], v[248:251], v[14:17]
	s_barrier
	s_setprio 0
	ds_read_b128 v[142:145], v139
	ds_read_b128 v[170:173], v139 offset:1024
	ds_read_b128 v[174:177], v139 offset:2048
	ds_read_b128 v[178:181], v139 offset:3072
	ds_read_b128 v[182:185], v140
	ds_read_b128 v[186:189], v140 offset:1024
	ds_read_b128 v[190:193], v140 offset:2048
	ds_read_b128 v[194:197], v140 offset:3072
	s_add_i32 s97, s97, 0x80000
	s_mov_b32 m0, s23
	ds_read_b128 v[198:201], v138 offset:32768
	ds_read_b128 v[202:205], v138 offset:33792
	ds_read_b128 v[228:231], v138 offset:34816
	ds_read_b128 v[232:235], v138 offset:35840
	ds_read_b128 v[236:239], v138 offset:36864
	ds_read_b128 v[240:243], v138 offset:37888
	ds_read_b128 v[244:247], v138 offset:38912
	ds_read_b128 v[248:251], v138 offset:39936
	buffer_load_dwordx4 v132, s[60:63], s97 offen lds
	s_mov_b32 m0, s24
	s_nop 0
	buffer_load_dwordx4 v134, s[60:63], s97 offen lds
	s_waitcnt vmcnt(8)
	s_waitcnt lgkmcnt(0)
	s_setprio 1
	s_barrier
	v_mfma_f32_16x16x32_bf16 v[114:117], v[142:145], v[198:201], v[114:117]
	v_mfma_f32_16x16x32_bf16 v[114:117], v[170:173], v[202:205], v[114:117]
	v_mfma_f32_16x16x32_bf16 v[110:113], v[174:177], v[198:201], v[110:113]
	v_mfma_f32_16x16x32_bf16 v[110:113], v[178:181], v[202:205], v[110:113]
	v_mfma_f32_16x16x32_bf16 v[122:125], v[190:193], v[198:201], v[122:125]
	v_mfma_f32_16x16x32_bf16 v[122:125], v[194:197], v[202:205], v[122:125]
	v_mfma_f32_16x16x32_bf16 v[126:129], v[182:185], v[198:201], v[126:129]
	v_mfma_f32_16x16x32_bf16 v[126:129], v[186:189], v[202:205], v[126:129]
	v_mfma_f32_16x16x32_bf16 v[118:121], v[182:185], v[228:231], v[118:121]
	v_mfma_f32_16x16x32_bf16 v[118:121], v[186:189], v[232:235], v[118:121]
	v_mfma_f32_16x16x32_bf16 v[98:101], v[190:193], v[228:231], v[98:101]
	v_mfma_f32_16x16x32_bf16 v[98:101], v[194:197], v[232:235], v[98:101]
	v_mfma_f32_16x16x32_bf16 v[102:105], v[174:177], v[228:231], v[102:105]
	v_mfma_f32_16x16x32_bf16 v[102:105], v[178:181], v[232:235], v[102:105]
	v_mfma_f32_16x16x32_bf16 v[106:109], v[142:145], v[228:231], v[106:109]
	v_mfma_f32_16x16x32_bf16 v[106:109], v[170:173], v[232:235], v[106:109]
	v_mfma_f32_16x16x32_bf16 v[94:97], v[142:145], v[236:239], v[94:97]
	v_mfma_f32_16x16x32_bf16 v[94:97], v[170:173], v[240:243], v[94:97]
	v_mfma_f32_16x16x32_bf16 v[86:89], v[174:177], v[236:239], v[86:89]
	v_mfma_f32_16x16x32_bf16 v[86:89], v[178:181], v[240:243], v[86:89]
	v_mfma_f32_16x16x32_bf16 v[82:85], v[190:193], v[236:239], v[82:85]
	v_mfma_f32_16x16x32_bf16 v[82:85], v[194:197], v[240:243], v[82:85]
	v_mfma_f32_16x16x32_bf16 v[90:93], v[182:185], v[236:239], v[90:93]
	v_mfma_f32_16x16x32_bf16 v[90:93], v[186:189], v[240:243], v[90:93]
	v_mfma_f32_16x16x32_bf16 v[74:77], v[182:185], v[244:247], v[74:77]
	v_mfma_f32_16x16x32_bf16 v[74:77], v[186:189], v[248:251], v[74:77]
	v_mfma_f32_16x16x32_bf16 v[66:69], v[190:193], v[244:247], v[66:69]
	v_mfma_f32_16x16x32_bf16 v[66:69], v[194:197], v[248:251], v[66:69]
	v_mfma_f32_16x16x32_bf16 v[70:73], v[174:177], v[244:247], v[70:73]
	v_mfma_f32_16x16x32_bf16 v[70:73], v[178:181], v[248:251], v[70:73]
	v_mfma_f32_16x16x32_bf16 v[78:81], v[142:145], v[244:247], v[78:81]
	v_mfma_f32_16x16x32_bf16 v[78:81], v[170:173], v[248:251], v[78:81]
	s_barrier
	s_setprio 0
	s_or_b32 s53, s52, 0x80
	s_mov_b32 m0, s31
	ds_read_b128 v[198:201], v138 offset:49152
	buffer_load_dwordx4 v133, s[40:43], s53 offen lds
	s_add_i32 s52, s52, 0x80080
	s_mov_b32 m0, s33
	ds_read_b128 v[202:205], v138 offset:50176
	buffer_load_dwordx4 v135, s[40:43], s53 offen lds
	s_mov_b32 m0, s68
	ds_read_b128 v[228:231], v138 offset:51200
	buffer_load_dwordx4 v133, s[40:43], s52 offen lds
	s_mov_b32 m0, s69
	ds_read_b128 v[232:235], v138 offset:52224
	buffer_load_dwordx4 v135, s[40:43], s52 offen lds
	s_mov_b32 m0, s36
	ds_read_b128 v[236:239], v138 offset:53248
	buffer_load_dwordx4 v132, s[60:63], vcc_hi offen lds
	s_mov_b32 m0, s37
	ds_read_b128 v[240:243], v138 offset:54272
	buffer_load_dwordx4 v134, s[60:63], vcc_hi offen lds
	ds_read_b128 v[244:247], v138 offset:55296
	ds_read_b128 v[248:251], v138 offset:56320
	s_waitcnt vmcnt(8)
	s_waitcnt lgkmcnt(0)
	s_setprio 1
	s_barrier
	v_mfma_f32_16x16x32_bf16 v[62:65], v[142:145], v[198:201], v[62:65]
	v_mfma_f32_16x16x32_bf16 v[62:65], v[170:173], v[202:205], v[62:65]
	v_mfma_f32_16x16x32_bf16 v[54:57], v[174:177], v[198:201], v[54:57]
	v_mfma_f32_16x16x32_bf16 v[54:57], v[178:181], v[202:205], v[54:57]
	v_mfma_f32_16x16x32_bf16 v[50:53], v[190:193], v[198:201], v[50:53]
	v_mfma_f32_16x16x32_bf16 v[50:53], v[194:197], v[202:205], v[50:53]
	v_mfma_f32_16x16x32_bf16 v[58:61], v[182:185], v[198:201], v[58:61]
	v_mfma_f32_16x16x32_bf16 v[58:61], v[186:189], v[202:205], v[58:61]
	v_mfma_f32_16x16x32_bf16 v[42:45], v[182:185], v[228:231], v[42:45]
	v_mfma_f32_16x16x32_bf16 v[42:45], v[186:189], v[232:235], v[42:45]
	v_mfma_f32_16x16x32_bf16 v[34:37], v[190:193], v[228:231], v[34:37]
	v_mfma_f32_16x16x32_bf16 v[34:37], v[194:197], v[232:235], v[34:37]
	v_mfma_f32_16x16x32_bf16 v[38:41], v[174:177], v[228:231], v[38:41]
	v_mfma_f32_16x16x32_bf16 v[38:41], v[178:181], v[232:235], v[38:41]
	v_mfma_f32_16x16x32_bf16 v[46:49], v[142:145], v[228:231], v[46:49]
	v_mfma_f32_16x16x32_bf16 v[46:49], v[170:173], v[232:235], v[46:49]
	v_mfma_f32_16x16x32_bf16 v[30:33], v[142:145], v[236:239], v[30:33]
	v_mfma_f32_16x16x32_bf16 v[30:33], v[170:173], v[240:243], v[30:33]
	v_mfma_f32_16x16x32_bf16 v[22:25], v[174:177], v[236:239], v[22:25]
	v_mfma_f32_16x16x32_bf16 v[22:25], v[178:181], v[240:243], v[22:25]
	v_mfma_f32_16x16x32_bf16 v[18:21], v[190:193], v[236:239], v[18:21]
	v_mfma_f32_16x16x32_bf16 v[18:21], v[194:197], v[240:243], v[18:21]
	v_mfma_f32_16x16x32_bf16 v[26:29], v[182:185], v[236:239], v[26:29]
	v_mfma_f32_16x16x32_bf16 v[26:29], v[186:189], v[240:243], v[26:29]
	v_mfma_f32_16x16x32_bf16 v[10:13], v[182:185], v[244:247], v[10:13]
	v_mfma_f32_16x16x32_bf16 v[10:13], v[186:189], v[248:251], v[10:13]
	v_mfma_f32_16x16x32_bf16 v[2:5], v[190:193], v[244:247], v[2:5]
	v_mfma_f32_16x16x32_bf16 v[2:5], v[194:197], v[248:251], v[2:5]
	v_mfma_f32_16x16x32_bf16 v[6:9], v[174:177], v[244:247], v[6:9]
	v_mfma_f32_16x16x32_bf16 v[6:9], v[178:181], v[248:251], v[6:9]
	v_mfma_f32_16x16x32_bf16 v[14:17], v[142:145], v[244:247], v[14:17]
	v_mfma_f32_16x16x32_bf16 v[14:17], v[170:173], v[248:251], v[14:17]
	s_barrier
	s_setprio 0
	s_add_i32 vcc_lo, vcc_lo, 2
	s_addk_i32 s94, 0x100
	s_addk_i32 s95, 0x100
	s_cmp_gt_u32 vcc_lo, 29
.LBB0_304:
	ds_read_b128 v[142:145], v136
	ds_read_b128 v[170:173], v136 offset:1024
	ds_read_b128 v[174:177], v136 offset:2048
	ds_read_b128 v[178:181], v136 offset:3072
	ds_read_b128 v[182:185], v137
	ds_read_b128 v[186:189], v137 offset:1024
	ds_read_b128 v[190:193], v137 offset:2048
	ds_read_b128 v[194:197], v137 offset:3072
	s_add_i32 s42, s94, 0xfff80080
	s_cmp_eq_u32 vcc_lo, 28
	s_cselect_b32 s97, s8, s42
	s_cselect_b32 s52, s9, s95
	s_or_b32 vcc_hi, s97, 0x80
	s_mov_b32 m0, s72
	ds_read_b128 v[198:201], v138
	ds_read_b128 v[202:205], v138 offset:1024
	ds_read_b128 v[228:231], v138 offset:2048
	ds_read_b128 v[232:235], v138 offset:3072
	ds_read_b128 v[236:239], v138 offset:4096
	ds_read_b128 v[240:243], v138 offset:5120
	ds_read_b128 v[244:247], v138 offset:6144
	ds_read_b128 v[248:251], v138 offset:7168
	buffer_load_dwordx4 v132, s[60:63], s94 offen lds
	s_mov_b32 m0, s47
	s_nop 0
	buffer_load_dwordx4 v134, s[60:63], s94 offen lds
	s_waitcnt vmcnt(8)
	s_waitcnt lgkmcnt(0)
	s_setprio 1
	s_barrier
	v_mfma_f32_16x16x32_bf16 v[114:117], v[142:145], v[198:201], v[114:117]
	v_mfma_f32_16x16x32_bf16 v[114:117], v[170:173], v[202:205], v[114:117]
	v_mfma_f32_16x16x32_bf16 v[110:113], v[174:177], v[198:201], v[110:113]
	v_mfma_f32_16x16x32_bf16 v[110:113], v[178:181], v[202:205], v[110:113]
	v_mfma_f32_16x16x32_bf16 v[122:125], v[190:193], v[198:201], v[122:125]
	v_mfma_f32_16x16x32_bf16 v[122:125], v[194:197], v[202:205], v[122:125]
	v_mfma_f32_16x16x32_bf16 v[126:129], v[182:185], v[198:201], v[126:129]
	v_mfma_f32_16x16x32_bf16 v[126:129], v[186:189], v[202:205], v[126:129]
	v_mfma_f32_16x16x32_bf16 v[118:121], v[182:185], v[228:231], v[118:121]
	v_mfma_f32_16x16x32_bf16 v[118:121], v[186:189], v[232:235], v[118:121]
	v_mfma_f32_16x16x32_bf16 v[98:101], v[190:193], v[228:231], v[98:101]
	v_mfma_f32_16x16x32_bf16 v[98:101], v[194:197], v[232:235], v[98:101]
	v_mfma_f32_16x16x32_bf16 v[102:105], v[174:177], v[228:231], v[102:105]
	v_mfma_f32_16x16x32_bf16 v[102:105], v[178:181], v[232:235], v[102:105]
	v_mfma_f32_16x16x32_bf16 v[106:109], v[142:145], v[228:231], v[106:109]
	v_mfma_f32_16x16x32_bf16 v[106:109], v[170:173], v[232:235], v[106:109]
	v_mfma_f32_16x16x32_bf16 v[94:97], v[142:145], v[236:239], v[94:97]
	v_mfma_f32_16x16x32_bf16 v[94:97], v[170:173], v[240:243], v[94:97]
	v_mfma_f32_16x16x32_bf16 v[86:89], v[174:177], v[236:239], v[86:89]
	v_mfma_f32_16x16x32_bf16 v[86:89], v[178:181], v[240:243], v[86:89]
	v_mfma_f32_16x16x32_bf16 v[82:85], v[190:193], v[236:239], v[82:85]
	v_mfma_f32_16x16x32_bf16 v[82:85], v[194:197], v[240:243], v[82:85]
	v_mfma_f32_16x16x32_bf16 v[90:93], v[182:185], v[236:239], v[90:93]
	v_mfma_f32_16x16x32_bf16 v[90:93], v[186:189], v[240:243], v[90:93]
	v_mfma_f32_16x16x32_bf16 v[74:77], v[182:185], v[244:247], v[74:77]
	v_mfma_f32_16x16x32_bf16 v[74:77], v[186:189], v[248:251], v[74:77]
	v_mfma_f32_16x16x32_bf16 v[66:69], v[190:193], v[244:247], v[66:69]
	v_mfma_f32_16x16x32_bf16 v[66:69], v[194:197], v[248:251], v[66:69]
	v_mfma_f32_16x16x32_bf16 v[70:73], v[174:177], v[244:247], v[70:73]
	v_mfma_f32_16x16x32_bf16 v[70:73], v[178:181], v[248:251], v[70:73]
	v_mfma_f32_16x16x32_bf16 v[78:81], v[142:145], v[244:247], v[78:81]
	v_mfma_f32_16x16x32_bf16 v[78:81], v[170:173], v[248:251], v[78:81]
	s_barrier
	s_setprio 0
	s_mov_b32 s42, s62
	s_mov_b32 s43, s63
	s_mov_b32 m0, s13
	ds_read_b128 v[198:201], v138 offset:16384
	buffer_load_dwordx4 v133, s[40:43], s52 offen lds
	s_add_i32 s96, s52, 0x80000
	s_mov_b32 m0, s14
	ds_read_b128 v[202:205], v138 offset:17408
	buffer_load_dwordx4 v135, s[40:43], s52 offen lds
	s_mov_b32 m0, s15
	ds_read_b128 v[228:231], v138 offset:18432
	buffer_load_dwordx4 v133, s[40:43], s96 offen lds
	s_mov_b32 m0, s16
	ds_read_b128 v[232:235], v138 offset:19456
	buffer_load_dwordx4 v135, s[40:43], s96 offen lds
	s_mov_b32 m0, s2
	ds_read_b128 v[236:239], v138 offset:20480
	buffer_load_dwordx4 v132, s[60:63], s97 offen lds
	s_mov_b32 m0, s21
	ds_read_b128 v[240:243], v138 offset:21504
	buffer_load_dwordx4 v134, s[60:63], s97 offen lds
	ds_read_b128 v[244:247], v138 offset:22528
	ds_read_b128 v[248:251], v138 offset:23552
	s_waitcnt vmcnt(8)
	s_waitcnt lgkmcnt(0)
	s_setprio 1
	s_barrier
	v_mfma_f32_16x16x32_bf16 v[62:65], v[142:145], v[198:201], v[62:65]
	v_mfma_f32_16x16x32_bf16 v[62:65], v[170:173], v[202:205], v[62:65]
	v_mfma_f32_16x16x32_bf16 v[54:57], v[174:177], v[198:201], v[54:57]
	v_mfma_f32_16x16x32_bf16 v[54:57], v[178:181], v[202:205], v[54:57]
	v_mfma_f32_16x16x32_bf16 v[50:53], v[190:193], v[198:201], v[50:53]
	v_mfma_f32_16x16x32_bf16 v[50:53], v[194:197], v[202:205], v[50:53]
	v_mfma_f32_16x16x32_bf16 v[58:61], v[182:185], v[198:201], v[58:61]
	v_mfma_f32_16x16x32_bf16 v[58:61], v[186:189], v[202:205], v[58:61]
	v_mfma_f32_16x16x32_bf16 v[42:45], v[182:185], v[228:231], v[42:45]
	v_mfma_f32_16x16x32_bf16 v[42:45], v[186:189], v[232:235], v[42:45]
	v_mfma_f32_16x16x32_bf16 v[34:37], v[190:193], v[228:231], v[34:37]
	v_mfma_f32_16x16x32_bf16 v[34:37], v[194:197], v[232:235], v[34:37]
	v_mfma_f32_16x16x32_bf16 v[38:41], v[174:177], v[228:231], v[38:41]
	v_mfma_f32_16x16x32_bf16 v[38:41], v[178:181], v[232:235], v[38:41]
	v_mfma_f32_16x16x32_bf16 v[46:49], v[142:145], v[228:231], v[46:49]
	v_mfma_f32_16x16x32_bf16 v[46:49], v[170:173], v[232:235], v[46:49]
	v_mfma_f32_16x16x32_bf16 v[30:33], v[142:145], v[236:239], v[30:33]
	v_mfma_f32_16x16x32_bf16 v[30:33], v[170:173], v[240:243], v[30:33]
	v_mfma_f32_16x16x32_bf16 v[22:25], v[174:177], v[236:239], v[22:25]
	v_mfma_f32_16x16x32_bf16 v[22:25], v[178:181], v[240:243], v[22:25]
	v_mfma_f32_16x16x32_bf16 v[18:21], v[190:193], v[236:239], v[18:21]
	v_mfma_f32_16x16x32_bf16 v[18:21], v[194:197], v[240:243], v[18:21]
	v_mfma_f32_16x16x32_bf16 v[26:29], v[182:185], v[236:239], v[26:29]
	v_mfma_f32_16x16x32_bf16 v[26:29], v[186:189], v[240:243], v[26:29]
	v_mfma_f32_16x16x32_bf16 v[10:13], v[182:185], v[244:247], v[10:13]
	v_mfma_f32_16x16x32_bf16 v[10:13], v[186:189], v[248:251], v[10:13]
	v_mfma_f32_16x16x32_bf16 v[2:5], v[190:193], v[244:247], v[2:5]
	v_mfma_f32_16x16x32_bf16 v[2:5], v[194:197], v[248:251], v[2:5]
	v_mfma_f32_16x16x32_bf16 v[6:9], v[174:177], v[244:247], v[6:9]
	v_mfma_f32_16x16x32_bf16 v[6:9], v[178:181], v[248:251], v[6:9]
	v_mfma_f32_16x16x32_bf16 v[14:17], v[142:145], v[244:247], v[14:17]
	v_mfma_f32_16x16x32_bf16 v[14:17], v[170:173], v[248:251], v[14:17]
	s_barrier
	s_setprio 0
	ds_read_b128 v[142:145], v139
	ds_read_b128 v[170:173], v139 offset:1024
	ds_read_b128 v[174:177], v139 offset:2048
	ds_read_b128 v[178:181], v139 offset:3072
	ds_read_b128 v[182:185], v140
	ds_read_b128 v[186:189], v140 offset:1024
	ds_read_b128 v[190:193], v140 offset:2048
	ds_read_b128 v[194:197], v140 offset:3072
	s_add_i32 s97, s97, 0x80000
	s_mov_b32 m0, s23
	ds_read_b128 v[198:201], v138 offset:32768
	ds_read_b128 v[202:205], v138 offset:33792
	ds_read_b128 v[228:231], v138 offset:34816
	ds_read_b128 v[232:235], v138 offset:35840
	ds_read_b128 v[236:239], v138 offset:36864
	ds_read_b128 v[240:243], v138 offset:37888
	ds_read_b128 v[244:247], v138 offset:38912
	ds_read_b128 v[248:251], v138 offset:39936
	buffer_load_dwordx4 v132, s[60:63], s97 offen lds
	s_mov_b32 m0, s24
	s_nop 0
	buffer_load_dwordx4 v134, s[60:63], s97 offen lds
	s_waitcnt vmcnt(8)
	s_waitcnt lgkmcnt(0)
	s_setprio 1
	s_barrier
	v_mfma_f32_16x16x32_bf16 v[114:117], v[142:145], v[198:201], v[114:117]
	v_mfma_f32_16x16x32_bf16 v[114:117], v[170:173], v[202:205], v[114:117]
	v_mfma_f32_16x16x32_bf16 v[110:113], v[174:177], v[198:201], v[110:113]
	v_mfma_f32_16x16x32_bf16 v[110:113], v[178:181], v[202:205], v[110:113]
	v_mfma_f32_16x16x32_bf16 v[122:125], v[190:193], v[198:201], v[122:125]
	v_mfma_f32_16x16x32_bf16 v[122:125], v[194:197], v[202:205], v[122:125]
	v_mfma_f32_16x16x32_bf16 v[126:129], v[182:185], v[198:201], v[126:129]
	v_mfma_f32_16x16x32_bf16 v[126:129], v[186:189], v[202:205], v[126:129]
	v_mfma_f32_16x16x32_bf16 v[118:121], v[182:185], v[228:231], v[118:121]
	v_mfma_f32_16x16x32_bf16 v[118:121], v[186:189], v[232:235], v[118:121]
	v_mfma_f32_16x16x32_bf16 v[98:101], v[190:193], v[228:231], v[98:101]
	v_mfma_f32_16x16x32_bf16 v[98:101], v[194:197], v[232:235], v[98:101]
	v_mfma_f32_16x16x32_bf16 v[102:105], v[174:177], v[228:231], v[102:105]
	v_mfma_f32_16x16x32_bf16 v[102:105], v[178:181], v[232:235], v[102:105]
	v_mfma_f32_16x16x32_bf16 v[106:109], v[142:145], v[228:231], v[106:109]
	v_mfma_f32_16x16x32_bf16 v[106:109], v[170:173], v[232:235], v[106:109]
	v_mfma_f32_16x16x32_bf16 v[94:97], v[142:145], v[236:239], v[94:97]
	v_mfma_f32_16x16x32_bf16 v[94:97], v[170:173], v[240:243], v[94:97]
	v_mfma_f32_16x16x32_bf16 v[86:89], v[174:177], v[236:239], v[86:89]
	v_mfma_f32_16x16x32_bf16 v[86:89], v[178:181], v[240:243], v[86:89]
	v_mfma_f32_16x16x32_bf16 v[82:85], v[190:193], v[236:239], v[82:85]
	v_mfma_f32_16x16x32_bf16 v[82:85], v[194:197], v[240:243], v[82:85]
	v_mfma_f32_16x16x32_bf16 v[90:93], v[182:185], v[236:239], v[90:93]
	v_mfma_f32_16x16x32_bf16 v[90:93], v[186:189], v[240:243], v[90:93]
	v_mfma_f32_16x16x32_bf16 v[74:77], v[182:185], v[244:247], v[74:77]
	v_mfma_f32_16x16x32_bf16 v[74:77], v[186:189], v[248:251], v[74:77]
	v_mfma_f32_16x16x32_bf16 v[66:69], v[190:193], v[244:247], v[66:69]
	v_mfma_f32_16x16x32_bf16 v[66:69], v[194:197], v[248:251], v[66:69]
	v_mfma_f32_16x16x32_bf16 v[70:73], v[174:177], v[244:247], v[70:73]
	v_mfma_f32_16x16x32_bf16 v[70:73], v[178:181], v[248:251], v[70:73]
	v_mfma_f32_16x16x32_bf16 v[78:81], v[142:145], v[244:247], v[78:81]
	v_mfma_f32_16x16x32_bf16 v[78:81], v[170:173], v[248:251], v[78:81]
	s_barrier
	s_setprio 0
	s_or_b32 s53, s52, 0x80
	s_mov_b32 m0, s31
	ds_read_b128 v[198:201], v138 offset:49152
	buffer_load_dwordx4 v133, s[40:43], s53 offen lds
	s_add_i32 s52, s52, 0x80080
	s_mov_b32 m0, s33
	ds_read_b128 v[202:205], v138 offset:50176
	buffer_load_dwordx4 v135, s[40:43], s53 offen lds
	s_mov_b32 m0, s68
	ds_read_b128 v[228:231], v138 offset:51200
	buffer_load_dwordx4 v133, s[40:43], s52 offen lds
	s_mov_b32 m0, s69
	ds_read_b128 v[232:235], v138 offset:52224
	buffer_load_dwordx4 v135, s[40:43], s52 offen lds
	s_mov_b32 m0, s36
	ds_read_b128 v[236:239], v138 offset:53248
	buffer_load_dwordx4 v132, s[60:63], vcc_hi offen lds
	s_mov_b32 m0, s37
	ds_read_b128 v[240:243], v138 offset:54272
	buffer_load_dwordx4 v134, s[60:63], vcc_hi offen lds
	ds_read_b128 v[244:247], v138 offset:55296
	ds_read_b128 v[248:251], v138 offset:56320
	s_waitcnt vmcnt(8)
	s_waitcnt lgkmcnt(0)
	s_setprio 1
	s_barrier
	v_mfma_f32_16x16x32_bf16 v[62:65], v[142:145], v[198:201], v[62:65]
	v_mfma_f32_16x16x32_bf16 v[62:65], v[170:173], v[202:205], v[62:65]
	v_mfma_f32_16x16x32_bf16 v[54:57], v[174:177], v[198:201], v[54:57]
	v_mfma_f32_16x16x32_bf16 v[54:57], v[178:181], v[202:205], v[54:57]
	v_mfma_f32_16x16x32_bf16 v[50:53], v[190:193], v[198:201], v[50:53]
	v_mfma_f32_16x16x32_bf16 v[50:53], v[194:197], v[202:205], v[50:53]
	v_mfma_f32_16x16x32_bf16 v[58:61], v[182:185], v[198:201], v[58:61]
	v_mfma_f32_16x16x32_bf16 v[58:61], v[186:189], v[202:205], v[58:61]
	v_mfma_f32_16x16x32_bf16 v[42:45], v[182:185], v[228:231], v[42:45]
	v_mfma_f32_16x16x32_bf16 v[42:45], v[186:189], v[232:235], v[42:45]
	v_mfma_f32_16x16x32_bf16 v[34:37], v[190:193], v[228:231], v[34:37]
	v_mfma_f32_16x16x32_bf16 v[34:37], v[194:197], v[232:235], v[34:37]
	v_mfma_f32_16x16x32_bf16 v[38:41], v[174:177], v[228:231], v[38:41]
	v_mfma_f32_16x16x32_bf16 v[38:41], v[178:181], v[232:235], v[38:41]
	v_mfma_f32_16x16x32_bf16 v[46:49], v[142:145], v[228:231], v[46:49]
	v_mfma_f32_16x16x32_bf16 v[46:49], v[170:173], v[232:235], v[46:49]
	v_mfma_f32_16x16x32_bf16 v[30:33], v[142:145], v[236:239], v[30:33]
	v_mfma_f32_16x16x32_bf16 v[30:33], v[170:173], v[240:243], v[30:33]
	v_mfma_f32_16x16x32_bf16 v[22:25], v[174:177], v[236:239], v[22:25]
	v_mfma_f32_16x16x32_bf16 v[22:25], v[178:181], v[240:243], v[22:25]
	v_mfma_f32_16x16x32_bf16 v[18:21], v[190:193], v[236:239], v[18:21]
	v_mfma_f32_16x16x32_bf16 v[18:21], v[194:197], v[240:243], v[18:21]
	v_mfma_f32_16x16x32_bf16 v[26:29], v[182:185], v[236:239], v[26:29]
	v_mfma_f32_16x16x32_bf16 v[26:29], v[186:189], v[240:243], v[26:29]
	v_mfma_f32_16x16x32_bf16 v[10:13], v[182:185], v[244:247], v[10:13]
	v_mfma_f32_16x16x32_bf16 v[10:13], v[186:189], v[248:251], v[10:13]
	v_mfma_f32_16x16x32_bf16 v[2:5], v[190:193], v[244:247], v[2:5]
	v_mfma_f32_16x16x32_bf16 v[2:5], v[194:197], v[248:251], v[2:5]
	v_mfma_f32_16x16x32_bf16 v[6:9], v[174:177], v[244:247], v[6:9]
	v_mfma_f32_16x16x32_bf16 v[6:9], v[178:181], v[248:251], v[6:9]
	v_mfma_f32_16x16x32_bf16 v[14:17], v[142:145], v[244:247], v[14:17]
	v_mfma_f32_16x16x32_bf16 v[14:17], v[170:173], v[248:251], v[14:17]
	s_barrier
	s_setprio 0
	s_add_i32 vcc_lo, vcc_lo, 2
	s_addk_i32 s94, 0x100
	s_addk_i32 s95, 0x100
	s_cmp_gt_u32 vcc_lo, 29
	s_cbranch_scc0 .LBB0_304
	s_and_b64 vcc, exec, s[48:49]
	s_cbranch_vccz .LBB0_307
	s_barrier

.LBB0_579:
	s_mul_i32 s73, s72, 0x2c0000
	s_and_b64 s[8:9], s[42:43], exec
	s_mul_i32 s84, s71, 0x2c0000
	s_cselect_b32 s8, s73, s21
	s_cselect_b32 s9, s84, s13
	s_addk_i32 s13, 0x100
	s_add_i32 s21, s21, 0xc000
	s_mov_b32 s22, -2
	s_waitcnt lgkmcnt(0)
	v_add_u32_e32 v154, 0x10000, v140
	ds_read_b128 v[132:135], v154
	ds_read_b128 v[142:145], v154 offset:1024
	ds_read_b128 v[170:173], v154 offset:2048
	ds_read_b128 v[174:177], v154 offset:3072
	v_add_u32_e32 v154, 0x14000, v140
	ds_read_b128 v[178:181], v154
	ds_read_b128 v[182:185], v154 offset:1024
	ds_read_b128 v[186:189], v154 offset:2048
	ds_read_b128 v[190:193], v154 offset:3072
	s_add_i32 s23, s21, 0x4000
	s_cmpk_eq_i32 s22, 0x54
	s_cselect_b32 s27, s8, s23
	s_cselect_b32 s26, s9, s13
	s_or_b32 s23, s27, 0x8000
	s_mov_b32 m0, s68
	ds_read_b128 v[194:197], v141
	ds_read_b128 v[198:201], v141 offset:1024
	ds_read_b128 v[202:205], v141 offset:2048
	ds_read_b128 v[228:231], v141 offset:3072
	ds_read_b128 v[232:235], v141 offset:4096
	ds_read_b128 v[236:239], v141 offset:5120
	ds_read_b128 v[240:243], v141 offset:6144
	ds_read_b128 v[244:247], v141 offset:7168
	buffer_load_dwordx4 v136, s[60:63], s21 offen lds
	s_mov_b32 m0, s70
	s_nop 0
	buffer_load_dwordx4 v138, s[60:63], s21 offen lds
	s_waitcnt vmcnt(8)
	s_waitcnt lgkmcnt(0)
	s_setprio 1
	s_barrier
	v_mfma_f32_16x16x32_bf16 v[126:129], v[132:135], v[194:197], 0
	v_mfma_f32_16x16x32_bf16 v[126:129], v[142:145], v[198:201], v[126:129]
	v_mfma_f32_16x16x32_bf16 v[106:109], v[170:173], v[194:197], 0
	v_mfma_f32_16x16x32_bf16 v[106:109], v[174:177], v[198:201], v[106:109]
	v_mfma_f32_16x16x32_bf16 v[110:113], v[186:189], v[194:197], 0
	v_mfma_f32_16x16x32_bf16 v[110:113], v[190:193], v[198:201], v[110:113]
	v_mfma_f32_16x16x32_bf16 v[122:125], v[178:181], v[194:197], 0
	v_mfma_f32_16x16x32_bf16 v[122:125], v[182:185], v[198:201], v[122:125]
	v_mfma_f32_16x16x32_bf16 v[102:105], v[178:181], v[202:205], 0
	v_mfma_f32_16x16x32_bf16 v[102:105], v[182:185], v[228:231], v[102:105]
	v_mfma_f32_16x16x32_bf16 v[98:101], v[186:189], v[202:205], 0
	v_mfma_f32_16x16x32_bf16 v[98:101], v[190:193], v[228:231], v[98:101]
	v_mfma_f32_16x16x32_bf16 v[114:117], v[170:173], v[202:205], 0
	v_mfma_f32_16x16x32_bf16 v[114:117], v[174:177], v[228:231], v[114:117]
	v_mfma_f32_16x16x32_bf16 v[118:121], v[132:135], v[202:205], 0
	v_mfma_f32_16x16x32_bf16 v[118:121], v[142:145], v[228:231], v[118:121]
	v_mfma_f32_16x16x32_bf16 v[94:97], v[132:135], v[232:235], 0
	v_mfma_f32_16x16x32_bf16 v[94:97], v[142:145], v[236:239], v[94:97]
	v_mfma_f32_16x16x32_bf16 v[90:93], v[170:173], v[232:235], 0
	v_mfma_f32_16x16x32_bf16 v[90:93], v[174:177], v[236:239], v[90:93]
	v_mfma_f32_16x16x32_bf16 v[82:85], v[186:189], v[232:235], 0
	v_mfma_f32_16x16x32_bf16 v[82:85], v[190:193], v[236:239], v[82:85]
	v_mfma_f32_16x16x32_bf16 v[86:89], v[178:181], v[232:235], 0
	v_mfma_f32_16x16x32_bf16 v[86:89], v[182:185], v[236:239], v[86:89]
	v_mfma_f32_16x16x32_bf16 v[70:73], v[178:181], v[240:243], 0
	v_mfma_f32_16x16x32_bf16 v[70:73], v[182:185], v[244:247], v[70:73]
	v_mfma_f32_16x16x32_bf16 v[66:69], v[186:189], v[240:243], 0
	v_mfma_f32_16x16x32_bf16 v[66:69], v[190:193], v[244:247], v[66:69]
	v_mfma_f32_16x16x32_bf16 v[74:77], v[170:173], v[240:243], 0
	v_mfma_f32_16x16x32_bf16 v[74:77], v[174:177], v[244:247], v[74:77]
	v_mfma_f32_16x16x32_bf16 v[78:81], v[132:135], v[240:243], 0
	v_mfma_f32_16x16x32_bf16 v[78:81], v[142:145], v[244:247], v[78:81]
	s_barrier
	s_setprio 0
	s_mov_b32 s46, s62
	s_mov_b32 s47, s63
	s_mov_b32 m0, s15
	ds_read_b128 v[194:197], v141 offset:16384
	buffer_load_dwordx4 v137, s[44:47], s26 offen lds
	s_add_i32 s52, s26, 0x160000
	s_mov_b32 m0, s16
	ds_read_b128 v[198:201], v141 offset:17408
	buffer_load_dwordx4 v139, s[44:47], s26 offen lds
	s_mov_b32 m0, s18
	ds_read_b128 v[202:205], v141 offset:18432
	buffer_load_dwordx4 v137, s[44:47], s52 offen lds
	s_mov_b32 m0, s19
	ds_read_b128 v[228:231], v141 offset:19456
	buffer_load_dwordx4 v139, s[44:47], s52 offen lds
	s_mov_b32 m0, s14
	ds_read_b128 v[232:235], v141 offset:20480
	buffer_load_dwordx4 v136, s[60:63], s27 offen lds
	s_mov_b32 m0, s24
	ds_read_b128 v[236:239], v141 offset:21504
	buffer_load_dwordx4 v138, s[60:63], s27 offen lds
	ds_read_b128 v[240:243], v141 offset:22528
	ds_read_b128 v[244:247], v141 offset:23552
	s_waitcnt vmcnt(8)
	s_waitcnt lgkmcnt(0)
	s_setprio 1
	s_barrier
	v_mfma_f32_16x16x32_bf16 v[62:65], v[132:135], v[194:197], 0
	v_mfma_f32_16x16x32_bf16 v[62:65], v[142:145], v[198:201], v[62:65]
	v_mfma_f32_16x16x32_bf16 v[58:61], v[170:173], v[194:197], 0
	v_mfma_f32_16x16x32_bf16 v[58:61], v[174:177], v[198:201], v[58:61]
	v_mfma_f32_16x16x32_bf16 v[50:53], v[186:189], v[194:197], 0
	v_mfma_f32_16x16x32_bf16 v[50:53], v[190:193], v[198:201], v[50:53]
	v_mfma_f32_16x16x32_bf16 v[54:57], v[178:181], v[194:197], 0
	v_mfma_f32_16x16x32_bf16 v[54:57], v[182:185], v[198:201], v[54:57]
	v_mfma_f32_16x16x32_bf16 v[38:41], v[178:181], v[202:205], 0
	v_mfma_f32_16x16x32_bf16 v[38:41], v[182:185], v[228:231], v[38:41]
	v_mfma_f32_16x16x32_bf16 v[34:37], v[186:189], v[202:205], 0
	v_mfma_f32_16x16x32_bf16 v[34:37], v[190:193], v[228:231], v[34:37]
	v_mfma_f32_16x16x32_bf16 v[42:45], v[170:173], v[202:205], 0
	v_mfma_f32_16x16x32_bf16 v[42:45], v[174:177], v[228:231], v[42:45]
	v_mfma_f32_16x16x32_bf16 v[46:49], v[132:135], v[202:205], 0
	v_mfma_f32_16x16x32_bf16 v[46:49], v[142:145], v[228:231], v[46:49]
	v_mfma_f32_16x16x32_bf16 v[30:33], v[132:135], v[232:235], 0
	v_mfma_f32_16x16x32_bf16 v[30:33], v[142:145], v[236:239], v[30:33]
	v_mfma_f32_16x16x32_bf16 v[26:29], v[170:173], v[232:235], 0
	v_mfma_f32_16x16x32_bf16 v[26:29], v[174:177], v[236:239], v[26:29]
	v_mfma_f32_16x16x32_bf16 v[18:21], v[186:189], v[232:235], 0
	v_mfma_f32_16x16x32_bf16 v[18:21], v[190:193], v[236:239], v[18:21]
	v_mfma_f32_16x16x32_bf16 v[22:25], v[178:181], v[232:235], 0
	v_mfma_f32_16x16x32_bf16 v[22:25], v[182:185], v[236:239], v[22:25]
	v_mfma_f32_16x16x32_bf16 v[6:9], v[178:181], v[240:243], 0
	v_mfma_f32_16x16x32_bf16 v[6:9], v[182:185], v[244:247], v[6:9]
	v_mfma_f32_16x16x32_bf16 v[2:5], v[186:189], v[240:243], 0
	v_mfma_f32_16x16x32_bf16 v[2:5], v[190:193], v[244:247], v[2:5]
	v_mfma_f32_16x16x32_bf16 v[10:13], v[170:173], v[240:243], 0
	v_mfma_f32_16x16x32_bf16 v[10:13], v[174:177], v[244:247], v[10:13]
	v_mfma_f32_16x16x32_bf16 v[14:17], v[132:135], v[240:243], 0
	v_mfma_f32_16x16x32_bf16 v[14:17], v[142:145], v[244:247], v[14:17]
	s_barrier
	s_setprio 0
	v_add_u32_e32 v154, 0x18000, v140
	ds_read_b128 v[132:135], v154
	ds_read_b128 v[142:145], v154 offset:1024
	ds_read_b128 v[170:173], v154 offset:2048
	ds_read_b128 v[174:177], v154 offset:3072
	v_add_u32_e32 v154, 0x1c000, v140
	ds_read_b128 v[178:181], v154
	ds_read_b128 v[182:185], v154 offset:1024
	ds_read_b128 v[186:189], v154 offset:2048
	ds_read_b128 v[190:193], v154 offset:3072
	s_bitset1_b32 s27, 14
	s_mov_b32 m0, s25
	ds_read_b128 v[194:197], v141 offset:32768
	ds_read_b128 v[198:201], v141 offset:33792
	ds_read_b128 v[202:205], v141 offset:34816
	ds_read_b128 v[228:231], v141 offset:35840
	ds_read_b128 v[232:235], v141 offset:36864
	ds_read_b128 v[236:239], v141 offset:37888
	ds_read_b128 v[240:243], v141 offset:38912
	ds_read_b128 v[244:247], v141 offset:39936
	buffer_load_dwordx4 v136, s[60:63], s27 offen lds
	s_mov_b32 m0, s30
	s_nop 0
	buffer_load_dwordx4 v138, s[60:63], s27 offen lds
	s_waitcnt vmcnt(8)
	s_waitcnt lgkmcnt(0)
	s_setprio 1
	s_barrier
	v_mfma_f32_16x16x32_bf16 v[126:129], v[132:135], v[194:197], v[126:129]
	v_mfma_f32_16x16x32_bf16 v[126:129], v[142:145], v[198:201], v[126:129]
	v_mfma_f32_16x16x32_bf16 v[106:109], v[170:173], v[194:197], v[106:109]
	v_mfma_f32_16x16x32_bf16 v[106:109], v[174:177], v[198:201], v[106:109]
	v_mfma_f32_16x16x32_bf16 v[110:113], v[186:189], v[194:197], v[110:113]
	v_mfma_f32_16x16x32_bf16 v[110:113], v[190:193], v[198:201], v[110:113]
	v_mfma_f32_16x16x32_bf16 v[122:125], v[178:181], v[194:197], v[122:125]
	v_mfma_f32_16x16x32_bf16 v[122:125], v[182:185], v[198:201], v[122:125]
	v_mfma_f32_16x16x32_bf16 v[102:105], v[178:181], v[202:205], v[102:105]
	v_mfma_f32_16x16x32_bf16 v[102:105], v[182:185], v[228:231], v[102:105]
	v_mfma_f32_16x16x32_bf16 v[98:101], v[186:189], v[202:205], v[98:101]
	v_mfma_f32_16x16x32_bf16 v[98:101], v[190:193], v[228:231], v[98:101]
	v_mfma_f32_16x16x32_bf16 v[114:117], v[170:173], v[202:205], v[114:117]
	v_mfma_f32_16x16x32_bf16 v[114:117], v[174:177], v[228:231], v[114:117]
	v_mfma_f32_16x16x32_bf16 v[118:121], v[132:135], v[202:205], v[118:121]
	v_mfma_f32_16x16x32_bf16 v[118:121], v[142:145], v[228:231], v[118:121]
	v_mfma_f32_16x16x32_bf16 v[94:97], v[132:135], v[232:235], v[94:97]
	v_mfma_f32_16x16x32_bf16 v[94:97], v[142:145], v[236:239], v[94:97]
	v_mfma_f32_16x16x32_bf16 v[90:93], v[170:173], v[232:235], v[90:93]
	v_mfma_f32_16x16x32_bf16 v[90:93], v[174:177], v[236:239], v[90:93]
	v_mfma_f32_16x16x32_bf16 v[82:85], v[186:189], v[232:235], v[82:85]
	v_mfma_f32_16x16x32_bf16 v[82:85], v[190:193], v[236:239], v[82:85]
	v_mfma_f32_16x16x32_bf16 v[86:89], v[178:181], v[232:235], v[86:89]
	v_mfma_f32_16x16x32_bf16 v[86:89], v[182:185], v[236:239], v[86:89]
	v_mfma_f32_16x16x32_bf16 v[70:73], v[178:181], v[240:243], v[70:73]
	v_mfma_f32_16x16x32_bf16 v[70:73], v[182:185], v[244:247], v[70:73]
	v_mfma_f32_16x16x32_bf16 v[66:69], v[186:189], v[240:243], v[66:69]
	v_mfma_f32_16x16x32_bf16 v[66:69], v[190:193], v[244:247], v[66:69]
	v_mfma_f32_16x16x32_bf16 v[74:77], v[170:173], v[240:243], v[74:77]
	v_mfma_f32_16x16x32_bf16 v[74:77], v[174:177], v[244:247], v[74:77]
	v_mfma_f32_16x16x32_bf16 v[78:81], v[132:135], v[240:243], v[78:81]
	v_mfma_f32_16x16x32_bf16 v[78:81], v[142:145], v[244:247], v[78:81]
	s_barrier
	s_setprio 0
	s_or_b32 s27, s26, 0x80
	s_mov_b32 m0, s36
	ds_read_b128 v[194:197], v141 offset:49152
	buffer_load_dwordx4 v137, s[44:47], s27 offen lds
	s_add_i32 s26, s26, 0x160080
	s_mov_b32 m0, s37
	ds_read_b128 v[198:201], v141 offset:50176
	buffer_load_dwordx4 v139, s[44:47], s27 offen lds
	s_mov_b32 m0, s66
	ds_read_b128 v[202:205], v141 offset:51200
	buffer_load_dwordx4 v137, s[44:47], s26 offen lds
	s_mov_b32 m0, s67
	ds_read_b128 v[228:231], v141 offset:52224
	buffer_load_dwordx4 v139, s[44:47], s26 offen lds
	s_mov_b32 m0, s48
	ds_read_b128 v[232:235], v141 offset:53248
	buffer_load_dwordx4 v136, s[60:63], s23 offen lds
	s_mov_b32 m0, s49
	ds_read_b128 v[236:239], v141 offset:54272
	buffer_load_dwordx4 v138, s[60:63], s23 offen lds
	ds_read_b128 v[240:243], v141 offset:55296
	ds_read_b128 v[244:247], v141 offset:56320
	s_waitcnt vmcnt(8)
	s_waitcnt lgkmcnt(0)
	s_setprio 1
	s_barrier
	v_mfma_f32_16x16x32_bf16 v[62:65], v[132:135], v[194:197], v[62:65]
	v_mfma_f32_16x16x32_bf16 v[62:65], v[142:145], v[198:201], v[62:65]
	v_mfma_f32_16x16x32_bf16 v[58:61], v[170:173], v[194:197], v[58:61]
	v_mfma_f32_16x16x32_bf16 v[58:61], v[174:177], v[198:201], v[58:61]
	v_mfma_f32_16x16x32_bf16 v[50:53], v[186:189], v[194:197], v[50:53]
	v_mfma_f32_16x16x32_bf16 v[50:53], v[190:193], v[198:201], v[50:53]
	v_mfma_f32_16x16x32_bf16 v[54:57], v[178:181], v[194:197], v[54:57]
	v_mfma_f32_16x16x32_bf16 v[54:57], v[182:185], v[198:201], v[54:57]
	v_mfma_f32_16x16x32_bf16 v[38:41], v[178:181], v[202:205], v[38:41]
	v_mfma_f32_16x16x32_bf16 v[38:41], v[182:185], v[228:231], v[38:41]
	v_mfma_f32_16x16x32_bf16 v[34:37], v[186:189], v[202:205], v[34:37]
	v_mfma_f32_16x16x32_bf16 v[34:37], v[190:193], v[228:231], v[34:37]
	v_mfma_f32_16x16x32_bf16 v[42:45], v[170:173], v[202:205], v[42:45]
	v_mfma_f32_16x16x32_bf16 v[42:45], v[174:177], v[228:231], v[42:45]
	v_mfma_f32_16x16x32_bf16 v[46:49], v[132:135], v[202:205], v[46:49]
	v_mfma_f32_16x16x32_bf16 v[46:49], v[142:145], v[228:231], v[46:49]
	v_mfma_f32_16x16x32_bf16 v[30:33], v[132:135], v[232:235], v[30:33]
	v_mfma_f32_16x16x32_bf16 v[30:33], v[142:145], v[236:239], v[30:33]
	v_mfma_f32_16x16x32_bf16 v[26:29], v[170:173], v[232:235], v[26:29]
	v_mfma_f32_16x16x32_bf16 v[26:29], v[174:177], v[236:239], v[26:29]
	v_mfma_f32_16x16x32_bf16 v[18:21], v[186:189], v[232:235], v[18:21]
	v_mfma_f32_16x16x32_bf16 v[18:21], v[190:193], v[236:239], v[18:21]
	v_mfma_f32_16x16x32_bf16 v[22:25], v[178:181], v[232:235], v[22:25]
	v_mfma_f32_16x16x32_bf16 v[22:25], v[182:185], v[236:239], v[22:25]
	v_mfma_f32_16x16x32_bf16 v[6:9], v[178:181], v[240:243], v[6:9]
	v_mfma_f32_16x16x32_bf16 v[6:9], v[182:185], v[244:247], v[6:9]
	v_mfma_f32_16x16x32_bf16 v[2:5], v[186:189], v[240:243], v[2:5]
	v_mfma_f32_16x16x32_bf16 v[2:5], v[190:193], v[244:247], v[2:5]
	v_mfma_f32_16x16x32_bf16 v[10:13], v[170:173], v[240:243], v[10:13]
	v_mfma_f32_16x16x32_bf16 v[10:13], v[174:177], v[244:247], v[10:13]
	v_mfma_f32_16x16x32_bf16 v[14:17], v[132:135], v[240:243], v[14:17]
	v_mfma_f32_16x16x32_bf16 v[14:17], v[142:145], v[244:247], v[14:17]
	s_barrier
	s_setprio 0
	s_addk_i32 s13, 0x100
	s_add_i32 s22, s22, 2
	s_add_i32 s21, s21, 0x10000
	s_cmpk_gt_u32 s22, 0x55
.LBB0_580:
	v_add_u32_e32 v154, 0x10000, v140
	ds_read_b128 v[132:135], v154
	ds_read_b128 v[142:145], v154 offset:1024
	ds_read_b128 v[170:173], v154 offset:2048
	ds_read_b128 v[174:177], v154 offset:3072
	v_add_u32_e32 v154, 0x14000, v140
	ds_read_b128 v[178:181], v154
	ds_read_b128 v[182:185], v154 offset:1024
	ds_read_b128 v[186:189], v154 offset:2048
	ds_read_b128 v[190:193], v154 offset:3072
	s_add_i32 s23, s21, 0x4000
	s_cmpk_eq_i32 s22, 0x54
	s_cselect_b32 s27, s8, s23
	s_cselect_b32 s26, s9, s13
	s_or_b32 s23, s27, 0x8000
	s_mov_b32 m0, s68
	ds_read_b128 v[194:197], v141
	ds_read_b128 v[198:201], v141 offset:1024
	ds_read_b128 v[202:205], v141 offset:2048
	ds_read_b128 v[228:231], v141 offset:3072
	ds_read_b128 v[232:235], v141 offset:4096
	ds_read_b128 v[236:239], v141 offset:5120
	ds_read_b128 v[240:243], v141 offset:6144
	ds_read_b128 v[244:247], v141 offset:7168
	buffer_load_dwordx4 v136, s[60:63], s21 offen lds
	s_mov_b32 m0, s70
	s_nop 0
	buffer_load_dwordx4 v138, s[60:63], s21 offen lds
	s_waitcnt vmcnt(8)
	s_waitcnt lgkmcnt(0)
	s_setprio 1
	s_barrier
	v_mfma_f32_16x16x32_bf16 v[126:129], v[132:135], v[194:197], v[126:129]
	v_mfma_f32_16x16x32_bf16 v[126:129], v[142:145], v[198:201], v[126:129]
	v_mfma_f32_16x16x32_bf16 v[106:109], v[170:173], v[194:197], v[106:109]
	v_mfma_f32_16x16x32_bf16 v[106:109], v[174:177], v[198:201], v[106:109]
	v_mfma_f32_16x16x32_bf16 v[110:113], v[186:189], v[194:197], v[110:113]
	v_mfma_f32_16x16x32_bf16 v[110:113], v[190:193], v[198:201], v[110:113]
	v_mfma_f32_16x16x32_bf16 v[122:125], v[178:181], v[194:197], v[122:125]
	v_mfma_f32_16x16x32_bf16 v[122:125], v[182:185], v[198:201], v[122:125]
	v_mfma_f32_16x16x32_bf16 v[102:105], v[178:181], v[202:205], v[102:105]
	v_mfma_f32_16x16x32_bf16 v[102:105], v[182:185], v[228:231], v[102:105]
	v_mfma_f32_16x16x32_bf16 v[98:101], v[186:189], v[202:205], v[98:101]
	v_mfma_f32_16x16x32_bf16 v[98:101], v[190:193], v[228:231], v[98:101]
	v_mfma_f32_16x16x32_bf16 v[114:117], v[170:173], v[202:205], v[114:117]
	v_mfma_f32_16x16x32_bf16 v[114:117], v[174:177], v[228:231], v[114:117]
	v_mfma_f32_16x16x32_bf16 v[118:121], v[132:135], v[202:205], v[118:121]
	v_mfma_f32_16x16x32_bf16 v[118:121], v[142:145], v[228:231], v[118:121]
	v_mfma_f32_16x16x32_bf16 v[94:97], v[132:135], v[232:235], v[94:97]
	v_mfma_f32_16x16x32_bf16 v[94:97], v[142:145], v[236:239], v[94:97]
	v_mfma_f32_16x16x32_bf16 v[90:93], v[170:173], v[232:235], v[90:93]
	v_mfma_f32_16x16x32_bf16 v[90:93], v[174:177], v[236:239], v[90:93]
	v_mfma_f32_16x16x32_bf16 v[82:85], v[186:189], v[232:235], v[82:85]
	v_mfma_f32_16x16x32_bf16 v[82:85], v[190:193], v[236:239], v[82:85]
	v_mfma_f32_16x16x32_bf16 v[86:89], v[178:181], v[232:235], v[86:89]
	v_mfma_f32_16x16x32_bf16 v[86:89], v[182:185], v[236:239], v[86:89]
	v_mfma_f32_16x16x32_bf16 v[70:73], v[178:181], v[240:243], v[70:73]
	v_mfma_f32_16x16x32_bf16 v[70:73], v[182:185], v[244:247], v[70:73]
	v_mfma_f32_16x16x32_bf16 v[66:69], v[186:189], v[240:243], v[66:69]
	v_mfma_f32_16x16x32_bf16 v[66:69], v[190:193], v[244:247], v[66:69]
	v_mfma_f32_16x16x32_bf16 v[74:77], v[170:173], v[240:243], v[74:77]
	v_mfma_f32_16x16x32_bf16 v[74:77], v[174:177], v[244:247], v[74:77]
	v_mfma_f32_16x16x32_bf16 v[78:81], v[132:135], v[240:243], v[78:81]
	v_mfma_f32_16x16x32_bf16 v[78:81], v[142:145], v[244:247], v[78:81]
	s_barrier
	s_setprio 0
	s_mov_b32 s46, s62
	s_mov_b32 s47, s63
	s_mov_b32 m0, s15
	ds_read_b128 v[194:197], v141 offset:16384
	buffer_load_dwordx4 v137, s[44:47], s26 offen lds
	s_add_i32 s52, s26, 0x160000
	s_mov_b32 m0, s16
	ds_read_b128 v[198:201], v141 offset:17408
	buffer_load_dwordx4 v139, s[44:47], s26 offen lds
	s_mov_b32 m0, s18
	ds_read_b128 v[202:205], v141 offset:18432
	buffer_load_dwordx4 v137, s[44:47], s52 offen lds
	s_mov_b32 m0, s19
	ds_read_b128 v[228:231], v141 offset:19456
	buffer_load_dwordx4 v139, s[44:47], s52 offen lds
	s_mov_b32 m0, s14
	ds_read_b128 v[232:235], v141 offset:20480
	buffer_load_dwordx4 v136, s[60:63], s27 offen lds
	s_mov_b32 m0, s24
	ds_read_b128 v[236:239], v141 offset:21504
	buffer_load_dwordx4 v138, s[60:63], s27 offen lds
	ds_read_b128 v[240:243], v141 offset:22528
	ds_read_b128 v[244:247], v141 offset:23552
	s_waitcnt vmcnt(8)
	s_waitcnt lgkmcnt(0)
	s_setprio 1
	s_barrier
	v_mfma_f32_16x16x32_bf16 v[62:65], v[132:135], v[194:197], v[62:65]
	v_mfma_f32_16x16x32_bf16 v[62:65], v[142:145], v[198:201], v[62:65]
	v_mfma_f32_16x16x32_bf16 v[58:61], v[170:173], v[194:197], v[58:61]
	v_mfma_f32_16x16x32_bf16 v[58:61], v[174:177], v[198:201], v[58:61]
	v_mfma_f32_16x16x32_bf16 v[50:53], v[186:189], v[194:197], v[50:53]
	v_mfma_f32_16x16x32_bf16 v[50:53], v[190:193], v[198:201], v[50:53]
	v_mfma_f32_16x16x32_bf16 v[54:57], v[178:181], v[194:197], v[54:57]
	v_mfma_f32_16x16x32_bf16 v[54:57], v[182:185], v[198:201], v[54:57]
	v_mfma_f32_16x16x32_bf16 v[38:41], v[178:181], v[202:205], v[38:41]
	v_mfma_f32_16x16x32_bf16 v[38:41], v[182:185], v[228:231], v[38:41]
	v_mfma_f32_16x16x32_bf16 v[34:37], v[186:189], v[202:205], v[34:37]
	v_mfma_f32_16x16x32_bf16 v[34:37], v[190:193], v[228:231], v[34:37]
	v_mfma_f32_16x16x32_bf16 v[42:45], v[170:173], v[202:205], v[42:45]
	v_mfma_f32_16x16x32_bf16 v[42:45], v[174:177], v[228:231], v[42:45]
	v_mfma_f32_16x16x32_bf16 v[46:49], v[132:135], v[202:205], v[46:49]
	v_mfma_f32_16x16x32_bf16 v[46:49], v[142:145], v[228:231], v[46:49]
	v_mfma_f32_16x16x32_bf16 v[30:33], v[132:135], v[232:235], v[30:33]
	v_mfma_f32_16x16x32_bf16 v[30:33], v[142:145], v[236:239], v[30:33]
	v_mfma_f32_16x16x32_bf16 v[26:29], v[170:173], v[232:235], v[26:29]
	v_mfma_f32_16x16x32_bf16 v[26:29], v[174:177], v[236:239], v[26:29]
	v_mfma_f32_16x16x32_bf16 v[18:21], v[186:189], v[232:235], v[18:21]
	v_mfma_f32_16x16x32_bf16 v[18:21], v[190:193], v[236:239], v[18:21]
	v_mfma_f32_16x16x32_bf16 v[22:25], v[178:181], v[232:235], v[22:25]
	v_mfma_f32_16x16x32_bf16 v[22:25], v[182:185], v[236:239], v[22:25]
	v_mfma_f32_16x16x32_bf16 v[6:9], v[178:181], v[240:243], v[6:9]
	v_mfma_f32_16x16x32_bf16 v[6:9], v[182:185], v[244:247], v[6:9]
	v_mfma_f32_16x16x32_bf16 v[2:5], v[186:189], v[240:243], v[2:5]
	v_mfma_f32_16x16x32_bf16 v[2:5], v[190:193], v[244:247], v[2:5]
	v_mfma_f32_16x16x32_bf16 v[10:13], v[170:173], v[240:243], v[10:13]
	v_mfma_f32_16x16x32_bf16 v[10:13], v[174:177], v[244:247], v[10:13]
	v_mfma_f32_16x16x32_bf16 v[14:17], v[132:135], v[240:243], v[14:17]
	v_mfma_f32_16x16x32_bf16 v[14:17], v[142:145], v[244:247], v[14:17]
	s_barrier
	s_setprio 0
	v_add_u32_e32 v154, 0x18000, v140
	ds_read_b128 v[132:135], v154
	ds_read_b128 v[142:145], v154 offset:1024
	ds_read_b128 v[170:173], v154 offset:2048
	ds_read_b128 v[174:177], v154 offset:3072
	v_add_u32_e32 v154, 0x1c000, v140
	ds_read_b128 v[178:181], v154
	ds_read_b128 v[182:185], v154 offset:1024
	ds_read_b128 v[186:189], v154 offset:2048
	ds_read_b128 v[190:193], v154 offset:3072
	s_bitset1_b32 s27, 14
	s_mov_b32 m0, s25
	ds_read_b128 v[194:197], v141 offset:32768
	ds_read_b128 v[198:201], v141 offset:33792
	ds_read_b128 v[202:205], v141 offset:34816
	ds_read_b128 v[228:231], v141 offset:35840
	ds_read_b128 v[232:235], v141 offset:36864
	ds_read_b128 v[236:239], v141 offset:37888
	ds_read_b128 v[240:243], v141 offset:38912
	ds_read_b128 v[244:247], v141 offset:39936
	buffer_load_dwordx4 v136, s[60:63], s27 offen lds
	s_mov_b32 m0, s30
	s_nop 0
	buffer_load_dwordx4 v138, s[60:63], s27 offen lds
	s_waitcnt vmcnt(8)
	s_waitcnt lgkmcnt(0)
	s_setprio 1
	s_barrier
	v_mfma_f32_16x16x32_bf16 v[126:129], v[132:135], v[194:197], v[126:129]
	v_mfma_f32_16x16x32_bf16 v[126:129], v[142:145], v[198:201], v[126:129]
	v_mfma_f32_16x16x32_bf16 v[106:109], v[170:173], v[194:197], v[106:109]
	v_mfma_f32_16x16x32_bf16 v[106:109], v[174:177], v[198:201], v[106:109]
	v_mfma_f32_16x16x32_bf16 v[110:113], v[186:189], v[194:197], v[110:113]
	v_mfma_f32_16x16x32_bf16 v[110:113], v[190:193], v[198:201], v[110:113]
	v_mfma_f32_16x16x32_bf16 v[122:125], v[178:181], v[194:197], v[122:125]
	v_mfma_f32_16x16x32_bf16 v[122:125], v[182:185], v[198:201], v[122:125]
	v_mfma_f32_16x16x32_bf16 v[102:105], v[178:181], v[202:205], v[102:105]
	v_mfma_f32_16x16x32_bf16 v[102:105], v[182:185], v[228:231], v[102:105]
	v_mfma_f32_16x16x32_bf16 v[98:101], v[186:189], v[202:205], v[98:101]
	v_mfma_f32_16x16x32_bf16 v[98:101], v[190:193], v[228:231], v[98:101]
	v_mfma_f32_16x16x32_bf16 v[114:117], v[170:173], v[202:205], v[114:117]
	v_mfma_f32_16x16x32_bf16 v[114:117], v[174:177], v[228:231], v[114:117]
	v_mfma_f32_16x16x32_bf16 v[118:121], v[132:135], v[202:205], v[118:121]
	v_mfma_f32_16x16x32_bf16 v[118:121], v[142:145], v[228:231], v[118:121]
	v_mfma_f32_16x16x32_bf16 v[94:97], v[132:135], v[232:235], v[94:97]
	v_mfma_f32_16x16x32_bf16 v[94:97], v[142:145], v[236:239], v[94:97]
	v_mfma_f32_16x16x32_bf16 v[90:93], v[170:173], v[232:235], v[90:93]
	v_mfma_f32_16x16x32_bf16 v[90:93], v[174:177], v[236:239], v[90:93]
	v_mfma_f32_16x16x32_bf16 v[82:85], v[186:189], v[232:235], v[82:85]
	v_mfma_f32_16x16x32_bf16 v[82:85], v[190:193], v[236:239], v[82:85]
	v_mfma_f32_16x16x32_bf16 v[86:89], v[178:181], v[232:235], v[86:89]
	v_mfma_f32_16x16x32_bf16 v[86:89], v[182:185], v[236:239], v[86:89]
	v_mfma_f32_16x16x32_bf16 v[70:73], v[178:181], v[240:243], v[70:73]
	v_mfma_f32_16x16x32_bf16 v[70:73], v[182:185], v[244:247], v[70:73]
	v_mfma_f32_16x16x32_bf16 v[66:69], v[186:189], v[240:243], v[66:69]
	v_mfma_f32_16x16x32_bf16 v[66:69], v[190:193], v[244:247], v[66:69]
	v_mfma_f32_16x16x32_bf16 v[74:77], v[170:173], v[240:243], v[74:77]
	v_mfma_f32_16x16x32_bf16 v[74:77], v[174:177], v[244:247], v[74:77]
	v_mfma_f32_16x16x32_bf16 v[78:81], v[132:135], v[240:243], v[78:81]
	v_mfma_f32_16x16x32_bf16 v[78:81], v[142:145], v[244:247], v[78:81]
	s_barrier
	s_setprio 0
	s_or_b32 s27, s26, 0x80
	s_mov_b32 m0, s36
	ds_read_b128 v[194:197], v141 offset:49152
	buffer_load_dwordx4 v137, s[44:47], s27 offen lds
	s_add_i32 s26, s26, 0x160080
	s_mov_b32 m0, s37
	ds_read_b128 v[198:201], v141 offset:50176
	buffer_load_dwordx4 v139, s[44:47], s27 offen lds
	s_mov_b32 m0, s66
	ds_read_b128 v[202:205], v141 offset:51200
	buffer_load_dwordx4 v137, s[44:47], s26 offen lds
	s_mov_b32 m0, s67
	ds_read_b128 v[228:231], v141 offset:52224
	buffer_load_dwordx4 v139, s[44:47], s26 offen lds
	s_mov_b32 m0, s48
	ds_read_b128 v[232:235], v141 offset:53248
	buffer_load_dwordx4 v136, s[60:63], s23 offen lds
	s_mov_b32 m0, s49
	ds_read_b128 v[236:239], v141 offset:54272
	buffer_load_dwordx4 v138, s[60:63], s23 offen lds
	ds_read_b128 v[240:243], v141 offset:55296
	ds_read_b128 v[244:247], v141 offset:56320
	s_waitcnt vmcnt(8)
	s_waitcnt lgkmcnt(0)
	s_setprio 1
	s_barrier
	v_mfma_f32_16x16x32_bf16 v[62:65], v[132:135], v[194:197], v[62:65]
	v_mfma_f32_16x16x32_bf16 v[62:65], v[142:145], v[198:201], v[62:65]
	v_mfma_f32_16x16x32_bf16 v[58:61], v[170:173], v[194:197], v[58:61]
	v_mfma_f32_16x16x32_bf16 v[58:61], v[174:177], v[198:201], v[58:61]
	v_mfma_f32_16x16x32_bf16 v[50:53], v[186:189], v[194:197], v[50:53]
	v_mfma_f32_16x16x32_bf16 v[50:53], v[190:193], v[198:201], v[50:53]
	v_mfma_f32_16x16x32_bf16 v[54:57], v[178:181], v[194:197], v[54:57]
	v_mfma_f32_16x16x32_bf16 v[54:57], v[182:185], v[198:201], v[54:57]
	v_mfma_f32_16x16x32_bf16 v[38:41], v[178:181], v[202:205], v[38:41]
	v_mfma_f32_16x16x32_bf16 v[38:41], v[182:185], v[228:231], v[38:41]
	v_mfma_f32_16x16x32_bf16 v[34:37], v[186:189], v[202:205], v[34:37]
	v_mfma_f32_16x16x32_bf16 v[34:37], v[190:193], v[228:231], v[34:37]
	v_mfma_f32_16x16x32_bf16 v[42:45], v[170:173], v[202:205], v[42:45]
	v_mfma_f32_16x16x32_bf16 v[42:45], v[174:177], v[228:231], v[42:45]
	v_mfma_f32_16x16x32_bf16 v[46:49], v[132:135], v[202:205], v[46:49]
	v_mfma_f32_16x16x32_bf16 v[46:49], v[142:145], v[228:231], v[46:49]
	v_mfma_f32_16x16x32_bf16 v[30:33], v[132:135], v[232:235], v[30:33]
	v_mfma_f32_16x16x32_bf16 v[30:33], v[142:145], v[236:239], v[30:33]
	v_mfma_f32_16x16x32_bf16 v[26:29], v[170:173], v[232:235], v[26:29]
	v_mfma_f32_16x16x32_bf16 v[26:29], v[174:177], v[236:239], v[26:29]
	v_mfma_f32_16x16x32_bf16 v[18:21], v[186:189], v[232:235], v[18:21]
	v_mfma_f32_16x16x32_bf16 v[18:21], v[190:193], v[236:239], v[18:21]
	v_mfma_f32_16x16x32_bf16 v[22:25], v[178:181], v[232:235], v[22:25]
	v_mfma_f32_16x16x32_bf16 v[22:25], v[182:185], v[236:239], v[22:25]
	v_mfma_f32_16x16x32_bf16 v[6:9], v[178:181], v[240:243], v[6:9]
	v_mfma_f32_16x16x32_bf16 v[6:9], v[182:185], v[244:247], v[6:9]
	v_mfma_f32_16x16x32_bf16 v[2:5], v[186:189], v[240:243], v[2:5]
	v_mfma_f32_16x16x32_bf16 v[2:5], v[190:193], v[244:247], v[2:5]
	v_mfma_f32_16x16x32_bf16 v[10:13], v[170:173], v[240:243], v[10:13]
	v_mfma_f32_16x16x32_bf16 v[10:13], v[174:177], v[244:247], v[10:13]
	v_mfma_f32_16x16x32_bf16 v[14:17], v[132:135], v[240:243], v[14:17]
	v_mfma_f32_16x16x32_bf16 v[14:17], v[142:145], v[244:247], v[14:17]
	s_barrier
	s_setprio 0
	s_addk_i32 s13, 0x100
	s_add_i32 s22, s22, 2
	s_add_i32 s21, s21, 0x10000
	s_cmpk_gt_u32 s22, 0x55
	s_cbranch_scc0 .LBB0_580
	s_and_b64 vcc, exec, s[64:65]
	s_cbranch_vccz .LBB0_583
	s_barrier

.LBB0_858:
	s_lshl_b32 s2, s21, 20
	s_and_b64 s[8:9], s[42:43], exec
	s_cselect_b32 s8, s2, s18
	s_lshl_b32 s82, s71, 20
	s_and_b64 s[26:27], s[42:43], exec
	s_cselect_b32 s9, s82, s19
	s_add_i32 s18, s18, 0x80080
	s_addk_i32 s19, 0x100
	s_mov_b32 s22, -2
	v_add_u32_e32 v146, 0x10000, v195
	ds_read_b128 v[130:133], v146
	ds_read_b128 v[138:141], v146 offset:1024
	ds_read_b128 v[142:145], v146 offset:2048
	ds_read_b128 v[154:157], v146 offset:3072
	v_add_u32_e32 v146, 0x14000, v195
	ds_read_b128 v[170:173], v146
	ds_read_b128 v[174:177], v146 offset:1024
	ds_read_b128 v[178:181], v146 offset:2048
	ds_read_b128 v[182:185], v146 offset:3072
	s_add_i32 s26, s18, 0xfff80080
	s_cmp_eq_u32 s22, 28
	s_cselect_b32 s52, s8, s26
	s_cselect_b32 s27, s9, s19
	s_or_b32 s26, s52, 0x80
	s_mov_b32 m0, s85
	ds_read_b128 v[186:189], v196
	ds_read_b128 v[198:201], v196 offset:1024
	ds_read_b128 v[202:205], v196 offset:2048
	ds_read_b128 v[228:231], v196 offset:3072
	ds_read_b128 v[232:235], v196 offset:4096
	ds_read_b128 v[236:239], v196 offset:5120
	ds_read_b128 v[240:243], v196 offset:6144
	ds_read_b128 v[244:247], v196 offset:7168
	buffer_load_dwordx4 v135, s[44:47], s18 offen lds
	s_mov_b32 m0, s15
	s_nop 0
	buffer_load_dwordx4 v193, s[44:47], s18 offen lds
	s_waitcnt vmcnt(8)
	s_waitcnt lgkmcnt(0)
	s_setprio 1
	s_barrier
	v_mfma_f32_16x16x32_bf16 v[126:129], v[130:133], v[186:189], 0
	v_mfma_f32_16x16x32_bf16 v[126:129], v[138:141], v[198:201], v[126:129]
	v_mfma_f32_16x16x32_bf16 v[122:125], v[142:145], v[186:189], 0
	v_mfma_f32_16x16x32_bf16 v[122:125], v[154:157], v[198:201], v[122:125]
	v_mfma_f32_16x16x32_bf16 v[114:117], v[178:181], v[186:189], 0
	v_mfma_f32_16x16x32_bf16 v[114:117], v[182:185], v[198:201], v[114:117]
	v_mfma_f32_16x16x32_bf16 v[118:121], v[170:173], v[186:189], 0
	v_mfma_f32_16x16x32_bf16 v[118:121], v[174:177], v[198:201], v[118:121]
	v_mfma_f32_16x16x32_bf16 v[102:105], v[170:173], v[202:205], 0
	v_mfma_f32_16x16x32_bf16 v[102:105], v[174:177], v[228:231], v[102:105]
	v_mfma_f32_16x16x32_bf16 v[98:101], v[178:181], v[202:205], 0
	v_mfma_f32_16x16x32_bf16 v[98:101], v[182:185], v[228:231], v[98:101]
	v_mfma_f32_16x16x32_bf16 v[106:109], v[142:145], v[202:205], 0
	v_mfma_f32_16x16x32_bf16 v[106:109], v[154:157], v[228:231], v[106:109]
	v_mfma_f32_16x16x32_bf16 v[110:113], v[130:133], v[202:205], 0
	v_mfma_f32_16x16x32_bf16 v[110:113], v[138:141], v[228:231], v[110:113]
	v_mfma_f32_16x16x32_bf16 v[94:97], v[130:133], v[232:235], 0
	v_mfma_f32_16x16x32_bf16 v[94:97], v[138:141], v[236:239], v[94:97]
	v_mfma_f32_16x16x32_bf16 v[90:93], v[142:145], v[232:235], 0
	v_mfma_f32_16x16x32_bf16 v[90:93], v[154:157], v[236:239], v[90:93]
	v_mfma_f32_16x16x32_bf16 v[82:85], v[178:181], v[232:235], 0
	v_mfma_f32_16x16x32_bf16 v[82:85], v[182:185], v[236:239], v[82:85]
	v_mfma_f32_16x16x32_bf16 v[86:89], v[170:173], v[232:235], 0
	v_mfma_f32_16x16x32_bf16 v[86:89], v[174:177], v[236:239], v[86:89]
	v_mfma_f32_16x16x32_bf16 v[70:73], v[170:173], v[240:243], 0
	v_mfma_f32_16x16x32_bf16 v[70:73], v[174:177], v[244:247], v[70:73]
	v_mfma_f32_16x16x32_bf16 v[66:69], v[178:181], v[240:243], 0
	v_mfma_f32_16x16x32_bf16 v[66:69], v[182:185], v[244:247], v[66:69]
	v_mfma_f32_16x16x32_bf16 v[74:77], v[142:145], v[240:243], 0
	v_mfma_f32_16x16x32_bf16 v[74:77], v[154:157], v[244:247], v[74:77]
	v_mfma_f32_16x16x32_bf16 v[78:81], v[130:133], v[240:243], 0
	v_mfma_f32_16x16x32_bf16 v[78:81], v[138:141], v[244:247], v[78:81]
	s_barrier
	s_setprio 0
	s_mov_b32 s66, s46
	s_mov_b32 s67, s47
	s_mov_b32 m0, s23
	ds_read_b128 v[186:189], v196 offset:16384
	buffer_load_dwordx4 v192, s[64:67], s27 offen lds
	s_add_i32 s53, s27, 0x80000
	s_mov_b32 m0, s24
	ds_read_b128 v[198:201], v196 offset:17408
	buffer_load_dwordx4 v194, s[64:67], s27 offen lds
	s_mov_b32 m0, s25
	ds_read_b128 v[202:205], v196 offset:18432
	buffer_load_dwordx4 v192, s[64:67], s53 offen lds
	s_mov_b32 m0, s33
	ds_read_b128 v[228:231], v196 offset:19456
	buffer_load_dwordx4 v194, s[64:67], s53 offen lds
	s_mov_b32 m0, s13
	ds_read_b128 v[232:235], v196 offset:20480
	buffer_load_dwordx4 v135, s[44:47], s52 offen lds
	s_mov_b32 m0, s34
	ds_read_b128 v[236:239], v196 offset:21504
	buffer_load_dwordx4 v193, s[44:47], s52 offen lds
	ds_read_b128 v[240:243], v196 offset:22528
	ds_read_b128 v[244:247], v196 offset:23552
	s_waitcnt vmcnt(8)
	s_waitcnt lgkmcnt(0)
	s_setprio 1
	s_barrier
	v_mfma_f32_16x16x32_bf16 v[62:65], v[130:133], v[186:189], 0
	v_mfma_f32_16x16x32_bf16 v[62:65], v[138:141], v[198:201], v[62:65]
	v_mfma_f32_16x16x32_bf16 v[58:61], v[142:145], v[186:189], 0
	v_mfma_f32_16x16x32_bf16 v[58:61], v[154:157], v[198:201], v[58:61]
	v_mfma_f32_16x16x32_bf16 v[50:53], v[178:181], v[186:189], 0
	v_mfma_f32_16x16x32_bf16 v[50:53], v[182:185], v[198:201], v[50:53]
	v_mfma_f32_16x16x32_bf16 v[54:57], v[170:173], v[186:189], 0
	v_mfma_f32_16x16x32_bf16 v[54:57], v[174:177], v[198:201], v[54:57]
	v_mfma_f32_16x16x32_bf16 v[38:41], v[170:173], v[202:205], 0
	v_mfma_f32_16x16x32_bf16 v[38:41], v[174:177], v[228:231], v[38:41]
	v_mfma_f32_16x16x32_bf16 v[34:37], v[178:181], v[202:205], 0
	v_mfma_f32_16x16x32_bf16 v[34:37], v[182:185], v[228:231], v[34:37]
	v_mfma_f32_16x16x32_bf16 v[42:45], v[142:145], v[202:205], 0
	v_mfma_f32_16x16x32_bf16 v[42:45], v[154:157], v[228:231], v[42:45]
	v_mfma_f32_16x16x32_bf16 v[46:49], v[130:133], v[202:205], 0
	v_mfma_f32_16x16x32_bf16 v[46:49], v[138:141], v[228:231], v[46:49]
	v_mfma_f32_16x16x32_bf16 v[30:33], v[130:133], v[232:235], 0
	v_mfma_f32_16x16x32_bf16 v[30:33], v[138:141], v[236:239], v[30:33]
	v_mfma_f32_16x16x32_bf16 v[26:29], v[142:145], v[232:235], 0
	v_mfma_f32_16x16x32_bf16 v[26:29], v[154:157], v[236:239], v[26:29]
	v_mfma_f32_16x16x32_bf16 v[18:21], v[178:181], v[232:235], 0
	v_mfma_f32_16x16x32_bf16 v[18:21], v[182:185], v[236:239], v[18:21]
	v_mfma_f32_16x16x32_bf16 v[22:25], v[170:173], v[232:235], 0
	v_mfma_f32_16x16x32_bf16 v[22:25], v[174:177], v[236:239], v[22:25]
	v_mfma_f32_16x16x32_bf16 v[6:9], v[170:173], v[240:243], 0
	v_mfma_f32_16x16x32_bf16 v[6:9], v[174:177], v[244:247], v[6:9]
	v_mfma_f32_16x16x32_bf16 v[2:5], v[178:181], v[240:243], 0
	v_mfma_f32_16x16x32_bf16 v[2:5], v[182:185], v[244:247], v[2:5]
	v_mfma_f32_16x16x32_bf16 v[10:13], v[142:145], v[240:243], 0
	v_mfma_f32_16x16x32_bf16 v[10:13], v[154:157], v[244:247], v[10:13]
	v_mfma_f32_16x16x32_bf16 v[14:17], v[130:133], v[240:243], 0
	v_mfma_f32_16x16x32_bf16 v[14:17], v[138:141], v[244:247], v[14:17]
	s_barrier
	s_setprio 0
	v_add_u32_e32 v146, 0x18000, v195
	ds_read_b128 v[130:133], v146
	ds_read_b128 v[138:141], v146 offset:1024
	ds_read_b128 v[142:145], v146 offset:2048
	ds_read_b128 v[154:157], v146 offset:3072
	v_add_u32_e32 v146, 0x1c000, v195
	ds_read_b128 v[170:173], v146
	ds_read_b128 v[174:177], v146 offset:1024
	ds_read_b128 v[178:181], v146 offset:2048
	ds_read_b128 v[182:185], v146 offset:3072
	s_add_i32 s52, s52, 0x80000
	s_mov_b32 m0, s35
	ds_read_b128 v[186:189], v196 offset:32768
	ds_read_b128 v[198:201], v196 offset:33792
	ds_read_b128 v[202:205], v196 offset:34816
	ds_read_b128 v[228:231], v196 offset:35840
	ds_read_b128 v[232:235], v196 offset:36864
	ds_read_b128 v[236:239], v196 offset:37888
	ds_read_b128 v[240:243], v196 offset:38912
	ds_read_b128 v[244:247], v196 offset:39936
	buffer_load_dwordx4 v135, s[44:47], s52 offen lds
	s_mov_b32 m0, s36
	s_nop 0
	buffer_load_dwordx4 v193, s[44:47], s52 offen lds
	s_waitcnt vmcnt(8)
	s_waitcnt lgkmcnt(0)
	s_setprio 1
	s_barrier
	v_mfma_f32_16x16x32_bf16 v[126:129], v[130:133], v[186:189], v[126:129]
	v_mfma_f32_16x16x32_bf16 v[126:129], v[138:141], v[198:201], v[126:129]
	v_mfma_f32_16x16x32_bf16 v[122:125], v[142:145], v[186:189], v[122:125]
	v_mfma_f32_16x16x32_bf16 v[122:125], v[154:157], v[198:201], v[122:125]
	v_mfma_f32_16x16x32_bf16 v[114:117], v[178:181], v[186:189], v[114:117]
	v_mfma_f32_16x16x32_bf16 v[114:117], v[182:185], v[198:201], v[114:117]
	v_mfma_f32_16x16x32_bf16 v[118:121], v[170:173], v[186:189], v[118:121]
	v_mfma_f32_16x16x32_bf16 v[118:121], v[174:177], v[198:201], v[118:121]
	v_mfma_f32_16x16x32_bf16 v[102:105], v[170:173], v[202:205], v[102:105]
	v_mfma_f32_16x16x32_bf16 v[102:105], v[174:177], v[228:231], v[102:105]
	v_mfma_f32_16x16x32_bf16 v[98:101], v[178:181], v[202:205], v[98:101]
	v_mfma_f32_16x16x32_bf16 v[98:101], v[182:185], v[228:231], v[98:101]
	v_mfma_f32_16x16x32_bf16 v[106:109], v[142:145], v[202:205], v[106:109]
	v_mfma_f32_16x16x32_bf16 v[106:109], v[154:157], v[228:231], v[106:109]
	v_mfma_f32_16x16x32_bf16 v[110:113], v[130:133], v[202:205], v[110:113]
	v_mfma_f32_16x16x32_bf16 v[110:113], v[138:141], v[228:231], v[110:113]
	v_mfma_f32_16x16x32_bf16 v[94:97], v[130:133], v[232:235], v[94:97]
	v_mfma_f32_16x16x32_bf16 v[94:97], v[138:141], v[236:239], v[94:97]
	v_mfma_f32_16x16x32_bf16 v[90:93], v[142:145], v[232:235], v[90:93]
	v_mfma_f32_16x16x32_bf16 v[90:93], v[154:157], v[236:239], v[90:93]
	v_mfma_f32_16x16x32_bf16 v[82:85], v[178:181], v[232:235], v[82:85]
	v_mfma_f32_16x16x32_bf16 v[82:85], v[182:185], v[236:239], v[82:85]
	v_mfma_f32_16x16x32_bf16 v[86:89], v[170:173], v[232:235], v[86:89]
	v_mfma_f32_16x16x32_bf16 v[86:89], v[174:177], v[236:239], v[86:89]
	v_mfma_f32_16x16x32_bf16 v[70:73], v[170:173], v[240:243], v[70:73]
	v_mfma_f32_16x16x32_bf16 v[70:73], v[174:177], v[244:247], v[70:73]
	v_mfma_f32_16x16x32_bf16 v[66:69], v[178:181], v[240:243], v[66:69]
	v_mfma_f32_16x16x32_bf16 v[66:69], v[182:185], v[244:247], v[66:69]
	v_mfma_f32_16x16x32_bf16 v[74:77], v[142:145], v[240:243], v[74:77]
	v_mfma_f32_16x16x32_bf16 v[74:77], v[154:157], v[244:247], v[74:77]
	v_mfma_f32_16x16x32_bf16 v[78:81], v[130:133], v[240:243], v[78:81]
	v_mfma_f32_16x16x32_bf16 v[78:81], v[138:141], v[244:247], v[78:81]
	s_barrier
	s_setprio 0
	s_or_b32 s52, s27, 0x80
	s_mov_b32 m0, s41
	ds_read_b128 v[186:189], v196 offset:49152
	buffer_load_dwordx4 v192, s[64:67], s52 offen lds
	s_add_i32 s27, s27, 0x80080
	s_mov_b32 m0, s48
	ds_read_b128 v[198:201], v196 offset:50176
	buffer_load_dwordx4 v194, s[64:67], s52 offen lds
	s_mov_b32 m0, s69
	ds_read_b128 v[202:205], v196 offset:51200
	buffer_load_dwordx4 v192, s[64:67], s27 offen lds
	s_mov_b32 m0, s72
	ds_read_b128 v[228:231], v196 offset:52224
	buffer_load_dwordx4 v194, s[64:67], s27 offen lds
	s_mov_b32 m0, s49
	ds_read_b128 v[232:235], v196 offset:53248
	buffer_load_dwordx4 v135, s[44:47], s26 offen lds
	s_mov_b32 m0, s68
	ds_read_b128 v[236:239], v196 offset:54272
	buffer_load_dwordx4 v193, s[44:47], s26 offen lds
	ds_read_b128 v[240:243], v196 offset:55296
	ds_read_b128 v[244:247], v196 offset:56320
	s_waitcnt vmcnt(8)
	s_waitcnt lgkmcnt(0)
	s_setprio 1
	s_barrier
	v_mfma_f32_16x16x32_bf16 v[62:65], v[130:133], v[186:189], v[62:65]
	v_mfma_f32_16x16x32_bf16 v[62:65], v[138:141], v[198:201], v[62:65]
	v_mfma_f32_16x16x32_bf16 v[58:61], v[142:145], v[186:189], v[58:61]
	v_mfma_f32_16x16x32_bf16 v[58:61], v[154:157], v[198:201], v[58:61]
	v_mfma_f32_16x16x32_bf16 v[50:53], v[178:181], v[186:189], v[50:53]
	v_mfma_f32_16x16x32_bf16 v[50:53], v[182:185], v[198:201], v[50:53]
	v_mfma_f32_16x16x32_bf16 v[54:57], v[170:173], v[186:189], v[54:57]
	v_mfma_f32_16x16x32_bf16 v[54:57], v[174:177], v[198:201], v[54:57]
	v_mfma_f32_16x16x32_bf16 v[38:41], v[170:173], v[202:205], v[38:41]
	v_mfma_f32_16x16x32_bf16 v[38:41], v[174:177], v[228:231], v[38:41]
	v_mfma_f32_16x16x32_bf16 v[34:37], v[178:181], v[202:205], v[34:37]
	v_mfma_f32_16x16x32_bf16 v[34:37], v[182:185], v[228:231], v[34:37]
	v_mfma_f32_16x16x32_bf16 v[42:45], v[142:145], v[202:205], v[42:45]
	v_mfma_f32_16x16x32_bf16 v[42:45], v[154:157], v[228:231], v[42:45]
	v_mfma_f32_16x16x32_bf16 v[46:49], v[130:133], v[202:205], v[46:49]
	v_mfma_f32_16x16x32_bf16 v[46:49], v[138:141], v[228:231], v[46:49]
	v_mfma_f32_16x16x32_bf16 v[30:33], v[130:133], v[232:235], v[30:33]
	v_mfma_f32_16x16x32_bf16 v[30:33], v[138:141], v[236:239], v[30:33]
	v_mfma_f32_16x16x32_bf16 v[26:29], v[142:145], v[232:235], v[26:29]
	v_mfma_f32_16x16x32_bf16 v[26:29], v[154:157], v[236:239], v[26:29]
	v_mfma_f32_16x16x32_bf16 v[18:21], v[178:181], v[232:235], v[18:21]
	v_mfma_f32_16x16x32_bf16 v[18:21], v[182:185], v[236:239], v[18:21]
	v_mfma_f32_16x16x32_bf16 v[22:25], v[170:173], v[232:235], v[22:25]
	v_mfma_f32_16x16x32_bf16 v[22:25], v[174:177], v[236:239], v[22:25]
	v_mfma_f32_16x16x32_bf16 v[6:9], v[170:173], v[240:243], v[6:9]
	v_mfma_f32_16x16x32_bf16 v[6:9], v[174:177], v[244:247], v[6:9]
	v_mfma_f32_16x16x32_bf16 v[2:5], v[178:181], v[240:243], v[2:5]
	v_mfma_f32_16x16x32_bf16 v[2:5], v[182:185], v[244:247], v[2:5]
	v_mfma_f32_16x16x32_bf16 v[10:13], v[142:145], v[240:243], v[10:13]
	v_mfma_f32_16x16x32_bf16 v[10:13], v[154:157], v[244:247], v[10:13]
	v_mfma_f32_16x16x32_bf16 v[14:17], v[130:133], v[240:243], v[14:17]
	v_mfma_f32_16x16x32_bf16 v[14:17], v[138:141], v[244:247], v[14:17]
	s_barrier
	s_setprio 0
	s_add_i32 s22, s22, 2
	s_addk_i32 s18, 0x100
	s_addk_i32 s19, 0x100
	s_cmp_gt_u32 s22, 29
.LBB0_859:
	v_add_u32_e32 v146, 0x10000, v195
	ds_read_b128 v[130:133], v146
	ds_read_b128 v[138:141], v146 offset:1024
	ds_read_b128 v[142:145], v146 offset:2048
	ds_read_b128 v[154:157], v146 offset:3072
	v_add_u32_e32 v146, 0x14000, v195
	ds_read_b128 v[170:173], v146
	ds_read_b128 v[174:177], v146 offset:1024
	ds_read_b128 v[178:181], v146 offset:2048
	ds_read_b128 v[182:185], v146 offset:3072
	s_add_i32 s26, s18, 0xfff80080
	s_cmp_eq_u32 s22, 28
	s_cselect_b32 s52, s8, s26
	s_cselect_b32 s27, s9, s19
	s_or_b32 s26, s52, 0x80
	s_mov_b32 m0, s85
	ds_read_b128 v[186:189], v196
	ds_read_b128 v[198:201], v196 offset:1024
	ds_read_b128 v[202:205], v196 offset:2048
	ds_read_b128 v[228:231], v196 offset:3072
	ds_read_b128 v[232:235], v196 offset:4096
	ds_read_b128 v[236:239], v196 offset:5120
	ds_read_b128 v[240:243], v196 offset:6144
	ds_read_b128 v[244:247], v196 offset:7168
	buffer_load_dwordx4 v135, s[44:47], s18 offen lds
	s_mov_b32 m0, s15
	s_nop 0
	buffer_load_dwordx4 v193, s[44:47], s18 offen lds
	s_waitcnt vmcnt(8)
	s_waitcnt lgkmcnt(0)
	s_setprio 1
	s_barrier
	v_mfma_f32_16x16x32_bf16 v[126:129], v[130:133], v[186:189], v[126:129]
	v_mfma_f32_16x16x32_bf16 v[126:129], v[138:141], v[198:201], v[126:129]
	v_mfma_f32_16x16x32_bf16 v[122:125], v[142:145], v[186:189], v[122:125]
	v_mfma_f32_16x16x32_bf16 v[122:125], v[154:157], v[198:201], v[122:125]
	v_mfma_f32_16x16x32_bf16 v[114:117], v[178:181], v[186:189], v[114:117]
	v_mfma_f32_16x16x32_bf16 v[114:117], v[182:185], v[198:201], v[114:117]
	v_mfma_f32_16x16x32_bf16 v[118:121], v[170:173], v[186:189], v[118:121]
	v_mfma_f32_16x16x32_bf16 v[118:121], v[174:177], v[198:201], v[118:121]
	v_mfma_f32_16x16x32_bf16 v[102:105], v[170:173], v[202:205], v[102:105]
	v_mfma_f32_16x16x32_bf16 v[102:105], v[174:177], v[228:231], v[102:105]
	v_mfma_f32_16x16x32_bf16 v[98:101], v[178:181], v[202:205], v[98:101]
	v_mfma_f32_16x16x32_bf16 v[98:101], v[182:185], v[228:231], v[98:101]
	v_mfma_f32_16x16x32_bf16 v[106:109], v[142:145], v[202:205], v[106:109]
	v_mfma_f32_16x16x32_bf16 v[106:109], v[154:157], v[228:231], v[106:109]
	v_mfma_f32_16x16x32_bf16 v[110:113], v[130:133], v[202:205], v[110:113]
	v_mfma_f32_16x16x32_bf16 v[110:113], v[138:141], v[228:231], v[110:113]
	v_mfma_f32_16x16x32_bf16 v[94:97], v[130:133], v[232:235], v[94:97]
	v_mfma_f32_16x16x32_bf16 v[94:97], v[138:141], v[236:239], v[94:97]
	v_mfma_f32_16x16x32_bf16 v[90:93], v[142:145], v[232:235], v[90:93]
	v_mfma_f32_16x16x32_bf16 v[90:93], v[154:157], v[236:239], v[90:93]
	v_mfma_f32_16x16x32_bf16 v[82:85], v[178:181], v[232:235], v[82:85]
	v_mfma_f32_16x16x32_bf16 v[82:85], v[182:185], v[236:239], v[82:85]
	v_mfma_f32_16x16x32_bf16 v[86:89], v[170:173], v[232:235], v[86:89]
	v_mfma_f32_16x16x32_bf16 v[86:89], v[174:177], v[236:239], v[86:89]
	v_mfma_f32_16x16x32_bf16 v[70:73], v[170:173], v[240:243], v[70:73]
	v_mfma_f32_16x16x32_bf16 v[70:73], v[174:177], v[244:247], v[70:73]
	v_mfma_f32_16x16x32_bf16 v[66:69], v[178:181], v[240:243], v[66:69]
	v_mfma_f32_16x16x32_bf16 v[66:69], v[182:185], v[244:247], v[66:69]
	v_mfma_f32_16x16x32_bf16 v[74:77], v[142:145], v[240:243], v[74:77]
	v_mfma_f32_16x16x32_bf16 v[74:77], v[154:157], v[244:247], v[74:77]
	v_mfma_f32_16x16x32_bf16 v[78:81], v[130:133], v[240:243], v[78:81]
	v_mfma_f32_16x16x32_bf16 v[78:81], v[138:141], v[244:247], v[78:81]
	s_barrier
	s_setprio 0
	s_mov_b32 s66, s46
	s_mov_b32 s67, s47
	s_mov_b32 m0, s23
	ds_read_b128 v[186:189], v196 offset:16384
	buffer_load_dwordx4 v192, s[64:67], s27 offen lds
	s_add_i32 s53, s27, 0x80000
	s_mov_b32 m0, s24
	ds_read_b128 v[198:201], v196 offset:17408
	buffer_load_dwordx4 v194, s[64:67], s27 offen lds
	s_mov_b32 m0, s25
	ds_read_b128 v[202:205], v196 offset:18432
	buffer_load_dwordx4 v192, s[64:67], s53 offen lds
	s_mov_b32 m0, s33
	ds_read_b128 v[228:231], v196 offset:19456
	buffer_load_dwordx4 v194, s[64:67], s53 offen lds
	s_mov_b32 m0, s13
	ds_read_b128 v[232:235], v196 offset:20480
	buffer_load_dwordx4 v135, s[44:47], s52 offen lds
	s_mov_b32 m0, s34
	ds_read_b128 v[236:239], v196 offset:21504
	buffer_load_dwordx4 v193, s[44:47], s52 offen lds
	ds_read_b128 v[240:243], v196 offset:22528
	ds_read_b128 v[244:247], v196 offset:23552
	s_waitcnt vmcnt(8)
	s_waitcnt lgkmcnt(0)
	s_setprio 1
	s_barrier
	v_mfma_f32_16x16x32_bf16 v[62:65], v[130:133], v[186:189], v[62:65]
	v_mfma_f32_16x16x32_bf16 v[62:65], v[138:141], v[198:201], v[62:65]
	v_mfma_f32_16x16x32_bf16 v[58:61], v[142:145], v[186:189], v[58:61]
	v_mfma_f32_16x16x32_bf16 v[58:61], v[154:157], v[198:201], v[58:61]
	v_mfma_f32_16x16x32_bf16 v[50:53], v[178:181], v[186:189], v[50:53]
	v_mfma_f32_16x16x32_bf16 v[50:53], v[182:185], v[198:201], v[50:53]
	v_mfma_f32_16x16x32_bf16 v[54:57], v[170:173], v[186:189], v[54:57]
	v_mfma_f32_16x16x32_bf16 v[54:57], v[174:177], v[198:201], v[54:57]
	v_mfma_f32_16x16x32_bf16 v[38:41], v[170:173], v[202:205], v[38:41]
	v_mfma_f32_16x16x32_bf16 v[38:41], v[174:177], v[228:231], v[38:41]
	v_mfma_f32_16x16x32_bf16 v[34:37], v[178:181], v[202:205], v[34:37]
	v_mfma_f32_16x16x32_bf16 v[34:37], v[182:185], v[228:231], v[34:37]
	v_mfma_f32_16x16x32_bf16 v[42:45], v[142:145], v[202:205], v[42:45]
	v_mfma_f32_16x16x32_bf16 v[42:45], v[154:157], v[228:231], v[42:45]
	v_mfma_f32_16x16x32_bf16 v[46:49], v[130:133], v[202:205], v[46:49]
	v_mfma_f32_16x16x32_bf16 v[46:49], v[138:141], v[228:231], v[46:49]
	v_mfma_f32_16x16x32_bf16 v[30:33], v[130:133], v[232:235], v[30:33]
	v_mfma_f32_16x16x32_bf16 v[30:33], v[138:141], v[236:239], v[30:33]
	v_mfma_f32_16x16x32_bf16 v[26:29], v[142:145], v[232:235], v[26:29]
	v_mfma_f32_16x16x32_bf16 v[26:29], v[154:157], v[236:239], v[26:29]
	v_mfma_f32_16x16x32_bf16 v[18:21], v[178:181], v[232:235], v[18:21]
	v_mfma_f32_16x16x32_bf16 v[18:21], v[182:185], v[236:239], v[18:21]
	v_mfma_f32_16x16x32_bf16 v[22:25], v[170:173], v[232:235], v[22:25]
	v_mfma_f32_16x16x32_bf16 v[22:25], v[174:177], v[236:239], v[22:25]
	v_mfma_f32_16x16x32_bf16 v[6:9], v[170:173], v[240:243], v[6:9]
	v_mfma_f32_16x16x32_bf16 v[6:9], v[174:177], v[244:247], v[6:9]
	v_mfma_f32_16x16x32_bf16 v[2:5], v[178:181], v[240:243], v[2:5]
	v_mfma_f32_16x16x32_bf16 v[2:5], v[182:185], v[244:247], v[2:5]
	v_mfma_f32_16x16x32_bf16 v[10:13], v[142:145], v[240:243], v[10:13]
	v_mfma_f32_16x16x32_bf16 v[10:13], v[154:157], v[244:247], v[10:13]
	v_mfma_f32_16x16x32_bf16 v[14:17], v[130:133], v[240:243], v[14:17]
	v_mfma_f32_16x16x32_bf16 v[14:17], v[138:141], v[244:247], v[14:17]
	s_barrier
	s_setprio 0
	v_add_u32_e32 v146, 0x18000, v195
	ds_read_b128 v[130:133], v146
	ds_read_b128 v[138:141], v146 offset:1024
	ds_read_b128 v[142:145], v146 offset:2048
	ds_read_b128 v[154:157], v146 offset:3072
	v_add_u32_e32 v146, 0x1c000, v195
	ds_read_b128 v[170:173], v146
	ds_read_b128 v[174:177], v146 offset:1024
	ds_read_b128 v[178:181], v146 offset:2048
	ds_read_b128 v[182:185], v146 offset:3072
	s_add_i32 s52, s52, 0x80000
	s_mov_b32 m0, s35
	ds_read_b128 v[186:189], v196 offset:32768
	ds_read_b128 v[198:201], v196 offset:33792
	ds_read_b128 v[202:205], v196 offset:34816
	ds_read_b128 v[228:231], v196 offset:35840
	ds_read_b128 v[232:235], v196 offset:36864
	ds_read_b128 v[236:239], v196 offset:37888
	ds_read_b128 v[240:243], v196 offset:38912
	ds_read_b128 v[244:247], v196 offset:39936
	buffer_load_dwordx4 v135, s[44:47], s52 offen lds
	s_mov_b32 m0, s36
	s_nop 0
	buffer_load_dwordx4 v193, s[44:47], s52 offen lds
	s_waitcnt vmcnt(8)
	s_waitcnt lgkmcnt(0)
	s_setprio 1
	s_barrier
	v_mfma_f32_16x16x32_bf16 v[126:129], v[130:133], v[186:189], v[126:129]
	v_mfma_f32_16x16x32_bf16 v[126:129], v[138:141], v[198:201], v[126:129]
	v_mfma_f32_16x16x32_bf16 v[122:125], v[142:145], v[186:189], v[122:125]
	v_mfma_f32_16x16x32_bf16 v[122:125], v[154:157], v[198:201], v[122:125]
	v_mfma_f32_16x16x32_bf16 v[114:117], v[178:181], v[186:189], v[114:117]
	v_mfma_f32_16x16x32_bf16 v[114:117], v[182:185], v[198:201], v[114:117]
	v_mfma_f32_16x16x32_bf16 v[118:121], v[170:173], v[186:189], v[118:121]
	v_mfma_f32_16x16x32_bf16 v[118:121], v[174:177], v[198:201], v[118:121]
	v_mfma_f32_16x16x32_bf16 v[102:105], v[170:173], v[202:205], v[102:105]
	v_mfma_f32_16x16x32_bf16 v[102:105], v[174:177], v[228:231], v[102:105]
	v_mfma_f32_16x16x32_bf16 v[98:101], v[178:181], v[202:205], v[98:101]
	v_mfma_f32_16x16x32_bf16 v[98:101], v[182:185], v[228:231], v[98:101]
	v_mfma_f32_16x16x32_bf16 v[106:109], v[142:145], v[202:205], v[106:109]
	v_mfma_f32_16x16x32_bf16 v[106:109], v[154:157], v[228:231], v[106:109]
	v_mfma_f32_16x16x32_bf16 v[110:113], v[130:133], v[202:205], v[110:113]
	v_mfma_f32_16x16x32_bf16 v[110:113], v[138:141], v[228:231], v[110:113]
	v_mfma_f32_16x16x32_bf16 v[94:97], v[130:133], v[232:235], v[94:97]
	v_mfma_f32_16x16x32_bf16 v[94:97], v[138:141], v[236:239], v[94:97]
	v_mfma_f32_16x16x32_bf16 v[90:93], v[142:145], v[232:235], v[90:93]
	v_mfma_f32_16x16x32_bf16 v[90:93], v[154:157], v[236:239], v[90:93]
	v_mfma_f32_16x16x32_bf16 v[82:85], v[178:181], v[232:235], v[82:85]
	v_mfma_f32_16x16x32_bf16 v[82:85], v[182:185], v[236:239], v[82:85]
	v_mfma_f32_16x16x32_bf16 v[86:89], v[170:173], v[232:235], v[86:89]
	v_mfma_f32_16x16x32_bf16 v[86:89], v[174:177], v[236:239], v[86:89]
	v_mfma_f32_16x16x32_bf16 v[70:73], v[170:173], v[240:243], v[70:73]
	v_mfma_f32_16x16x32_bf16 v[70:73], v[174:177], v[244:247], v[70:73]
	v_mfma_f32_16x16x32_bf16 v[66:69], v[178:181], v[240:243], v[66:69]
	v_mfma_f32_16x16x32_bf16 v[66:69], v[182:185], v[244:247], v[66:69]
	v_mfma_f32_16x16x32_bf16 v[74:77], v[142:145], v[240:243], v[74:77]
	v_mfma_f32_16x16x32_bf16 v[74:77], v[154:157], v[244:247], v[74:77]
	v_mfma_f32_16x16x32_bf16 v[78:81], v[130:133], v[240:243], v[78:81]
	v_mfma_f32_16x16x32_bf16 v[78:81], v[138:141], v[244:247], v[78:81]
	s_barrier
	s_setprio 0
	s_or_b32 s52, s27, 0x80
	s_mov_b32 m0, s41
	ds_read_b128 v[186:189], v196 offset:49152
	buffer_load_dwordx4 v192, s[64:67], s52 offen lds
	s_add_i32 s27, s27, 0x80080
	s_mov_b32 m0, s48
	ds_read_b128 v[198:201], v196 offset:50176
	buffer_load_dwordx4 v194, s[64:67], s52 offen lds
	s_mov_b32 m0, s69
	ds_read_b128 v[202:205], v196 offset:51200
	buffer_load_dwordx4 v192, s[64:67], s27 offen lds
	s_mov_b32 m0, s72
	ds_read_b128 v[228:231], v196 offset:52224
	buffer_load_dwordx4 v194, s[64:67], s27 offen lds
	s_mov_b32 m0, s49
	ds_read_b128 v[232:235], v196 offset:53248
	buffer_load_dwordx4 v135, s[44:47], s26 offen lds
	s_mov_b32 m0, s68
	ds_read_b128 v[236:239], v196 offset:54272
	buffer_load_dwordx4 v193, s[44:47], s26 offen lds
	ds_read_b128 v[240:243], v196 offset:55296
	ds_read_b128 v[244:247], v196 offset:56320
	s_waitcnt vmcnt(8)
	s_waitcnt lgkmcnt(0)
	s_setprio 1
	s_barrier
	v_mfma_f32_16x16x32_bf16 v[62:65], v[130:133], v[186:189], v[62:65]
	v_mfma_f32_16x16x32_bf16 v[62:65], v[138:141], v[198:201], v[62:65]
	v_mfma_f32_16x16x32_bf16 v[58:61], v[142:145], v[186:189], v[58:61]
	v_mfma_f32_16x16x32_bf16 v[58:61], v[154:157], v[198:201], v[58:61]
	v_mfma_f32_16x16x32_bf16 v[50:53], v[178:181], v[186:189], v[50:53]
	v_mfma_f32_16x16x32_bf16 v[50:53], v[182:185], v[198:201], v[50:53]
	v_mfma_f32_16x16x32_bf16 v[54:57], v[170:173], v[186:189], v[54:57]
	v_mfma_f32_16x16x32_bf16 v[54:57], v[174:177], v[198:201], v[54:57]
	v_mfma_f32_16x16x32_bf16 v[38:41], v[170:173], v[202:205], v[38:41]
	v_mfma_f32_16x16x32_bf16 v[38:41], v[174:177], v[228:231], v[38:41]
	v_mfma_f32_16x16x32_bf16 v[34:37], v[178:181], v[202:205], v[34:37]
	v_mfma_f32_16x16x32_bf16 v[34:37], v[182:185], v[228:231], v[34:37]
	v_mfma_f32_16x16x32_bf16 v[42:45], v[142:145], v[202:205], v[42:45]
	v_mfma_f32_16x16x32_bf16 v[42:45], v[154:157], v[228:231], v[42:45]
	v_mfma_f32_16x16x32_bf16 v[46:49], v[130:133], v[202:205], v[46:49]
	v_mfma_f32_16x16x32_bf16 v[46:49], v[138:141], v[228:231], v[46:49]
	v_mfma_f32_16x16x32_bf16 v[30:33], v[130:133], v[232:235], v[30:33]
	v_mfma_f32_16x16x32_bf16 v[30:33], v[138:141], v[236:239], v[30:33]
	v_mfma_f32_16x16x32_bf16 v[26:29], v[142:145], v[232:235], v[26:29]
	v_mfma_f32_16x16x32_bf16 v[26:29], v[154:157], v[236:239], v[26:29]
	v_mfma_f32_16x16x32_bf16 v[18:21], v[178:181], v[232:235], v[18:21]
	v_mfma_f32_16x16x32_bf16 v[18:21], v[182:185], v[236:239], v[18:21]
	v_mfma_f32_16x16x32_bf16 v[22:25], v[170:173], v[232:235], v[22:25]
	v_mfma_f32_16x16x32_bf16 v[22:25], v[174:177], v[236:239], v[22:25]
	v_mfma_f32_16x16x32_bf16 v[6:9], v[170:173], v[240:243], v[6:9]
	v_mfma_f32_16x16x32_bf16 v[6:9], v[174:177], v[244:247], v[6:9]
	v_mfma_f32_16x16x32_bf16 v[2:5], v[178:181], v[240:243], v[2:5]
	v_mfma_f32_16x16x32_bf16 v[2:5], v[182:185], v[244:247], v[2:5]
	v_mfma_f32_16x16x32_bf16 v[10:13], v[142:145], v[240:243], v[10:13]
	v_mfma_f32_16x16x32_bf16 v[10:13], v[154:157], v[244:247], v[10:13]
	v_mfma_f32_16x16x32_bf16 v[14:17], v[130:133], v[240:243], v[14:17]
	v_mfma_f32_16x16x32_bf16 v[14:17], v[138:141], v[244:247], v[14:17]
	s_barrier
	s_setprio 0
	s_add_i32 s22, s22, 2
	s_addk_i32 s18, 0x100
	s_addk_i32 s19, 0x100
	s_cmp_gt_u32 s22, 29
	s_cbranch_scc0 .LBB0_859
	s_and_b64 vcc, exec, s[60:61]
	s_cbranch_vccz .LBB0_862
	s_barrier

.LBB0_880:
	s_lshl_b32 s14, s85, 20
	s_and_b64 s[8:9], s[42:43], exec
	s_cselect_b32 s8, s14, s12
	s_lshl_b32 s15, s66, 20
	s_and_b64 s[22:23], s[42:43], exec
	s_cselect_b32 s9, s15, s13
	s_add_i32 s12, s12, 0x80080
	s_addk_i32 s13, 0x100
	s_mov_b32 s16, -2
	v_add_u32_e32 v139, 0x10000, v234
	ds_read_b128 v[130:133], v139
	ds_read_b128 v[140:143], v139 offset:1024
	ds_read_b128 v[170:173], v139 offset:2048
	ds_read_b128 v[174:177], v139 offset:3072
	v_add_u32_e32 v139, 0x14000, v234
	ds_read_b128 v[178:181], v139
	ds_read_b128 v[182:185], v139 offset:1024
	ds_read_b128 v[186:189], v139 offset:2048
	ds_read_b128 v[190:193], v139 offset:3072
	s_add_i32 s21, s12, 0xfff80080
	s_cmp_eq_u32 s16, 28
	s_cselect_b32 s23, s8, s21
	s_cselect_b32 s22, s9, s13
	s_or_b32 s21, s23, 0x80
	s_mov_b32 m0, s72
	ds_read_b128 v[194:197], v235
	ds_read_b128 v[198:201], v235 offset:1024
	ds_read_b128 v[202:205], v235 offset:2048
	ds_read_b128 v[236:239], v235 offset:3072
	ds_read_b128 v[240:243], v235 offset:4096
	ds_read_b128 v[244:247], v235 offset:5120
	ds_read_b128 v[248:251], v235 offset:6144
	ds_read_b128 v[154:157], v235 offset:7168
	buffer_load_dwordx4 v228, s[60:63], s12 offen lds
	s_mov_b32 m0, s73
	s_nop 0
	buffer_load_dwordx4 v230, s[60:63], s12 offen lds
	s_waitcnt vmcnt(8)
	s_waitcnt lgkmcnt(0)
	s_setprio 1
	s_barrier
	v_mfma_f32_16x16x32_bf16 v[126:129], v[130:133], v[194:197], 0
	v_mfma_f32_16x16x32_bf16 v[126:129], v[140:143], v[198:201], v[126:129]
	v_mfma_f32_16x16x32_bf16 v[122:125], v[170:173], v[194:197], 0
	v_mfma_f32_16x16x32_bf16 v[122:125], v[174:177], v[198:201], v[122:125]
	v_mfma_f32_16x16x32_bf16 v[110:113], v[186:189], v[194:197], 0
	v_mfma_f32_16x16x32_bf16 v[110:113], v[190:193], v[198:201], v[110:113]
	v_mfma_f32_16x16x32_bf16 v[118:121], v[178:181], v[194:197], 0
	v_mfma_f32_16x16x32_bf16 v[118:121], v[182:185], v[198:201], v[118:121]
	v_mfma_f32_16x16x32_bf16 v[102:105], v[178:181], v[202:205], 0
	v_mfma_f32_16x16x32_bf16 v[102:105], v[182:185], v[236:239], v[102:105]
	v_mfma_f32_16x16x32_bf16 v[94:97], v[186:189], v[202:205], 0
	v_mfma_f32_16x16x32_bf16 v[94:97], v[190:193], v[236:239], v[94:97]
	v_mfma_f32_16x16x32_bf16 v[106:109], v[170:173], v[202:205], 0
	v_mfma_f32_16x16x32_bf16 v[106:109], v[174:177], v[236:239], v[106:109]
	v_mfma_f32_16x16x32_bf16 v[114:117], v[130:133], v[202:205], 0
	v_mfma_f32_16x16x32_bf16 v[114:117], v[140:143], v[236:239], v[114:117]
	v_mfma_f32_16x16x32_bf16 v[98:101], v[130:133], v[240:243], 0
	v_mfma_f32_16x16x32_bf16 v[98:101], v[140:143], v[244:247], v[98:101]
	v_mfma_f32_16x16x32_bf16 v[90:93], v[170:173], v[240:243], 0
	v_mfma_f32_16x16x32_bf16 v[90:93], v[174:177], v[244:247], v[90:93]
	v_mfma_f32_16x16x32_bf16 v[78:81], v[186:189], v[240:243], 0
	v_mfma_f32_16x16x32_bf16 v[78:81], v[190:193], v[244:247], v[78:81]
	v_mfma_f32_16x16x32_bf16 v[86:89], v[178:181], v[240:243], 0
	v_mfma_f32_16x16x32_bf16 v[86:89], v[182:185], v[244:247], v[86:89]
	v_mfma_f32_16x16x32_bf16 v[70:73], v[178:181], v[248:251], 0
	v_mfma_f32_16x16x32_bf16 v[70:73], v[182:185], v[154:157], v[70:73]
	v_mfma_f32_16x16x32_bf16 v[66:69], v[186:189], v[248:251], 0
	v_mfma_f32_16x16x32_bf16 v[66:69], v[190:193], v[154:157], v[66:69]
	v_mfma_f32_16x16x32_bf16 v[74:77], v[170:173], v[248:251], 0
	v_mfma_f32_16x16x32_bf16 v[74:77], v[174:177], v[154:157], v[74:77]
	v_mfma_f32_16x16x32_bf16 v[82:85], v[130:133], v[248:251], 0
	v_mfma_f32_16x16x32_bf16 v[82:85], v[140:143], v[154:157], v[82:85]
	s_barrier
	s_setprio 0
	s_mov_b32 s46, s62
	s_mov_b32 s47, s63
	s_mov_b32 m0, s26
	ds_read_b128 v[154:157], v235 offset:16384
	buffer_load_dwordx4 v229, s[44:47], s22 offen lds
	s_add_i32 s38, s22, 0x80000
	s_mov_b32 m0, s27
	ds_read_b128 v[194:197], v235 offset:17408
	buffer_load_dwordx4 v231, s[44:47], s22 offen lds
	s_mov_b32 m0, s34
	ds_read_b128 v[198:201], v235 offset:18432
	buffer_load_dwordx4 v229, s[44:47], s38 offen lds
	s_mov_b32 m0, s35
	ds_read_b128 v[202:205], v235 offset:19456
	buffer_load_dwordx4 v231, s[44:47], s38 offen lds
	s_mov_b32 m0, s19
	ds_read_b128 v[236:239], v235 offset:20480
	buffer_load_dwordx4 v228, s[60:63], s23 offen lds
	s_mov_b32 m0, s36
	ds_read_b128 v[240:243], v235 offset:21504
	buffer_load_dwordx4 v230, s[60:63], s23 offen lds
	ds_read_b128 v[244:247], v235 offset:22528
	ds_read_b128 v[248:251], v235 offset:23552
	s_waitcnt vmcnt(8)
	s_waitcnt lgkmcnt(0)
	s_setprio 1
	s_barrier
	v_mfma_f32_16x16x32_bf16 v[62:65], v[130:133], v[154:157], 0
	v_mfma_f32_16x16x32_bf16 v[62:65], v[140:143], v[194:197], v[62:65]
	v_mfma_f32_16x16x32_bf16 v[58:61], v[170:173], v[154:157], 0
	v_mfma_f32_16x16x32_bf16 v[58:61], v[174:177], v[194:197], v[58:61]
	v_mfma_f32_16x16x32_bf16 v[46:49], v[186:189], v[154:157], 0
	v_mfma_f32_16x16x32_bf16 v[46:49], v[190:193], v[194:197], v[46:49]
	v_mfma_f32_16x16x32_bf16 v[54:57], v[178:181], v[154:157], 0
	v_mfma_f32_16x16x32_bf16 v[54:57], v[182:185], v[194:197], v[54:57]
	v_mfma_f32_16x16x32_bf16 v[38:41], v[178:181], v[198:201], 0
	v_mfma_f32_16x16x32_bf16 v[38:41], v[182:185], v[202:205], v[38:41]
	v_mfma_f32_16x16x32_bf16 v[30:33], v[186:189], v[198:201], 0
	v_mfma_f32_16x16x32_bf16 v[30:33], v[190:193], v[202:205], v[30:33]
	v_mfma_f32_16x16x32_bf16 v[42:45], v[170:173], v[198:201], 0
	v_mfma_f32_16x16x32_bf16 v[42:45], v[174:177], v[202:205], v[42:45]
	v_mfma_f32_16x16x32_bf16 v[50:53], v[130:133], v[198:201], 0
	v_mfma_f32_16x16x32_bf16 v[50:53], v[140:143], v[202:205], v[50:53]
	v_mfma_f32_16x16x32_bf16 v[34:37], v[130:133], v[236:239], 0
	v_mfma_f32_16x16x32_bf16 v[34:37], v[140:143], v[240:243], v[34:37]
	v_mfma_f32_16x16x32_bf16 v[26:29], v[170:173], v[236:239], 0
	v_mfma_f32_16x16x32_bf16 v[26:29], v[174:177], v[240:243], v[26:29]
	v_mfma_f32_16x16x32_bf16 v[14:17], v[186:189], v[236:239], 0
	v_mfma_f32_16x16x32_bf16 v[14:17], v[190:193], v[240:243], v[14:17]
	v_mfma_f32_16x16x32_bf16 v[22:25], v[178:181], v[236:239], 0
	v_mfma_f32_16x16x32_bf16 v[22:25], v[182:185], v[240:243], v[22:25]
	v_mfma_f32_16x16x32_bf16 v[6:9], v[178:181], v[244:247], 0
	v_mfma_f32_16x16x32_bf16 v[6:9], v[182:185], v[248:251], v[6:9]
	v_mfma_f32_16x16x32_bf16 v[2:5], v[186:189], v[244:247], 0
	v_mfma_f32_16x16x32_bf16 v[2:5], v[190:193], v[248:251], v[2:5]
	v_mfma_f32_16x16x32_bf16 v[10:13], v[170:173], v[244:247], 0
	v_mfma_f32_16x16x32_bf16 v[10:13], v[174:177], v[248:251], v[10:13]
	v_mfma_f32_16x16x32_bf16 v[18:21], v[130:133], v[244:247], 0
	v_mfma_f32_16x16x32_bf16 v[18:21], v[140:143], v[248:251], v[18:21]
	s_barrier
	s_setprio 0
	v_add_u32_e32 v139, 0x18000, v234
	ds_read_b128 v[130:133], v139
	ds_read_b128 v[140:143], v139 offset:1024
	ds_read_b128 v[154:157], v139 offset:2048
	ds_read_b128 v[170:173], v139 offset:3072
	v_add_u32_e32 v139, 0x1c000, v234
	ds_read_b128 v[174:177], v139
	ds_read_b128 v[178:181], v139 offset:1024
	ds_read_b128 v[182:185], v139 offset:2048
	ds_read_b128 v[186:189], v139 offset:3072
	s_add_i32 s23, s23, 0x80000
	s_mov_b32 m0, s37
	ds_read_b128 v[190:193], v235 offset:32768
	ds_read_b128 v[194:197], v235 offset:33792
	ds_read_b128 v[198:201], v235 offset:34816
	ds_read_b128 v[202:205], v235 offset:35840
	ds_read_b128 v[236:239], v235 offset:36864
	ds_read_b128 v[240:243], v235 offset:37888
	ds_read_b128 v[244:247], v235 offset:38912
	ds_read_b128 v[248:251], v235 offset:39936
	buffer_load_dwordx4 v228, s[60:63], s23 offen lds
	s_mov_b32 m0, s18
	s_nop 0
	buffer_load_dwordx4 v230, s[60:63], s23 offen lds
	s_waitcnt vmcnt(8)
	s_waitcnt lgkmcnt(0)
	s_setprio 1
	s_barrier
	v_mfma_f32_16x16x32_bf16 v[126:129], v[130:133], v[190:193], v[126:129]
	v_mfma_f32_16x16x32_bf16 v[126:129], v[140:143], v[194:197], v[126:129]
	v_mfma_f32_16x16x32_bf16 v[122:125], v[154:157], v[190:193], v[122:125]
	v_mfma_f32_16x16x32_bf16 v[122:125], v[170:173], v[194:197], v[122:125]
	v_mfma_f32_16x16x32_bf16 v[110:113], v[182:185], v[190:193], v[110:113]
	v_mfma_f32_16x16x32_bf16 v[110:113], v[186:189], v[194:197], v[110:113]
	v_mfma_f32_16x16x32_bf16 v[118:121], v[174:177], v[190:193], v[118:121]
	v_mfma_f32_16x16x32_bf16 v[118:121], v[178:181], v[194:197], v[118:121]
	v_mfma_f32_16x16x32_bf16 v[102:105], v[174:177], v[198:201], v[102:105]
	v_mfma_f32_16x16x32_bf16 v[102:105], v[178:181], v[202:205], v[102:105]
	v_mfma_f32_16x16x32_bf16 v[94:97], v[182:185], v[198:201], v[94:97]
	v_mfma_f32_16x16x32_bf16 v[94:97], v[186:189], v[202:205], v[94:97]
	v_mfma_f32_16x16x32_bf16 v[106:109], v[154:157], v[198:201], v[106:109]
	v_mfma_f32_16x16x32_bf16 v[106:109], v[170:173], v[202:205], v[106:109]
	v_mfma_f32_16x16x32_bf16 v[114:117], v[130:133], v[198:201], v[114:117]
	v_mfma_f32_16x16x32_bf16 v[114:117], v[140:143], v[202:205], v[114:117]
	v_mfma_f32_16x16x32_bf16 v[98:101], v[130:133], v[236:239], v[98:101]
	v_mfma_f32_16x16x32_bf16 v[98:101], v[140:143], v[240:243], v[98:101]
	v_mfma_f32_16x16x32_bf16 v[90:93], v[154:157], v[236:239], v[90:93]
	v_mfma_f32_16x16x32_bf16 v[90:93], v[170:173], v[240:243], v[90:93]
	v_mfma_f32_16x16x32_bf16 v[78:81], v[182:185], v[236:239], v[78:81]
	v_mfma_f32_16x16x32_bf16 v[78:81], v[186:189], v[240:243], v[78:81]
	v_mfma_f32_16x16x32_bf16 v[86:89], v[174:177], v[236:239], v[86:89]
	v_mfma_f32_16x16x32_bf16 v[86:89], v[178:181], v[240:243], v[86:89]
	v_mfma_f32_16x16x32_bf16 v[70:73], v[174:177], v[244:247], v[70:73]
	v_mfma_f32_16x16x32_bf16 v[70:73], v[178:181], v[248:251], v[70:73]
	v_mfma_f32_16x16x32_bf16 v[66:69], v[182:185], v[244:247], v[66:69]
	v_mfma_f32_16x16x32_bf16 v[66:69], v[186:189], v[248:251], v[66:69]
	v_mfma_f32_16x16x32_bf16 v[74:77], v[154:157], v[244:247], v[74:77]
	v_mfma_f32_16x16x32_bf16 v[74:77], v[170:173], v[248:251], v[74:77]
	v_mfma_f32_16x16x32_bf16 v[82:85], v[130:133], v[244:247], v[82:85]
	v_mfma_f32_16x16x32_bf16 v[82:85], v[140:143], v[248:251], v[82:85]
	s_barrier
	s_setprio 0
	s_or_b32 s23, s22, 0x80
	s_mov_b32 m0, s24
	ds_read_b128 v[190:193], v235 offset:49152
	buffer_load_dwordx4 v229, s[44:47], s23 offen lds
	s_add_i32 s22, s22, 0x80080
	s_mov_b32 m0, s25
	ds_read_b128 v[194:197], v235 offset:50176
	buffer_load_dwordx4 v231, s[44:47], s23 offen lds
	s_mov_b32 m0, s64
	ds_read_b128 v[198:201], v235 offset:51200
	buffer_load_dwordx4 v229, s[44:47], s22 offen lds
	s_mov_b32 m0, s65
	ds_read_b128 v[202:205], v235 offset:52224
	buffer_load_dwordx4 v231, s[44:47], s22 offen lds
	s_mov_b32 m0, s48
	ds_read_b128 v[236:239], v235 offset:53248
	buffer_load_dwordx4 v228, s[60:63], s21 offen lds
	s_mov_b32 m0, s49
	ds_read_b128 v[240:243], v235 offset:54272
	buffer_load_dwordx4 v230, s[60:63], s21 offen lds
	ds_read_b128 v[244:247], v235 offset:55296
	ds_read_b128 v[248:251], v235 offset:56320
	s_waitcnt vmcnt(8)
	s_waitcnt lgkmcnt(0)
	s_setprio 1
	s_barrier
	v_mfma_f32_16x16x32_bf16 v[62:65], v[130:133], v[190:193], v[62:65]
	v_mfma_f32_16x16x32_bf16 v[62:65], v[140:143], v[194:197], v[62:65]
	v_mfma_f32_16x16x32_bf16 v[58:61], v[154:157], v[190:193], v[58:61]
	v_mfma_f32_16x16x32_bf16 v[58:61], v[170:173], v[194:197], v[58:61]
	v_mfma_f32_16x16x32_bf16 v[46:49], v[182:185], v[190:193], v[46:49]
	v_mfma_f32_16x16x32_bf16 v[46:49], v[186:189], v[194:197], v[46:49]
	v_mfma_f32_16x16x32_bf16 v[54:57], v[174:177], v[190:193], v[54:57]
	v_mfma_f32_16x16x32_bf16 v[54:57], v[178:181], v[194:197], v[54:57]
	v_mfma_f32_16x16x32_bf16 v[38:41], v[174:177], v[198:201], v[38:41]
	v_mfma_f32_16x16x32_bf16 v[38:41], v[178:181], v[202:205], v[38:41]
	v_mfma_f32_16x16x32_bf16 v[30:33], v[182:185], v[198:201], v[30:33]
	v_mfma_f32_16x16x32_bf16 v[30:33], v[186:189], v[202:205], v[30:33]
	v_mfma_f32_16x16x32_bf16 v[42:45], v[154:157], v[198:201], v[42:45]
	v_mfma_f32_16x16x32_bf16 v[42:45], v[170:173], v[202:205], v[42:45]
	v_mfma_f32_16x16x32_bf16 v[50:53], v[130:133], v[198:201], v[50:53]
	v_mfma_f32_16x16x32_bf16 v[50:53], v[140:143], v[202:205], v[50:53]
	v_mfma_f32_16x16x32_bf16 v[34:37], v[130:133], v[236:239], v[34:37]
	v_mfma_f32_16x16x32_bf16 v[34:37], v[140:143], v[240:243], v[34:37]
	v_mfma_f32_16x16x32_bf16 v[26:29], v[154:157], v[236:239], v[26:29]
	v_mfma_f32_16x16x32_bf16 v[26:29], v[170:173], v[240:243], v[26:29]
	v_mfma_f32_16x16x32_bf16 v[14:17], v[182:185], v[236:239], v[14:17]
	v_mfma_f32_16x16x32_bf16 v[14:17], v[186:189], v[240:243], v[14:17]
	v_mfma_f32_16x16x32_bf16 v[22:25], v[174:177], v[236:239], v[22:25]
	v_mfma_f32_16x16x32_bf16 v[22:25], v[178:181], v[240:243], v[22:25]
	v_mfma_f32_16x16x32_bf16 v[6:9], v[174:177], v[244:247], v[6:9]
	v_mfma_f32_16x16x32_bf16 v[6:9], v[178:181], v[248:251], v[6:9]
	v_mfma_f32_16x16x32_bf16 v[2:5], v[182:185], v[244:247], v[2:5]
	v_mfma_f32_16x16x32_bf16 v[2:5], v[186:189], v[248:251], v[2:5]
	v_mfma_f32_16x16x32_bf16 v[10:13], v[154:157], v[244:247], v[10:13]
	v_mfma_f32_16x16x32_bf16 v[10:13], v[170:173], v[248:251], v[10:13]
	v_mfma_f32_16x16x32_bf16 v[18:21], v[130:133], v[244:247], v[18:21]
	v_mfma_f32_16x16x32_bf16 v[18:21], v[140:143], v[248:251], v[18:21]
	s_barrier
	s_setprio 0
	s_add_i32 s16, s16, 2
	s_addk_i32 s12, 0x100
	s_addk_i32 s13, 0x100
	s_cmp_gt_u32 s16, 29
.LBB0_881:
	v_add_u32_e32 v139, 0x10000, v234
	ds_read_b128 v[130:133], v139
	ds_read_b128 v[140:143], v139 offset:1024
	ds_read_b128 v[170:173], v139 offset:2048
	ds_read_b128 v[174:177], v139 offset:3072
	v_add_u32_e32 v139, 0x14000, v234
	ds_read_b128 v[178:181], v139
	ds_read_b128 v[182:185], v139 offset:1024
	ds_read_b128 v[186:189], v139 offset:2048
	ds_read_b128 v[190:193], v139 offset:3072
	s_add_i32 s21, s12, 0xfff80080
	s_cmp_eq_u32 s16, 28
	s_cselect_b32 s23, s8, s21
	s_cselect_b32 s22, s9, s13
	s_or_b32 s21, s23, 0x80
	s_mov_b32 m0, s72
	ds_read_b128 v[194:197], v235
	ds_read_b128 v[198:201], v235 offset:1024
	ds_read_b128 v[202:205], v235 offset:2048
	ds_read_b128 v[236:239], v235 offset:3072
	ds_read_b128 v[240:243], v235 offset:4096
	ds_read_b128 v[244:247], v235 offset:5120
	ds_read_b128 v[248:251], v235 offset:6144
	ds_read_b128 v[154:157], v235 offset:7168
	buffer_load_dwordx4 v228, s[60:63], s12 offen lds
	s_mov_b32 m0, s73
	s_nop 0
	buffer_load_dwordx4 v230, s[60:63], s12 offen lds
	s_waitcnt vmcnt(8)
	s_waitcnt lgkmcnt(0)
	s_setprio 1
	s_barrier
	v_mfma_f32_16x16x32_bf16 v[126:129], v[130:133], v[194:197], v[126:129]
	v_mfma_f32_16x16x32_bf16 v[126:129], v[140:143], v[198:201], v[126:129]
	v_mfma_f32_16x16x32_bf16 v[122:125], v[170:173], v[194:197], v[122:125]
	v_mfma_f32_16x16x32_bf16 v[122:125], v[174:177], v[198:201], v[122:125]
	v_mfma_f32_16x16x32_bf16 v[110:113], v[186:189], v[194:197], v[110:113]
	v_mfma_f32_16x16x32_bf16 v[110:113], v[190:193], v[198:201], v[110:113]
	v_mfma_f32_16x16x32_bf16 v[118:121], v[178:181], v[194:197], v[118:121]
	v_mfma_f32_16x16x32_bf16 v[118:121], v[182:185], v[198:201], v[118:121]
	v_mfma_f32_16x16x32_bf16 v[102:105], v[178:181], v[202:205], v[102:105]
	v_mfma_f32_16x16x32_bf16 v[102:105], v[182:185], v[236:239], v[102:105]
	v_mfma_f32_16x16x32_bf16 v[94:97], v[186:189], v[202:205], v[94:97]
	v_mfma_f32_16x16x32_bf16 v[94:97], v[190:193], v[236:239], v[94:97]
	v_mfma_f32_16x16x32_bf16 v[106:109], v[170:173], v[202:205], v[106:109]
	v_mfma_f32_16x16x32_bf16 v[106:109], v[174:177], v[236:239], v[106:109]
	v_mfma_f32_16x16x32_bf16 v[114:117], v[130:133], v[202:205], v[114:117]
	v_mfma_f32_16x16x32_bf16 v[114:117], v[140:143], v[236:239], v[114:117]
	v_mfma_f32_16x16x32_bf16 v[98:101], v[130:133], v[240:243], v[98:101]
	v_mfma_f32_16x16x32_bf16 v[98:101], v[140:143], v[244:247], v[98:101]
	v_mfma_f32_16x16x32_bf16 v[90:93], v[170:173], v[240:243], v[90:93]
	v_mfma_f32_16x16x32_bf16 v[90:93], v[174:177], v[244:247], v[90:93]
	v_mfma_f32_16x16x32_bf16 v[78:81], v[186:189], v[240:243], v[78:81]
	v_mfma_f32_16x16x32_bf16 v[78:81], v[190:193], v[244:247], v[78:81]
	v_mfma_f32_16x16x32_bf16 v[86:89], v[178:181], v[240:243], v[86:89]
	v_mfma_f32_16x16x32_bf16 v[86:89], v[182:185], v[244:247], v[86:89]
	v_mfma_f32_16x16x32_bf16 v[70:73], v[178:181], v[248:251], v[70:73]
	v_mfma_f32_16x16x32_bf16 v[70:73], v[182:185], v[154:157], v[70:73]
	v_mfma_f32_16x16x32_bf16 v[66:69], v[186:189], v[248:251], v[66:69]
	v_mfma_f32_16x16x32_bf16 v[66:69], v[190:193], v[154:157], v[66:69]
	v_mfma_f32_16x16x32_bf16 v[74:77], v[170:173], v[248:251], v[74:77]
	v_mfma_f32_16x16x32_bf16 v[74:77], v[174:177], v[154:157], v[74:77]
	v_mfma_f32_16x16x32_bf16 v[82:85], v[130:133], v[248:251], v[82:85]
	v_mfma_f32_16x16x32_bf16 v[82:85], v[140:143], v[154:157], v[82:85]
	s_barrier
	s_setprio 0
	s_mov_b32 s46, s62
	s_mov_b32 s47, s63
	s_mov_b32 m0, s26
	ds_read_b128 v[154:157], v235 offset:16384
	buffer_load_dwordx4 v229, s[44:47], s22 offen lds
	s_add_i32 s38, s22, 0x80000
	s_mov_b32 m0, s27
	ds_read_b128 v[194:197], v235 offset:17408
	buffer_load_dwordx4 v231, s[44:47], s22 offen lds
	s_mov_b32 m0, s34
	ds_read_b128 v[198:201], v235 offset:18432
	buffer_load_dwordx4 v229, s[44:47], s38 offen lds
	s_mov_b32 m0, s35
	ds_read_b128 v[202:205], v235 offset:19456
	buffer_load_dwordx4 v231, s[44:47], s38 offen lds
	s_mov_b32 m0, s19
	ds_read_b128 v[236:239], v235 offset:20480
	buffer_load_dwordx4 v228, s[60:63], s23 offen lds
	s_mov_b32 m0, s36
	ds_read_b128 v[240:243], v235 offset:21504
	buffer_load_dwordx4 v230, s[60:63], s23 offen lds
	ds_read_b128 v[244:247], v235 offset:22528
	ds_read_b128 v[248:251], v235 offset:23552
	s_waitcnt vmcnt(8)
	s_waitcnt lgkmcnt(0)
	s_setprio 1
	s_barrier
	v_mfma_f32_16x16x32_bf16 v[62:65], v[130:133], v[154:157], v[62:65]
	v_mfma_f32_16x16x32_bf16 v[62:65], v[140:143], v[194:197], v[62:65]
	v_mfma_f32_16x16x32_bf16 v[58:61], v[170:173], v[154:157], v[58:61]
	v_mfma_f32_16x16x32_bf16 v[58:61], v[174:177], v[194:197], v[58:61]
	v_mfma_f32_16x16x32_bf16 v[46:49], v[186:189], v[154:157], v[46:49]
	v_mfma_f32_16x16x32_bf16 v[46:49], v[190:193], v[194:197], v[46:49]
	v_mfma_f32_16x16x32_bf16 v[54:57], v[178:181], v[154:157], v[54:57]
	v_mfma_f32_16x16x32_bf16 v[54:57], v[182:185], v[194:197], v[54:57]
	v_mfma_f32_16x16x32_bf16 v[38:41], v[178:181], v[198:201], v[38:41]
	v_mfma_f32_16x16x32_bf16 v[38:41], v[182:185], v[202:205], v[38:41]
	v_mfma_f32_16x16x32_bf16 v[30:33], v[186:189], v[198:201], v[30:33]
	v_mfma_f32_16x16x32_bf16 v[30:33], v[190:193], v[202:205], v[30:33]
	v_mfma_f32_16x16x32_bf16 v[42:45], v[170:173], v[198:201], v[42:45]
	v_mfma_f32_16x16x32_bf16 v[42:45], v[174:177], v[202:205], v[42:45]
	v_mfma_f32_16x16x32_bf16 v[50:53], v[130:133], v[198:201], v[50:53]
	v_mfma_f32_16x16x32_bf16 v[50:53], v[140:143], v[202:205], v[50:53]
	v_mfma_f32_16x16x32_bf16 v[34:37], v[130:133], v[236:239], v[34:37]
	v_mfma_f32_16x16x32_bf16 v[34:37], v[140:143], v[240:243], v[34:37]
	v_mfma_f32_16x16x32_bf16 v[26:29], v[170:173], v[236:239], v[26:29]
	v_mfma_f32_16x16x32_bf16 v[26:29], v[174:177], v[240:243], v[26:29]
	v_mfma_f32_16x16x32_bf16 v[14:17], v[186:189], v[236:239], v[14:17]
	v_mfma_f32_16x16x32_bf16 v[14:17], v[190:193], v[240:243], v[14:17]
	v_mfma_f32_16x16x32_bf16 v[22:25], v[178:181], v[236:239], v[22:25]
	v_mfma_f32_16x16x32_bf16 v[22:25], v[182:185], v[240:243], v[22:25]
	v_mfma_f32_16x16x32_bf16 v[6:9], v[178:181], v[244:247], v[6:9]
	v_mfma_f32_16x16x32_bf16 v[6:9], v[182:185], v[248:251], v[6:9]
	v_mfma_f32_16x16x32_bf16 v[2:5], v[186:189], v[244:247], v[2:5]
	v_mfma_f32_16x16x32_bf16 v[2:5], v[190:193], v[248:251], v[2:5]
	v_mfma_f32_16x16x32_bf16 v[10:13], v[170:173], v[244:247], v[10:13]
	v_mfma_f32_16x16x32_bf16 v[10:13], v[174:177], v[248:251], v[10:13]
	v_mfma_f32_16x16x32_bf16 v[18:21], v[130:133], v[244:247], v[18:21]
	v_mfma_f32_16x16x32_bf16 v[18:21], v[140:143], v[248:251], v[18:21]
	s_barrier
	s_setprio 0
	v_add_u32_e32 v139, 0x18000, v234
	ds_read_b128 v[130:133], v139
	ds_read_b128 v[140:143], v139 offset:1024
	ds_read_b128 v[154:157], v139 offset:2048
	ds_read_b128 v[170:173], v139 offset:3072
	v_add_u32_e32 v139, 0x1c000, v234
	ds_read_b128 v[174:177], v139
	ds_read_b128 v[178:181], v139 offset:1024
	ds_read_b128 v[182:185], v139 offset:2048
	ds_read_b128 v[186:189], v139 offset:3072
	s_add_i32 s23, s23, 0x80000
	s_mov_b32 m0, s37
	ds_read_b128 v[190:193], v235 offset:32768
	ds_read_b128 v[194:197], v235 offset:33792
	ds_read_b128 v[198:201], v235 offset:34816
	ds_read_b128 v[202:205], v235 offset:35840
	ds_read_b128 v[236:239], v235 offset:36864
	ds_read_b128 v[240:243], v235 offset:37888
	ds_read_b128 v[244:247], v235 offset:38912
	ds_read_b128 v[248:251], v235 offset:39936
	buffer_load_dwordx4 v228, s[60:63], s23 offen lds
	s_mov_b32 m0, s18
	s_nop 0
	buffer_load_dwordx4 v230, s[60:63], s23 offen lds
	s_waitcnt vmcnt(8)
	s_waitcnt lgkmcnt(0)
	s_setprio 1
	s_barrier
	v_mfma_f32_16x16x32_bf16 v[126:129], v[130:133], v[190:193], v[126:129]
	v_mfma_f32_16x16x32_bf16 v[126:129], v[140:143], v[194:197], v[126:129]
	v_mfma_f32_16x16x32_bf16 v[122:125], v[154:157], v[190:193], v[122:125]
	v_mfma_f32_16x16x32_bf16 v[122:125], v[170:173], v[194:197], v[122:125]
	v_mfma_f32_16x16x32_bf16 v[110:113], v[182:185], v[190:193], v[110:113]
	v_mfma_f32_16x16x32_bf16 v[110:113], v[186:189], v[194:197], v[110:113]
	v_mfma_f32_16x16x32_bf16 v[118:121], v[174:177], v[190:193], v[118:121]
	v_mfma_f32_16x16x32_bf16 v[118:121], v[178:181], v[194:197], v[118:121]
	v_mfma_f32_16x16x32_bf16 v[102:105], v[174:177], v[198:201], v[102:105]
	v_mfma_f32_16x16x32_bf16 v[102:105], v[178:181], v[202:205], v[102:105]
	v_mfma_f32_16x16x32_bf16 v[94:97], v[182:185], v[198:201], v[94:97]
	v_mfma_f32_16x16x32_bf16 v[94:97], v[186:189], v[202:205], v[94:97]
	v_mfma_f32_16x16x32_bf16 v[106:109], v[154:157], v[198:201], v[106:109]
	v_mfma_f32_16x16x32_bf16 v[106:109], v[170:173], v[202:205], v[106:109]
	v_mfma_f32_16x16x32_bf16 v[114:117], v[130:133], v[198:201], v[114:117]
	v_mfma_f32_16x16x32_bf16 v[114:117], v[140:143], v[202:205], v[114:117]
	v_mfma_f32_16x16x32_bf16 v[98:101], v[130:133], v[236:239], v[98:101]
	v_mfma_f32_16x16x32_bf16 v[98:101], v[140:143], v[240:243], v[98:101]
	v_mfma_f32_16x16x32_bf16 v[90:93], v[154:157], v[236:239], v[90:93]
	v_mfma_f32_16x16x32_bf16 v[90:93], v[170:173], v[240:243], v[90:93]
	v_mfma_f32_16x16x32_bf16 v[78:81], v[182:185], v[236:239], v[78:81]
	v_mfma_f32_16x16x32_bf16 v[78:81], v[186:189], v[240:243], v[78:81]
	v_mfma_f32_16x16x32_bf16 v[86:89], v[174:177], v[236:239], v[86:89]
	v_mfma_f32_16x16x32_bf16 v[86:89], v[178:181], v[240:243], v[86:89]
	v_mfma_f32_16x16x32_bf16 v[70:73], v[174:177], v[244:247], v[70:73]
	v_mfma_f32_16x16x32_bf16 v[70:73], v[178:181], v[248:251], v[70:73]
	v_mfma_f32_16x16x32_bf16 v[66:69], v[182:185], v[244:247], v[66:69]
	v_mfma_f32_16x16x32_bf16 v[66:69], v[186:189], v[248:251], v[66:69]
	v_mfma_f32_16x16x32_bf16 v[74:77], v[154:157], v[244:247], v[74:77]
	v_mfma_f32_16x16x32_bf16 v[74:77], v[170:173], v[248:251], v[74:77]
	v_mfma_f32_16x16x32_bf16 v[82:85], v[130:133], v[244:247], v[82:85]
	v_mfma_f32_16x16x32_bf16 v[82:85], v[140:143], v[248:251], v[82:85]
	s_barrier
	s_setprio 0
	s_or_b32 s23, s22, 0x80
	s_mov_b32 m0, s24
	ds_read_b128 v[190:193], v235 offset:49152
	buffer_load_dwordx4 v229, s[44:47], s23 offen lds
	s_add_i32 s22, s22, 0x80080
	s_mov_b32 m0, s25
	ds_read_b128 v[194:197], v235 offset:50176
	buffer_load_dwordx4 v231, s[44:47], s23 offen lds
	s_mov_b32 m0, s64
	ds_read_b128 v[198:201], v235 offset:51200
	buffer_load_dwordx4 v229, s[44:47], s22 offen lds
	s_mov_b32 m0, s65
	ds_read_b128 v[202:205], v235 offset:52224
	buffer_load_dwordx4 v231, s[44:47], s22 offen lds
	s_mov_b32 m0, s48
	ds_read_b128 v[236:239], v235 offset:53248
	buffer_load_dwordx4 v228, s[60:63], s21 offen lds
	s_mov_b32 m0, s49
	ds_read_b128 v[240:243], v235 offset:54272
	buffer_load_dwordx4 v230, s[60:63], s21 offen lds
	ds_read_b128 v[244:247], v235 offset:55296
	ds_read_b128 v[248:251], v235 offset:56320
	s_waitcnt vmcnt(8)
	s_waitcnt lgkmcnt(0)
	s_setprio 1
	s_barrier
	v_mfma_f32_16x16x32_bf16 v[62:65], v[130:133], v[190:193], v[62:65]
	v_mfma_f32_16x16x32_bf16 v[62:65], v[140:143], v[194:197], v[62:65]
	v_mfma_f32_16x16x32_bf16 v[58:61], v[154:157], v[190:193], v[58:61]
	v_mfma_f32_16x16x32_bf16 v[58:61], v[170:173], v[194:197], v[58:61]
	v_mfma_f32_16x16x32_bf16 v[46:49], v[182:185], v[190:193], v[46:49]
	v_mfma_f32_16x16x32_bf16 v[46:49], v[186:189], v[194:197], v[46:49]
	v_mfma_f32_16x16x32_bf16 v[54:57], v[174:177], v[190:193], v[54:57]
	v_mfma_f32_16x16x32_bf16 v[54:57], v[178:181], v[194:197], v[54:57]
	v_mfma_f32_16x16x32_bf16 v[38:41], v[174:177], v[198:201], v[38:41]
	v_mfma_f32_16x16x32_bf16 v[38:41], v[178:181], v[202:205], v[38:41]
	v_mfma_f32_16x16x32_bf16 v[30:33], v[182:185], v[198:201], v[30:33]
	v_mfma_f32_16x16x32_bf16 v[30:33], v[186:189], v[202:205], v[30:33]
	v_mfma_f32_16x16x32_bf16 v[42:45], v[154:157], v[198:201], v[42:45]
	v_mfma_f32_16x16x32_bf16 v[42:45], v[170:173], v[202:205], v[42:45]
	v_mfma_f32_16x16x32_bf16 v[50:53], v[130:133], v[198:201], v[50:53]
	v_mfma_f32_16x16x32_bf16 v[50:53], v[140:143], v[202:205], v[50:53]
	v_mfma_f32_16x16x32_bf16 v[34:37], v[130:133], v[236:239], v[34:37]
	v_mfma_f32_16x16x32_bf16 v[34:37], v[140:143], v[240:243], v[34:37]
	v_mfma_f32_16x16x32_bf16 v[26:29], v[154:157], v[236:239], v[26:29]
	v_mfma_f32_16x16x32_bf16 v[26:29], v[170:173], v[240:243], v[26:29]
	v_mfma_f32_16x16x32_bf16 v[14:17], v[182:185], v[236:239], v[14:17]
	v_mfma_f32_16x16x32_bf16 v[14:17], v[186:189], v[240:243], v[14:17]
	v_mfma_f32_16x16x32_bf16 v[22:25], v[174:177], v[236:239], v[22:25]
	v_mfma_f32_16x16x32_bf16 v[22:25], v[178:181], v[240:243], v[22:25]
	v_mfma_f32_16x16x32_bf16 v[6:9], v[174:177], v[244:247], v[6:9]
	v_mfma_f32_16x16x32_bf16 v[6:9], v[178:181], v[248:251], v[6:9]
	v_mfma_f32_16x16x32_bf16 v[2:5], v[182:185], v[244:247], v[2:5]
	v_mfma_f32_16x16x32_bf16 v[2:5], v[186:189], v[248:251], v[2:5]
	v_mfma_f32_16x16x32_bf16 v[10:13], v[154:157], v[244:247], v[10:13]
	v_mfma_f32_16x16x32_bf16 v[10:13], v[170:173], v[248:251], v[10:13]
	v_mfma_f32_16x16x32_bf16 v[18:21], v[130:133], v[244:247], v[18:21]
	v_mfma_f32_16x16x32_bf16 v[18:21], v[140:143], v[248:251], v[18:21]
	s_barrier
	s_setprio 0
	s_add_i32 s16, s16, 2
	s_addk_i32 s12, 0x100
	s_addk_i32 s13, 0x100
	s_cmp_gt_u32 s16, 29
	s_cbranch_scc0 .LBB0_881
	v_readlane_b32 s8, v255, 44
	v_readlane_b32 s9, v255, 45
	s_and_b64 vcc, exec, s[8:9]
	s_cbranch_vccz .LBB0_884
	s_barrier

.LBB0_904:
	s_lshl_b32 s73, s72, 20
	s_and_b64 s[8:9], s[42:43], exec
	s_cselect_b32 s8, s73, s13
	s_lshl_b32 s84, s71, 20
	s_and_b64 s[22:23], s[42:43], exec
	s_cselect_b32 s9, s84, s21
	s_add_i32 s13, s13, 0x80080
	s_addk_i32 s21, 0x100
	s_mov_b32 s22, -2
	v_add_u32_e32 v133, 0x10000, v178
	ds_read_b128 v[134:137], v133
	ds_read_b128 v[138:141], v133 offset:1024
	ds_read_b128 v[142:145], v133 offset:2048
	ds_read_b128 v[154:157], v133 offset:3072
	v_add_u32_e32 v133, 0x14000, v178
	ds_read_b128 v[170:173], v133
	ds_read_b128 v[180:183], v133 offset:1024
	ds_read_b128 v[184:187], v133 offset:2048
	ds_read_b128 v[188:191], v133 offset:3072
	s_add_i32 s23, s13, 0xfff80080
	s_cmp_eq_u32 s22, 28
	s_cselect_b32 s27, s8, s23
	s_cselect_b32 s26, s9, s21
	s_or_b32 s23, s27, 0x80
	s_mov_b32 s46, s62
	s_mov_b32 s47, s63
	s_mov_b32 m0, s68
	ds_read_b128 v[192:195], v179
	ds_read_b128 v[196:199], v179 offset:1024
	ds_read_b128 v[200:203], v179 offset:2048
	ds_read_b128 v[204:207], v179 offset:3072
	ds_read_b128 v[228:231], v179 offset:4096
	ds_read_b128 v[232:235], v179 offset:5120
	ds_read_b128 v[236:239], v179 offset:6144
	ds_read_b128 v[240:243], v179 offset:7168
	buffer_load_dwordx4 v174, s[44:47], s13 offen lds
	s_mov_b32 m0, s69
	s_nop 0
	buffer_load_dwordx4 v176, s[44:47], s13 offen lds
	s_waitcnt vmcnt(8)
	s_waitcnt lgkmcnt(0)
	s_setprio 1
	s_barrier
	v_mfma_f32_16x16x32_bf16 v[126:129], v[134:137], v[192:195], 0
	v_mfma_f32_16x16x32_bf16 v[126:129], v[138:141], v[196:199], v[126:129]
	v_mfma_f32_16x16x32_bf16 v[122:125], v[142:145], v[192:195], 0
	v_mfma_f32_16x16x32_bf16 v[122:125], v[154:157], v[196:199], v[122:125]
	v_mfma_f32_16x16x32_bf16 v[114:117], v[184:187], v[192:195], 0
	v_mfma_f32_16x16x32_bf16 v[114:117], v[188:191], v[196:199], v[114:117]
	v_mfma_f32_16x16x32_bf16 v[118:121], v[170:173], v[192:195], 0
	v_mfma_f32_16x16x32_bf16 v[118:121], v[180:183], v[196:199], v[118:121]
	v_mfma_f32_16x16x32_bf16 v[102:105], v[170:173], v[200:203], 0
	v_mfma_f32_16x16x32_bf16 v[102:105], v[180:183], v[204:207], v[102:105]
	v_mfma_f32_16x16x32_bf16 v[98:101], v[184:187], v[200:203], 0
	v_mfma_f32_16x16x32_bf16 v[98:101], v[188:191], v[204:207], v[98:101]
	v_mfma_f32_16x16x32_bf16 v[106:109], v[142:145], v[200:203], 0
	v_mfma_f32_16x16x32_bf16 v[106:109], v[154:157], v[204:207], v[106:109]
	v_mfma_f32_16x16x32_bf16 v[110:113], v[134:137], v[200:203], 0
	v_mfma_f32_16x16x32_bf16 v[110:113], v[138:141], v[204:207], v[110:113]
	v_mfma_f32_16x16x32_bf16 v[94:97], v[134:137], v[228:231], 0
	v_mfma_f32_16x16x32_bf16 v[94:97], v[138:141], v[232:235], v[94:97]
	v_mfma_f32_16x16x32_bf16 v[90:93], v[142:145], v[228:231], 0
	v_mfma_f32_16x16x32_bf16 v[90:93], v[154:157], v[232:235], v[90:93]
	v_mfma_f32_16x16x32_bf16 v[82:85], v[184:187], v[228:231], 0
	v_mfma_f32_16x16x32_bf16 v[82:85], v[188:191], v[232:235], v[82:85]
	v_mfma_f32_16x16x32_bf16 v[86:89], v[170:173], v[228:231], 0
	v_mfma_f32_16x16x32_bf16 v[86:89], v[180:183], v[232:235], v[86:89]
	v_mfma_f32_16x16x32_bf16 v[70:73], v[170:173], v[236:239], 0
	v_mfma_f32_16x16x32_bf16 v[70:73], v[180:183], v[240:243], v[70:73]
	v_mfma_f32_16x16x32_bf16 v[66:69], v[184:187], v[236:239], 0
	v_mfma_f32_16x16x32_bf16 v[66:69], v[188:191], v[240:243], v[66:69]
	v_mfma_f32_16x16x32_bf16 v[74:77], v[142:145], v[236:239], 0
	v_mfma_f32_16x16x32_bf16 v[74:77], v[154:157], v[240:243], v[74:77]
	v_mfma_f32_16x16x32_bf16 v[78:81], v[134:137], v[236:239], 0
	v_mfma_f32_16x16x32_bf16 v[78:81], v[138:141], v[240:243], v[78:81]
	s_barrier
	s_setprio 0
	s_mov_b32 m0, s15
	ds_read_b128 v[192:195], v179 offset:16384
	buffer_load_dwordx4 v175, s[60:63], s26 offen lds
	s_add_i32 s34, s26, 0x80000
	s_mov_b32 m0, s16
	ds_read_b128 v[196:199], v179 offset:17408
	buffer_load_dwordx4 v177, s[60:63], s26 offen lds
	s_mov_b32 m0, s18
	ds_read_b128 v[200:203], v179 offset:18432
	buffer_load_dwordx4 v175, s[60:63], s34 offen lds
	s_mov_b32 m0, s19
	ds_read_b128 v[204:207], v179 offset:19456
	buffer_load_dwordx4 v177, s[60:63], s34 offen lds
	s_mov_b32 m0, s14
	ds_read_b128 v[228:231], v179 offset:20480
	buffer_load_dwordx4 v174, s[44:47], s27 offen lds
	s_mov_b32 m0, s24
	ds_read_b128 v[232:235], v179 offset:21504
	buffer_load_dwordx4 v176, s[44:47], s27 offen lds
	ds_read_b128 v[236:239], v179 offset:22528
	ds_read_b128 v[240:243], v179 offset:23552
	s_waitcnt vmcnt(8)
	s_waitcnt lgkmcnt(0)
	s_setprio 1
	s_barrier
	v_mfma_f32_16x16x32_bf16 v[62:65], v[134:137], v[192:195], 0
	v_mfma_f32_16x16x32_bf16 v[62:65], v[138:141], v[196:199], v[62:65]
	v_mfma_f32_16x16x32_bf16 v[58:61], v[142:145], v[192:195], 0
	v_mfma_f32_16x16x32_bf16 v[58:61], v[154:157], v[196:199], v[58:61]
	v_mfma_f32_16x16x32_bf16 v[50:53], v[184:187], v[192:195], 0
	v_mfma_f32_16x16x32_bf16 v[50:53], v[188:191], v[196:199], v[50:53]
	v_mfma_f32_16x16x32_bf16 v[54:57], v[170:173], v[192:195], 0
	v_mfma_f32_16x16x32_bf16 v[54:57], v[180:183], v[196:199], v[54:57]
	v_mfma_f32_16x16x32_bf16 v[38:41], v[170:173], v[200:203], 0
	v_mfma_f32_16x16x32_bf16 v[38:41], v[180:183], v[204:207], v[38:41]
	v_mfma_f32_16x16x32_bf16 v[34:37], v[184:187], v[200:203], 0
	v_mfma_f32_16x16x32_bf16 v[34:37], v[188:191], v[204:207], v[34:37]
	v_mfma_f32_16x16x32_bf16 v[42:45], v[142:145], v[200:203], 0
	v_mfma_f32_16x16x32_bf16 v[42:45], v[154:157], v[204:207], v[42:45]
	v_mfma_f32_16x16x32_bf16 v[46:49], v[134:137], v[200:203], 0
	v_mfma_f32_16x16x32_bf16 v[46:49], v[138:141], v[204:207], v[46:49]
	v_mfma_f32_16x16x32_bf16 v[30:33], v[134:137], v[228:231], 0
	v_mfma_f32_16x16x32_bf16 v[30:33], v[138:141], v[232:235], v[30:33]
	v_mfma_f32_16x16x32_bf16 v[26:29], v[142:145], v[228:231], 0
	v_mfma_f32_16x16x32_bf16 v[26:29], v[154:157], v[232:235], v[26:29]
	v_mfma_f32_16x16x32_bf16 v[18:21], v[184:187], v[228:231], 0
	v_mfma_f32_16x16x32_bf16 v[18:21], v[188:191], v[232:235], v[18:21]
	v_mfma_f32_16x16x32_bf16 v[22:25], v[170:173], v[228:231], 0
	v_mfma_f32_16x16x32_bf16 v[22:25], v[180:183], v[232:235], v[22:25]
	v_mfma_f32_16x16x32_bf16 v[6:9], v[170:173], v[236:239], 0
	v_mfma_f32_16x16x32_bf16 v[6:9], v[180:183], v[240:243], v[6:9]
	v_mfma_f32_16x16x32_bf16 v[2:5], v[184:187], v[236:239], 0
	v_mfma_f32_16x16x32_bf16 v[2:5], v[188:191], v[240:243], v[2:5]
	v_mfma_f32_16x16x32_bf16 v[10:13], v[142:145], v[236:239], 0
	v_mfma_f32_16x16x32_bf16 v[10:13], v[154:157], v[240:243], v[10:13]
	v_mfma_f32_16x16x32_bf16 v[14:17], v[134:137], v[236:239], 0
	v_mfma_f32_16x16x32_bf16 v[14:17], v[138:141], v[240:243], v[14:17]
	s_barrier
	s_setprio 0
	v_add_u32_e32 v133, 0x18000, v178
	ds_read_b128 v[134:137], v133
	ds_read_b128 v[138:141], v133 offset:1024
	ds_read_b128 v[142:145], v133 offset:2048
	ds_read_b128 v[154:157], v133 offset:3072
	v_add_u32_e32 v133, 0x1c000, v178
	ds_read_b128 v[170:173], v133
	ds_read_b128 v[180:183], v133 offset:1024
	ds_read_b128 v[184:187], v133 offset:2048
	ds_read_b128 v[188:191], v133 offset:3072
	s_add_i32 s27, s27, 0x80000
	s_mov_b32 m0, s25
	ds_read_b128 v[192:195], v179 offset:32768
	ds_read_b128 v[196:199], v179 offset:33792
	ds_read_b128 v[200:203], v179 offset:34816
	ds_read_b128 v[204:207], v179 offset:35840
	ds_read_b128 v[228:231], v179 offset:36864
	ds_read_b128 v[232:235], v179 offset:37888
	ds_read_b128 v[236:239], v179 offset:38912
	ds_read_b128 v[240:243], v179 offset:39936
	buffer_load_dwordx4 v174, s[44:47], s27 offen lds
	s_mov_b32 m0, s30
	s_nop 0
	buffer_load_dwordx4 v176, s[44:47], s27 offen lds
	s_waitcnt vmcnt(8)
	s_waitcnt lgkmcnt(0)
	s_setprio 1
	s_barrier
	v_mfma_f32_16x16x32_bf16 v[126:129], v[134:137], v[192:195], v[126:129]
	v_mfma_f32_16x16x32_bf16 v[126:129], v[138:141], v[196:199], v[126:129]
	v_mfma_f32_16x16x32_bf16 v[122:125], v[142:145], v[192:195], v[122:125]
	v_mfma_f32_16x16x32_bf16 v[122:125], v[154:157], v[196:199], v[122:125]
	v_mfma_f32_16x16x32_bf16 v[114:117], v[184:187], v[192:195], v[114:117]
	v_mfma_f32_16x16x32_bf16 v[114:117], v[188:191], v[196:199], v[114:117]
	v_mfma_f32_16x16x32_bf16 v[118:121], v[170:173], v[192:195], v[118:121]
	v_mfma_f32_16x16x32_bf16 v[118:121], v[180:183], v[196:199], v[118:121]
	v_mfma_f32_16x16x32_bf16 v[102:105], v[170:173], v[200:203], v[102:105]
	v_mfma_f32_16x16x32_bf16 v[102:105], v[180:183], v[204:207], v[102:105]
	v_mfma_f32_16x16x32_bf16 v[98:101], v[184:187], v[200:203], v[98:101]
	v_mfma_f32_16x16x32_bf16 v[98:101], v[188:191], v[204:207], v[98:101]
	v_mfma_f32_16x16x32_bf16 v[106:109], v[142:145], v[200:203], v[106:109]
	v_mfma_f32_16x16x32_bf16 v[106:109], v[154:157], v[204:207], v[106:109]
	v_mfma_f32_16x16x32_bf16 v[110:113], v[134:137], v[200:203], v[110:113]
	v_mfma_f32_16x16x32_bf16 v[110:113], v[138:141], v[204:207], v[110:113]
	v_mfma_f32_16x16x32_bf16 v[94:97], v[134:137], v[228:231], v[94:97]
	v_mfma_f32_16x16x32_bf16 v[94:97], v[138:141], v[232:235], v[94:97]
	v_mfma_f32_16x16x32_bf16 v[90:93], v[142:145], v[228:231], v[90:93]
	v_mfma_f32_16x16x32_bf16 v[90:93], v[154:157], v[232:235], v[90:93]
	v_mfma_f32_16x16x32_bf16 v[82:85], v[184:187], v[228:231], v[82:85]
	v_mfma_f32_16x16x32_bf16 v[82:85], v[188:191], v[232:235], v[82:85]
	v_mfma_f32_16x16x32_bf16 v[86:89], v[170:173], v[228:231], v[86:89]
	v_mfma_f32_16x16x32_bf16 v[86:89], v[180:183], v[232:235], v[86:89]
	v_mfma_f32_16x16x32_bf16 v[70:73], v[170:173], v[236:239], v[70:73]
	v_mfma_f32_16x16x32_bf16 v[70:73], v[180:183], v[240:243], v[70:73]
	v_mfma_f32_16x16x32_bf16 v[66:69], v[184:187], v[236:239], v[66:69]
	v_mfma_f32_16x16x32_bf16 v[66:69], v[188:191], v[240:243], v[66:69]
	v_mfma_f32_16x16x32_bf16 v[74:77], v[142:145], v[236:239], v[74:77]
	v_mfma_f32_16x16x32_bf16 v[74:77], v[154:157], v[240:243], v[74:77]
	v_mfma_f32_16x16x32_bf16 v[78:81], v[134:137], v[236:239], v[78:81]
	v_mfma_f32_16x16x32_bf16 v[78:81], v[138:141], v[240:243], v[78:81]
	s_barrier
	s_setprio 0
	s_or_b32 s27, s26, 0x80
	s_mov_b32 m0, s36
	ds_read_b128 v[192:195], v179 offset:49152
	buffer_load_dwordx4 v175, s[60:63], s27 offen lds
	s_add_i32 s26, s26, 0x80080
	s_mov_b32 m0, s37
	ds_read_b128 v[196:199], v179 offset:50176
	buffer_load_dwordx4 v177, s[60:63], s27 offen lds
	s_mov_b32 m0, s48
	ds_read_b128 v[200:203], v179 offset:51200
	buffer_load_dwordx4 v175, s[60:63], s26 offen lds
	s_mov_b32 m0, s49
	ds_read_b128 v[204:207], v179 offset:52224
	buffer_load_dwordx4 v177, s[60:63], s26 offen lds
	s_mov_b32 m0, s40
	ds_read_b128 v[228:231], v179 offset:53248
	buffer_load_dwordx4 v174, s[44:47], s23 offen lds
	s_mov_b32 m0, s41
	ds_read_b128 v[232:235], v179 offset:54272
	buffer_load_dwordx4 v176, s[44:47], s23 offen lds
	ds_read_b128 v[236:239], v179 offset:55296
	ds_read_b128 v[240:243], v179 offset:56320
	s_waitcnt vmcnt(8)
	s_waitcnt lgkmcnt(0)
	s_setprio 1
	s_barrier
	v_mfma_f32_16x16x32_bf16 v[62:65], v[134:137], v[192:195], v[62:65]
	v_mfma_f32_16x16x32_bf16 v[62:65], v[138:141], v[196:199], v[62:65]
	v_mfma_f32_16x16x32_bf16 v[58:61], v[142:145], v[192:195], v[58:61]
	v_mfma_f32_16x16x32_bf16 v[58:61], v[154:157], v[196:199], v[58:61]
	v_mfma_f32_16x16x32_bf16 v[50:53], v[184:187], v[192:195], v[50:53]
	v_mfma_f32_16x16x32_bf16 v[50:53], v[188:191], v[196:199], v[50:53]
	v_mfma_f32_16x16x32_bf16 v[54:57], v[170:173], v[192:195], v[54:57]
	v_mfma_f32_16x16x32_bf16 v[54:57], v[180:183], v[196:199], v[54:57]
	v_mfma_f32_16x16x32_bf16 v[38:41], v[170:173], v[200:203], v[38:41]
	v_mfma_f32_16x16x32_bf16 v[38:41], v[180:183], v[204:207], v[38:41]
	v_mfma_f32_16x16x32_bf16 v[34:37], v[184:187], v[200:203], v[34:37]
	v_mfma_f32_16x16x32_bf16 v[34:37], v[188:191], v[204:207], v[34:37]
	v_mfma_f32_16x16x32_bf16 v[42:45], v[142:145], v[200:203], v[42:45]
	v_mfma_f32_16x16x32_bf16 v[42:45], v[154:157], v[204:207], v[42:45]
	v_mfma_f32_16x16x32_bf16 v[46:49], v[134:137], v[200:203], v[46:49]
	v_mfma_f32_16x16x32_bf16 v[46:49], v[138:141], v[204:207], v[46:49]
	v_mfma_f32_16x16x32_bf16 v[30:33], v[134:137], v[228:231], v[30:33]
	v_mfma_f32_16x16x32_bf16 v[30:33], v[138:141], v[232:235], v[30:33]
	v_mfma_f32_16x16x32_bf16 v[26:29], v[142:145], v[228:231], v[26:29]
	v_mfma_f32_16x16x32_bf16 v[26:29], v[154:157], v[232:235], v[26:29]
	v_mfma_f32_16x16x32_bf16 v[18:21], v[184:187], v[228:231], v[18:21]
	v_mfma_f32_16x16x32_bf16 v[18:21], v[188:191], v[232:235], v[18:21]
	v_mfma_f32_16x16x32_bf16 v[22:25], v[170:173], v[228:231], v[22:25]
	v_mfma_f32_16x16x32_bf16 v[22:25], v[180:183], v[232:235], v[22:25]
	v_mfma_f32_16x16x32_bf16 v[6:9], v[170:173], v[236:239], v[6:9]
	v_mfma_f32_16x16x32_bf16 v[6:9], v[180:183], v[240:243], v[6:9]
	v_mfma_f32_16x16x32_bf16 v[2:5], v[184:187], v[236:239], v[2:5]
	v_mfma_f32_16x16x32_bf16 v[2:5], v[188:191], v[240:243], v[2:5]
	v_mfma_f32_16x16x32_bf16 v[10:13], v[142:145], v[236:239], v[10:13]
	v_mfma_f32_16x16x32_bf16 v[10:13], v[154:157], v[240:243], v[10:13]
	v_mfma_f32_16x16x32_bf16 v[14:17], v[134:137], v[236:239], v[14:17]
	v_mfma_f32_16x16x32_bf16 v[14:17], v[138:141], v[240:243], v[14:17]
	s_barrier
	s_setprio 0
	s_add_i32 s22, s22, 2
	s_addk_i32 s13, 0x100
	s_addk_i32 s21, 0x100
	s_cmp_gt_u32 s22, 29
.LBB0_905:
	v_add_u32_e32 v133, 0x10000, v178
	ds_read_b128 v[134:137], v133
	ds_read_b128 v[138:141], v133 offset:1024
	ds_read_b128 v[142:145], v133 offset:2048
	ds_read_b128 v[154:157], v133 offset:3072
	v_add_u32_e32 v133, 0x14000, v178
	ds_read_b128 v[170:173], v133
	ds_read_b128 v[180:183], v133 offset:1024
	ds_read_b128 v[184:187], v133 offset:2048
	ds_read_b128 v[188:191], v133 offset:3072
	s_add_i32 s23, s13, 0xfff80080
	s_cmp_eq_u32 s22, 28
	s_cselect_b32 s27, s8, s23
	s_cselect_b32 s26, s9, s21
	s_or_b32 s23, s27, 0x80
	s_mov_b32 s46, s62
	s_mov_b32 s47, s63
	s_mov_b32 m0, s68
	ds_read_b128 v[192:195], v179
	ds_read_b128 v[196:199], v179 offset:1024
	ds_read_b128 v[200:203], v179 offset:2048
	ds_read_b128 v[204:207], v179 offset:3072
	ds_read_b128 v[228:231], v179 offset:4096
	ds_read_b128 v[232:235], v179 offset:5120
	ds_read_b128 v[236:239], v179 offset:6144
	ds_read_b128 v[240:243], v179 offset:7168
	buffer_load_dwordx4 v174, s[44:47], s13 offen lds
	s_mov_b32 m0, s69
	s_nop 0
	buffer_load_dwordx4 v176, s[44:47], s13 offen lds
	s_waitcnt vmcnt(8)
	s_waitcnt lgkmcnt(0)
	s_setprio 1
	s_barrier
	v_mfma_f32_16x16x32_bf16 v[126:129], v[134:137], v[192:195], v[126:129]
	v_mfma_f32_16x16x32_bf16 v[126:129], v[138:141], v[196:199], v[126:129]
	v_mfma_f32_16x16x32_bf16 v[122:125], v[142:145], v[192:195], v[122:125]
	v_mfma_f32_16x16x32_bf16 v[122:125], v[154:157], v[196:199], v[122:125]
	v_mfma_f32_16x16x32_bf16 v[114:117], v[184:187], v[192:195], v[114:117]
	v_mfma_f32_16x16x32_bf16 v[114:117], v[188:191], v[196:199], v[114:117]
	v_mfma_f32_16x16x32_bf16 v[118:121], v[170:173], v[192:195], v[118:121]
	v_mfma_f32_16x16x32_bf16 v[118:121], v[180:183], v[196:199], v[118:121]
	v_mfma_f32_16x16x32_bf16 v[102:105], v[170:173], v[200:203], v[102:105]
	v_mfma_f32_16x16x32_bf16 v[102:105], v[180:183], v[204:207], v[102:105]
	v_mfma_f32_16x16x32_bf16 v[98:101], v[184:187], v[200:203], v[98:101]
	v_mfma_f32_16x16x32_bf16 v[98:101], v[188:191], v[204:207], v[98:101]
	v_mfma_f32_16x16x32_bf16 v[106:109], v[142:145], v[200:203], v[106:109]
	v_mfma_f32_16x16x32_bf16 v[106:109], v[154:157], v[204:207], v[106:109]
	v_mfma_f32_16x16x32_bf16 v[110:113], v[134:137], v[200:203], v[110:113]
	v_mfma_f32_16x16x32_bf16 v[110:113], v[138:141], v[204:207], v[110:113]
	v_mfma_f32_16x16x32_bf16 v[94:97], v[134:137], v[228:231], v[94:97]
	v_mfma_f32_16x16x32_bf16 v[94:97], v[138:141], v[232:235], v[94:97]
	v_mfma_f32_16x16x32_bf16 v[90:93], v[142:145], v[228:231], v[90:93]
	v_mfma_f32_16x16x32_bf16 v[90:93], v[154:157], v[232:235], v[90:93]
	v_mfma_f32_16x16x32_bf16 v[82:85], v[184:187], v[228:231], v[82:85]
	v_mfma_f32_16x16x32_bf16 v[82:85], v[188:191], v[232:235], v[82:85]
	v_mfma_f32_16x16x32_bf16 v[86:89], v[170:173], v[228:231], v[86:89]
	v_mfma_f32_16x16x32_bf16 v[86:89], v[180:183], v[232:235], v[86:89]
	v_mfma_f32_16x16x32_bf16 v[70:73], v[170:173], v[236:239], v[70:73]
	v_mfma_f32_16x16x32_bf16 v[70:73], v[180:183], v[240:243], v[70:73]
	v_mfma_f32_16x16x32_bf16 v[66:69], v[184:187], v[236:239], v[66:69]
	v_mfma_f32_16x16x32_bf16 v[66:69], v[188:191], v[240:243], v[66:69]
	v_mfma_f32_16x16x32_bf16 v[74:77], v[142:145], v[236:239], v[74:77]
	v_mfma_f32_16x16x32_bf16 v[74:77], v[154:157], v[240:243], v[74:77]
	v_mfma_f32_16x16x32_bf16 v[78:81], v[134:137], v[236:239], v[78:81]
	v_mfma_f32_16x16x32_bf16 v[78:81], v[138:141], v[240:243], v[78:81]
	s_barrier
	s_setprio 0
	s_mov_b32 m0, s15
	ds_read_b128 v[192:195], v179 offset:16384
	buffer_load_dwordx4 v175, s[60:63], s26 offen lds
	s_add_i32 s34, s26, 0x80000
	s_mov_b32 m0, s16
	ds_read_b128 v[196:199], v179 offset:17408
	buffer_load_dwordx4 v177, s[60:63], s26 offen lds
	s_mov_b32 m0, s18
	ds_read_b128 v[200:203], v179 offset:18432
	buffer_load_dwordx4 v175, s[60:63], s34 offen lds
	s_mov_b32 m0, s19
	ds_read_b128 v[204:207], v179 offset:19456
	buffer_load_dwordx4 v177, s[60:63], s34 offen lds
	s_mov_b32 m0, s14
	ds_read_b128 v[228:231], v179 offset:20480
	buffer_load_dwordx4 v174, s[44:47], s27 offen lds
	s_mov_b32 m0, s24
	ds_read_b128 v[232:235], v179 offset:21504
	buffer_load_dwordx4 v176, s[44:47], s27 offen lds
	ds_read_b128 v[236:239], v179 offset:22528
	ds_read_b128 v[240:243], v179 offset:23552
	s_waitcnt vmcnt(8)
	s_waitcnt lgkmcnt(0)
	s_setprio 1
	s_barrier
	v_mfma_f32_16x16x32_bf16 v[62:65], v[134:137], v[192:195], v[62:65]
	v_mfma_f32_16x16x32_bf16 v[62:65], v[138:141], v[196:199], v[62:65]
	v_mfma_f32_16x16x32_bf16 v[58:61], v[142:145], v[192:195], v[58:61]
	v_mfma_f32_16x16x32_bf16 v[58:61], v[154:157], v[196:199], v[58:61]
	v_mfma_f32_16x16x32_bf16 v[50:53], v[184:187], v[192:195], v[50:53]
	v_mfma_f32_16x16x32_bf16 v[50:53], v[188:191], v[196:199], v[50:53]
	v_mfma_f32_16x16x32_bf16 v[54:57], v[170:173], v[192:195], v[54:57]
	v_mfma_f32_16x16x32_bf16 v[54:57], v[180:183], v[196:199], v[54:57]
	v_mfma_f32_16x16x32_bf16 v[38:41], v[170:173], v[200:203], v[38:41]
	v_mfma_f32_16x16x32_bf16 v[38:41], v[180:183], v[204:207], v[38:41]
	v_mfma_f32_16x16x32_bf16 v[34:37], v[184:187], v[200:203], v[34:37]
	v_mfma_f32_16x16x32_bf16 v[34:37], v[188:191], v[204:207], v[34:37]
	v_mfma_f32_16x16x32_bf16 v[42:45], v[142:145], v[200:203], v[42:45]
	v_mfma_f32_16x16x32_bf16 v[42:45], v[154:157], v[204:207], v[42:45]
	v_mfma_f32_16x16x32_bf16 v[46:49], v[134:137], v[200:203], v[46:49]
	v_mfma_f32_16x16x32_bf16 v[46:49], v[138:141], v[204:207], v[46:49]
	v_mfma_f32_16x16x32_bf16 v[30:33], v[134:137], v[228:231], v[30:33]
	v_mfma_f32_16x16x32_bf16 v[30:33], v[138:141], v[232:235], v[30:33]
	v_mfma_f32_16x16x32_bf16 v[26:29], v[142:145], v[228:231], v[26:29]
	v_mfma_f32_16x16x32_bf16 v[26:29], v[154:157], v[232:235], v[26:29]
	v_mfma_f32_16x16x32_bf16 v[18:21], v[184:187], v[228:231], v[18:21]
	v_mfma_f32_16x16x32_bf16 v[18:21], v[188:191], v[232:235], v[18:21]
	v_mfma_f32_16x16x32_bf16 v[22:25], v[170:173], v[228:231], v[22:25]
	v_mfma_f32_16x16x32_bf16 v[22:25], v[180:183], v[232:235], v[22:25]
	v_mfma_f32_16x16x32_bf16 v[6:9], v[170:173], v[236:239], v[6:9]
	v_mfma_f32_16x16x32_bf16 v[6:9], v[180:183], v[240:243], v[6:9]
	v_mfma_f32_16x16x32_bf16 v[2:5], v[184:187], v[236:239], v[2:5]
	v_mfma_f32_16x16x32_bf16 v[2:5], v[188:191], v[240:243], v[2:5]
	v_mfma_f32_16x16x32_bf16 v[10:13], v[142:145], v[236:239], v[10:13]
	v_mfma_f32_16x16x32_bf16 v[10:13], v[154:157], v[240:243], v[10:13]
	v_mfma_f32_16x16x32_bf16 v[14:17], v[134:137], v[236:239], v[14:17]
	v_mfma_f32_16x16x32_bf16 v[14:17], v[138:141], v[240:243], v[14:17]
	s_barrier
	s_setprio 0
	v_add_u32_e32 v133, 0x18000, v178
	ds_read_b128 v[134:137], v133
	ds_read_b128 v[138:141], v133 offset:1024
	ds_read_b128 v[142:145], v133 offset:2048
	ds_read_b128 v[154:157], v133 offset:3072
	v_add_u32_e32 v133, 0x1c000, v178
	ds_read_b128 v[170:173], v133
	ds_read_b128 v[180:183], v133 offset:1024
	ds_read_b128 v[184:187], v133 offset:2048
	ds_read_b128 v[188:191], v133 offset:3072
	s_add_i32 s27, s27, 0x80000
	s_mov_b32 m0, s25
	ds_read_b128 v[192:195], v179 offset:32768
	ds_read_b128 v[196:199], v179 offset:33792
	ds_read_b128 v[200:203], v179 offset:34816
	ds_read_b128 v[204:207], v179 offset:35840
	ds_read_b128 v[228:231], v179 offset:36864
	ds_read_b128 v[232:235], v179 offset:37888
	ds_read_b128 v[236:239], v179 offset:38912
	ds_read_b128 v[240:243], v179 offset:39936
	buffer_load_dwordx4 v174, s[44:47], s27 offen lds
	s_mov_b32 m0, s30
	s_nop 0
	buffer_load_dwordx4 v176, s[44:47], s27 offen lds
	s_waitcnt vmcnt(8)
	s_waitcnt lgkmcnt(0)
	s_setprio 1
	s_barrier
	v_mfma_f32_16x16x32_bf16 v[126:129], v[134:137], v[192:195], v[126:129]
	v_mfma_f32_16x16x32_bf16 v[126:129], v[138:141], v[196:199], v[126:129]
	v_mfma_f32_16x16x32_bf16 v[122:125], v[142:145], v[192:195], v[122:125]
	v_mfma_f32_16x16x32_bf16 v[122:125], v[154:157], v[196:199], v[122:125]
	v_mfma_f32_16x16x32_bf16 v[114:117], v[184:187], v[192:195], v[114:117]
	v_mfma_f32_16x16x32_bf16 v[114:117], v[188:191], v[196:199], v[114:117]
	v_mfma_f32_16x16x32_bf16 v[118:121], v[170:173], v[192:195], v[118:121]
	v_mfma_f32_16x16x32_bf16 v[118:121], v[180:183], v[196:199], v[118:121]
	v_mfma_f32_16x16x32_bf16 v[102:105], v[170:173], v[200:203], v[102:105]
	v_mfma_f32_16x16x32_bf16 v[102:105], v[180:183], v[204:207], v[102:105]
	v_mfma_f32_16x16x32_bf16 v[98:101], v[184:187], v[200:203], v[98:101]
	v_mfma_f32_16x16x32_bf16 v[98:101], v[188:191], v[204:207], v[98:101]
	v_mfma_f32_16x16x32_bf16 v[106:109], v[142:145], v[200:203], v[106:109]
	v_mfma_f32_16x16x32_bf16 v[106:109], v[154:157], v[204:207], v[106:109]
	v_mfma_f32_16x16x32_bf16 v[110:113], v[134:137], v[200:203], v[110:113]
	v_mfma_f32_16x16x32_bf16 v[110:113], v[138:141], v[204:207], v[110:113]
	v_mfma_f32_16x16x32_bf16 v[94:97], v[134:137], v[228:231], v[94:97]
	v_mfma_f32_16x16x32_bf16 v[94:97], v[138:141], v[232:235], v[94:97]
	v_mfma_f32_16x16x32_bf16 v[90:93], v[142:145], v[228:231], v[90:93]
	v_mfma_f32_16x16x32_bf16 v[90:93], v[154:157], v[232:235], v[90:93]
	v_mfma_f32_16x16x32_bf16 v[82:85], v[184:187], v[228:231], v[82:85]
	v_mfma_f32_16x16x32_bf16 v[82:85], v[188:191], v[232:235], v[82:85]
	v_mfma_f32_16x16x32_bf16 v[86:89], v[170:173], v[228:231], v[86:89]
	v_mfma_f32_16x16x32_bf16 v[86:89], v[180:183], v[232:235], v[86:89]
	v_mfma_f32_16x16x32_bf16 v[70:73], v[170:173], v[236:239], v[70:73]
	v_mfma_f32_16x16x32_bf16 v[70:73], v[180:183], v[240:243], v[70:73]
	v_mfma_f32_16x16x32_bf16 v[66:69], v[184:187], v[236:239], v[66:69]
	v_mfma_f32_16x16x32_bf16 v[66:69], v[188:191], v[240:243], v[66:69]
	v_mfma_f32_16x16x32_bf16 v[74:77], v[142:145], v[236:239], v[74:77]
	v_mfma_f32_16x16x32_bf16 v[74:77], v[154:157], v[240:243], v[74:77]
	v_mfma_f32_16x16x32_bf16 v[78:81], v[134:137], v[236:239], v[78:81]
	v_mfma_f32_16x16x32_bf16 v[78:81], v[138:141], v[240:243], v[78:81]
	s_barrier
	s_setprio 0
	s_or_b32 s27, s26, 0x80
	s_mov_b32 m0, s36
	ds_read_b128 v[192:195], v179 offset:49152
	buffer_load_dwordx4 v175, s[60:63], s27 offen lds
	s_add_i32 s26, s26, 0x80080
	s_mov_b32 m0, s37
	ds_read_b128 v[196:199], v179 offset:50176
	buffer_load_dwordx4 v177, s[60:63], s27 offen lds
	s_mov_b32 m0, s48
	ds_read_b128 v[200:203], v179 offset:51200
	buffer_load_dwordx4 v175, s[60:63], s26 offen lds
	s_mov_b32 m0, s49
	ds_read_b128 v[204:207], v179 offset:52224
	buffer_load_dwordx4 v177, s[60:63], s26 offen lds
	s_mov_b32 m0, s40
	ds_read_b128 v[228:231], v179 offset:53248
	buffer_load_dwordx4 v174, s[44:47], s23 offen lds
	s_mov_b32 m0, s41
	ds_read_b128 v[232:235], v179 offset:54272
	buffer_load_dwordx4 v176, s[44:47], s23 offen lds
	ds_read_b128 v[236:239], v179 offset:55296
	ds_read_b128 v[240:243], v179 offset:56320
	s_waitcnt vmcnt(8)
	s_waitcnt lgkmcnt(0)
	s_setprio 1
	s_barrier
	v_mfma_f32_16x16x32_bf16 v[62:65], v[134:137], v[192:195], v[62:65]
	v_mfma_f32_16x16x32_bf16 v[62:65], v[138:141], v[196:199], v[62:65]
	v_mfma_f32_16x16x32_bf16 v[58:61], v[142:145], v[192:195], v[58:61]
	v_mfma_f32_16x16x32_bf16 v[58:61], v[154:157], v[196:199], v[58:61]
	v_mfma_f32_16x16x32_bf16 v[50:53], v[184:187], v[192:195], v[50:53]
	v_mfma_f32_16x16x32_bf16 v[50:53], v[188:191], v[196:199], v[50:53]
	v_mfma_f32_16x16x32_bf16 v[54:57], v[170:173], v[192:195], v[54:57]
	v_mfma_f32_16x16x32_bf16 v[54:57], v[180:183], v[196:199], v[54:57]
	v_mfma_f32_16x16x32_bf16 v[38:41], v[170:173], v[200:203], v[38:41]
	v_mfma_f32_16x16x32_bf16 v[38:41], v[180:183], v[204:207], v[38:41]
	v_mfma_f32_16x16x32_bf16 v[34:37], v[184:187], v[200:203], v[34:37]
	v_mfma_f32_16x16x32_bf16 v[34:37], v[188:191], v[204:207], v[34:37]
	v_mfma_f32_16x16x32_bf16 v[42:45], v[142:145], v[200:203], v[42:45]
	v_mfma_f32_16x16x32_bf16 v[42:45], v[154:157], v[204:207], v[42:45]
	v_mfma_f32_16x16x32_bf16 v[46:49], v[134:137], v[200:203], v[46:49]
	v_mfma_f32_16x16x32_bf16 v[46:49], v[138:141], v[204:207], v[46:49]
	v_mfma_f32_16x16x32_bf16 v[30:33], v[134:137], v[228:231], v[30:33]
	v_mfma_f32_16x16x32_bf16 v[30:33], v[138:141], v[232:235], v[30:33]
	v_mfma_f32_16x16x32_bf16 v[26:29], v[142:145], v[228:231], v[26:29]
	v_mfma_f32_16x16x32_bf16 v[26:29], v[154:157], v[232:235], v[26:29]
	v_mfma_f32_16x16x32_bf16 v[18:21], v[184:187], v[228:231], v[18:21]
	v_mfma_f32_16x16x32_bf16 v[18:21], v[188:191], v[232:235], v[18:21]
	v_mfma_f32_16x16x32_bf16 v[22:25], v[170:173], v[228:231], v[22:25]
	v_mfma_f32_16x16x32_bf16 v[22:25], v[180:183], v[232:235], v[22:25]
	v_mfma_f32_16x16x32_bf16 v[6:9], v[170:173], v[236:239], v[6:9]
	v_mfma_f32_16x16x32_bf16 v[6:9], v[180:183], v[240:243], v[6:9]
	v_mfma_f32_16x16x32_bf16 v[2:5], v[184:187], v[236:239], v[2:5]
	v_mfma_f32_16x16x32_bf16 v[2:5], v[188:191], v[240:243], v[2:5]
	v_mfma_f32_16x16x32_bf16 v[10:13], v[142:145], v[236:239], v[10:13]
	v_mfma_f32_16x16x32_bf16 v[10:13], v[154:157], v[240:243], v[10:13]
	v_mfma_f32_16x16x32_bf16 v[14:17], v[134:137], v[236:239], v[14:17]
	v_mfma_f32_16x16x32_bf16 v[14:17], v[138:141], v[240:243], v[14:17]
	s_barrier
	s_setprio 0
	s_add_i32 s22, s22, 2
	s_addk_i32 s13, 0x100
	s_addk_i32 s21, 0x100
	s_cmp_gt_u32 s22, 29
	s_cbranch_scc0 .LBB0_905
	s_and_b64 vcc, exec, s[64:65]
	s_cbranch_vccz .LBB0_908
	s_barrier

.LBB0_1192:
	s_lshl_b32 s12, s70, 22
	s_and_b64 s[8:9], s[26:27], exec
	s_cselect_b32 s8, s12, s30
	s_lshl_b32 s22, s71, 22
	s_and_b64 s[66:67], s[26:27], exec
	s_cselect_b32 s9, s22, s31
	s_add_i32 s30, s30, 0x200080
	s_addk_i32 s31, 0x100
	s_mov_b32 s72, -2
	v_add_u32_e32 v141, 0x10000, v139
	ds_read_b128 v[142:145], v141
	ds_read_b128 v[154:157], v141 offset:1024
	ds_read_b128 v[170:173], v141 offset:2048
	ds_read_b128 v[174:177], v141 offset:3072
	v_add_u32_e32 v141, 0x14000, v139
	ds_read_b128 v[178:181], v141
	ds_read_b128 v[182:185], v141 offset:1024
	ds_read_b128 v[186:189], v141 offset:2048
	ds_read_b128 v[190:193], v141 offset:3072
	s_add_i32 s52, s30, 0xffe00080
	s_cmpk_eq_i32 s72, 0x7c
	s_cselect_b32 s52, s8, s52
	s_cselect_b32 s82, s9, s31
	s_or_b32 s73, s52, 0x80
	s_mov_b32 m0, s69
	ds_read_b128 v[194:197], v140
	ds_read_b128 v[198:201], v140 offset:1024
	ds_read_b128 v[202:205], v140 offset:2048
	ds_read_b128 v[228:231], v140 offset:3072
	ds_read_b128 v[232:235], v140 offset:4096
	ds_read_b128 v[236:239], v140 offset:5120
	ds_read_b128 v[240:243], v140 offset:6144
	ds_read_b128 v[244:247], v140 offset:7168
	buffer_load_dwordx4 v131, s[60:63], s30 offen lds
	s_mov_b32 m0, s46
	s_nop 0
	buffer_load_dwordx4 v135, s[60:63], s30 offen lds
	s_waitcnt vmcnt(8)
	s_waitcnt lgkmcnt(0)
	s_setprio 1
	s_barrier
	v_mfma_f32_16x16x32_bf16 v[126:129], v[142:145], v[194:197], 0
	v_mfma_f32_16x16x32_bf16 v[126:129], v[154:157], v[198:201], v[126:129]
	v_mfma_f32_16x16x32_bf16 v[122:125], v[170:173], v[194:197], 0
	v_mfma_f32_16x16x32_bf16 v[122:125], v[174:177], v[198:201], v[122:125]
	v_mfma_f32_16x16x32_bf16 v[58:61], v[186:189], v[194:197], 0
	v_mfma_f32_16x16x32_bf16 v[58:61], v[190:193], v[198:201], v[58:61]
	v_mfma_f32_16x16x32_bf16 v[62:65], v[178:181], v[194:197], 0
	v_mfma_f32_16x16x32_bf16 v[62:65], v[182:185], v[198:201], v[62:65]
	v_mfma_f32_16x16x32_bf16 v[54:57], v[178:181], v[202:205], 0
	v_mfma_f32_16x16x32_bf16 v[54:57], v[182:185], v[228:231], v[54:57]
	v_mfma_f32_16x16x32_bf16 v[50:53], v[186:189], v[202:205], 0
	v_mfma_f32_16x16x32_bf16 v[50:53], v[190:193], v[228:231], v[50:53]
	v_mfma_f32_16x16x32_bf16 v[114:117], v[170:173], v[202:205], 0
	v_mfma_f32_16x16x32_bf16 v[114:117], v[174:177], v[228:231], v[114:117]
	v_mfma_f32_16x16x32_bf16 v[118:121], v[142:145], v[202:205], 0
	v_mfma_f32_16x16x32_bf16 v[118:121], v[154:157], v[228:231], v[118:121]
	v_mfma_f32_16x16x32_bf16 v[110:113], v[142:145], v[232:235], 0
	v_mfma_f32_16x16x32_bf16 v[110:113], v[154:157], v[236:239], v[110:113]
	v_mfma_f32_16x16x32_bf16 v[106:109], v[170:173], v[232:235], 0
	v_mfma_f32_16x16x32_bf16 v[106:109], v[174:177], v[236:239], v[106:109]
	v_mfma_f32_16x16x32_bf16 v[42:45], v[186:189], v[232:235], 0
	v_mfma_f32_16x16x32_bf16 v[42:45], v[190:193], v[236:239], v[42:45]
	v_mfma_f32_16x16x32_bf16 v[46:49], v[178:181], v[232:235], 0
	v_mfma_f32_16x16x32_bf16 v[46:49], v[182:185], v[236:239], v[46:49]
	v_mfma_f32_16x16x32_bf16 v[38:41], v[178:181], v[240:243], 0
	v_mfma_f32_16x16x32_bf16 v[38:41], v[182:185], v[244:247], v[38:41]
	v_mfma_f32_16x16x32_bf16 v[34:37], v[186:189], v[240:243], 0
	v_mfma_f32_16x16x32_bf16 v[34:37], v[190:193], v[244:247], v[34:37]
	v_mfma_f32_16x16x32_bf16 v[98:101], v[170:173], v[240:243], 0
	v_mfma_f32_16x16x32_bf16 v[98:101], v[174:177], v[244:247], v[98:101]
	v_mfma_f32_16x16x32_bf16 v[102:105], v[142:145], v[240:243], 0
	v_mfma_f32_16x16x32_bf16 v[102:105], v[154:157], v[244:247], v[102:105]
	s_barrier
	s_setprio 0
	s_mov_b32 s66, s62
	s_mov_b32 s67, s63
	s_mov_b32 m0, s15
	ds_read_b128 v[194:197], v140 offset:16384
	buffer_load_dwordx4 v134, s[64:67], s82 offen lds
	s_add_i32 s53, s82, 0x200000
	s_mov_b32 m0, s16
	ds_read_b128 v[198:201], v140 offset:17408
	buffer_load_dwordx4 v136, s[64:67], s82 offen lds
	s_mov_b32 m0, s21
	ds_read_b128 v[202:205], v140 offset:18432
	buffer_load_dwordx4 v134, s[64:67], s53 offen lds
	s_mov_b32 m0, s23
	ds_read_b128 v[228:231], v140 offset:19456
	buffer_load_dwordx4 v136, s[64:67], s53 offen lds
	s_mov_b32 m0, s2
	ds_read_b128 v[232:235], v140 offset:20480
	buffer_load_dwordx4 v131, s[60:63], s52 offen lds
	s_mov_b32 m0, s24
	ds_read_b128 v[236:239], v140 offset:21504
	buffer_load_dwordx4 v135, s[60:63], s52 offen lds
	ds_read_b128 v[240:243], v140 offset:22528
	ds_read_b128 v[244:247], v140 offset:23552
	s_waitcnt vmcnt(8)
	s_waitcnt lgkmcnt(0)
	s_setprio 1
	s_barrier
	v_mfma_f32_16x16x32_bf16 v[94:97], v[142:145], v[194:197], 0
	v_mfma_f32_16x16x32_bf16 v[94:97], v[154:157], v[198:201], v[94:97]
	v_mfma_f32_16x16x32_bf16 v[90:93], v[170:173], v[194:197], 0
	v_mfma_f32_16x16x32_bf16 v[90:93], v[174:177], v[198:201], v[90:93]
	v_mfma_f32_16x16x32_bf16 v[26:29], v[186:189], v[194:197], 0
	v_mfma_f32_16x16x32_bf16 v[26:29], v[190:193], v[198:201], v[26:29]
	v_mfma_f32_16x16x32_bf16 v[30:33], v[178:181], v[194:197], 0
	v_mfma_f32_16x16x32_bf16 v[30:33], v[182:185], v[198:201], v[30:33]
	v_mfma_f32_16x16x32_bf16 v[22:25], v[178:181], v[202:205], 0
	v_mfma_f32_16x16x32_bf16 v[22:25], v[182:185], v[228:231], v[22:25]
	v_mfma_f32_16x16x32_bf16 v[18:21], v[186:189], v[202:205], 0
	v_mfma_f32_16x16x32_bf16 v[18:21], v[190:193], v[228:231], v[18:21]
	v_mfma_f32_16x16x32_bf16 v[82:85], v[170:173], v[202:205], 0
	v_mfma_f32_16x16x32_bf16 v[82:85], v[174:177], v[228:231], v[82:85]
	v_mfma_f32_16x16x32_bf16 v[86:89], v[142:145], v[202:205], 0
	v_mfma_f32_16x16x32_bf16 v[86:89], v[154:157], v[228:231], v[86:89]
	v_mfma_f32_16x16x32_bf16 v[78:81], v[142:145], v[232:235], 0
	v_mfma_f32_16x16x32_bf16 v[78:81], v[154:157], v[236:239], v[78:81]
	v_mfma_f32_16x16x32_bf16 v[74:77], v[170:173], v[232:235], 0
	v_mfma_f32_16x16x32_bf16 v[74:77], v[174:177], v[236:239], v[74:77]
	v_mfma_f32_16x16x32_bf16 v[10:13], v[186:189], v[232:235], 0
	v_mfma_f32_16x16x32_bf16 v[10:13], v[190:193], v[236:239], v[10:13]
	v_mfma_f32_16x16x32_bf16 v[14:17], v[178:181], v[232:235], 0
	v_mfma_f32_16x16x32_bf16 v[14:17], v[182:185], v[236:239], v[14:17]
	v_mfma_f32_16x16x32_bf16 v[6:9], v[178:181], v[240:243], 0
	v_mfma_f32_16x16x32_bf16 v[6:9], v[182:185], v[244:247], v[6:9]
	v_mfma_f32_16x16x32_bf16 v[2:5], v[186:189], v[240:243], 0
	v_mfma_f32_16x16x32_bf16 v[2:5], v[190:193], v[244:247], v[2:5]
	v_mfma_f32_16x16x32_bf16 v[66:69], v[170:173], v[240:243], 0
	v_mfma_f32_16x16x32_bf16 v[66:69], v[174:177], v[244:247], v[66:69]
	v_mfma_f32_16x16x32_bf16 v[70:73], v[142:145], v[240:243], 0
	v_mfma_f32_16x16x32_bf16 v[70:73], v[154:157], v[244:247], v[70:73]
	s_barrier
	s_setprio 0
	v_add_u32_e32 v141, 0x18000, v139
	ds_read_b128 v[142:145], v141
	ds_read_b128 v[154:157], v141 offset:1024
	ds_read_b128 v[170:173], v141 offset:2048
	ds_read_b128 v[174:177], v141 offset:3072
	v_add_u32_e32 v141, 0x1c000, v139
	ds_read_b128 v[178:181], v141
	ds_read_b128 v[182:185], v141 offset:1024
	ds_read_b128 v[186:189], v141 offset:2048
	ds_read_b128 v[190:193], v141 offset:3072
	s_add_i32 s52, s52, 0x200000
	s_mov_b32 m0, s25
	ds_read_b128 v[194:197], v140 offset:32768
	ds_read_b128 v[198:201], v140 offset:33792
	ds_read_b128 v[202:205], v140 offset:34816
	ds_read_b128 v[228:231], v140 offset:35840
	ds_read_b128 v[232:235], v140 offset:36864
	ds_read_b128 v[236:239], v140 offset:37888
	ds_read_b128 v[240:243], v140 offset:38912
	ds_read_b128 v[244:247], v140 offset:39936
	buffer_load_dwordx4 v131, s[60:63], s52 offen lds
	s_mov_b32 m0, s33
	s_nop 0
	buffer_load_dwordx4 v135, s[60:63], s52 offen lds
	s_waitcnt vmcnt(8)
	s_waitcnt lgkmcnt(0)
	s_setprio 1
	s_barrier
	v_mfma_f32_16x16x32_bf16 v[126:129], v[142:145], v[194:197], v[126:129]
	v_mfma_f32_16x16x32_bf16 v[126:129], v[154:157], v[198:201], v[126:129]
	v_mfma_f32_16x16x32_bf16 v[122:125], v[170:173], v[194:197], v[122:125]
	v_mfma_f32_16x16x32_bf16 v[122:125], v[174:177], v[198:201], v[122:125]
	v_mfma_f32_16x16x32_bf16 v[58:61], v[186:189], v[194:197], v[58:61]
	v_mfma_f32_16x16x32_bf16 v[58:61], v[190:193], v[198:201], v[58:61]
	v_mfma_f32_16x16x32_bf16 v[62:65], v[178:181], v[194:197], v[62:65]
	v_mfma_f32_16x16x32_bf16 v[62:65], v[182:185], v[198:201], v[62:65]
	v_mfma_f32_16x16x32_bf16 v[54:57], v[178:181], v[202:205], v[54:57]
	v_mfma_f32_16x16x32_bf16 v[54:57], v[182:185], v[228:231], v[54:57]
	v_mfma_f32_16x16x32_bf16 v[50:53], v[186:189], v[202:205], v[50:53]
	v_mfma_f32_16x16x32_bf16 v[50:53], v[190:193], v[228:231], v[50:53]
	v_mfma_f32_16x16x32_bf16 v[114:117], v[170:173], v[202:205], v[114:117]
	v_mfma_f32_16x16x32_bf16 v[114:117], v[174:177], v[228:231], v[114:117]
	v_mfma_f32_16x16x32_bf16 v[118:121], v[142:145], v[202:205], v[118:121]
	v_mfma_f32_16x16x32_bf16 v[118:121], v[154:157], v[228:231], v[118:121]
	v_mfma_f32_16x16x32_bf16 v[110:113], v[142:145], v[232:235], v[110:113]
	v_mfma_f32_16x16x32_bf16 v[110:113], v[154:157], v[236:239], v[110:113]
	v_mfma_f32_16x16x32_bf16 v[106:109], v[170:173], v[232:235], v[106:109]
	v_mfma_f32_16x16x32_bf16 v[106:109], v[174:177], v[236:239], v[106:109]
	v_mfma_f32_16x16x32_bf16 v[42:45], v[186:189], v[232:235], v[42:45]
	v_mfma_f32_16x16x32_bf16 v[42:45], v[190:193], v[236:239], v[42:45]
	v_mfma_f32_16x16x32_bf16 v[46:49], v[178:181], v[232:235], v[46:49]
	v_mfma_f32_16x16x32_bf16 v[46:49], v[182:185], v[236:239], v[46:49]
	v_mfma_f32_16x16x32_bf16 v[38:41], v[178:181], v[240:243], v[38:41]
	v_mfma_f32_16x16x32_bf16 v[38:41], v[182:185], v[244:247], v[38:41]
	v_mfma_f32_16x16x32_bf16 v[34:37], v[186:189], v[240:243], v[34:37]
	v_mfma_f32_16x16x32_bf16 v[34:37], v[190:193], v[244:247], v[34:37]
	v_mfma_f32_16x16x32_bf16 v[98:101], v[170:173], v[240:243], v[98:101]
	v_mfma_f32_16x16x32_bf16 v[98:101], v[174:177], v[244:247], v[98:101]
	v_mfma_f32_16x16x32_bf16 v[102:105], v[142:145], v[240:243], v[102:105]
	v_mfma_f32_16x16x32_bf16 v[102:105], v[154:157], v[244:247], v[102:105]
	s_barrier
	s_setprio 0
	s_or_b32 s52, s82, 0x80
	s_mov_b32 m0, s34
	ds_read_b128 v[194:197], v140 offset:49152
	buffer_load_dwordx4 v134, s[64:67], s52 offen lds
	s_add_i32 s82, s82, 0x200080
	s_mov_b32 m0, s35
	ds_read_b128 v[198:201], v140 offset:50176
	buffer_load_dwordx4 v136, s[64:67], s52 offen lds
	s_mov_b32 m0, s37
	ds_read_b128 v[202:205], v140 offset:51200
	buffer_load_dwordx4 v134, s[64:67], s82 offen lds
	s_mov_b32 m0, s44
	ds_read_b128 v[228:231], v140 offset:52224
	buffer_load_dwordx4 v136, s[64:67], s82 offen lds
	s_mov_b32 m0, s14
	ds_read_b128 v[232:235], v140 offset:53248
	buffer_load_dwordx4 v131, s[60:63], s73 offen lds
	s_mov_b32 m0, s36
	ds_read_b128 v[236:239], v140 offset:54272
	buffer_load_dwordx4 v135, s[60:63], s73 offen lds
	ds_read_b128 v[240:243], v140 offset:55296
	ds_read_b128 v[244:247], v140 offset:56320
	s_waitcnt vmcnt(8)
	s_waitcnt lgkmcnt(0)
	s_setprio 1
	s_barrier
	v_mfma_f32_16x16x32_bf16 v[94:97], v[142:145], v[194:197], v[94:97]
	v_mfma_f32_16x16x32_bf16 v[94:97], v[154:157], v[198:201], v[94:97]
	v_mfma_f32_16x16x32_bf16 v[90:93], v[170:173], v[194:197], v[90:93]
	v_mfma_f32_16x16x32_bf16 v[90:93], v[174:177], v[198:201], v[90:93]
	v_mfma_f32_16x16x32_bf16 v[26:29], v[186:189], v[194:197], v[26:29]
	v_mfma_f32_16x16x32_bf16 v[26:29], v[190:193], v[198:201], v[26:29]
	v_mfma_f32_16x16x32_bf16 v[30:33], v[178:181], v[194:197], v[30:33]
	v_mfma_f32_16x16x32_bf16 v[30:33], v[182:185], v[198:201], v[30:33]
	v_mfma_f32_16x16x32_bf16 v[22:25], v[178:181], v[202:205], v[22:25]
	v_mfma_f32_16x16x32_bf16 v[22:25], v[182:185], v[228:231], v[22:25]
	v_mfma_f32_16x16x32_bf16 v[18:21], v[186:189], v[202:205], v[18:21]
	v_mfma_f32_16x16x32_bf16 v[18:21], v[190:193], v[228:231], v[18:21]
	v_mfma_f32_16x16x32_bf16 v[82:85], v[170:173], v[202:205], v[82:85]
	v_mfma_f32_16x16x32_bf16 v[82:85], v[174:177], v[228:231], v[82:85]
	v_mfma_f32_16x16x32_bf16 v[86:89], v[142:145], v[202:205], v[86:89]
	v_mfma_f32_16x16x32_bf16 v[86:89], v[154:157], v[228:231], v[86:89]
	v_mfma_f32_16x16x32_bf16 v[78:81], v[142:145], v[232:235], v[78:81]
	v_mfma_f32_16x16x32_bf16 v[78:81], v[154:157], v[236:239], v[78:81]
	v_mfma_f32_16x16x32_bf16 v[74:77], v[170:173], v[232:235], v[74:77]
	v_mfma_f32_16x16x32_bf16 v[74:77], v[174:177], v[236:239], v[74:77]
	v_mfma_f32_16x16x32_bf16 v[10:13], v[186:189], v[232:235], v[10:13]
	v_mfma_f32_16x16x32_bf16 v[10:13], v[190:193], v[236:239], v[10:13]
	v_mfma_f32_16x16x32_bf16 v[14:17], v[178:181], v[232:235], v[14:17]
	v_mfma_f32_16x16x32_bf16 v[14:17], v[182:185], v[236:239], v[14:17]
	v_mfma_f32_16x16x32_bf16 v[6:9], v[178:181], v[240:243], v[6:9]
	v_mfma_f32_16x16x32_bf16 v[6:9], v[182:185], v[244:247], v[6:9]
	v_mfma_f32_16x16x32_bf16 v[2:5], v[186:189], v[240:243], v[2:5]
	v_mfma_f32_16x16x32_bf16 v[2:5], v[190:193], v[244:247], v[2:5]
	v_mfma_f32_16x16x32_bf16 v[66:69], v[170:173], v[240:243], v[66:69]
	v_mfma_f32_16x16x32_bf16 v[66:69], v[174:177], v[244:247], v[66:69]
	v_mfma_f32_16x16x32_bf16 v[70:73], v[142:145], v[240:243], v[70:73]
	v_mfma_f32_16x16x32_bf16 v[70:73], v[154:157], v[244:247], v[70:73]
	s_barrier
	s_setprio 0
	s_add_i32 s72, s72, 2
	s_addk_i32 s30, 0x100
	s_addk_i32 s31, 0x100
	s_cmpk_gt_u32 s72, 0x7d
.LBB0_1193:
	v_add_u32_e32 v141, 0x10000, v139
	ds_read_b128 v[142:145], v141
	ds_read_b128 v[154:157], v141 offset:1024
	ds_read_b128 v[170:173], v141 offset:2048
	ds_read_b128 v[174:177], v141 offset:3072
	v_add_u32_e32 v141, 0x14000, v139
	ds_read_b128 v[178:181], v141
	ds_read_b128 v[182:185], v141 offset:1024
	ds_read_b128 v[186:189], v141 offset:2048
	ds_read_b128 v[190:193], v141 offset:3072
	s_add_i32 s52, s30, 0xffe00080
	s_cmpk_eq_i32 s72, 0x7c
	s_cselect_b32 s52, s8, s52
	s_cselect_b32 s82, s9, s31
	s_or_b32 s73, s52, 0x80
	s_mov_b32 m0, s69
	ds_read_b128 v[194:197], v140
	ds_read_b128 v[198:201], v140 offset:1024
	ds_read_b128 v[202:205], v140 offset:2048
	ds_read_b128 v[228:231], v140 offset:3072
	ds_read_b128 v[232:235], v140 offset:4096
	ds_read_b128 v[236:239], v140 offset:5120
	ds_read_b128 v[240:243], v140 offset:6144
	ds_read_b128 v[244:247], v140 offset:7168
	buffer_load_dwordx4 v131, s[60:63], s30 offen lds
	s_mov_b32 m0, s46
	s_nop 0
	buffer_load_dwordx4 v135, s[60:63], s30 offen lds
	s_waitcnt vmcnt(8)
	s_waitcnt lgkmcnt(0)
	s_setprio 1
	s_barrier
	v_mfma_f32_16x16x32_bf16 v[126:129], v[142:145], v[194:197], v[126:129]
	v_mfma_f32_16x16x32_bf16 v[126:129], v[154:157], v[198:201], v[126:129]
	v_mfma_f32_16x16x32_bf16 v[122:125], v[170:173], v[194:197], v[122:125]
	v_mfma_f32_16x16x32_bf16 v[122:125], v[174:177], v[198:201], v[122:125]
	v_mfma_f32_16x16x32_bf16 v[58:61], v[186:189], v[194:197], v[58:61]
	v_mfma_f32_16x16x32_bf16 v[58:61], v[190:193], v[198:201], v[58:61]
	v_mfma_f32_16x16x32_bf16 v[62:65], v[178:181], v[194:197], v[62:65]
	v_mfma_f32_16x16x32_bf16 v[62:65], v[182:185], v[198:201], v[62:65]
	v_mfma_f32_16x16x32_bf16 v[54:57], v[178:181], v[202:205], v[54:57]
	v_mfma_f32_16x16x32_bf16 v[54:57], v[182:185], v[228:231], v[54:57]
	v_mfma_f32_16x16x32_bf16 v[50:53], v[186:189], v[202:205], v[50:53]
	v_mfma_f32_16x16x32_bf16 v[50:53], v[190:193], v[228:231], v[50:53]
	v_mfma_f32_16x16x32_bf16 v[114:117], v[170:173], v[202:205], v[114:117]
	v_mfma_f32_16x16x32_bf16 v[114:117], v[174:177], v[228:231], v[114:117]
	v_mfma_f32_16x16x32_bf16 v[118:121], v[142:145], v[202:205], v[118:121]
	v_mfma_f32_16x16x32_bf16 v[118:121], v[154:157], v[228:231], v[118:121]
	v_mfma_f32_16x16x32_bf16 v[110:113], v[142:145], v[232:235], v[110:113]
	v_mfma_f32_16x16x32_bf16 v[110:113], v[154:157], v[236:239], v[110:113]
	v_mfma_f32_16x16x32_bf16 v[106:109], v[170:173], v[232:235], v[106:109]
	v_mfma_f32_16x16x32_bf16 v[106:109], v[174:177], v[236:239], v[106:109]
	v_mfma_f32_16x16x32_bf16 v[42:45], v[186:189], v[232:235], v[42:45]
	v_mfma_f32_16x16x32_bf16 v[42:45], v[190:193], v[236:239], v[42:45]
	v_mfma_f32_16x16x32_bf16 v[46:49], v[178:181], v[232:235], v[46:49]
	v_mfma_f32_16x16x32_bf16 v[46:49], v[182:185], v[236:239], v[46:49]
	v_mfma_f32_16x16x32_bf16 v[38:41], v[178:181], v[240:243], v[38:41]
	v_mfma_f32_16x16x32_bf16 v[38:41], v[182:185], v[244:247], v[38:41]
	v_mfma_f32_16x16x32_bf16 v[34:37], v[186:189], v[240:243], v[34:37]
	v_mfma_f32_16x16x32_bf16 v[34:37], v[190:193], v[244:247], v[34:37]
	v_mfma_f32_16x16x32_bf16 v[98:101], v[170:173], v[240:243], v[98:101]
	v_mfma_f32_16x16x32_bf16 v[98:101], v[174:177], v[244:247], v[98:101]
	v_mfma_f32_16x16x32_bf16 v[102:105], v[142:145], v[240:243], v[102:105]
	v_mfma_f32_16x16x32_bf16 v[102:105], v[154:157], v[244:247], v[102:105]
	s_barrier
	s_setprio 0
	s_mov_b32 s66, s62
	s_mov_b32 s67, s63
	s_mov_b32 m0, s15
	ds_read_b128 v[194:197], v140 offset:16384
	buffer_load_dwordx4 v134, s[64:67], s82 offen lds
	s_add_i32 s53, s82, 0x200000
	s_mov_b32 m0, s16
	ds_read_b128 v[198:201], v140 offset:17408
	buffer_load_dwordx4 v136, s[64:67], s82 offen lds
	s_mov_b32 m0, s21
	ds_read_b128 v[202:205], v140 offset:18432
	buffer_load_dwordx4 v134, s[64:67], s53 offen lds
	s_mov_b32 m0, s23
	ds_read_b128 v[228:231], v140 offset:19456
	buffer_load_dwordx4 v136, s[64:67], s53 offen lds
	s_mov_b32 m0, s2
	ds_read_b128 v[232:235], v140 offset:20480
	buffer_load_dwordx4 v131, s[60:63], s52 offen lds
	s_mov_b32 m0, s24
	ds_read_b128 v[236:239], v140 offset:21504
	buffer_load_dwordx4 v135, s[60:63], s52 offen lds
	ds_read_b128 v[240:243], v140 offset:22528
	ds_read_b128 v[244:247], v140 offset:23552
	s_waitcnt vmcnt(8)
	s_waitcnt lgkmcnt(0)
	s_setprio 1
	s_barrier
	v_mfma_f32_16x16x32_bf16 v[94:97], v[142:145], v[194:197], v[94:97]
	v_mfma_f32_16x16x32_bf16 v[94:97], v[154:157], v[198:201], v[94:97]
	v_mfma_f32_16x16x32_bf16 v[90:93], v[170:173], v[194:197], v[90:93]
	v_mfma_f32_16x16x32_bf16 v[90:93], v[174:177], v[198:201], v[90:93]
	v_mfma_f32_16x16x32_bf16 v[26:29], v[186:189], v[194:197], v[26:29]
	v_mfma_f32_16x16x32_bf16 v[26:29], v[190:193], v[198:201], v[26:29]
	v_mfma_f32_16x16x32_bf16 v[30:33], v[178:181], v[194:197], v[30:33]
	v_mfma_f32_16x16x32_bf16 v[30:33], v[182:185], v[198:201], v[30:33]
	v_mfma_f32_16x16x32_bf16 v[22:25], v[178:181], v[202:205], v[22:25]
	v_mfma_f32_16x16x32_bf16 v[22:25], v[182:185], v[228:231], v[22:25]
	v_mfma_f32_16x16x32_bf16 v[18:21], v[186:189], v[202:205], v[18:21]
	v_mfma_f32_16x16x32_bf16 v[18:21], v[190:193], v[228:231], v[18:21]
	v_mfma_f32_16x16x32_bf16 v[82:85], v[170:173], v[202:205], v[82:85]
	v_mfma_f32_16x16x32_bf16 v[82:85], v[174:177], v[228:231], v[82:85]
	v_mfma_f32_16x16x32_bf16 v[86:89], v[142:145], v[202:205], v[86:89]
	v_mfma_f32_16x16x32_bf16 v[86:89], v[154:157], v[228:231], v[86:89]
	v_mfma_f32_16x16x32_bf16 v[78:81], v[142:145], v[232:235], v[78:81]
	v_mfma_f32_16x16x32_bf16 v[78:81], v[154:157], v[236:239], v[78:81]
	v_mfma_f32_16x16x32_bf16 v[74:77], v[170:173], v[232:235], v[74:77]
	v_mfma_f32_16x16x32_bf16 v[74:77], v[174:177], v[236:239], v[74:77]
	v_mfma_f32_16x16x32_bf16 v[10:13], v[186:189], v[232:235], v[10:13]
	v_mfma_f32_16x16x32_bf16 v[10:13], v[190:193], v[236:239], v[10:13]
	v_mfma_f32_16x16x32_bf16 v[14:17], v[178:181], v[232:235], v[14:17]
	v_mfma_f32_16x16x32_bf16 v[14:17], v[182:185], v[236:239], v[14:17]
	v_mfma_f32_16x16x32_bf16 v[6:9], v[178:181], v[240:243], v[6:9]
	v_mfma_f32_16x16x32_bf16 v[6:9], v[182:185], v[244:247], v[6:9]
	v_mfma_f32_16x16x32_bf16 v[2:5], v[186:189], v[240:243], v[2:5]
	v_mfma_f32_16x16x32_bf16 v[2:5], v[190:193], v[244:247], v[2:5]
	v_mfma_f32_16x16x32_bf16 v[66:69], v[170:173], v[240:243], v[66:69]
	v_mfma_f32_16x16x32_bf16 v[66:69], v[174:177], v[244:247], v[66:69]
	v_mfma_f32_16x16x32_bf16 v[70:73], v[142:145], v[240:243], v[70:73]
	v_mfma_f32_16x16x32_bf16 v[70:73], v[154:157], v[244:247], v[70:73]
	s_barrier
	s_setprio 0
	v_add_u32_e32 v141, 0x18000, v139
	ds_read_b128 v[142:145], v141
	ds_read_b128 v[154:157], v141 offset:1024
	ds_read_b128 v[170:173], v141 offset:2048
	ds_read_b128 v[174:177], v141 offset:3072
	v_add_u32_e32 v141, 0x1c000, v139
	ds_read_b128 v[178:181], v141
	ds_read_b128 v[182:185], v141 offset:1024
	ds_read_b128 v[186:189], v141 offset:2048
	ds_read_b128 v[190:193], v141 offset:3072
	s_add_i32 s52, s52, 0x200000
	s_mov_b32 m0, s25
	ds_read_b128 v[194:197], v140 offset:32768
	ds_read_b128 v[198:201], v140 offset:33792
	ds_read_b128 v[202:205], v140 offset:34816
	ds_read_b128 v[228:231], v140 offset:35840
	ds_read_b128 v[232:235], v140 offset:36864
	ds_read_b128 v[236:239], v140 offset:37888
	ds_read_b128 v[240:243], v140 offset:38912
	ds_read_b128 v[244:247], v140 offset:39936
	buffer_load_dwordx4 v131, s[60:63], s52 offen lds
	s_mov_b32 m0, s33
	s_nop 0
	buffer_load_dwordx4 v135, s[60:63], s52 offen lds
	s_waitcnt vmcnt(8)
	s_waitcnt lgkmcnt(0)
	s_setprio 1
	s_barrier
	v_mfma_f32_16x16x32_bf16 v[126:129], v[142:145], v[194:197], v[126:129]
	v_mfma_f32_16x16x32_bf16 v[126:129], v[154:157], v[198:201], v[126:129]
	v_mfma_f32_16x16x32_bf16 v[122:125], v[170:173], v[194:197], v[122:125]
	v_mfma_f32_16x16x32_bf16 v[122:125], v[174:177], v[198:201], v[122:125]
	v_mfma_f32_16x16x32_bf16 v[58:61], v[186:189], v[194:197], v[58:61]
	v_mfma_f32_16x16x32_bf16 v[58:61], v[190:193], v[198:201], v[58:61]
	v_mfma_f32_16x16x32_bf16 v[62:65], v[178:181], v[194:197], v[62:65]
	v_mfma_f32_16x16x32_bf16 v[62:65], v[182:185], v[198:201], v[62:65]
	v_mfma_f32_16x16x32_bf16 v[54:57], v[178:181], v[202:205], v[54:57]
	v_mfma_f32_16x16x32_bf16 v[54:57], v[182:185], v[228:231], v[54:57]
	v_mfma_f32_16x16x32_bf16 v[50:53], v[186:189], v[202:205], v[50:53]
	v_mfma_f32_16x16x32_bf16 v[50:53], v[190:193], v[228:231], v[50:53]
	v_mfma_f32_16x16x32_bf16 v[114:117], v[170:173], v[202:205], v[114:117]
	v_mfma_f32_16x16x32_bf16 v[114:117], v[174:177], v[228:231], v[114:117]
	v_mfma_f32_16x16x32_bf16 v[118:121], v[142:145], v[202:205], v[118:121]
	v_mfma_f32_16x16x32_bf16 v[118:121], v[154:157], v[228:231], v[118:121]
	v_mfma_f32_16x16x32_bf16 v[110:113], v[142:145], v[232:235], v[110:113]
	v_mfma_f32_16x16x32_bf16 v[110:113], v[154:157], v[236:239], v[110:113]
	v_mfma_f32_16x16x32_bf16 v[106:109], v[170:173], v[232:235], v[106:109]
	v_mfma_f32_16x16x32_bf16 v[106:109], v[174:177], v[236:239], v[106:109]
	v_mfma_f32_16x16x32_bf16 v[42:45], v[186:189], v[232:235], v[42:45]
	v_mfma_f32_16x16x32_bf16 v[42:45], v[190:193], v[236:239], v[42:45]
	v_mfma_f32_16x16x32_bf16 v[46:49], v[178:181], v[232:235], v[46:49]
	v_mfma_f32_16x16x32_bf16 v[46:49], v[182:185], v[236:239], v[46:49]
	v_mfma_f32_16x16x32_bf16 v[38:41], v[178:181], v[240:243], v[38:41]
	v_mfma_f32_16x16x32_bf16 v[38:41], v[182:185], v[244:247], v[38:41]
	v_mfma_f32_16x16x32_bf16 v[34:37], v[186:189], v[240:243], v[34:37]
	v_mfma_f32_16x16x32_bf16 v[34:37], v[190:193], v[244:247], v[34:37]
	v_mfma_f32_16x16x32_bf16 v[98:101], v[170:173], v[240:243], v[98:101]
	v_mfma_f32_16x16x32_bf16 v[98:101], v[174:177], v[244:247], v[98:101]
	v_mfma_f32_16x16x32_bf16 v[102:105], v[142:145], v[240:243], v[102:105]
	v_mfma_f32_16x16x32_bf16 v[102:105], v[154:157], v[244:247], v[102:105]
	s_barrier
	s_setprio 0
	s_or_b32 s52, s82, 0x80
	s_mov_b32 m0, s34
	ds_read_b128 v[194:197], v140 offset:49152
	buffer_load_dwordx4 v134, s[64:67], s52 offen lds
	s_add_i32 s82, s82, 0x200080
	s_mov_b32 m0, s35
	ds_read_b128 v[198:201], v140 offset:50176
	buffer_load_dwordx4 v136, s[64:67], s52 offen lds
	s_mov_b32 m0, s37
	ds_read_b128 v[202:205], v140 offset:51200
	buffer_load_dwordx4 v134, s[64:67], s82 offen lds
	s_mov_b32 m0, s44
	ds_read_b128 v[228:231], v140 offset:52224
	buffer_load_dwordx4 v136, s[64:67], s82 offen lds
	s_mov_b32 m0, s14
	ds_read_b128 v[232:235], v140 offset:53248
	buffer_load_dwordx4 v131, s[60:63], s73 offen lds
	s_mov_b32 m0, s36
	ds_read_b128 v[236:239], v140 offset:54272
	buffer_load_dwordx4 v135, s[60:63], s73 offen lds
	ds_read_b128 v[240:243], v140 offset:55296
	ds_read_b128 v[244:247], v140 offset:56320
	s_waitcnt vmcnt(8)
	s_waitcnt lgkmcnt(0)
	s_setprio 1
	s_barrier
	v_mfma_f32_16x16x32_bf16 v[94:97], v[142:145], v[194:197], v[94:97]
	v_mfma_f32_16x16x32_bf16 v[94:97], v[154:157], v[198:201], v[94:97]
	v_mfma_f32_16x16x32_bf16 v[90:93], v[170:173], v[194:197], v[90:93]
	v_mfma_f32_16x16x32_bf16 v[90:93], v[174:177], v[198:201], v[90:93]
	v_mfma_f32_16x16x32_bf16 v[26:29], v[186:189], v[194:197], v[26:29]
	v_mfma_f32_16x16x32_bf16 v[26:29], v[190:193], v[198:201], v[26:29]
	v_mfma_f32_16x16x32_bf16 v[30:33], v[178:181], v[194:197], v[30:33]
	v_mfma_f32_16x16x32_bf16 v[30:33], v[182:185], v[198:201], v[30:33]
	v_mfma_f32_16x16x32_bf16 v[22:25], v[178:181], v[202:205], v[22:25]
	v_mfma_f32_16x16x32_bf16 v[22:25], v[182:185], v[228:231], v[22:25]
	v_mfma_f32_16x16x32_bf16 v[18:21], v[186:189], v[202:205], v[18:21]
	v_mfma_f32_16x16x32_bf16 v[18:21], v[190:193], v[228:231], v[18:21]
	v_mfma_f32_16x16x32_bf16 v[82:85], v[170:173], v[202:205], v[82:85]
	v_mfma_f32_16x16x32_bf16 v[82:85], v[174:177], v[228:231], v[82:85]
	v_mfma_f32_16x16x32_bf16 v[86:89], v[142:145], v[202:205], v[86:89]
	v_mfma_f32_16x16x32_bf16 v[86:89], v[154:157], v[228:231], v[86:89]
	v_mfma_f32_16x16x32_bf16 v[78:81], v[142:145], v[232:235], v[78:81]
	v_mfma_f32_16x16x32_bf16 v[78:81], v[154:157], v[236:239], v[78:81]
	v_mfma_f32_16x16x32_bf16 v[74:77], v[170:173], v[232:235], v[74:77]
	v_mfma_f32_16x16x32_bf16 v[74:77], v[174:177], v[236:239], v[74:77]
	v_mfma_f32_16x16x32_bf16 v[10:13], v[186:189], v[232:235], v[10:13]
	v_mfma_f32_16x16x32_bf16 v[10:13], v[190:193], v[236:239], v[10:13]
	v_mfma_f32_16x16x32_bf16 v[14:17], v[178:181], v[232:235], v[14:17]
	v_mfma_f32_16x16x32_bf16 v[14:17], v[182:185], v[236:239], v[14:17]
	v_mfma_f32_16x16x32_bf16 v[6:9], v[178:181], v[240:243], v[6:9]
	v_mfma_f32_16x16x32_bf16 v[6:9], v[182:185], v[244:247], v[6:9]
	v_mfma_f32_16x16x32_bf16 v[2:5], v[186:189], v[240:243], v[2:5]
	v_mfma_f32_16x16x32_bf16 v[2:5], v[190:193], v[244:247], v[2:5]
	v_mfma_f32_16x16x32_bf16 v[66:69], v[170:173], v[240:243], v[66:69]
	v_mfma_f32_16x16x32_bf16 v[66:69], v[174:177], v[244:247], v[66:69]
	v_mfma_f32_16x16x32_bf16 v[70:73], v[142:145], v[240:243], v[70:73]
	v_mfma_f32_16x16x32_bf16 v[70:73], v[154:157], v[244:247], v[70:73]
	s_barrier
	s_setprio 0
	s_add_i32 s72, s72, 2
	s_addk_i32 s30, 0x100
	s_addk_i32 s31, 0x100
	s_cmpk_gt_u32 s72, 0x7d
	s_cbranch_scc0 .LBB0_1193
	s_and_b64 vcc, exec, s[42:43]
	s_cbranch_vccz .LBB0_1196
	s_barrier

.LBB0_1222:
	s_lshl_b32 s14, s82, 22
	s_and_b64 s[8:9], s[44:45], exec
	s_cselect_b32 s8, s14, s19
	s_lshl_b32 s46, s84, 22
	s_and_b64 s[26:27], s[44:45], exec
	s_cselect_b32 s9, s46, s22
	s_add_i32 s19, s19, 0x200080
	s_addk_i32 s22, 0x100
	s_mov_b32 s26, -2
	v_add_u32_e32 v141, 0x10000, v139
	ds_read_b128 v[142:145], v141
	ds_read_b128 v[154:157], v141 offset:1024
	ds_read_b128 v[170:173], v141 offset:2048
	ds_read_b128 v[174:177], v141 offset:3072
	v_add_u32_e32 v141, 0x14000, v139
	ds_read_b128 v[178:181], v141
	ds_read_b128 v[182:185], v141 offset:1024
	ds_read_b128 v[186:189], v141 offset:2048
	ds_read_b128 v[190:193], v141 offset:3072
	s_add_i32 s27, s19, 0xffe00080
	s_cmpk_eq_i32 s26, 0x7c
	s_cselect_b32 s52, s8, s27
	s_cselect_b32 s47, s9, s22
	s_or_b32 s27, s52, 0x80
	s_mov_b32 m0, s71
	ds_read_b128 v[194:197], v140
	ds_read_b128 v[198:201], v140 offset:1024
	ds_read_b128 v[202:205], v140 offset:2048
	ds_read_b128 v[228:231], v140 offset:3072
	ds_read_b128 v[232:235], v140 offset:4096
	ds_read_b128 v[236:239], v140 offset:5120
	ds_read_b128 v[240:243], v140 offset:6144
	ds_read_b128 v[244:247], v140 offset:7168
	buffer_load_dwordx4 v131, s[60:63], s19 offen lds
	s_mov_b32 m0, s72
	s_nop 0
	buffer_load_dwordx4 v135, s[60:63], s19 offen lds
	s_waitcnt vmcnt(8)
	s_waitcnt lgkmcnt(0)
	s_setprio 1
	s_barrier
	v_mfma_f32_16x16x32_bf16 v[126:129], v[142:145], v[194:197], 0
	v_mfma_f32_16x16x32_bf16 v[126:129], v[154:157], v[198:201], v[126:129]
	v_mfma_f32_16x16x32_bf16 v[122:125], v[170:173], v[194:197], 0
	v_mfma_f32_16x16x32_bf16 v[122:125], v[174:177], v[198:201], v[122:125]
	v_mfma_f32_16x16x32_bf16 v[58:61], v[186:189], v[194:197], 0
	v_mfma_f32_16x16x32_bf16 v[58:61], v[190:193], v[198:201], v[58:61]
	v_mfma_f32_16x16x32_bf16 v[62:65], v[178:181], v[194:197], 0
	v_mfma_f32_16x16x32_bf16 v[62:65], v[182:185], v[198:201], v[62:65]
	v_mfma_f32_16x16x32_bf16 v[54:57], v[178:181], v[202:205], 0
	v_mfma_f32_16x16x32_bf16 v[54:57], v[182:185], v[228:231], v[54:57]
	v_mfma_f32_16x16x32_bf16 v[50:53], v[186:189], v[202:205], 0
	v_mfma_f32_16x16x32_bf16 v[50:53], v[190:193], v[228:231], v[50:53]
	v_mfma_f32_16x16x32_bf16 v[114:117], v[170:173], v[202:205], 0
	v_mfma_f32_16x16x32_bf16 v[114:117], v[174:177], v[228:231], v[114:117]
	v_mfma_f32_16x16x32_bf16 v[118:121], v[142:145], v[202:205], 0
	v_mfma_f32_16x16x32_bf16 v[118:121], v[154:157], v[228:231], v[118:121]
	v_mfma_f32_16x16x32_bf16 v[110:113], v[142:145], v[232:235], 0
	v_mfma_f32_16x16x32_bf16 v[110:113], v[154:157], v[236:239], v[110:113]
	v_mfma_f32_16x16x32_bf16 v[106:109], v[170:173], v[232:235], 0
	v_mfma_f32_16x16x32_bf16 v[106:109], v[174:177], v[236:239], v[106:109]
	v_mfma_f32_16x16x32_bf16 v[42:45], v[186:189], v[232:235], 0
	v_mfma_f32_16x16x32_bf16 v[42:45], v[190:193], v[236:239], v[42:45]
	v_mfma_f32_16x16x32_bf16 v[46:49], v[178:181], v[232:235], 0
	v_mfma_f32_16x16x32_bf16 v[46:49], v[182:185], v[236:239], v[46:49]
	v_mfma_f32_16x16x32_bf16 v[38:41], v[178:181], v[240:243], 0
	v_mfma_f32_16x16x32_bf16 v[38:41], v[182:185], v[244:247], v[38:41]
	v_mfma_f32_16x16x32_bf16 v[34:37], v[186:189], v[240:243], 0
	v_mfma_f32_16x16x32_bf16 v[34:37], v[190:193], v[244:247], v[34:37]
	v_mfma_f32_16x16x32_bf16 v[98:101], v[170:173], v[240:243], 0
	v_mfma_f32_16x16x32_bf16 v[98:101], v[174:177], v[244:247], v[98:101]
	v_mfma_f32_16x16x32_bf16 v[102:105], v[142:145], v[240:243], 0
	v_mfma_f32_16x16x32_bf16 v[102:105], v[154:157], v[244:247], v[102:105]
	s_barrier
	s_setprio 0
	s_mov_b32 s66, s62
	s_mov_b32 s67, s63
	s_mov_b32 m0, s2
	ds_read_b128 v[194:197], v140 offset:16384
	buffer_load_dwordx4 v134, s[64:67], s47 offen lds
	s_add_i32 s53, s47, 0x200000
	s_mov_b32 m0, s21
	ds_read_b128 v[198:201], v140 offset:17408
	buffer_load_dwordx4 v136, s[64:67], s47 offen lds
	s_mov_b32 m0, s23
	ds_read_b128 v[202:205], v140 offset:18432
	buffer_load_dwordx4 v134, s[64:67], s53 offen lds
	s_mov_b32 m0, s24
	ds_read_b128 v[228:231], v140 offset:19456
	buffer_load_dwordx4 v136, s[64:67], s53 offen lds
	s_mov_b32 m0, s16
	ds_read_b128 v[232:235], v140 offset:20480
	buffer_load_dwordx4 v131, s[60:63], s52 offen lds
	s_mov_b32 m0, s25
	ds_read_b128 v[236:239], v140 offset:21504
	buffer_load_dwordx4 v135, s[60:63], s52 offen lds
	ds_read_b128 v[240:243], v140 offset:22528
	ds_read_b128 v[244:247], v140 offset:23552
	s_waitcnt vmcnt(8)
	s_waitcnt lgkmcnt(0)
	s_setprio 1
	s_barrier
	v_mfma_f32_16x16x32_bf16 v[94:97], v[142:145], v[194:197], 0
	v_mfma_f32_16x16x32_bf16 v[94:97], v[154:157], v[198:201], v[94:97]
	v_mfma_f32_16x16x32_bf16 v[90:93], v[170:173], v[194:197], 0
	v_mfma_f32_16x16x32_bf16 v[90:93], v[174:177], v[198:201], v[90:93]
	v_mfma_f32_16x16x32_bf16 v[26:29], v[186:189], v[194:197], 0
	v_mfma_f32_16x16x32_bf16 v[26:29], v[190:193], v[198:201], v[26:29]
	v_mfma_f32_16x16x32_bf16 v[30:33], v[178:181], v[194:197], 0
	v_mfma_f32_16x16x32_bf16 v[30:33], v[182:185], v[198:201], v[30:33]
	v_mfma_f32_16x16x32_bf16 v[22:25], v[178:181], v[202:205], 0
	v_mfma_f32_16x16x32_bf16 v[22:25], v[182:185], v[228:231], v[22:25]
	v_mfma_f32_16x16x32_bf16 v[18:21], v[186:189], v[202:205], 0
	v_mfma_f32_16x16x32_bf16 v[18:21], v[190:193], v[228:231], v[18:21]
	v_mfma_f32_16x16x32_bf16 v[82:85], v[170:173], v[202:205], 0
	v_mfma_f32_16x16x32_bf16 v[82:85], v[174:177], v[228:231], v[82:85]
	v_mfma_f32_16x16x32_bf16 v[86:89], v[142:145], v[202:205], 0
	v_mfma_f32_16x16x32_bf16 v[86:89], v[154:157], v[228:231], v[86:89]
	v_mfma_f32_16x16x32_bf16 v[78:81], v[142:145], v[232:235], 0
	v_mfma_f32_16x16x32_bf16 v[78:81], v[154:157], v[236:239], v[78:81]
	v_mfma_f32_16x16x32_bf16 v[74:77], v[170:173], v[232:235], 0
	v_mfma_f32_16x16x32_bf16 v[74:77], v[174:177], v[236:239], v[74:77]
	v_mfma_f32_16x16x32_bf16 v[10:13], v[186:189], v[232:235], 0
	v_mfma_f32_16x16x32_bf16 v[10:13], v[190:193], v[236:239], v[10:13]
	v_mfma_f32_16x16x32_bf16 v[14:17], v[178:181], v[232:235], 0
	v_mfma_f32_16x16x32_bf16 v[14:17], v[182:185], v[236:239], v[14:17]
	v_mfma_f32_16x16x32_bf16 v[6:9], v[178:181], v[240:243], 0
	v_mfma_f32_16x16x32_bf16 v[6:9], v[182:185], v[244:247], v[6:9]
	v_mfma_f32_16x16x32_bf16 v[2:5], v[186:189], v[240:243], 0
	v_mfma_f32_16x16x32_bf16 v[2:5], v[190:193], v[244:247], v[2:5]
	v_mfma_f32_16x16x32_bf16 v[66:69], v[170:173], v[240:243], 0
	v_mfma_f32_16x16x32_bf16 v[66:69], v[174:177], v[244:247], v[66:69]
	v_mfma_f32_16x16x32_bf16 v[70:73], v[142:145], v[240:243], 0
	v_mfma_f32_16x16x32_bf16 v[70:73], v[154:157], v[244:247], v[70:73]
	s_barrier
	s_setprio 0
	v_add_u32_e32 v141, 0x18000, v139
	ds_read_b128 v[142:145], v141
	ds_read_b128 v[154:157], v141 offset:1024
	ds_read_b128 v[170:173], v141 offset:2048
	ds_read_b128 v[174:177], v141 offset:3072
	v_add_u32_e32 v141, 0x1c000, v139
	ds_read_b128 v[178:181], v141
	ds_read_b128 v[182:185], v141 offset:1024
	ds_read_b128 v[186:189], v141 offset:2048
	ds_read_b128 v[190:193], v141 offset:3072
	s_add_i32 s52, s52, 0x200000
	s_mov_b32 m0, s30
	ds_read_b128 v[194:197], v140 offset:32768
	ds_read_b128 v[198:201], v140 offset:33792
	ds_read_b128 v[202:205], v140 offset:34816
	ds_read_b128 v[228:231], v140 offset:35840
	ds_read_b128 v[232:235], v140 offset:36864
	ds_read_b128 v[236:239], v140 offset:37888
	ds_read_b128 v[240:243], v140 offset:38912
	ds_read_b128 v[244:247], v140 offset:39936
	buffer_load_dwordx4 v131, s[60:63], s52 offen lds
	s_mov_b32 m0, s31
	s_nop 0
	buffer_load_dwordx4 v135, s[60:63], s52 offen lds
	s_waitcnt vmcnt(8)
	s_waitcnt lgkmcnt(0)
	s_setprio 1
	s_barrier
	v_mfma_f32_16x16x32_bf16 v[126:129], v[142:145], v[194:197], v[126:129]
	v_mfma_f32_16x16x32_bf16 v[126:129], v[154:157], v[198:201], v[126:129]
	v_mfma_f32_16x16x32_bf16 v[122:125], v[170:173], v[194:197], v[122:125]
	v_mfma_f32_16x16x32_bf16 v[122:125], v[174:177], v[198:201], v[122:125]
	v_mfma_f32_16x16x32_bf16 v[58:61], v[186:189], v[194:197], v[58:61]
	v_mfma_f32_16x16x32_bf16 v[58:61], v[190:193], v[198:201], v[58:61]
	v_mfma_f32_16x16x32_bf16 v[62:65], v[178:181], v[194:197], v[62:65]
	v_mfma_f32_16x16x32_bf16 v[62:65], v[182:185], v[198:201], v[62:65]
	v_mfma_f32_16x16x32_bf16 v[54:57], v[178:181], v[202:205], v[54:57]
	v_mfma_f32_16x16x32_bf16 v[54:57], v[182:185], v[228:231], v[54:57]
	v_mfma_f32_16x16x32_bf16 v[50:53], v[186:189], v[202:205], v[50:53]
	v_mfma_f32_16x16x32_bf16 v[50:53], v[190:193], v[228:231], v[50:53]
	v_mfma_f32_16x16x32_bf16 v[114:117], v[170:173], v[202:205], v[114:117]
	v_mfma_f32_16x16x32_bf16 v[114:117], v[174:177], v[228:231], v[114:117]
	v_mfma_f32_16x16x32_bf16 v[118:121], v[142:145], v[202:205], v[118:121]
	v_mfma_f32_16x16x32_bf16 v[118:121], v[154:157], v[228:231], v[118:121]
	v_mfma_f32_16x16x32_bf16 v[110:113], v[142:145], v[232:235], v[110:113]
	v_mfma_f32_16x16x32_bf16 v[110:113], v[154:157], v[236:239], v[110:113]
	v_mfma_f32_16x16x32_bf16 v[106:109], v[170:173], v[232:235], v[106:109]
	v_mfma_f32_16x16x32_bf16 v[106:109], v[174:177], v[236:239], v[106:109]
	v_mfma_f32_16x16x32_bf16 v[42:45], v[186:189], v[232:235], v[42:45]
	v_mfma_f32_16x16x32_bf16 v[42:45], v[190:193], v[236:239], v[42:45]
	v_mfma_f32_16x16x32_bf16 v[46:49], v[178:181], v[232:235], v[46:49]
	v_mfma_f32_16x16x32_bf16 v[46:49], v[182:185], v[236:239], v[46:49]
	v_mfma_f32_16x16x32_bf16 v[38:41], v[178:181], v[240:243], v[38:41]
	v_mfma_f32_16x16x32_bf16 v[38:41], v[182:185], v[244:247], v[38:41]
	v_mfma_f32_16x16x32_bf16 v[34:37], v[186:189], v[240:243], v[34:37]
	v_mfma_f32_16x16x32_bf16 v[34:37], v[190:193], v[244:247], v[34:37]
	v_mfma_f32_16x16x32_bf16 v[98:101], v[170:173], v[240:243], v[98:101]
	v_mfma_f32_16x16x32_bf16 v[98:101], v[174:177], v[244:247], v[98:101]
	v_mfma_f32_16x16x32_bf16 v[102:105], v[142:145], v[240:243], v[102:105]
	v_mfma_f32_16x16x32_bf16 v[102:105], v[154:157], v[244:247], v[102:105]
	s_barrier
	s_setprio 0
	s_or_b32 s52, s47, 0x80
	s_mov_b32 m0, s33
	ds_read_b128 v[194:197], v140 offset:49152
	buffer_load_dwordx4 v134, s[64:67], s52 offen lds
	s_add_i32 s47, s47, 0x200080
	s_mov_b32 m0, s34
	ds_read_b128 v[198:201], v140 offset:50176
	buffer_load_dwordx4 v136, s[64:67], s52 offen lds
	s_mov_b32 m0, s37
	ds_read_b128 v[202:205], v140 offset:51200
	buffer_load_dwordx4 v134, s[64:67], s47 offen lds
	s_mov_b32 m0, s68
	ds_read_b128 v[228:231], v140 offset:52224
	buffer_load_dwordx4 v136, s[64:67], s47 offen lds
	s_mov_b32 m0, s35
	ds_read_b128 v[232:235], v140 offset:53248
	buffer_load_dwordx4 v131, s[60:63], s27 offen lds
	s_mov_b32 m0, s36
	ds_read_b128 v[236:239], v140 offset:54272
	buffer_load_dwordx4 v135, s[60:63], s27 offen lds
	ds_read_b128 v[240:243], v140 offset:55296
	ds_read_b128 v[244:247], v140 offset:56320
	s_waitcnt vmcnt(8)
	s_waitcnt lgkmcnt(0)
	s_setprio 1
	s_barrier
	v_mfma_f32_16x16x32_bf16 v[94:97], v[142:145], v[194:197], v[94:97]
	v_mfma_f32_16x16x32_bf16 v[94:97], v[154:157], v[198:201], v[94:97]
	v_mfma_f32_16x16x32_bf16 v[90:93], v[170:173], v[194:197], v[90:93]
	v_mfma_f32_16x16x32_bf16 v[90:93], v[174:177], v[198:201], v[90:93]
	v_mfma_f32_16x16x32_bf16 v[26:29], v[186:189], v[194:197], v[26:29]
	v_mfma_f32_16x16x32_bf16 v[26:29], v[190:193], v[198:201], v[26:29]
	v_mfma_f32_16x16x32_bf16 v[30:33], v[178:181], v[194:197], v[30:33]
	v_mfma_f32_16x16x32_bf16 v[30:33], v[182:185], v[198:201], v[30:33]
	v_mfma_f32_16x16x32_bf16 v[22:25], v[178:181], v[202:205], v[22:25]
	v_mfma_f32_16x16x32_bf16 v[22:25], v[182:185], v[228:231], v[22:25]
	v_mfma_f32_16x16x32_bf16 v[18:21], v[186:189], v[202:205], v[18:21]
	v_mfma_f32_16x16x32_bf16 v[18:21], v[190:193], v[228:231], v[18:21]
	v_mfma_f32_16x16x32_bf16 v[82:85], v[170:173], v[202:205], v[82:85]
	v_mfma_f32_16x16x32_bf16 v[82:85], v[174:177], v[228:231], v[82:85]
	v_mfma_f32_16x16x32_bf16 v[86:89], v[142:145], v[202:205], v[86:89]
	v_mfma_f32_16x16x32_bf16 v[86:89], v[154:157], v[228:231], v[86:89]
	v_mfma_f32_16x16x32_bf16 v[78:81], v[142:145], v[232:235], v[78:81]
	v_mfma_f32_16x16x32_bf16 v[78:81], v[154:157], v[236:239], v[78:81]
	v_mfma_f32_16x16x32_bf16 v[74:77], v[170:173], v[232:235], v[74:77]
	v_mfma_f32_16x16x32_bf16 v[74:77], v[174:177], v[236:239], v[74:77]
	v_mfma_f32_16x16x32_bf16 v[10:13], v[186:189], v[232:235], v[10:13]
	v_mfma_f32_16x16x32_bf16 v[10:13], v[190:193], v[236:239], v[10:13]
	v_mfma_f32_16x16x32_bf16 v[14:17], v[178:181], v[232:235], v[14:17]
	v_mfma_f32_16x16x32_bf16 v[14:17], v[182:185], v[236:239], v[14:17]
	v_mfma_f32_16x16x32_bf16 v[6:9], v[178:181], v[240:243], v[6:9]
	v_mfma_f32_16x16x32_bf16 v[6:9], v[182:185], v[244:247], v[6:9]
	v_mfma_f32_16x16x32_bf16 v[2:5], v[186:189], v[240:243], v[2:5]
	v_mfma_f32_16x16x32_bf16 v[2:5], v[190:193], v[244:247], v[2:5]
	v_mfma_f32_16x16x32_bf16 v[66:69], v[170:173], v[240:243], v[66:69]
	v_mfma_f32_16x16x32_bf16 v[66:69], v[174:177], v[244:247], v[66:69]
	v_mfma_f32_16x16x32_bf16 v[70:73], v[142:145], v[240:243], v[70:73]
	v_mfma_f32_16x16x32_bf16 v[70:73], v[154:157], v[244:247], v[70:73]
	s_barrier
	s_setprio 0
	s_add_i32 s26, s26, 2
	s_addk_i32 s19, 0x100
	s_addk_i32 s22, 0x100
	s_cmpk_gt_u32 s26, 0x7d
.LBB0_1223:
	v_add_u32_e32 v141, 0x10000, v139
	ds_read_b128 v[142:145], v141
	ds_read_b128 v[154:157], v141 offset:1024
	ds_read_b128 v[170:173], v141 offset:2048
	ds_read_b128 v[174:177], v141 offset:3072
	v_add_u32_e32 v141, 0x14000, v139
	ds_read_b128 v[178:181], v141
	ds_read_b128 v[182:185], v141 offset:1024
	ds_read_b128 v[186:189], v141 offset:2048
	ds_read_b128 v[190:193], v141 offset:3072
	s_add_i32 s27, s19, 0xffe00080
	s_cmpk_eq_i32 s26, 0x7c
	s_cselect_b32 s52, s8, s27
	s_cselect_b32 s47, s9, s22
	s_or_b32 s27, s52, 0x80
	s_mov_b32 m0, s71
	ds_read_b128 v[194:197], v140
	ds_read_b128 v[198:201], v140 offset:1024
	ds_read_b128 v[202:205], v140 offset:2048
	ds_read_b128 v[228:231], v140 offset:3072
	ds_read_b128 v[232:235], v140 offset:4096
	ds_read_b128 v[236:239], v140 offset:5120
	ds_read_b128 v[240:243], v140 offset:6144
	ds_read_b128 v[244:247], v140 offset:7168
	buffer_load_dwordx4 v131, s[60:63], s19 offen lds
	s_mov_b32 m0, s72
	s_nop 0
	buffer_load_dwordx4 v135, s[60:63], s19 offen lds
	s_waitcnt vmcnt(8)
	s_waitcnt lgkmcnt(0)
	s_setprio 1
	s_barrier
	v_mfma_f32_16x16x32_bf16 v[126:129], v[142:145], v[194:197], v[126:129]
	v_mfma_f32_16x16x32_bf16 v[126:129], v[154:157], v[198:201], v[126:129]
	v_mfma_f32_16x16x32_bf16 v[122:125], v[170:173], v[194:197], v[122:125]
	v_mfma_f32_16x16x32_bf16 v[122:125], v[174:177], v[198:201], v[122:125]
	v_mfma_f32_16x16x32_bf16 v[58:61], v[186:189], v[194:197], v[58:61]
	v_mfma_f32_16x16x32_bf16 v[58:61], v[190:193], v[198:201], v[58:61]
	v_mfma_f32_16x16x32_bf16 v[62:65], v[178:181], v[194:197], v[62:65]
	v_mfma_f32_16x16x32_bf16 v[62:65], v[182:185], v[198:201], v[62:65]
	v_mfma_f32_16x16x32_bf16 v[54:57], v[178:181], v[202:205], v[54:57]
	v_mfma_f32_16x16x32_bf16 v[54:57], v[182:185], v[228:231], v[54:57]
	v_mfma_f32_16x16x32_bf16 v[50:53], v[186:189], v[202:205], v[50:53]
	v_mfma_f32_16x16x32_bf16 v[50:53], v[190:193], v[228:231], v[50:53]
	v_mfma_f32_16x16x32_bf16 v[114:117], v[170:173], v[202:205], v[114:117]
	v_mfma_f32_16x16x32_bf16 v[114:117], v[174:177], v[228:231], v[114:117]
	v_mfma_f32_16x16x32_bf16 v[118:121], v[142:145], v[202:205], v[118:121]
	v_mfma_f32_16x16x32_bf16 v[118:121], v[154:157], v[228:231], v[118:121]
	v_mfma_f32_16x16x32_bf16 v[110:113], v[142:145], v[232:235], v[110:113]
	v_mfma_f32_16x16x32_bf16 v[110:113], v[154:157], v[236:239], v[110:113]
	v_mfma_f32_16x16x32_bf16 v[106:109], v[170:173], v[232:235], v[106:109]
	v_mfma_f32_16x16x32_bf16 v[106:109], v[174:177], v[236:239], v[106:109]
	v_mfma_f32_16x16x32_bf16 v[42:45], v[186:189], v[232:235], v[42:45]
	v_mfma_f32_16x16x32_bf16 v[42:45], v[190:193], v[236:239], v[42:45]
	v_mfma_f32_16x16x32_bf16 v[46:49], v[178:181], v[232:235], v[46:49]
	v_mfma_f32_16x16x32_bf16 v[46:49], v[182:185], v[236:239], v[46:49]
	v_mfma_f32_16x16x32_bf16 v[38:41], v[178:181], v[240:243], v[38:41]
	v_mfma_f32_16x16x32_bf16 v[38:41], v[182:185], v[244:247], v[38:41]
	v_mfma_f32_16x16x32_bf16 v[34:37], v[186:189], v[240:243], v[34:37]
	v_mfma_f32_16x16x32_bf16 v[34:37], v[190:193], v[244:247], v[34:37]
	v_mfma_f32_16x16x32_bf16 v[98:101], v[170:173], v[240:243], v[98:101]
	v_mfma_f32_16x16x32_bf16 v[98:101], v[174:177], v[244:247], v[98:101]
	v_mfma_f32_16x16x32_bf16 v[102:105], v[142:145], v[240:243], v[102:105]
	v_mfma_f32_16x16x32_bf16 v[102:105], v[154:157], v[244:247], v[102:105]
	s_barrier
	s_setprio 0
	s_mov_b32 s66, s62
	s_mov_b32 s67, s63
	s_mov_b32 m0, s2
	ds_read_b128 v[194:197], v140 offset:16384
	buffer_load_dwordx4 v134, s[64:67], s47 offen lds
	s_add_i32 s53, s47, 0x200000
	s_mov_b32 m0, s21
	ds_read_b128 v[198:201], v140 offset:17408
	buffer_load_dwordx4 v136, s[64:67], s47 offen lds
	s_mov_b32 m0, s23
	ds_read_b128 v[202:205], v140 offset:18432
	buffer_load_dwordx4 v134, s[64:67], s53 offen lds
	s_mov_b32 m0, s24
	ds_read_b128 v[228:231], v140 offset:19456
	buffer_load_dwordx4 v136, s[64:67], s53 offen lds
	s_mov_b32 m0, s16
	ds_read_b128 v[232:235], v140 offset:20480
	buffer_load_dwordx4 v131, s[60:63], s52 offen lds
	s_mov_b32 m0, s25
	ds_read_b128 v[236:239], v140 offset:21504
	buffer_load_dwordx4 v135, s[60:63], s52 offen lds
	ds_read_b128 v[240:243], v140 offset:22528
	ds_read_b128 v[244:247], v140 offset:23552
	s_waitcnt vmcnt(8)
	s_waitcnt lgkmcnt(0)
	s_setprio 1
	s_barrier
	v_mfma_f32_16x16x32_bf16 v[94:97], v[142:145], v[194:197], v[94:97]
	v_mfma_f32_16x16x32_bf16 v[94:97], v[154:157], v[198:201], v[94:97]
	v_mfma_f32_16x16x32_bf16 v[90:93], v[170:173], v[194:197], v[90:93]
	v_mfma_f32_16x16x32_bf16 v[90:93], v[174:177], v[198:201], v[90:93]
	v_mfma_f32_16x16x32_bf16 v[26:29], v[186:189], v[194:197], v[26:29]
	v_mfma_f32_16x16x32_bf16 v[26:29], v[190:193], v[198:201], v[26:29]
	v_mfma_f32_16x16x32_bf16 v[30:33], v[178:181], v[194:197], v[30:33]
	v_mfma_f32_16x16x32_bf16 v[30:33], v[182:185], v[198:201], v[30:33]
	v_mfma_f32_16x16x32_bf16 v[22:25], v[178:181], v[202:205], v[22:25]
	v_mfma_f32_16x16x32_bf16 v[22:25], v[182:185], v[228:231], v[22:25]
	v_mfma_f32_16x16x32_bf16 v[18:21], v[186:189], v[202:205], v[18:21]
	v_mfma_f32_16x16x32_bf16 v[18:21], v[190:193], v[228:231], v[18:21]
	v_mfma_f32_16x16x32_bf16 v[82:85], v[170:173], v[202:205], v[82:85]
	v_mfma_f32_16x16x32_bf16 v[82:85], v[174:177], v[228:231], v[82:85]
	v_mfma_f32_16x16x32_bf16 v[86:89], v[142:145], v[202:205], v[86:89]
	v_mfma_f32_16x16x32_bf16 v[86:89], v[154:157], v[228:231], v[86:89]
	v_mfma_f32_16x16x32_bf16 v[78:81], v[142:145], v[232:235], v[78:81]
	v_mfma_f32_16x16x32_bf16 v[78:81], v[154:157], v[236:239], v[78:81]
	v_mfma_f32_16x16x32_bf16 v[74:77], v[170:173], v[232:235], v[74:77]
	v_mfma_f32_16x16x32_bf16 v[74:77], v[174:177], v[236:239], v[74:77]
	v_mfma_f32_16x16x32_bf16 v[10:13], v[186:189], v[232:235], v[10:13]
	v_mfma_f32_16x16x32_bf16 v[10:13], v[190:193], v[236:239], v[10:13]
	v_mfma_f32_16x16x32_bf16 v[14:17], v[178:181], v[232:235], v[14:17]
	v_mfma_f32_16x16x32_bf16 v[14:17], v[182:185], v[236:239], v[14:17]
	v_mfma_f32_16x16x32_bf16 v[6:9], v[178:181], v[240:243], v[6:9]
	v_mfma_f32_16x16x32_bf16 v[6:9], v[182:185], v[244:247], v[6:9]
	v_mfma_f32_16x16x32_bf16 v[2:5], v[186:189], v[240:243], v[2:5]
	v_mfma_f32_16x16x32_bf16 v[2:5], v[190:193], v[244:247], v[2:5]
	v_mfma_f32_16x16x32_bf16 v[66:69], v[170:173], v[240:243], v[66:69]
	v_mfma_f32_16x16x32_bf16 v[66:69], v[174:177], v[244:247], v[66:69]
	v_mfma_f32_16x16x32_bf16 v[70:73], v[142:145], v[240:243], v[70:73]
	v_mfma_f32_16x16x32_bf16 v[70:73], v[154:157], v[244:247], v[70:73]
	s_barrier
	s_setprio 0
	v_add_u32_e32 v141, 0x18000, v139
	ds_read_b128 v[142:145], v141
	ds_read_b128 v[154:157], v141 offset:1024
	ds_read_b128 v[170:173], v141 offset:2048
	ds_read_b128 v[174:177], v141 offset:3072
	v_add_u32_e32 v141, 0x1c000, v139
	ds_read_b128 v[178:181], v141
	ds_read_b128 v[182:185], v141 offset:1024
	ds_read_b128 v[186:189], v141 offset:2048
	ds_read_b128 v[190:193], v141 offset:3072
	s_add_i32 s52, s52, 0x200000
	s_mov_b32 m0, s30
	ds_read_b128 v[194:197], v140 offset:32768
	ds_read_b128 v[198:201], v140 offset:33792
	ds_read_b128 v[202:205], v140 offset:34816
	ds_read_b128 v[228:231], v140 offset:35840
	ds_read_b128 v[232:235], v140 offset:36864
	ds_read_b128 v[236:239], v140 offset:37888
	ds_read_b128 v[240:243], v140 offset:38912
	ds_read_b128 v[244:247], v140 offset:39936
	buffer_load_dwordx4 v131, s[60:63], s52 offen lds
	s_mov_b32 m0, s31
	s_nop 0
	buffer_load_dwordx4 v135, s[60:63], s52 offen lds
	s_waitcnt vmcnt(8)
	s_waitcnt lgkmcnt(0)
	s_setprio 1
	s_barrier
	v_mfma_f32_16x16x32_bf16 v[126:129], v[142:145], v[194:197], v[126:129]
	v_mfma_f32_16x16x32_bf16 v[126:129], v[154:157], v[198:201], v[126:129]
	v_mfma_f32_16x16x32_bf16 v[122:125], v[170:173], v[194:197], v[122:125]
	v_mfma_f32_16x16x32_bf16 v[122:125], v[174:177], v[198:201], v[122:125]
	v_mfma_f32_16x16x32_bf16 v[58:61], v[186:189], v[194:197], v[58:61]
	v_mfma_f32_16x16x32_bf16 v[58:61], v[190:193], v[198:201], v[58:61]
	v_mfma_f32_16x16x32_bf16 v[62:65], v[178:181], v[194:197], v[62:65]
	v_mfma_f32_16x16x32_bf16 v[62:65], v[182:185], v[198:201], v[62:65]
	v_mfma_f32_16x16x32_bf16 v[54:57], v[178:181], v[202:205], v[54:57]
	v_mfma_f32_16x16x32_bf16 v[54:57], v[182:185], v[228:231], v[54:57]
	v_mfma_f32_16x16x32_bf16 v[50:53], v[186:189], v[202:205], v[50:53]
	v_mfma_f32_16x16x32_bf16 v[50:53], v[190:193], v[228:231], v[50:53]
	v_mfma_f32_16x16x32_bf16 v[114:117], v[170:173], v[202:205], v[114:117]
	v_mfma_f32_16x16x32_bf16 v[114:117], v[174:177], v[228:231], v[114:117]
	v_mfma_f32_16x16x32_bf16 v[118:121], v[142:145], v[202:205], v[118:121]
	v_mfma_f32_16x16x32_bf16 v[118:121], v[154:157], v[228:231], v[118:121]
	v_mfma_f32_16x16x32_bf16 v[110:113], v[142:145], v[232:235], v[110:113]
	v_mfma_f32_16x16x32_bf16 v[110:113], v[154:157], v[236:239], v[110:113]
	v_mfma_f32_16x16x32_bf16 v[106:109], v[170:173], v[232:235], v[106:109]
	v_mfma_f32_16x16x32_bf16 v[106:109], v[174:177], v[236:239], v[106:109]
	v_mfma_f32_16x16x32_bf16 v[42:45], v[186:189], v[232:235], v[42:45]
	v_mfma_f32_16x16x32_bf16 v[42:45], v[190:193], v[236:239], v[42:45]
	v_mfma_f32_16x16x32_bf16 v[46:49], v[178:181], v[232:235], v[46:49]
	v_mfma_f32_16x16x32_bf16 v[46:49], v[182:185], v[236:239], v[46:49]
	v_mfma_f32_16x16x32_bf16 v[38:41], v[178:181], v[240:243], v[38:41]
	v_mfma_f32_16x16x32_bf16 v[38:41], v[182:185], v[244:247], v[38:41]
	v_mfma_f32_16x16x32_bf16 v[34:37], v[186:189], v[240:243], v[34:37]
	v_mfma_f32_16x16x32_bf16 v[34:37], v[190:193], v[244:247], v[34:37]
	v_mfma_f32_16x16x32_bf16 v[98:101], v[170:173], v[240:243], v[98:101]
	v_mfma_f32_16x16x32_bf16 v[98:101], v[174:177], v[244:247], v[98:101]
	v_mfma_f32_16x16x32_bf16 v[102:105], v[142:145], v[240:243], v[102:105]
	v_mfma_f32_16x16x32_bf16 v[102:105], v[154:157], v[244:247], v[102:105]
	s_barrier
	s_setprio 0
	s_or_b32 s52, s47, 0x80
	s_mov_b32 m0, s33
	ds_read_b128 v[194:197], v140 offset:49152
	buffer_load_dwordx4 v134, s[64:67], s52 offen lds
	s_add_i32 s47, s47, 0x200080
	s_mov_b32 m0, s34
	ds_read_b128 v[198:201], v140 offset:50176
	buffer_load_dwordx4 v136, s[64:67], s52 offen lds
	s_mov_b32 m0, s37
	ds_read_b128 v[202:205], v140 offset:51200
	buffer_load_dwordx4 v134, s[64:67], s47 offen lds
	s_mov_b32 m0, s68
	ds_read_b128 v[228:231], v140 offset:52224
	buffer_load_dwordx4 v136, s[64:67], s47 offen lds
	s_mov_b32 m0, s35
	ds_read_b128 v[232:235], v140 offset:53248
	buffer_load_dwordx4 v131, s[60:63], s27 offen lds
	s_mov_b32 m0, s36
	ds_read_b128 v[236:239], v140 offset:54272
	buffer_load_dwordx4 v135, s[60:63], s27 offen lds
	ds_read_b128 v[240:243], v140 offset:55296
	ds_read_b128 v[244:247], v140 offset:56320
	s_waitcnt vmcnt(8)
	s_waitcnt lgkmcnt(0)
	s_setprio 1
	s_barrier
	v_mfma_f32_16x16x32_bf16 v[94:97], v[142:145], v[194:197], v[94:97]
	v_mfma_f32_16x16x32_bf16 v[94:97], v[154:157], v[198:201], v[94:97]
	v_mfma_f32_16x16x32_bf16 v[90:93], v[170:173], v[194:197], v[90:93]
	v_mfma_f32_16x16x32_bf16 v[90:93], v[174:177], v[198:201], v[90:93]
	v_mfma_f32_16x16x32_bf16 v[26:29], v[186:189], v[194:197], v[26:29]
	v_mfma_f32_16x16x32_bf16 v[26:29], v[190:193], v[198:201], v[26:29]
	v_mfma_f32_16x16x32_bf16 v[30:33], v[178:181], v[194:197], v[30:33]
	v_mfma_f32_16x16x32_bf16 v[30:33], v[182:185], v[198:201], v[30:33]
	v_mfma_f32_16x16x32_bf16 v[22:25], v[178:181], v[202:205], v[22:25]
	v_mfma_f32_16x16x32_bf16 v[22:25], v[182:185], v[228:231], v[22:25]
	v_mfma_f32_16x16x32_bf16 v[18:21], v[186:189], v[202:205], v[18:21]
	v_mfma_f32_16x16x32_bf16 v[18:21], v[190:193], v[228:231], v[18:21]
	v_mfma_f32_16x16x32_bf16 v[82:85], v[170:173], v[202:205], v[82:85]
	v_mfma_f32_16x16x32_bf16 v[82:85], v[174:177], v[228:231], v[82:85]
	v_mfma_f32_16x16x32_bf16 v[86:89], v[142:145], v[202:205], v[86:89]
	v_mfma_f32_16x16x32_bf16 v[86:89], v[154:157], v[228:231], v[86:89]
	v_mfma_f32_16x16x32_bf16 v[78:81], v[142:145], v[232:235], v[78:81]
	v_mfma_f32_16x16x32_bf16 v[78:81], v[154:157], v[236:239], v[78:81]
	v_mfma_f32_16x16x32_bf16 v[74:77], v[170:173], v[232:235], v[74:77]
	v_mfma_f32_16x16x32_bf16 v[74:77], v[174:177], v[236:239], v[74:77]
	v_mfma_f32_16x16x32_bf16 v[10:13], v[186:189], v[232:235], v[10:13]
	v_mfma_f32_16x16x32_bf16 v[10:13], v[190:193], v[236:239], v[10:13]
	v_mfma_f32_16x16x32_bf16 v[14:17], v[178:181], v[232:235], v[14:17]
	v_mfma_f32_16x16x32_bf16 v[14:17], v[182:185], v[236:239], v[14:17]
	v_mfma_f32_16x16x32_bf16 v[6:9], v[178:181], v[240:243], v[6:9]
	v_mfma_f32_16x16x32_bf16 v[6:9], v[182:185], v[244:247], v[6:9]
	v_mfma_f32_16x16x32_bf16 v[2:5], v[186:189], v[240:243], v[2:5]
	v_mfma_f32_16x16x32_bf16 v[2:5], v[190:193], v[244:247], v[2:5]
	v_mfma_f32_16x16x32_bf16 v[66:69], v[170:173], v[240:243], v[66:69]
	v_mfma_f32_16x16x32_bf16 v[66:69], v[174:177], v[244:247], v[66:69]
	v_mfma_f32_16x16x32_bf16 v[70:73], v[142:145], v[240:243], v[70:73]
	v_mfma_f32_16x16x32_bf16 v[70:73], v[154:157], v[244:247], v[70:73]
	s_barrier
	s_setprio 0
	s_add_i32 s26, s26, 2
	s_addk_i32 s19, 0x100
	s_addk_i32 s22, 0x100
	s_cmpk_gt_u32 s26, 0x7d
	s_cbranch_scc0 .LBB0_1223
	s_and_b64 vcc, exec, s[42:43]
	s_cbranch_vccz .LBB0_1226
	s_barrier

.LBB0_1252:
	s_lshl_b32 s12, s73, 20
	s_and_b64 s[8:9], s[40:41], exec
	s_cselect_b32 s8, s12, s26
	s_lshl_b32 s22, s82, 20
	s_and_b64 s[70:71], s[40:41], exec
	s_cselect_b32 s9, s22, s27
	s_add_i32 s26, s26, 0x80080
	s_addk_i32 s27, 0x100
	s_mov_b32 s83, -2
	v_add_u32_e32 v141, 0x10000, v139
	ds_read_b128 v[142:145], v141
	ds_read_b128 v[154:157], v141 offset:1024
	ds_read_b128 v[170:173], v141 offset:2048
	ds_read_b128 v[174:177], v141 offset:3072
	v_add_u32_e32 v141, 0x14000, v139
	ds_read_b128 v[178:181], v141
	ds_read_b128 v[182:185], v141 offset:1024
	ds_read_b128 v[186:189], v141 offset:2048
	ds_read_b128 v[190:193], v141 offset:3072
	s_add_i32 s52, s26, 0xfff80080
	s_cmp_eq_u32 s83, 28
	s_cselect_b32 s52, s8, s52
	s_cselect_b32 s85, s9, s27
	s_or_b32 s84, s52, 0x80
	s_mov_b32 m0, s72
	ds_read_b128 v[194:197], v140
	ds_read_b128 v[198:201], v140 offset:1024
	ds_read_b128 v[202:205], v140 offset:2048
	ds_read_b128 v[228:231], v140 offset:3072
	ds_read_b128 v[232:235], v140 offset:4096
	ds_read_b128 v[236:239], v140 offset:5120
	ds_read_b128 v[240:243], v140 offset:6144
	ds_read_b128 v[244:247], v140 offset:7168
	buffer_load_dwordx4 v131, s[60:63], s26 offen lds
	s_mov_b32 m0, s46
	s_nop 0
	buffer_load_dwordx4 v135, s[60:63], s26 offen lds
	s_waitcnt vmcnt(8)
	s_waitcnt lgkmcnt(0)
	s_setprio 1
	s_barrier
	v_mfma_f32_16x16x32_bf16 v[126:129], v[142:145], v[194:197], 0
	v_mfma_f32_16x16x32_bf16 v[126:129], v[154:157], v[198:201], v[126:129]
	v_mfma_f32_16x16x32_bf16 v[122:125], v[170:173], v[194:197], 0
	v_mfma_f32_16x16x32_bf16 v[122:125], v[174:177], v[198:201], v[122:125]
	v_mfma_f32_16x16x32_bf16 v[58:61], v[186:189], v[194:197], 0
	v_mfma_f32_16x16x32_bf16 v[58:61], v[190:193], v[198:201], v[58:61]
	v_mfma_f32_16x16x32_bf16 v[62:65], v[178:181], v[194:197], 0
	v_mfma_f32_16x16x32_bf16 v[62:65], v[182:185], v[198:201], v[62:65]
	v_mfma_f32_16x16x32_bf16 v[54:57], v[178:181], v[202:205], 0
	v_mfma_f32_16x16x32_bf16 v[54:57], v[182:185], v[228:231], v[54:57]
	v_mfma_f32_16x16x32_bf16 v[50:53], v[186:189], v[202:205], 0
	v_mfma_f32_16x16x32_bf16 v[50:53], v[190:193], v[228:231], v[50:53]
	v_mfma_f32_16x16x32_bf16 v[114:117], v[170:173], v[202:205], 0
	v_mfma_f32_16x16x32_bf16 v[114:117], v[174:177], v[228:231], v[114:117]
	v_mfma_f32_16x16x32_bf16 v[118:121], v[142:145], v[202:205], 0
	v_mfma_f32_16x16x32_bf16 v[118:121], v[154:157], v[228:231], v[118:121]
	v_mfma_f32_16x16x32_bf16 v[110:113], v[142:145], v[232:235], 0
	v_mfma_f32_16x16x32_bf16 v[110:113], v[154:157], v[236:239], v[110:113]
	v_mfma_f32_16x16x32_bf16 v[106:109], v[170:173], v[232:235], 0
	v_mfma_f32_16x16x32_bf16 v[106:109], v[174:177], v[236:239], v[106:109]
	v_mfma_f32_16x16x32_bf16 v[42:45], v[186:189], v[232:235], 0
	v_mfma_f32_16x16x32_bf16 v[42:45], v[190:193], v[236:239], v[42:45]
	v_mfma_f32_16x16x32_bf16 v[46:49], v[178:181], v[232:235], 0
	v_mfma_f32_16x16x32_bf16 v[46:49], v[182:185], v[236:239], v[46:49]
	v_mfma_f32_16x16x32_bf16 v[38:41], v[178:181], v[240:243], 0
	v_mfma_f32_16x16x32_bf16 v[38:41], v[182:185], v[244:247], v[38:41]
	v_mfma_f32_16x16x32_bf16 v[34:37], v[186:189], v[240:243], 0
	v_mfma_f32_16x16x32_bf16 v[34:37], v[190:193], v[244:247], v[34:37]
	v_mfma_f32_16x16x32_bf16 v[98:101], v[170:173], v[240:243], 0
	v_mfma_f32_16x16x32_bf16 v[98:101], v[174:177], v[244:247], v[98:101]
	v_mfma_f32_16x16x32_bf16 v[102:105], v[142:145], v[240:243], 0
	v_mfma_f32_16x16x32_bf16 v[102:105], v[154:157], v[244:247], v[102:105]
	s_barrier
	s_setprio 0
	s_mov_b32 s70, s62
	s_mov_b32 s71, s63
	s_mov_b32 m0, s21
	ds_read_b128 v[194:197], v140 offset:16384
	buffer_load_dwordx4 v134, s[68:71], s85 offen lds
	s_add_i32 s53, s85, 0x80000
	s_mov_b32 m0, s23
	ds_read_b128 v[198:201], v140 offset:17408
	buffer_load_dwordx4 v136, s[68:71], s85 offen lds
	s_mov_b32 m0, s24
	ds_read_b128 v[202:205], v140 offset:18432
	buffer_load_dwordx4 v134, s[68:71], s53 offen lds
	s_mov_b32 m0, s25
	ds_read_b128 v[228:231], v140 offset:19456
	buffer_load_dwordx4 v136, s[68:71], s53 offen lds
	s_mov_b32 m0, s16
	ds_read_b128 v[232:235], v140 offset:20480
	buffer_load_dwordx4 v131, s[60:63], s52 offen lds
	s_mov_b32 m0, s30
	ds_read_b128 v[236:239], v140 offset:21504
	buffer_load_dwordx4 v135, s[60:63], s52 offen lds
	ds_read_b128 v[240:243], v140 offset:22528
	ds_read_b128 v[244:247], v140 offset:23552
	s_waitcnt vmcnt(8)
	s_waitcnt lgkmcnt(0)
	s_setprio 1
	s_barrier
	v_mfma_f32_16x16x32_bf16 v[94:97], v[142:145], v[194:197], 0
	v_mfma_f32_16x16x32_bf16 v[94:97], v[154:157], v[198:201], v[94:97]
	v_mfma_f32_16x16x32_bf16 v[90:93], v[170:173], v[194:197], 0
	v_mfma_f32_16x16x32_bf16 v[90:93], v[174:177], v[198:201], v[90:93]
	v_mfma_f32_16x16x32_bf16 v[26:29], v[186:189], v[194:197], 0
	v_mfma_f32_16x16x32_bf16 v[26:29], v[190:193], v[198:201], v[26:29]
	v_mfma_f32_16x16x32_bf16 v[30:33], v[178:181], v[194:197], 0
	v_mfma_f32_16x16x32_bf16 v[30:33], v[182:185], v[198:201], v[30:33]
	v_mfma_f32_16x16x32_bf16 v[22:25], v[178:181], v[202:205], 0
	v_mfma_f32_16x16x32_bf16 v[22:25], v[182:185], v[228:231], v[22:25]
	v_mfma_f32_16x16x32_bf16 v[18:21], v[186:189], v[202:205], 0
	v_mfma_f32_16x16x32_bf16 v[18:21], v[190:193], v[228:231], v[18:21]
	v_mfma_f32_16x16x32_bf16 v[82:85], v[170:173], v[202:205], 0
	v_mfma_f32_16x16x32_bf16 v[82:85], v[174:177], v[228:231], v[82:85]
	v_mfma_f32_16x16x32_bf16 v[86:89], v[142:145], v[202:205], 0
	v_mfma_f32_16x16x32_bf16 v[86:89], v[154:157], v[228:231], v[86:89]
	v_mfma_f32_16x16x32_bf16 v[78:81], v[142:145], v[232:235], 0
	v_mfma_f32_16x16x32_bf16 v[78:81], v[154:157], v[236:239], v[78:81]
	v_mfma_f32_16x16x32_bf16 v[74:77], v[170:173], v[232:235], 0
	v_mfma_f32_16x16x32_bf16 v[74:77], v[174:177], v[236:239], v[74:77]
	v_mfma_f32_16x16x32_bf16 v[10:13], v[186:189], v[232:235], 0
	v_mfma_f32_16x16x32_bf16 v[10:13], v[190:193], v[236:239], v[10:13]
	v_mfma_f32_16x16x32_bf16 v[14:17], v[178:181], v[232:235], 0
	v_mfma_f32_16x16x32_bf16 v[14:17], v[182:185], v[236:239], v[14:17]
	v_mfma_f32_16x16x32_bf16 v[6:9], v[178:181], v[240:243], 0
	v_mfma_f32_16x16x32_bf16 v[6:9], v[182:185], v[244:247], v[6:9]
	v_mfma_f32_16x16x32_bf16 v[2:5], v[186:189], v[240:243], 0
	v_mfma_f32_16x16x32_bf16 v[2:5], v[190:193], v[244:247], v[2:5]
	v_mfma_f32_16x16x32_bf16 v[66:69], v[170:173], v[240:243], 0
	v_mfma_f32_16x16x32_bf16 v[66:69], v[174:177], v[244:247], v[66:69]
	v_mfma_f32_16x16x32_bf16 v[70:73], v[142:145], v[240:243], 0
	v_mfma_f32_16x16x32_bf16 v[70:73], v[154:157], v[244:247], v[70:73]
	s_barrier
	s_setprio 0
	v_add_u32_e32 v141, 0x18000, v139
	ds_read_b128 v[142:145], v141
	ds_read_b128 v[154:157], v141 offset:1024
	ds_read_b128 v[170:173], v141 offset:2048
	ds_read_b128 v[174:177], v141 offset:3072
	v_add_u32_e32 v141, 0x1c000, v139
	ds_read_b128 v[178:181], v141
	ds_read_b128 v[182:185], v141 offset:1024
	ds_read_b128 v[186:189], v141 offset:2048
	ds_read_b128 v[190:193], v141 offset:3072
	s_add_i32 s52, s52, 0x80000
	s_mov_b32 m0, s31
	ds_read_b128 v[194:197], v140 offset:32768
	ds_read_b128 v[198:201], v140 offset:33792
	ds_read_b128 v[202:205], v140 offset:34816
	ds_read_b128 v[228:231], v140 offset:35840
	ds_read_b128 v[232:235], v140 offset:36864
	ds_read_b128 v[236:239], v140 offset:37888
	ds_read_b128 v[240:243], v140 offset:38912
	ds_read_b128 v[244:247], v140 offset:39936
	buffer_load_dwordx4 v131, s[60:63], s52 offen lds
	s_mov_b32 m0, s33
	s_nop 0
	buffer_load_dwordx4 v135, s[60:63], s52 offen lds
	s_waitcnt vmcnt(8)
	s_waitcnt lgkmcnt(0)
	s_setprio 1
	s_barrier
	v_mfma_f32_16x16x32_bf16 v[126:129], v[142:145], v[194:197], v[126:129]
	v_mfma_f32_16x16x32_bf16 v[126:129], v[154:157], v[198:201], v[126:129]
	v_mfma_f32_16x16x32_bf16 v[122:125], v[170:173], v[194:197], v[122:125]
	v_mfma_f32_16x16x32_bf16 v[122:125], v[174:177], v[198:201], v[122:125]
	v_mfma_f32_16x16x32_bf16 v[58:61], v[186:189], v[194:197], v[58:61]
	v_mfma_f32_16x16x32_bf16 v[58:61], v[190:193], v[198:201], v[58:61]
	v_mfma_f32_16x16x32_bf16 v[62:65], v[178:181], v[194:197], v[62:65]
	v_mfma_f32_16x16x32_bf16 v[62:65], v[182:185], v[198:201], v[62:65]
	v_mfma_f32_16x16x32_bf16 v[54:57], v[178:181], v[202:205], v[54:57]
	v_mfma_f32_16x16x32_bf16 v[54:57], v[182:185], v[228:231], v[54:57]
	v_mfma_f32_16x16x32_bf16 v[50:53], v[186:189], v[202:205], v[50:53]
	v_mfma_f32_16x16x32_bf16 v[50:53], v[190:193], v[228:231], v[50:53]
	v_mfma_f32_16x16x32_bf16 v[114:117], v[170:173], v[202:205], v[114:117]
	v_mfma_f32_16x16x32_bf16 v[114:117], v[174:177], v[228:231], v[114:117]
	v_mfma_f32_16x16x32_bf16 v[118:121], v[142:145], v[202:205], v[118:121]
	v_mfma_f32_16x16x32_bf16 v[118:121], v[154:157], v[228:231], v[118:121]
	v_mfma_f32_16x16x32_bf16 v[110:113], v[142:145], v[232:235], v[110:113]
	v_mfma_f32_16x16x32_bf16 v[110:113], v[154:157], v[236:239], v[110:113]
	v_mfma_f32_16x16x32_bf16 v[106:109], v[170:173], v[232:235], v[106:109]
	v_mfma_f32_16x16x32_bf16 v[106:109], v[174:177], v[236:239], v[106:109]
	v_mfma_f32_16x16x32_bf16 v[42:45], v[186:189], v[232:235], v[42:45]
	v_mfma_f32_16x16x32_bf16 v[42:45], v[190:193], v[236:239], v[42:45]
	v_mfma_f32_16x16x32_bf16 v[46:49], v[178:181], v[232:235], v[46:49]
	v_mfma_f32_16x16x32_bf16 v[46:49], v[182:185], v[236:239], v[46:49]
	v_mfma_f32_16x16x32_bf16 v[38:41], v[178:181], v[240:243], v[38:41]
	v_mfma_f32_16x16x32_bf16 v[38:41], v[182:185], v[244:247], v[38:41]
	v_mfma_f32_16x16x32_bf16 v[34:37], v[186:189], v[240:243], v[34:37]
	v_mfma_f32_16x16x32_bf16 v[34:37], v[190:193], v[244:247], v[34:37]
	v_mfma_f32_16x16x32_bf16 v[98:101], v[170:173], v[240:243], v[98:101]
	v_mfma_f32_16x16x32_bf16 v[98:101], v[174:177], v[244:247], v[98:101]
	v_mfma_f32_16x16x32_bf16 v[102:105], v[142:145], v[240:243], v[102:105]
	v_mfma_f32_16x16x32_bf16 v[102:105], v[154:157], v[244:247], v[102:105]
	s_barrier
	s_setprio 0
	s_or_b32 s52, s85, 0x80
	s_mov_b32 m0, s34
	ds_read_b128 v[194:197], v140 offset:49152
	buffer_load_dwordx4 v134, s[68:71], s52 offen lds
	s_add_i32 s85, s85, 0x80080
	s_mov_b32 m0, s35
	ds_read_b128 v[198:201], v140 offset:50176
	buffer_load_dwordx4 v136, s[68:71], s52 offen lds
	s_mov_b32 m0, s37
	ds_read_b128 v[202:205], v140 offset:51200
	buffer_load_dwordx4 v134, s[68:71], s85 offen lds
	s_mov_b32 m0, s65
	ds_read_b128 v[228:231], v140 offset:52224
	buffer_load_dwordx4 v136, s[68:71], s85 offen lds
	s_mov_b32 m0, s14
	ds_read_b128 v[232:235], v140 offset:53248
	buffer_load_dwordx4 v131, s[60:63], s84 offen lds
	s_mov_b32 m0, s36
	ds_read_b128 v[236:239], v140 offset:54272
	buffer_load_dwordx4 v135, s[60:63], s84 offen lds
	ds_read_b128 v[240:243], v140 offset:55296
	ds_read_b128 v[244:247], v140 offset:56320
	s_waitcnt vmcnt(8)
	s_waitcnt lgkmcnt(0)
	s_setprio 1
	s_barrier
	v_mfma_f32_16x16x32_bf16 v[94:97], v[142:145], v[194:197], v[94:97]
	v_mfma_f32_16x16x32_bf16 v[94:97], v[154:157], v[198:201], v[94:97]
	v_mfma_f32_16x16x32_bf16 v[90:93], v[170:173], v[194:197], v[90:93]
	v_mfma_f32_16x16x32_bf16 v[90:93], v[174:177], v[198:201], v[90:93]
	v_mfma_f32_16x16x32_bf16 v[26:29], v[186:189], v[194:197], v[26:29]
	v_mfma_f32_16x16x32_bf16 v[26:29], v[190:193], v[198:201], v[26:29]
	v_mfma_f32_16x16x32_bf16 v[30:33], v[178:181], v[194:197], v[30:33]
	v_mfma_f32_16x16x32_bf16 v[30:33], v[182:185], v[198:201], v[30:33]
	v_mfma_f32_16x16x32_bf16 v[22:25], v[178:181], v[202:205], v[22:25]
	v_mfma_f32_16x16x32_bf16 v[22:25], v[182:185], v[228:231], v[22:25]
	v_mfma_f32_16x16x32_bf16 v[18:21], v[186:189], v[202:205], v[18:21]
	v_mfma_f32_16x16x32_bf16 v[18:21], v[190:193], v[228:231], v[18:21]
	v_mfma_f32_16x16x32_bf16 v[82:85], v[170:173], v[202:205], v[82:85]
	v_mfma_f32_16x16x32_bf16 v[82:85], v[174:177], v[228:231], v[82:85]
	v_mfma_f32_16x16x32_bf16 v[86:89], v[142:145], v[202:205], v[86:89]
	v_mfma_f32_16x16x32_bf16 v[86:89], v[154:157], v[228:231], v[86:89]
	v_mfma_f32_16x16x32_bf16 v[78:81], v[142:145], v[232:235], v[78:81]
	v_mfma_f32_16x16x32_bf16 v[78:81], v[154:157], v[236:239], v[78:81]
	v_mfma_f32_16x16x32_bf16 v[74:77], v[170:173], v[232:235], v[74:77]
	v_mfma_f32_16x16x32_bf16 v[74:77], v[174:177], v[236:239], v[74:77]
	v_mfma_f32_16x16x32_bf16 v[10:13], v[186:189], v[232:235], v[10:13]
	v_mfma_f32_16x16x32_bf16 v[10:13], v[190:193], v[236:239], v[10:13]
	v_mfma_f32_16x16x32_bf16 v[14:17], v[178:181], v[232:235], v[14:17]
	v_mfma_f32_16x16x32_bf16 v[14:17], v[182:185], v[236:239], v[14:17]
	v_mfma_f32_16x16x32_bf16 v[6:9], v[178:181], v[240:243], v[6:9]
	v_mfma_f32_16x16x32_bf16 v[6:9], v[182:185], v[244:247], v[6:9]
	v_mfma_f32_16x16x32_bf16 v[2:5], v[186:189], v[240:243], v[2:5]
	v_mfma_f32_16x16x32_bf16 v[2:5], v[190:193], v[244:247], v[2:5]
	v_mfma_f32_16x16x32_bf16 v[66:69], v[170:173], v[240:243], v[66:69]
	v_mfma_f32_16x16x32_bf16 v[66:69], v[174:177], v[244:247], v[66:69]
	v_mfma_f32_16x16x32_bf16 v[70:73], v[142:145], v[240:243], v[70:73]
	v_mfma_f32_16x16x32_bf16 v[70:73], v[154:157], v[244:247], v[70:73]
	s_barrier
	s_setprio 0
	s_add_i32 s83, s83, 2
	s_addk_i32 s26, 0x100
	s_addk_i32 s27, 0x100
	s_cmp_gt_u32 s83, 29
.LBB0_1253:
	v_add_u32_e32 v141, 0x10000, v139
	ds_read_b128 v[142:145], v141
	ds_read_b128 v[154:157], v141 offset:1024
	ds_read_b128 v[170:173], v141 offset:2048
	ds_read_b128 v[174:177], v141 offset:3072
	v_add_u32_e32 v141, 0x14000, v139
	ds_read_b128 v[178:181], v141
	ds_read_b128 v[182:185], v141 offset:1024
	ds_read_b128 v[186:189], v141 offset:2048
	ds_read_b128 v[190:193], v141 offset:3072
	s_add_i32 s52, s26, 0xfff80080
	s_cmp_eq_u32 s83, 28
	s_cselect_b32 s52, s8, s52
	s_cselect_b32 s85, s9, s27
	s_or_b32 s84, s52, 0x80
	s_mov_b32 m0, s72
	ds_read_b128 v[194:197], v140
	ds_read_b128 v[198:201], v140 offset:1024
	ds_read_b128 v[202:205], v140 offset:2048
	ds_read_b128 v[228:231], v140 offset:3072
	ds_read_b128 v[232:235], v140 offset:4096
	ds_read_b128 v[236:239], v140 offset:5120
	ds_read_b128 v[240:243], v140 offset:6144
	ds_read_b128 v[244:247], v140 offset:7168
	buffer_load_dwordx4 v131, s[60:63], s26 offen lds
	s_mov_b32 m0, s46
	s_nop 0
	buffer_load_dwordx4 v135, s[60:63], s26 offen lds
	s_waitcnt vmcnt(8)
	s_waitcnt lgkmcnt(0)
	s_setprio 1
	s_barrier
	v_mfma_f32_16x16x32_bf16 v[126:129], v[142:145], v[194:197], v[126:129]
	v_mfma_f32_16x16x32_bf16 v[126:129], v[154:157], v[198:201], v[126:129]
	v_mfma_f32_16x16x32_bf16 v[122:125], v[170:173], v[194:197], v[122:125]
	v_mfma_f32_16x16x32_bf16 v[122:125], v[174:177], v[198:201], v[122:125]
	v_mfma_f32_16x16x32_bf16 v[58:61], v[186:189], v[194:197], v[58:61]
	v_mfma_f32_16x16x32_bf16 v[58:61], v[190:193], v[198:201], v[58:61]
	v_mfma_f32_16x16x32_bf16 v[62:65], v[178:181], v[194:197], v[62:65]
	v_mfma_f32_16x16x32_bf16 v[62:65], v[182:185], v[198:201], v[62:65]
	v_mfma_f32_16x16x32_bf16 v[54:57], v[178:181], v[202:205], v[54:57]
	v_mfma_f32_16x16x32_bf16 v[54:57], v[182:185], v[228:231], v[54:57]
	v_mfma_f32_16x16x32_bf16 v[50:53], v[186:189], v[202:205], v[50:53]
	v_mfma_f32_16x16x32_bf16 v[50:53], v[190:193], v[228:231], v[50:53]
	v_mfma_f32_16x16x32_bf16 v[114:117], v[170:173], v[202:205], v[114:117]
	v_mfma_f32_16x16x32_bf16 v[114:117], v[174:177], v[228:231], v[114:117]
	v_mfma_f32_16x16x32_bf16 v[118:121], v[142:145], v[202:205], v[118:121]
	v_mfma_f32_16x16x32_bf16 v[118:121], v[154:157], v[228:231], v[118:121]
	v_mfma_f32_16x16x32_bf16 v[110:113], v[142:145], v[232:235], v[110:113]
	v_mfma_f32_16x16x32_bf16 v[110:113], v[154:157], v[236:239], v[110:113]
	v_mfma_f32_16x16x32_bf16 v[106:109], v[170:173], v[232:235], v[106:109]
	v_mfma_f32_16x16x32_bf16 v[106:109], v[174:177], v[236:239], v[106:109]
	v_mfma_f32_16x16x32_bf16 v[42:45], v[186:189], v[232:235], v[42:45]
	v_mfma_f32_16x16x32_bf16 v[42:45], v[190:193], v[236:239], v[42:45]
	v_mfma_f32_16x16x32_bf16 v[46:49], v[178:181], v[232:235], v[46:49]
	v_mfma_f32_16x16x32_bf16 v[46:49], v[182:185], v[236:239], v[46:49]
	v_mfma_f32_16x16x32_bf16 v[38:41], v[178:181], v[240:243], v[38:41]
	v_mfma_f32_16x16x32_bf16 v[38:41], v[182:185], v[244:247], v[38:41]
	v_mfma_f32_16x16x32_bf16 v[34:37], v[186:189], v[240:243], v[34:37]
	v_mfma_f32_16x16x32_bf16 v[34:37], v[190:193], v[244:247], v[34:37]
	v_mfma_f32_16x16x32_bf16 v[98:101], v[170:173], v[240:243], v[98:101]
	v_mfma_f32_16x16x32_bf16 v[98:101], v[174:177], v[244:247], v[98:101]
	v_mfma_f32_16x16x32_bf16 v[102:105], v[142:145], v[240:243], v[102:105]
	v_mfma_f32_16x16x32_bf16 v[102:105], v[154:157], v[244:247], v[102:105]
	s_barrier
	s_setprio 0
	s_mov_b32 s70, s62
	s_mov_b32 s71, s63
	s_mov_b32 m0, s21
	ds_read_b128 v[194:197], v140 offset:16384
	buffer_load_dwordx4 v134, s[68:71], s85 offen lds
	s_add_i32 s53, s85, 0x80000
	s_mov_b32 m0, s23
	ds_read_b128 v[198:201], v140 offset:17408
	buffer_load_dwordx4 v136, s[68:71], s85 offen lds
	s_mov_b32 m0, s24
	ds_read_b128 v[202:205], v140 offset:18432
	buffer_load_dwordx4 v134, s[68:71], s53 offen lds
	s_mov_b32 m0, s25
	ds_read_b128 v[228:231], v140 offset:19456
	buffer_load_dwordx4 v136, s[68:71], s53 offen lds
	s_mov_b32 m0, s16
	ds_read_b128 v[232:235], v140 offset:20480
	buffer_load_dwordx4 v131, s[60:63], s52 offen lds
	s_mov_b32 m0, s30
	ds_read_b128 v[236:239], v140 offset:21504
	buffer_load_dwordx4 v135, s[60:63], s52 offen lds
	ds_read_b128 v[240:243], v140 offset:22528
	ds_read_b128 v[244:247], v140 offset:23552
	s_waitcnt vmcnt(8)
	s_waitcnt lgkmcnt(0)
	s_setprio 1
	s_barrier
	v_mfma_f32_16x16x32_bf16 v[94:97], v[142:145], v[194:197], v[94:97]
	v_mfma_f32_16x16x32_bf16 v[94:97], v[154:157], v[198:201], v[94:97]
	v_mfma_f32_16x16x32_bf16 v[90:93], v[170:173], v[194:197], v[90:93]
	v_mfma_f32_16x16x32_bf16 v[90:93], v[174:177], v[198:201], v[90:93]
	v_mfma_f32_16x16x32_bf16 v[26:29], v[186:189], v[194:197], v[26:29]
	v_mfma_f32_16x16x32_bf16 v[26:29], v[190:193], v[198:201], v[26:29]
	v_mfma_f32_16x16x32_bf16 v[30:33], v[178:181], v[194:197], v[30:33]
	v_mfma_f32_16x16x32_bf16 v[30:33], v[182:185], v[198:201], v[30:33]
	v_mfma_f32_16x16x32_bf16 v[22:25], v[178:181], v[202:205], v[22:25]
	v_mfma_f32_16x16x32_bf16 v[22:25], v[182:185], v[228:231], v[22:25]
	v_mfma_f32_16x16x32_bf16 v[18:21], v[186:189], v[202:205], v[18:21]
	v_mfma_f32_16x16x32_bf16 v[18:21], v[190:193], v[228:231], v[18:21]
	v_mfma_f32_16x16x32_bf16 v[82:85], v[170:173], v[202:205], v[82:85]
	v_mfma_f32_16x16x32_bf16 v[82:85], v[174:177], v[228:231], v[82:85]
	v_mfma_f32_16x16x32_bf16 v[86:89], v[142:145], v[202:205], v[86:89]
	v_mfma_f32_16x16x32_bf16 v[86:89], v[154:157], v[228:231], v[86:89]
	v_mfma_f32_16x16x32_bf16 v[78:81], v[142:145], v[232:235], v[78:81]
	v_mfma_f32_16x16x32_bf16 v[78:81], v[154:157], v[236:239], v[78:81]
	v_mfma_f32_16x16x32_bf16 v[74:77], v[170:173], v[232:235], v[74:77]
	v_mfma_f32_16x16x32_bf16 v[74:77], v[174:177], v[236:239], v[74:77]
	v_mfma_f32_16x16x32_bf16 v[10:13], v[186:189], v[232:235], v[10:13]
	v_mfma_f32_16x16x32_bf16 v[10:13], v[190:193], v[236:239], v[10:13]
	v_mfma_f32_16x16x32_bf16 v[14:17], v[178:181], v[232:235], v[14:17]
	v_mfma_f32_16x16x32_bf16 v[14:17], v[182:185], v[236:239], v[14:17]
	v_mfma_f32_16x16x32_bf16 v[6:9], v[178:181], v[240:243], v[6:9]
	v_mfma_f32_16x16x32_bf16 v[6:9], v[182:185], v[244:247], v[6:9]
	v_mfma_f32_16x16x32_bf16 v[2:5], v[186:189], v[240:243], v[2:5]
	v_mfma_f32_16x16x32_bf16 v[2:5], v[190:193], v[244:247], v[2:5]
	v_mfma_f32_16x16x32_bf16 v[66:69], v[170:173], v[240:243], v[66:69]
	v_mfma_f32_16x16x32_bf16 v[66:69], v[174:177], v[244:247], v[66:69]
	v_mfma_f32_16x16x32_bf16 v[70:73], v[142:145], v[240:243], v[70:73]
	v_mfma_f32_16x16x32_bf16 v[70:73], v[154:157], v[244:247], v[70:73]
	s_barrier
	s_setprio 0
	v_add_u32_e32 v141, 0x18000, v139
	ds_read_b128 v[142:145], v141
	ds_read_b128 v[154:157], v141 offset:1024
	ds_read_b128 v[170:173], v141 offset:2048
	ds_read_b128 v[174:177], v141 offset:3072
	v_add_u32_e32 v141, 0x1c000, v139
	ds_read_b128 v[178:181], v141
	ds_read_b128 v[182:185], v141 offset:1024
	ds_read_b128 v[186:189], v141 offset:2048
	ds_read_b128 v[190:193], v141 offset:3072
	s_add_i32 s52, s52, 0x80000
	s_mov_b32 m0, s31
	ds_read_b128 v[194:197], v140 offset:32768
	ds_read_b128 v[198:201], v140 offset:33792
	ds_read_b128 v[202:205], v140 offset:34816
	ds_read_b128 v[228:231], v140 offset:35840
	ds_read_b128 v[232:235], v140 offset:36864
	ds_read_b128 v[236:239], v140 offset:37888
	ds_read_b128 v[240:243], v140 offset:38912
	ds_read_b128 v[244:247], v140 offset:39936
	buffer_load_dwordx4 v131, s[60:63], s52 offen lds
	s_mov_b32 m0, s33
	s_nop 0
	buffer_load_dwordx4 v135, s[60:63], s52 offen lds
	s_waitcnt vmcnt(8)
	s_waitcnt lgkmcnt(0)
	s_setprio 1
	s_barrier
	v_mfma_f32_16x16x32_bf16 v[126:129], v[142:145], v[194:197], v[126:129]
	v_mfma_f32_16x16x32_bf16 v[126:129], v[154:157], v[198:201], v[126:129]
	v_mfma_f32_16x16x32_bf16 v[122:125], v[170:173], v[194:197], v[122:125]
	v_mfma_f32_16x16x32_bf16 v[122:125], v[174:177], v[198:201], v[122:125]
	v_mfma_f32_16x16x32_bf16 v[58:61], v[186:189], v[194:197], v[58:61]
	v_mfma_f32_16x16x32_bf16 v[58:61], v[190:193], v[198:201], v[58:61]
	v_mfma_f32_16x16x32_bf16 v[62:65], v[178:181], v[194:197], v[62:65]
	v_mfma_f32_16x16x32_bf16 v[62:65], v[182:185], v[198:201], v[62:65]
	v_mfma_f32_16x16x32_bf16 v[54:57], v[178:181], v[202:205], v[54:57]
	v_mfma_f32_16x16x32_bf16 v[54:57], v[182:185], v[228:231], v[54:57]
	v_mfma_f32_16x16x32_bf16 v[50:53], v[186:189], v[202:205], v[50:53]
	v_mfma_f32_16x16x32_bf16 v[50:53], v[190:193], v[228:231], v[50:53]
	v_mfma_f32_16x16x32_bf16 v[114:117], v[170:173], v[202:205], v[114:117]
	v_mfma_f32_16x16x32_bf16 v[114:117], v[174:177], v[228:231], v[114:117]
	v_mfma_f32_16x16x32_bf16 v[118:121], v[142:145], v[202:205], v[118:121]
	v_mfma_f32_16x16x32_bf16 v[118:121], v[154:157], v[228:231], v[118:121]
	v_mfma_f32_16x16x32_bf16 v[110:113], v[142:145], v[232:235], v[110:113]
	v_mfma_f32_16x16x32_bf16 v[110:113], v[154:157], v[236:239], v[110:113]
	v_mfma_f32_16x16x32_bf16 v[106:109], v[170:173], v[232:235], v[106:109]
	v_mfma_f32_16x16x32_bf16 v[106:109], v[174:177], v[236:239], v[106:109]
	v_mfma_f32_16x16x32_bf16 v[42:45], v[186:189], v[232:235], v[42:45]
	v_mfma_f32_16x16x32_bf16 v[42:45], v[190:193], v[236:239], v[42:45]
	v_mfma_f32_16x16x32_bf16 v[46:49], v[178:181], v[232:235], v[46:49]
	v_mfma_f32_16x16x32_bf16 v[46:49], v[182:185], v[236:239], v[46:49]
	v_mfma_f32_16x16x32_bf16 v[38:41], v[178:181], v[240:243], v[38:41]
	v_mfma_f32_16x16x32_bf16 v[38:41], v[182:185], v[244:247], v[38:41]
	v_mfma_f32_16x16x32_bf16 v[34:37], v[186:189], v[240:243], v[34:37]
	v_mfma_f32_16x16x32_bf16 v[34:37], v[190:193], v[244:247], v[34:37]
	v_mfma_f32_16x16x32_bf16 v[98:101], v[170:173], v[240:243], v[98:101]
	v_mfma_f32_16x16x32_bf16 v[98:101], v[174:177], v[244:247], v[98:101]
	v_mfma_f32_16x16x32_bf16 v[102:105], v[142:145], v[240:243], v[102:105]
	v_mfma_f32_16x16x32_bf16 v[102:105], v[154:157], v[244:247], v[102:105]
	s_barrier
	s_setprio 0
	s_or_b32 s52, s85, 0x80
	s_mov_b32 m0, s34
	ds_read_b128 v[194:197], v140 offset:49152
	buffer_load_dwordx4 v134, s[68:71], s52 offen lds
	s_add_i32 s85, s85, 0x80080
	s_mov_b32 m0, s35
	ds_read_b128 v[198:201], v140 offset:50176
	buffer_load_dwordx4 v136, s[68:71], s52 offen lds
	s_mov_b32 m0, s37
	ds_read_b128 v[202:205], v140 offset:51200
	buffer_load_dwordx4 v134, s[68:71], s85 offen lds
	s_mov_b32 m0, s65
	ds_read_b128 v[228:231], v140 offset:52224
	buffer_load_dwordx4 v136, s[68:71], s85 offen lds
	s_mov_b32 m0, s14
	ds_read_b128 v[232:235], v140 offset:53248
	buffer_load_dwordx4 v131, s[60:63], s84 offen lds
	s_mov_b32 m0, s36
	ds_read_b128 v[236:239], v140 offset:54272
	buffer_load_dwordx4 v135, s[60:63], s84 offen lds
	ds_read_b128 v[240:243], v140 offset:55296
	ds_read_b128 v[244:247], v140 offset:56320
	s_waitcnt vmcnt(8)
	s_waitcnt lgkmcnt(0)
	s_setprio 1
	s_barrier
	v_mfma_f32_16x16x32_bf16 v[94:97], v[142:145], v[194:197], v[94:97]
	v_mfma_f32_16x16x32_bf16 v[94:97], v[154:157], v[198:201], v[94:97]
	v_mfma_f32_16x16x32_bf16 v[90:93], v[170:173], v[194:197], v[90:93]
	v_mfma_f32_16x16x32_bf16 v[90:93], v[174:177], v[198:201], v[90:93]
	v_mfma_f32_16x16x32_bf16 v[26:29], v[186:189], v[194:197], v[26:29]
	v_mfma_f32_16x16x32_bf16 v[26:29], v[190:193], v[198:201], v[26:29]
	v_mfma_f32_16x16x32_bf16 v[30:33], v[178:181], v[194:197], v[30:33]
	v_mfma_f32_16x16x32_bf16 v[30:33], v[182:185], v[198:201], v[30:33]
	v_mfma_f32_16x16x32_bf16 v[22:25], v[178:181], v[202:205], v[22:25]
	v_mfma_f32_16x16x32_bf16 v[22:25], v[182:185], v[228:231], v[22:25]
	v_mfma_f32_16x16x32_bf16 v[18:21], v[186:189], v[202:205], v[18:21]
	v_mfma_f32_16x16x32_bf16 v[18:21], v[190:193], v[228:231], v[18:21]
	v_mfma_f32_16x16x32_bf16 v[82:85], v[170:173], v[202:205], v[82:85]
	v_mfma_f32_16x16x32_bf16 v[82:85], v[174:177], v[228:231], v[82:85]
	v_mfma_f32_16x16x32_bf16 v[86:89], v[142:145], v[202:205], v[86:89]
	v_mfma_f32_16x16x32_bf16 v[86:89], v[154:157], v[228:231], v[86:89]
	v_mfma_f32_16x16x32_bf16 v[78:81], v[142:145], v[232:235], v[78:81]
	v_mfma_f32_16x16x32_bf16 v[78:81], v[154:157], v[236:239], v[78:81]
	v_mfma_f32_16x16x32_bf16 v[74:77], v[170:173], v[232:235], v[74:77]
	v_mfma_f32_16x16x32_bf16 v[74:77], v[174:177], v[236:239], v[74:77]
	v_mfma_f32_16x16x32_bf16 v[10:13], v[186:189], v[232:235], v[10:13]
	v_mfma_f32_16x16x32_bf16 v[10:13], v[190:193], v[236:239], v[10:13]
	v_mfma_f32_16x16x32_bf16 v[14:17], v[178:181], v[232:235], v[14:17]
	v_mfma_f32_16x16x32_bf16 v[14:17], v[182:185], v[236:239], v[14:17]
	v_mfma_f32_16x16x32_bf16 v[6:9], v[178:181], v[240:243], v[6:9]
	v_mfma_f32_16x16x32_bf16 v[6:9], v[182:185], v[244:247], v[6:9]
	v_mfma_f32_16x16x32_bf16 v[2:5], v[186:189], v[240:243], v[2:5]
	v_mfma_f32_16x16x32_bf16 v[2:5], v[190:193], v[244:247], v[2:5]
	v_mfma_f32_16x16x32_bf16 v[66:69], v[170:173], v[240:243], v[66:69]
	v_mfma_f32_16x16x32_bf16 v[66:69], v[174:177], v[244:247], v[66:69]
	v_mfma_f32_16x16x32_bf16 v[70:73], v[142:145], v[240:243], v[70:73]
	v_mfma_f32_16x16x32_bf16 v[70:73], v[154:157], v[244:247], v[70:73]
	s_barrier
	s_setprio 0
	s_add_i32 s83, s83, 2
	s_addk_i32 s26, 0x100
	s_addk_i32 s27, 0x100
	s_cmp_gt_u32 s83, 29
	s_cbranch_scc0 .LBB0_1253
	s_and_b64 vcc, exec, s[44:45]
	s_cbranch_vccz .LBB0_1256
	s_barrier

.LBB0_1282:
	s_lshl_b32 s46, s85, 20
	s_and_b64 s[8:9], s[40:41], exec
	s_cselect_b32 s8, s46, s19
	s_lshl_b32 s47, s14, 20
	s_and_b64 s[26:27], s[40:41], exec
	s_cselect_b32 s9, s47, s22
	s_add_i32 s19, s19, 0x80080
	s_addk_i32 s22, 0x100
	s_mov_b32 s26, -2
	v_add_u32_e32 v141, 0x10000, v139
	ds_read_b128 v[142:145], v141
	ds_read_b128 v[154:157], v141 offset:1024
	ds_read_b128 v[170:173], v141 offset:2048
	ds_read_b128 v[174:177], v141 offset:3072
	v_add_u32_e32 v141, 0x14000, v139
	ds_read_b128 v[178:181], v141
	ds_read_b128 v[182:185], v141 offset:1024
	ds_read_b128 v[186:189], v141 offset:2048
	ds_read_b128 v[190:193], v141 offset:3072
	s_add_i32 s27, s19, 0xfff80080
	s_cmp_eq_u32 s26, 28
	s_cselect_b32 s52, s8, s27
	s_cselect_b32 s83, s9, s22
	s_or_b32 s27, s52, 0x80
	s_mov_b32 m0, s73
	ds_read_b128 v[194:197], v140
	ds_read_b128 v[198:201], v140 offset:1024
	ds_read_b128 v[202:205], v140 offset:2048
	ds_read_b128 v[228:231], v140 offset:3072
	ds_read_b128 v[232:235], v140 offset:4096
	ds_read_b128 v[236:239], v140 offset:5120
	ds_read_b128 v[240:243], v140 offset:6144
	ds_read_b128 v[244:247], v140 offset:7168
	buffer_load_dwordx4 v131, s[60:63], s19 offen lds
	s_mov_b32 m0, s82
	s_nop 0
	buffer_load_dwordx4 v135, s[60:63], s19 offen lds
	s_waitcnt vmcnt(8)
	s_waitcnt lgkmcnt(0)
	s_setprio 1
	s_barrier
	v_mfma_f32_16x16x32_bf16 v[126:129], v[142:145], v[194:197], 0
	v_mfma_f32_16x16x32_bf16 v[126:129], v[154:157], v[198:201], v[126:129]
	v_mfma_f32_16x16x32_bf16 v[122:125], v[170:173], v[194:197], 0
	v_mfma_f32_16x16x32_bf16 v[122:125], v[174:177], v[198:201], v[122:125]
	v_mfma_f32_16x16x32_bf16 v[58:61], v[186:189], v[194:197], 0
	v_mfma_f32_16x16x32_bf16 v[58:61], v[190:193], v[198:201], v[58:61]
	v_mfma_f32_16x16x32_bf16 v[62:65], v[178:181], v[194:197], 0
	v_mfma_f32_16x16x32_bf16 v[62:65], v[182:185], v[198:201], v[62:65]
	v_mfma_f32_16x16x32_bf16 v[54:57], v[178:181], v[202:205], 0
	v_mfma_f32_16x16x32_bf16 v[54:57], v[182:185], v[228:231], v[54:57]
	v_mfma_f32_16x16x32_bf16 v[50:53], v[186:189], v[202:205], 0
	v_mfma_f32_16x16x32_bf16 v[50:53], v[190:193], v[228:231], v[50:53]
	v_mfma_f32_16x16x32_bf16 v[114:117], v[170:173], v[202:205], 0
	v_mfma_f32_16x16x32_bf16 v[114:117], v[174:177], v[228:231], v[114:117]
	v_mfma_f32_16x16x32_bf16 v[118:121], v[142:145], v[202:205], 0
	v_mfma_f32_16x16x32_bf16 v[118:121], v[154:157], v[228:231], v[118:121]
	v_mfma_f32_16x16x32_bf16 v[110:113], v[142:145], v[232:235], 0
	v_mfma_f32_16x16x32_bf16 v[110:113], v[154:157], v[236:239], v[110:113]
	v_mfma_f32_16x16x32_bf16 v[106:109], v[170:173], v[232:235], 0
	v_mfma_f32_16x16x32_bf16 v[106:109], v[174:177], v[236:239], v[106:109]
	v_mfma_f32_16x16x32_bf16 v[42:45], v[186:189], v[232:235], 0
	v_mfma_f32_16x16x32_bf16 v[42:45], v[190:193], v[236:239], v[42:45]
	v_mfma_f32_16x16x32_bf16 v[46:49], v[178:181], v[232:235], 0
	v_mfma_f32_16x16x32_bf16 v[46:49], v[182:185], v[236:239], v[46:49]
	v_mfma_f32_16x16x32_bf16 v[38:41], v[178:181], v[240:243], 0
	v_mfma_f32_16x16x32_bf16 v[38:41], v[182:185], v[244:247], v[38:41]
	v_mfma_f32_16x16x32_bf16 v[34:37], v[186:189], v[240:243], 0
	v_mfma_f32_16x16x32_bf16 v[34:37], v[190:193], v[244:247], v[34:37]
	v_mfma_f32_16x16x32_bf16 v[98:101], v[170:173], v[240:243], 0
	v_mfma_f32_16x16x32_bf16 v[98:101], v[174:177], v[244:247], v[98:101]
	v_mfma_f32_16x16x32_bf16 v[102:105], v[142:145], v[240:243], 0
	v_mfma_f32_16x16x32_bf16 v[102:105], v[154:157], v[244:247], v[102:105]
	s_barrier
	s_setprio 0
	s_mov_b32 s70, s62
	s_mov_b32 s71, s63
	s_mov_b32 m0, s21
	ds_read_b128 v[194:197], v140 offset:16384
	buffer_load_dwordx4 v134, s[68:71], s83 offen lds
	s_add_i32 s53, s83, 0x80000
	s_mov_b32 m0, s23
	ds_read_b128 v[198:201], v140 offset:17408
	buffer_load_dwordx4 v136, s[68:71], s83 offen lds
	s_mov_b32 m0, s24
	ds_read_b128 v[202:205], v140 offset:18432
	buffer_load_dwordx4 v134, s[68:71], s53 offen lds
	s_mov_b32 m0, s25
	ds_read_b128 v[228:231], v140 offset:19456
	buffer_load_dwordx4 v136, s[68:71], s53 offen lds
	s_mov_b32 m0, s2
	ds_read_b128 v[232:235], v140 offset:20480
	buffer_load_dwordx4 v131, s[60:63], s52 offen lds
	s_mov_b32 m0, s30
	ds_read_b128 v[236:239], v140 offset:21504
	buffer_load_dwordx4 v135, s[60:63], s52 offen lds
	ds_read_b128 v[240:243], v140 offset:22528
	ds_read_b128 v[244:247], v140 offset:23552
	s_waitcnt vmcnt(8)
	s_waitcnt lgkmcnt(0)
	s_setprio 1
	s_barrier
	v_mfma_f32_16x16x32_bf16 v[94:97], v[142:145], v[194:197], 0
	v_mfma_f32_16x16x32_bf16 v[94:97], v[154:157], v[198:201], v[94:97]
	v_mfma_f32_16x16x32_bf16 v[90:93], v[170:173], v[194:197], 0
	v_mfma_f32_16x16x32_bf16 v[90:93], v[174:177], v[198:201], v[90:93]
	v_mfma_f32_16x16x32_bf16 v[26:29], v[186:189], v[194:197], 0
	v_mfma_f32_16x16x32_bf16 v[26:29], v[190:193], v[198:201], v[26:29]
	v_mfma_f32_16x16x32_bf16 v[30:33], v[178:181], v[194:197], 0
	v_mfma_f32_16x16x32_bf16 v[30:33], v[182:185], v[198:201], v[30:33]
	v_mfma_f32_16x16x32_bf16 v[22:25], v[178:181], v[202:205], 0
	v_mfma_f32_16x16x32_bf16 v[22:25], v[182:185], v[228:231], v[22:25]
	v_mfma_f32_16x16x32_bf16 v[18:21], v[186:189], v[202:205], 0
	v_mfma_f32_16x16x32_bf16 v[18:21], v[190:193], v[228:231], v[18:21]
	v_mfma_f32_16x16x32_bf16 v[82:85], v[170:173], v[202:205], 0
	v_mfma_f32_16x16x32_bf16 v[82:85], v[174:177], v[228:231], v[82:85]
	v_mfma_f32_16x16x32_bf16 v[86:89], v[142:145], v[202:205], 0
	v_mfma_f32_16x16x32_bf16 v[86:89], v[154:157], v[228:231], v[86:89]
	v_mfma_f32_16x16x32_bf16 v[78:81], v[142:145], v[232:235], 0
	v_mfma_f32_16x16x32_bf16 v[78:81], v[154:157], v[236:239], v[78:81]
	v_mfma_f32_16x16x32_bf16 v[74:77], v[170:173], v[232:235], 0
	v_mfma_f32_16x16x32_bf16 v[74:77], v[174:177], v[236:239], v[74:77]
	v_mfma_f32_16x16x32_bf16 v[10:13], v[186:189], v[232:235], 0
	v_mfma_f32_16x16x32_bf16 v[10:13], v[190:193], v[236:239], v[10:13]
	v_mfma_f32_16x16x32_bf16 v[14:17], v[178:181], v[232:235], 0
	v_mfma_f32_16x16x32_bf16 v[14:17], v[182:185], v[236:239], v[14:17]
	v_mfma_f32_16x16x32_bf16 v[6:9], v[178:181], v[240:243], 0
	v_mfma_f32_16x16x32_bf16 v[6:9], v[182:185], v[244:247], v[6:9]
	v_mfma_f32_16x16x32_bf16 v[2:5], v[186:189], v[240:243], 0
	v_mfma_f32_16x16x32_bf16 v[2:5], v[190:193], v[244:247], v[2:5]
	v_mfma_f32_16x16x32_bf16 v[66:69], v[170:173], v[240:243], 0
	v_mfma_f32_16x16x32_bf16 v[66:69], v[174:177], v[244:247], v[66:69]
	v_mfma_f32_16x16x32_bf16 v[70:73], v[142:145], v[240:243], 0
	v_mfma_f32_16x16x32_bf16 v[70:73], v[154:157], v[244:247], v[70:73]
	s_barrier
	s_setprio 0
	v_add_u32_e32 v141, 0x18000, v139
	ds_read_b128 v[142:145], v141
	ds_read_b128 v[154:157], v141 offset:1024
	ds_read_b128 v[170:173], v141 offset:2048
	ds_read_b128 v[174:177], v141 offset:3072
	v_add_u32_e32 v141, 0x1c000, v139
	ds_read_b128 v[178:181], v141
	ds_read_b128 v[182:185], v141 offset:1024
	ds_read_b128 v[186:189], v141 offset:2048
	ds_read_b128 v[190:193], v141 offset:3072
	s_add_i32 s52, s52, 0x80000
	s_mov_b32 m0, s31
	ds_read_b128 v[194:197], v140 offset:32768
	ds_read_b128 v[198:201], v140 offset:33792
	ds_read_b128 v[202:205], v140 offset:34816
	ds_read_b128 v[228:231], v140 offset:35840
	ds_read_b128 v[232:235], v140 offset:36864
	ds_read_b128 v[236:239], v140 offset:37888
	ds_read_b128 v[240:243], v140 offset:38912
	ds_read_b128 v[244:247], v140 offset:39936
	buffer_load_dwordx4 v131, s[60:63], s52 offen lds
	s_mov_b32 m0, s33
	s_nop 0
	buffer_load_dwordx4 v135, s[60:63], s52 offen lds
	s_waitcnt vmcnt(8)
	s_waitcnt lgkmcnt(0)
	s_setprio 1
	s_barrier
	v_mfma_f32_16x16x32_bf16 v[126:129], v[142:145], v[194:197], v[126:129]
	v_mfma_f32_16x16x32_bf16 v[126:129], v[154:157], v[198:201], v[126:129]
	v_mfma_f32_16x16x32_bf16 v[122:125], v[170:173], v[194:197], v[122:125]
	v_mfma_f32_16x16x32_bf16 v[122:125], v[174:177], v[198:201], v[122:125]
	v_mfma_f32_16x16x32_bf16 v[58:61], v[186:189], v[194:197], v[58:61]
	v_mfma_f32_16x16x32_bf16 v[58:61], v[190:193], v[198:201], v[58:61]
	v_mfma_f32_16x16x32_bf16 v[62:65], v[178:181], v[194:197], v[62:65]
	v_mfma_f32_16x16x32_bf16 v[62:65], v[182:185], v[198:201], v[62:65]
	v_mfma_f32_16x16x32_bf16 v[54:57], v[178:181], v[202:205], v[54:57]
	v_mfma_f32_16x16x32_bf16 v[54:57], v[182:185], v[228:231], v[54:57]
	v_mfma_f32_16x16x32_bf16 v[50:53], v[186:189], v[202:205], v[50:53]
	v_mfma_f32_16x16x32_bf16 v[50:53], v[190:193], v[228:231], v[50:53]
	v_mfma_f32_16x16x32_bf16 v[114:117], v[170:173], v[202:205], v[114:117]
	v_mfma_f32_16x16x32_bf16 v[114:117], v[174:177], v[228:231], v[114:117]
	v_mfma_f32_16x16x32_bf16 v[118:121], v[142:145], v[202:205], v[118:121]
	v_mfma_f32_16x16x32_bf16 v[118:121], v[154:157], v[228:231], v[118:121]
	v_mfma_f32_16x16x32_bf16 v[110:113], v[142:145], v[232:235], v[110:113]
	v_mfma_f32_16x16x32_bf16 v[110:113], v[154:157], v[236:239], v[110:113]
	v_mfma_f32_16x16x32_bf16 v[106:109], v[170:173], v[232:235], v[106:109]
	v_mfma_f32_16x16x32_bf16 v[106:109], v[174:177], v[236:239], v[106:109]
	v_mfma_f32_16x16x32_bf16 v[42:45], v[186:189], v[232:235], v[42:45]
	v_mfma_f32_16x16x32_bf16 v[42:45], v[190:193], v[236:239], v[42:45]
	v_mfma_f32_16x16x32_bf16 v[46:49], v[178:181], v[232:235], v[46:49]
	v_mfma_f32_16x16x32_bf16 v[46:49], v[182:185], v[236:239], v[46:49]
	v_mfma_f32_16x16x32_bf16 v[38:41], v[178:181], v[240:243], v[38:41]
	v_mfma_f32_16x16x32_bf16 v[38:41], v[182:185], v[244:247], v[38:41]
	v_mfma_f32_16x16x32_bf16 v[34:37], v[186:189], v[240:243], v[34:37]
	v_mfma_f32_16x16x32_bf16 v[34:37], v[190:193], v[244:247], v[34:37]
	v_mfma_f32_16x16x32_bf16 v[98:101], v[170:173], v[240:243], v[98:101]
	v_mfma_f32_16x16x32_bf16 v[98:101], v[174:177], v[244:247], v[98:101]
	v_mfma_f32_16x16x32_bf16 v[102:105], v[142:145], v[240:243], v[102:105]
	v_mfma_f32_16x16x32_bf16 v[102:105], v[154:157], v[244:247], v[102:105]
	s_barrier
	s_setprio 0
	s_or_b32 s52, s83, 0x80
	s_mov_b32 m0, s34
	ds_read_b128 v[194:197], v140 offset:49152
	buffer_load_dwordx4 v134, s[68:71], s52 offen lds
	s_add_i32 s83, s83, 0x80080
	s_mov_b32 m0, s35
	ds_read_b128 v[198:201], v140 offset:50176
	buffer_load_dwordx4 v136, s[68:71], s52 offen lds
	s_mov_b32 m0, s65
	ds_read_b128 v[202:205], v140 offset:51200
	buffer_load_dwordx4 v134, s[68:71], s83 offen lds
	s_mov_b32 m0, s66
	ds_read_b128 v[228:231], v140 offset:52224
	buffer_load_dwordx4 v136, s[68:71], s83 offen lds
	s_mov_b32 m0, s36
	ds_read_b128 v[232:235], v140 offset:53248
	buffer_load_dwordx4 v131, s[60:63], s27 offen lds
	s_mov_b32 m0, s37
	ds_read_b128 v[236:239], v140 offset:54272
	buffer_load_dwordx4 v135, s[60:63], s27 offen lds
	ds_read_b128 v[240:243], v140 offset:55296
	ds_read_b128 v[244:247], v140 offset:56320
	s_waitcnt vmcnt(8)
	s_waitcnt lgkmcnt(0)
	s_setprio 1
	s_barrier
	v_mfma_f32_16x16x32_bf16 v[94:97], v[142:145], v[194:197], v[94:97]
	v_mfma_f32_16x16x32_bf16 v[94:97], v[154:157], v[198:201], v[94:97]
	v_mfma_f32_16x16x32_bf16 v[90:93], v[170:173], v[194:197], v[90:93]
	v_mfma_f32_16x16x32_bf16 v[90:93], v[174:177], v[198:201], v[90:93]
	v_mfma_f32_16x16x32_bf16 v[26:29], v[186:189], v[194:197], v[26:29]
	v_mfma_f32_16x16x32_bf16 v[26:29], v[190:193], v[198:201], v[26:29]
	v_mfma_f32_16x16x32_bf16 v[30:33], v[178:181], v[194:197], v[30:33]
	v_mfma_f32_16x16x32_bf16 v[30:33], v[182:185], v[198:201], v[30:33]
	v_mfma_f32_16x16x32_bf16 v[22:25], v[178:181], v[202:205], v[22:25]
	v_mfma_f32_16x16x32_bf16 v[22:25], v[182:185], v[228:231], v[22:25]
	v_mfma_f32_16x16x32_bf16 v[18:21], v[186:189], v[202:205], v[18:21]
	v_mfma_f32_16x16x32_bf16 v[18:21], v[190:193], v[228:231], v[18:21]
	v_mfma_f32_16x16x32_bf16 v[82:85], v[170:173], v[202:205], v[82:85]
	v_mfma_f32_16x16x32_bf16 v[82:85], v[174:177], v[228:231], v[82:85]
	v_mfma_f32_16x16x32_bf16 v[86:89], v[142:145], v[202:205], v[86:89]
	v_mfma_f32_16x16x32_bf16 v[86:89], v[154:157], v[228:231], v[86:89]
	v_mfma_f32_16x16x32_bf16 v[78:81], v[142:145], v[232:235], v[78:81]
	v_mfma_f32_16x16x32_bf16 v[78:81], v[154:157], v[236:239], v[78:81]
	v_mfma_f32_16x16x32_bf16 v[74:77], v[170:173], v[232:235], v[74:77]
	v_mfma_f32_16x16x32_bf16 v[74:77], v[174:177], v[236:239], v[74:77]
	v_mfma_f32_16x16x32_bf16 v[10:13], v[186:189], v[232:235], v[10:13]
	v_mfma_f32_16x16x32_bf16 v[10:13], v[190:193], v[236:239], v[10:13]
	v_mfma_f32_16x16x32_bf16 v[14:17], v[178:181], v[232:235], v[14:17]
	v_mfma_f32_16x16x32_bf16 v[14:17], v[182:185], v[236:239], v[14:17]
	v_mfma_f32_16x16x32_bf16 v[6:9], v[178:181], v[240:243], v[6:9]
	v_mfma_f32_16x16x32_bf16 v[6:9], v[182:185], v[244:247], v[6:9]
	v_mfma_f32_16x16x32_bf16 v[2:5], v[186:189], v[240:243], v[2:5]
	v_mfma_f32_16x16x32_bf16 v[2:5], v[190:193], v[244:247], v[2:5]
	v_mfma_f32_16x16x32_bf16 v[66:69], v[170:173], v[240:243], v[66:69]
	v_mfma_f32_16x16x32_bf16 v[66:69], v[174:177], v[244:247], v[66:69]
	v_mfma_f32_16x16x32_bf16 v[70:73], v[142:145], v[240:243], v[70:73]
	v_mfma_f32_16x16x32_bf16 v[70:73], v[154:157], v[244:247], v[70:73]
	s_barrier
	s_setprio 0
	s_add_i32 s26, s26, 2
	s_addk_i32 s19, 0x100
	s_addk_i32 s22, 0x100
	s_cmp_gt_u32 s26, 29
.LBB0_1283:
	v_add_u32_e32 v141, 0x10000, v139
	ds_read_b128 v[142:145], v141
	ds_read_b128 v[154:157], v141 offset:1024
	ds_read_b128 v[170:173], v141 offset:2048
	ds_read_b128 v[174:177], v141 offset:3072
	v_add_u32_e32 v141, 0x14000, v139
	ds_read_b128 v[178:181], v141
	ds_read_b128 v[182:185], v141 offset:1024
	ds_read_b128 v[186:189], v141 offset:2048
	ds_read_b128 v[190:193], v141 offset:3072
	s_add_i32 s27, s19, 0xfff80080
	s_cmp_eq_u32 s26, 28
	s_cselect_b32 s52, s8, s27
	s_cselect_b32 s83, s9, s22
	s_or_b32 s27, s52, 0x80
	s_mov_b32 m0, s73
	ds_read_b128 v[194:197], v140
	ds_read_b128 v[198:201], v140 offset:1024
	ds_read_b128 v[202:205], v140 offset:2048
	ds_read_b128 v[228:231], v140 offset:3072
	ds_read_b128 v[232:235], v140 offset:4096
	ds_read_b128 v[236:239], v140 offset:5120
	ds_read_b128 v[240:243], v140 offset:6144
	ds_read_b128 v[244:247], v140 offset:7168
	buffer_load_dwordx4 v131, s[60:63], s19 offen lds
	s_mov_b32 m0, s82
	s_nop 0
	buffer_load_dwordx4 v135, s[60:63], s19 offen lds
	s_waitcnt vmcnt(8)
	s_waitcnt lgkmcnt(0)
	s_setprio 1
	s_barrier
	v_mfma_f32_16x16x32_bf16 v[126:129], v[142:145], v[194:197], v[126:129]
	v_mfma_f32_16x16x32_bf16 v[126:129], v[154:157], v[198:201], v[126:129]
	v_mfma_f32_16x16x32_bf16 v[122:125], v[170:173], v[194:197], v[122:125]
	v_mfma_f32_16x16x32_bf16 v[122:125], v[174:177], v[198:201], v[122:125]
	v_mfma_f32_16x16x32_bf16 v[58:61], v[186:189], v[194:197], v[58:61]
	v_mfma_f32_16x16x32_bf16 v[58:61], v[190:193], v[198:201], v[58:61]
	v_mfma_f32_16x16x32_bf16 v[62:65], v[178:181], v[194:197], v[62:65]
	v_mfma_f32_16x16x32_bf16 v[62:65], v[182:185], v[198:201], v[62:65]
	v_mfma_f32_16x16x32_bf16 v[54:57], v[178:181], v[202:205], v[54:57]
	v_mfma_f32_16x16x32_bf16 v[54:57], v[182:185], v[228:231], v[54:57]
	v_mfma_f32_16x16x32_bf16 v[50:53], v[186:189], v[202:205], v[50:53]
	v_mfma_f32_16x16x32_bf16 v[50:53], v[190:193], v[228:231], v[50:53]
	v_mfma_f32_16x16x32_bf16 v[114:117], v[170:173], v[202:205], v[114:117]
	v_mfma_f32_16x16x32_bf16 v[114:117], v[174:177], v[228:231], v[114:117]
	v_mfma_f32_16x16x32_bf16 v[118:121], v[142:145], v[202:205], v[118:121]
	v_mfma_f32_16x16x32_bf16 v[118:121], v[154:157], v[228:231], v[118:121]
	v_mfma_f32_16x16x32_bf16 v[110:113], v[142:145], v[232:235], v[110:113]
	v_mfma_f32_16x16x32_bf16 v[110:113], v[154:157], v[236:239], v[110:113]
	v_mfma_f32_16x16x32_bf16 v[106:109], v[170:173], v[232:235], v[106:109]
	v_mfma_f32_16x16x32_bf16 v[106:109], v[174:177], v[236:239], v[106:109]
	v_mfma_f32_16x16x32_bf16 v[42:45], v[186:189], v[232:235], v[42:45]
	v_mfma_f32_16x16x32_bf16 v[42:45], v[190:193], v[236:239], v[42:45]
	v_mfma_f32_16x16x32_bf16 v[46:49], v[178:181], v[232:235], v[46:49]
	v_mfma_f32_16x16x32_bf16 v[46:49], v[182:185], v[236:239], v[46:49]
	v_mfma_f32_16x16x32_bf16 v[38:41], v[178:181], v[240:243], v[38:41]
	v_mfma_f32_16x16x32_bf16 v[38:41], v[182:185], v[244:247], v[38:41]
	v_mfma_f32_16x16x32_bf16 v[34:37], v[186:189], v[240:243], v[34:37]
	v_mfma_f32_16x16x32_bf16 v[34:37], v[190:193], v[244:247], v[34:37]
	v_mfma_f32_16x16x32_bf16 v[98:101], v[170:173], v[240:243], v[98:101]
	v_mfma_f32_16x16x32_bf16 v[98:101], v[174:177], v[244:247], v[98:101]
	v_mfma_f32_16x16x32_bf16 v[102:105], v[142:145], v[240:243], v[102:105]
	v_mfma_f32_16x16x32_bf16 v[102:105], v[154:157], v[244:247], v[102:105]
	s_barrier
	s_setprio 0
	s_mov_b32 s70, s62
	s_mov_b32 s71, s63
	s_mov_b32 m0, s21
	ds_read_b128 v[194:197], v140 offset:16384
	buffer_load_dwordx4 v134, s[68:71], s83 offen lds
	s_add_i32 s53, s83, 0x80000
	s_mov_b32 m0, s23
	ds_read_b128 v[198:201], v140 offset:17408
	buffer_load_dwordx4 v136, s[68:71], s83 offen lds
	s_mov_b32 m0, s24
	ds_read_b128 v[202:205], v140 offset:18432
	buffer_load_dwordx4 v134, s[68:71], s53 offen lds
	s_mov_b32 m0, s25
	ds_read_b128 v[228:231], v140 offset:19456
	buffer_load_dwordx4 v136, s[68:71], s53 offen lds
	s_mov_b32 m0, s2
	ds_read_b128 v[232:235], v140 offset:20480
	buffer_load_dwordx4 v131, s[60:63], s52 offen lds
	s_mov_b32 m0, s30
	ds_read_b128 v[236:239], v140 offset:21504
	buffer_load_dwordx4 v135, s[60:63], s52 offen lds
	ds_read_b128 v[240:243], v140 offset:22528
	ds_read_b128 v[244:247], v140 offset:23552
	s_waitcnt vmcnt(8)
	s_waitcnt lgkmcnt(0)
	s_setprio 1
	s_barrier
	v_mfma_f32_16x16x32_bf16 v[94:97], v[142:145], v[194:197], v[94:97]
	v_mfma_f32_16x16x32_bf16 v[94:97], v[154:157], v[198:201], v[94:97]
	v_mfma_f32_16x16x32_bf16 v[90:93], v[170:173], v[194:197], v[90:93]
	v_mfma_f32_16x16x32_bf16 v[90:93], v[174:177], v[198:201], v[90:93]
	v_mfma_f32_16x16x32_bf16 v[26:29], v[186:189], v[194:197], v[26:29]
	v_mfma_f32_16x16x32_bf16 v[26:29], v[190:193], v[198:201], v[26:29]
	v_mfma_f32_16x16x32_bf16 v[30:33], v[178:181], v[194:197], v[30:33]
	v_mfma_f32_16x16x32_bf16 v[30:33], v[182:185], v[198:201], v[30:33]
	v_mfma_f32_16x16x32_bf16 v[22:25], v[178:181], v[202:205], v[22:25]
	v_mfma_f32_16x16x32_bf16 v[22:25], v[182:185], v[228:231], v[22:25]
	v_mfma_f32_16x16x32_bf16 v[18:21], v[186:189], v[202:205], v[18:21]
	v_mfma_f32_16x16x32_bf16 v[18:21], v[190:193], v[228:231], v[18:21]
	v_mfma_f32_16x16x32_bf16 v[82:85], v[170:173], v[202:205], v[82:85]
	v_mfma_f32_16x16x32_bf16 v[82:85], v[174:177], v[228:231], v[82:85]
	v_mfma_f32_16x16x32_bf16 v[86:89], v[142:145], v[202:205], v[86:89]
	v_mfma_f32_16x16x32_bf16 v[86:89], v[154:157], v[228:231], v[86:89]
	v_mfma_f32_16x16x32_bf16 v[78:81], v[142:145], v[232:235], v[78:81]
	v_mfma_f32_16x16x32_bf16 v[78:81], v[154:157], v[236:239], v[78:81]
	v_mfma_f32_16x16x32_bf16 v[74:77], v[170:173], v[232:235], v[74:77]
	v_mfma_f32_16x16x32_bf16 v[74:77], v[174:177], v[236:239], v[74:77]
	v_mfma_f32_16x16x32_bf16 v[10:13], v[186:189], v[232:235], v[10:13]
	v_mfma_f32_16x16x32_bf16 v[10:13], v[190:193], v[236:239], v[10:13]
	v_mfma_f32_16x16x32_bf16 v[14:17], v[178:181], v[232:235], v[14:17]
	v_mfma_f32_16x16x32_bf16 v[14:17], v[182:185], v[236:239], v[14:17]
	v_mfma_f32_16x16x32_bf16 v[6:9], v[178:181], v[240:243], v[6:9]
	v_mfma_f32_16x16x32_bf16 v[6:9], v[182:185], v[244:247], v[6:9]
	v_mfma_f32_16x16x32_bf16 v[2:5], v[186:189], v[240:243], v[2:5]
	v_mfma_f32_16x16x32_bf16 v[2:5], v[190:193], v[244:247], v[2:5]
	v_mfma_f32_16x16x32_bf16 v[66:69], v[170:173], v[240:243], v[66:69]
	v_mfma_f32_16x16x32_bf16 v[66:69], v[174:177], v[244:247], v[66:69]
	v_mfma_f32_16x16x32_bf16 v[70:73], v[142:145], v[240:243], v[70:73]
	v_mfma_f32_16x16x32_bf16 v[70:73], v[154:157], v[244:247], v[70:73]
	s_barrier
	s_setprio 0
	v_add_u32_e32 v141, 0x18000, v139
	ds_read_b128 v[142:145], v141
	ds_read_b128 v[154:157], v141 offset:1024
	ds_read_b128 v[170:173], v141 offset:2048
	ds_read_b128 v[174:177], v141 offset:3072
	v_add_u32_e32 v141, 0x1c000, v139
	ds_read_b128 v[178:181], v141
	ds_read_b128 v[182:185], v141 offset:1024
	ds_read_b128 v[186:189], v141 offset:2048
	ds_read_b128 v[190:193], v141 offset:3072
	s_add_i32 s52, s52, 0x80000
	s_mov_b32 m0, s31
	ds_read_b128 v[194:197], v140 offset:32768
	ds_read_b128 v[198:201], v140 offset:33792
	ds_read_b128 v[202:205], v140 offset:34816
	ds_read_b128 v[228:231], v140 offset:35840
	ds_read_b128 v[232:235], v140 offset:36864
	ds_read_b128 v[236:239], v140 offset:37888
	ds_read_b128 v[240:243], v140 offset:38912
	ds_read_b128 v[244:247], v140 offset:39936
	buffer_load_dwordx4 v131, s[60:63], s52 offen lds
	s_mov_b32 m0, s33
	s_nop 0
	buffer_load_dwordx4 v135, s[60:63], s52 offen lds
	s_waitcnt vmcnt(8)
	s_waitcnt lgkmcnt(0)
	s_setprio 1
	s_barrier
	v_mfma_f32_16x16x32_bf16 v[126:129], v[142:145], v[194:197], v[126:129]
	v_mfma_f32_16x16x32_bf16 v[126:129], v[154:157], v[198:201], v[126:129]
	v_mfma_f32_16x16x32_bf16 v[122:125], v[170:173], v[194:197], v[122:125]
	v_mfma_f32_16x16x32_bf16 v[122:125], v[174:177], v[198:201], v[122:125]
	v_mfma_f32_16x16x32_bf16 v[58:61], v[186:189], v[194:197], v[58:61]
	v_mfma_f32_16x16x32_bf16 v[58:61], v[190:193], v[198:201], v[58:61]
	v_mfma_f32_16x16x32_bf16 v[62:65], v[178:181], v[194:197], v[62:65]
	v_mfma_f32_16x16x32_bf16 v[62:65], v[182:185], v[198:201], v[62:65]
	v_mfma_f32_16x16x32_bf16 v[54:57], v[178:181], v[202:205], v[54:57]
	v_mfma_f32_16x16x32_bf16 v[54:57], v[182:185], v[228:231], v[54:57]
	v_mfma_f32_16x16x32_bf16 v[50:53], v[186:189], v[202:205], v[50:53]
	v_mfma_f32_16x16x32_bf16 v[50:53], v[190:193], v[228:231], v[50:53]
	v_mfma_f32_16x16x32_bf16 v[114:117], v[170:173], v[202:205], v[114:117]
	v_mfma_f32_16x16x32_bf16 v[114:117], v[174:177], v[228:231], v[114:117]
	v_mfma_f32_16x16x32_bf16 v[118:121], v[142:145], v[202:205], v[118:121]
	v_mfma_f32_16x16x32_bf16 v[118:121], v[154:157], v[228:231], v[118:121]
	v_mfma_f32_16x16x32_bf16 v[110:113], v[142:145], v[232:235], v[110:113]
	v_mfma_f32_16x16x32_bf16 v[110:113], v[154:157], v[236:239], v[110:113]
	v_mfma_f32_16x16x32_bf16 v[106:109], v[170:173], v[232:235], v[106:109]
	v_mfma_f32_16x16x32_bf16 v[106:109], v[174:177], v[236:239], v[106:109]
	v_mfma_f32_16x16x32_bf16 v[42:45], v[186:189], v[232:235], v[42:45]
	v_mfma_f32_16x16x32_bf16 v[42:45], v[190:193], v[236:239], v[42:45]
	v_mfma_f32_16x16x32_bf16 v[46:49], v[178:181], v[232:235], v[46:49]
	v_mfma_f32_16x16x32_bf16 v[46:49], v[182:185], v[236:239], v[46:49]
	v_mfma_f32_16x16x32_bf16 v[38:41], v[178:181], v[240:243], v[38:41]
	v_mfma_f32_16x16x32_bf16 v[38:41], v[182:185], v[244:247], v[38:41]
	v_mfma_f32_16x16x32_bf16 v[34:37], v[186:189], v[240:243], v[34:37]
	v_mfma_f32_16x16x32_bf16 v[34:37], v[190:193], v[244:247], v[34:37]
	v_mfma_f32_16x16x32_bf16 v[98:101], v[170:173], v[240:243], v[98:101]
	v_mfma_f32_16x16x32_bf16 v[98:101], v[174:177], v[244:247], v[98:101]
	v_mfma_f32_16x16x32_bf16 v[102:105], v[142:145], v[240:243], v[102:105]
	v_mfma_f32_16x16x32_bf16 v[102:105], v[154:157], v[244:247], v[102:105]
	s_barrier
	s_setprio 0
	s_or_b32 s52, s83, 0x80
	s_mov_b32 m0, s34
	ds_read_b128 v[194:197], v140 offset:49152
	buffer_load_dwordx4 v134, s[68:71], s52 offen lds
	s_add_i32 s83, s83, 0x80080
	s_mov_b32 m0, s35
	ds_read_b128 v[198:201], v140 offset:50176
	buffer_load_dwordx4 v136, s[68:71], s52 offen lds
	s_mov_b32 m0, s65
	ds_read_b128 v[202:205], v140 offset:51200
	buffer_load_dwordx4 v134, s[68:71], s83 offen lds
	s_mov_b32 m0, s66
	ds_read_b128 v[228:231], v140 offset:52224
	buffer_load_dwordx4 v136, s[68:71], s83 offen lds
	s_mov_b32 m0, s36
	ds_read_b128 v[232:235], v140 offset:53248
	buffer_load_dwordx4 v131, s[60:63], s27 offen lds
	s_mov_b32 m0, s37
	ds_read_b128 v[236:239], v140 offset:54272
	buffer_load_dwordx4 v135, s[60:63], s27 offen lds
	ds_read_b128 v[240:243], v140 offset:55296
	ds_read_b128 v[244:247], v140 offset:56320
	s_waitcnt vmcnt(8)
	s_waitcnt lgkmcnt(0)
	s_setprio 1
	s_barrier
	v_mfma_f32_16x16x32_bf16 v[94:97], v[142:145], v[194:197], v[94:97]
	v_mfma_f32_16x16x32_bf16 v[94:97], v[154:157], v[198:201], v[94:97]
	v_mfma_f32_16x16x32_bf16 v[90:93], v[170:173], v[194:197], v[90:93]
	v_mfma_f32_16x16x32_bf16 v[90:93], v[174:177], v[198:201], v[90:93]
	v_mfma_f32_16x16x32_bf16 v[26:29], v[186:189], v[194:197], v[26:29]
	v_mfma_f32_16x16x32_bf16 v[26:29], v[190:193], v[198:201], v[26:29]
	v_mfma_f32_16x16x32_bf16 v[30:33], v[178:181], v[194:197], v[30:33]
	v_mfma_f32_16x16x32_bf16 v[30:33], v[182:185], v[198:201], v[30:33]
	v_mfma_f32_16x16x32_bf16 v[22:25], v[178:181], v[202:205], v[22:25]
	v_mfma_f32_16x16x32_bf16 v[22:25], v[182:185], v[228:231], v[22:25]
	v_mfma_f32_16x16x32_bf16 v[18:21], v[186:189], v[202:205], v[18:21]
	v_mfma_f32_16x16x32_bf16 v[18:21], v[190:193], v[228:231], v[18:21]
	v_mfma_f32_16x16x32_bf16 v[82:85], v[170:173], v[202:205], v[82:85]
	v_mfma_f32_16x16x32_bf16 v[82:85], v[174:177], v[228:231], v[82:85]
	v_mfma_f32_16x16x32_bf16 v[86:89], v[142:145], v[202:205], v[86:89]
	v_mfma_f32_16x16x32_bf16 v[86:89], v[154:157], v[228:231], v[86:89]
	v_mfma_f32_16x16x32_bf16 v[78:81], v[142:145], v[232:235], v[78:81]
	v_mfma_f32_16x16x32_bf16 v[78:81], v[154:157], v[236:239], v[78:81]
	v_mfma_f32_16x16x32_bf16 v[74:77], v[170:173], v[232:235], v[74:77]
	v_mfma_f32_16x16x32_bf16 v[74:77], v[174:177], v[236:239], v[74:77]
	v_mfma_f32_16x16x32_bf16 v[10:13], v[186:189], v[232:235], v[10:13]
	v_mfma_f32_16x16x32_bf16 v[10:13], v[190:193], v[236:239], v[10:13]
	v_mfma_f32_16x16x32_bf16 v[14:17], v[178:181], v[232:235], v[14:17]
	v_mfma_f32_16x16x32_bf16 v[14:17], v[182:185], v[236:239], v[14:17]
	v_mfma_f32_16x16x32_bf16 v[6:9], v[178:181], v[240:243], v[6:9]
	v_mfma_f32_16x16x32_bf16 v[6:9], v[182:185], v[244:247], v[6:9]
	v_mfma_f32_16x16x32_bf16 v[2:5], v[186:189], v[240:243], v[2:5]
	v_mfma_f32_16x16x32_bf16 v[2:5], v[190:193], v[244:247], v[2:5]
	v_mfma_f32_16x16x32_bf16 v[66:69], v[170:173], v[240:243], v[66:69]
	v_mfma_f32_16x16x32_bf16 v[66:69], v[174:177], v[244:247], v[66:69]
	v_mfma_f32_16x16x32_bf16 v[70:73], v[142:145], v[240:243], v[70:73]
	v_mfma_f32_16x16x32_bf16 v[70:73], v[154:157], v[244:247], v[70:73]
	s_barrier
	s_setprio 0
	s_add_i32 s26, s26, 2
	s_addk_i32 s19, 0x100
	s_addk_i32 s22, 0x100
	s_cmp_gt_u32 s26, 29
	s_cbranch_scc0 .LBB0_1283
	s_and_b64 vcc, exec, s[44:45]
	s_cbranch_vccz .LBB0_1286
	s_barrier

.LBB0_1588:
	s_lshl_b32 s85, s84, 20
	s_and_b64 s[8:9], s[42:43], exec
	s_cselect_b32 s8, s85, s13
	s_lshl_b32 s48, s73, 20
	s_and_b64 s[22:23], s[42:43], exec
	s_cselect_b32 s9, s48, s21
	s_add_i32 s13, s13, 0x80080
	s_addk_i32 s21, 0x100
	s_mov_b32 s22, -2
	s_waitcnt lgkmcnt(0)
	v_add_u32_e32 v170, 0x10000, v140
	v_add_u32_e32 v186, 0x14000, v140
	ds_read_b128 v[132:135], v170
	ds_read_b128 v[142:145], v170 offset:1024
	ds_read_b128 v[154:157], v170 offset:2048
	ds_read_b128 v[170:173], v170 offset:3072
	ds_read_b128 v[174:177], v186
	ds_read_b128 v[178:181], v186 offset:1024
	ds_read_b128 v[182:185], v186 offset:2048
	ds_read_b128 v[186:189], v186 offset:3072
	s_add_i32 s23, s13, 0xfff80080
	s_cmp_eq_u32 s22, 28
	s_cselect_b32 s27, s8, s23
	s_cselect_b32 s26, s9, s21
	s_or_b32 s23, s27, 0x80
	s_mov_b32 m0, s70
	ds_read_b128 v[190:193], v141
	ds_read_b128 v[194:197], v141 offset:1024
	ds_read_b128 v[198:201], v141 offset:2048
	ds_read_b128 v[202:205], v141 offset:3072
	ds_read_b128 v[228:231], v141 offset:4096
	ds_read_b128 v[232:235], v141 offset:5120
	ds_read_b128 v[236:239], v141 offset:6144
	ds_read_b128 v[240:243], v141 offset:7168
	buffer_load_dwordx4 v136, s[60:63], s13 offen lds
	s_mov_b32 m0, s72
	s_nop 0
	buffer_load_dwordx4 v138, s[60:63], s13 offen lds
	s_waitcnt vmcnt(8)
	s_waitcnt lgkmcnt(0)
	s_setprio 1
	s_barrier
	v_mfma_f32_16x16x32_bf16 v[126:129], v[132:135], v[190:193], 0
	v_mfma_f32_16x16x32_bf16 v[126:129], v[142:145], v[194:197], v[126:129]
	v_mfma_f32_16x16x32_bf16 v[106:109], v[154:157], v[190:193], 0
	v_mfma_f32_16x16x32_bf16 v[106:109], v[170:173], v[194:197], v[106:109]
	v_mfma_f32_16x16x32_bf16 v[110:113], v[182:185], v[190:193], 0
	v_mfma_f32_16x16x32_bf16 v[110:113], v[186:189], v[194:197], v[110:113]
	v_mfma_f32_16x16x32_bf16 v[122:125], v[174:177], v[190:193], 0
	v_mfma_f32_16x16x32_bf16 v[122:125], v[178:181], v[194:197], v[122:125]
	v_mfma_f32_16x16x32_bf16 v[102:105], v[174:177], v[198:201], 0
	v_mfma_f32_16x16x32_bf16 v[102:105], v[178:181], v[202:205], v[102:105]
	v_mfma_f32_16x16x32_bf16 v[98:101], v[182:185], v[198:201], 0
	v_mfma_f32_16x16x32_bf16 v[98:101], v[186:189], v[202:205], v[98:101]
	v_mfma_f32_16x16x32_bf16 v[114:117], v[154:157], v[198:201], 0
	v_mfma_f32_16x16x32_bf16 v[114:117], v[170:173], v[202:205], v[114:117]
	v_mfma_f32_16x16x32_bf16 v[118:121], v[132:135], v[198:201], 0
	v_mfma_f32_16x16x32_bf16 v[118:121], v[142:145], v[202:205], v[118:121]
	v_mfma_f32_16x16x32_bf16 v[94:97], v[132:135], v[228:231], 0
	v_mfma_f32_16x16x32_bf16 v[94:97], v[142:145], v[232:235], v[94:97]
	v_mfma_f32_16x16x32_bf16 v[90:93], v[154:157], v[228:231], 0
	v_mfma_f32_16x16x32_bf16 v[90:93], v[170:173], v[232:235], v[90:93]
	v_mfma_f32_16x16x32_bf16 v[82:85], v[182:185], v[228:231], 0
	v_mfma_f32_16x16x32_bf16 v[82:85], v[186:189], v[232:235], v[82:85]
	v_mfma_f32_16x16x32_bf16 v[86:89], v[174:177], v[228:231], 0
	v_mfma_f32_16x16x32_bf16 v[86:89], v[178:181], v[232:235], v[86:89]
	v_mfma_f32_16x16x32_bf16 v[70:73], v[174:177], v[236:239], 0
	v_mfma_f32_16x16x32_bf16 v[70:73], v[178:181], v[240:243], v[70:73]
	v_mfma_f32_16x16x32_bf16 v[66:69], v[182:185], v[236:239], 0
	v_mfma_f32_16x16x32_bf16 v[66:69], v[186:189], v[240:243], v[66:69]
	v_mfma_f32_16x16x32_bf16 v[74:77], v[154:157], v[236:239], 0
	v_mfma_f32_16x16x32_bf16 v[74:77], v[170:173], v[240:243], v[74:77]
	v_mfma_f32_16x16x32_bf16 v[78:81], v[132:135], v[236:239], 0
	v_mfma_f32_16x16x32_bf16 v[78:81], v[142:145], v[240:243], v[78:81]
	s_barrier
	s_setprio 0
	s_mov_b32 s46, s62
	s_mov_b32 s47, s63
	s_mov_b32 m0, s15
	ds_read_b128 v[190:193], v141 offset:16384
	buffer_load_dwordx4 v137, s[44:47], s26 offen lds
	s_add_i32 s49, s26, 0x80000
	s_mov_b32 m0, s16
	ds_read_b128 v[194:197], v141 offset:17408
	buffer_load_dwordx4 v139, s[44:47], s26 offen lds
	s_mov_b32 m0, s18
	ds_read_b128 v[198:201], v141 offset:18432
	buffer_load_dwordx4 v137, s[44:47], s49 offen lds
	s_mov_b32 m0, s19
	ds_read_b128 v[202:205], v141 offset:19456
	buffer_load_dwordx4 v139, s[44:47], s49 offen lds
	s_mov_b32 m0, s14
	ds_read_b128 v[228:231], v141 offset:20480
	buffer_load_dwordx4 v136, s[60:63], s27 offen lds
	s_mov_b32 m0, s24
	ds_read_b128 v[232:235], v141 offset:21504
	buffer_load_dwordx4 v138, s[60:63], s27 offen lds
	ds_read_b128 v[236:239], v141 offset:22528
	ds_read_b128 v[240:243], v141 offset:23552
	s_waitcnt vmcnt(8)
	s_waitcnt lgkmcnt(0)
	s_setprio 1
	s_barrier
	v_mfma_f32_16x16x32_bf16 v[62:65], v[132:135], v[190:193], 0
	v_mfma_f32_16x16x32_bf16 v[62:65], v[142:145], v[194:197], v[62:65]
	v_mfma_f32_16x16x32_bf16 v[58:61], v[154:157], v[190:193], 0
	v_mfma_f32_16x16x32_bf16 v[58:61], v[170:173], v[194:197], v[58:61]
	v_mfma_f32_16x16x32_bf16 v[50:53], v[182:185], v[190:193], 0
	v_mfma_f32_16x16x32_bf16 v[50:53], v[186:189], v[194:197], v[50:53]
	v_mfma_f32_16x16x32_bf16 v[54:57], v[174:177], v[190:193], 0
	v_mfma_f32_16x16x32_bf16 v[54:57], v[178:181], v[194:197], v[54:57]
	v_mfma_f32_16x16x32_bf16 v[38:41], v[174:177], v[198:201], 0
	v_mfma_f32_16x16x32_bf16 v[38:41], v[178:181], v[202:205], v[38:41]
	v_mfma_f32_16x16x32_bf16 v[34:37], v[182:185], v[198:201], 0
	v_mfma_f32_16x16x32_bf16 v[34:37], v[186:189], v[202:205], v[34:37]
	v_mfma_f32_16x16x32_bf16 v[42:45], v[154:157], v[198:201], 0
	v_mfma_f32_16x16x32_bf16 v[42:45], v[170:173], v[202:205], v[42:45]
	v_mfma_f32_16x16x32_bf16 v[46:49], v[132:135], v[198:201], 0
	v_mfma_f32_16x16x32_bf16 v[46:49], v[142:145], v[202:205], v[46:49]
	v_mfma_f32_16x16x32_bf16 v[30:33], v[132:135], v[228:231], 0
	v_mfma_f32_16x16x32_bf16 v[30:33], v[142:145], v[232:235], v[30:33]
	v_mfma_f32_16x16x32_bf16 v[26:29], v[154:157], v[228:231], 0
	v_mfma_f32_16x16x32_bf16 v[26:29], v[170:173], v[232:235], v[26:29]
	v_mfma_f32_16x16x32_bf16 v[18:21], v[182:185], v[228:231], 0
	v_mfma_f32_16x16x32_bf16 v[18:21], v[186:189], v[232:235], v[18:21]
	v_mfma_f32_16x16x32_bf16 v[22:25], v[174:177], v[228:231], 0
	v_mfma_f32_16x16x32_bf16 v[22:25], v[178:181], v[232:235], v[22:25]
	v_mfma_f32_16x16x32_bf16 v[6:9], v[174:177], v[236:239], 0
	v_mfma_f32_16x16x32_bf16 v[6:9], v[178:181], v[240:243], v[6:9]
	v_mfma_f32_16x16x32_bf16 v[2:5], v[182:185], v[236:239], 0
	v_mfma_f32_16x16x32_bf16 v[2:5], v[186:189], v[240:243], v[2:5]
	v_mfma_f32_16x16x32_bf16 v[10:13], v[154:157], v[236:239], 0
	v_mfma_f32_16x16x32_bf16 v[10:13], v[170:173], v[240:243], v[10:13]
	v_mfma_f32_16x16x32_bf16 v[14:17], v[132:135], v[236:239], 0
	v_mfma_f32_16x16x32_bf16 v[14:17], v[142:145], v[240:243], v[14:17]
	s_barrier
	s_setprio 0
	v_add_u32_e32 v170, 0x18000, v140
	v_add_u32_e32 v186, 0x1c000, v140
	ds_read_b128 v[132:135], v170
	ds_read_b128 v[142:145], v170 offset:1024
	ds_read_b128 v[154:157], v170 offset:2048
	ds_read_b128 v[170:173], v170 offset:3072
	ds_read_b128 v[174:177], v186
	ds_read_b128 v[178:181], v186 offset:1024
	ds_read_b128 v[182:185], v186 offset:2048
	ds_read_b128 v[186:189], v186 offset:3072
	s_add_i32 s27, s27, 0x80000
	s_mov_b32 m0, s25
	ds_read_b128 v[190:193], v141 offset:32768
	ds_read_b128 v[194:197], v141 offset:33792
	ds_read_b128 v[198:201], v141 offset:34816
	ds_read_b128 v[202:205], v141 offset:35840
	ds_read_b128 v[228:231], v141 offset:36864
	ds_read_b128 v[232:235], v141 offset:37888
	ds_read_b128 v[236:239], v141 offset:38912
	ds_read_b128 v[240:243], v141 offset:39936
	buffer_load_dwordx4 v136, s[60:63], s27 offen lds
	s_mov_b32 m0, s30
	s_nop 0
	buffer_load_dwordx4 v138, s[60:63], s27 offen lds
	s_waitcnt vmcnt(8)
	s_waitcnt lgkmcnt(0)
	s_setprio 1
	s_barrier
	v_mfma_f32_16x16x32_bf16 v[126:129], v[132:135], v[190:193], v[126:129]
	v_mfma_f32_16x16x32_bf16 v[126:129], v[142:145], v[194:197], v[126:129]
	v_mfma_f32_16x16x32_bf16 v[106:109], v[154:157], v[190:193], v[106:109]
	v_mfma_f32_16x16x32_bf16 v[106:109], v[170:173], v[194:197], v[106:109]
	v_mfma_f32_16x16x32_bf16 v[110:113], v[182:185], v[190:193], v[110:113]
	v_mfma_f32_16x16x32_bf16 v[110:113], v[186:189], v[194:197], v[110:113]
	v_mfma_f32_16x16x32_bf16 v[122:125], v[174:177], v[190:193], v[122:125]
	v_mfma_f32_16x16x32_bf16 v[122:125], v[178:181], v[194:197], v[122:125]
	v_mfma_f32_16x16x32_bf16 v[102:105], v[174:177], v[198:201], v[102:105]
	v_mfma_f32_16x16x32_bf16 v[102:105], v[178:181], v[202:205], v[102:105]
	v_mfma_f32_16x16x32_bf16 v[98:101], v[182:185], v[198:201], v[98:101]
	v_mfma_f32_16x16x32_bf16 v[98:101], v[186:189], v[202:205], v[98:101]
	v_mfma_f32_16x16x32_bf16 v[114:117], v[154:157], v[198:201], v[114:117]
	v_mfma_f32_16x16x32_bf16 v[114:117], v[170:173], v[202:205], v[114:117]
	v_mfma_f32_16x16x32_bf16 v[118:121], v[132:135], v[198:201], v[118:121]
	v_mfma_f32_16x16x32_bf16 v[118:121], v[142:145], v[202:205], v[118:121]
	v_mfma_f32_16x16x32_bf16 v[94:97], v[132:135], v[228:231], v[94:97]
	v_mfma_f32_16x16x32_bf16 v[94:97], v[142:145], v[232:235], v[94:97]
	v_mfma_f32_16x16x32_bf16 v[90:93], v[154:157], v[228:231], v[90:93]
	v_mfma_f32_16x16x32_bf16 v[90:93], v[170:173], v[232:235], v[90:93]
	v_mfma_f32_16x16x32_bf16 v[82:85], v[182:185], v[228:231], v[82:85]
	v_mfma_f32_16x16x32_bf16 v[82:85], v[186:189], v[232:235], v[82:85]
	v_mfma_f32_16x16x32_bf16 v[86:89], v[174:177], v[228:231], v[86:89]
	v_mfma_f32_16x16x32_bf16 v[86:89], v[178:181], v[232:235], v[86:89]
	v_mfma_f32_16x16x32_bf16 v[70:73], v[174:177], v[236:239], v[70:73]
	v_mfma_f32_16x16x32_bf16 v[70:73], v[178:181], v[240:243], v[70:73]
	v_mfma_f32_16x16x32_bf16 v[66:69], v[182:185], v[236:239], v[66:69]
	v_mfma_f32_16x16x32_bf16 v[66:69], v[186:189], v[240:243], v[66:69]
	v_mfma_f32_16x16x32_bf16 v[74:77], v[154:157], v[236:239], v[74:77]
	v_mfma_f32_16x16x32_bf16 v[74:77], v[170:173], v[240:243], v[74:77]
	v_mfma_f32_16x16x32_bf16 v[78:81], v[132:135], v[236:239], v[78:81]
	v_mfma_f32_16x16x32_bf16 v[78:81], v[142:145], v[240:243], v[78:81]
	s_barrier
	s_setprio 0
	s_or_b32 s27, s26, 0x80
	s_mov_b32 m0, s36
	ds_read_b128 v[190:193], v141 offset:49152
	buffer_load_dwordx4 v137, s[44:47], s27 offen lds
	s_add_i32 s26, s26, 0x80080
	s_mov_b32 m0, s37
	ds_read_b128 v[194:197], v141 offset:50176
	buffer_load_dwordx4 v139, s[44:47], s27 offen lds
	s_mov_b32 m0, s68
	ds_read_b128 v[198:201], v141 offset:51200
	buffer_load_dwordx4 v137, s[44:47], s26 offen lds
	s_mov_b32 m0, s69
	ds_read_b128 v[202:205], v141 offset:52224
	buffer_load_dwordx4 v139, s[44:47], s26 offen lds
	s_mov_b32 m0, s66
	ds_read_b128 v[228:231], v141 offset:53248
	buffer_load_dwordx4 v136, s[60:63], s23 offen lds
	s_mov_b32 m0, s67
	ds_read_b128 v[232:235], v141 offset:54272
	buffer_load_dwordx4 v138, s[60:63], s23 offen lds
	ds_read_b128 v[236:239], v141 offset:55296
	ds_read_b128 v[240:243], v141 offset:56320
	s_waitcnt vmcnt(8)
	s_waitcnt lgkmcnt(0)
	s_setprio 1
	s_barrier
	v_mfma_f32_16x16x32_bf16 v[62:65], v[132:135], v[190:193], v[62:65]
	v_mfma_f32_16x16x32_bf16 v[62:65], v[142:145], v[194:197], v[62:65]
	v_mfma_f32_16x16x32_bf16 v[58:61], v[154:157], v[190:193], v[58:61]
	v_mfma_f32_16x16x32_bf16 v[58:61], v[170:173], v[194:197], v[58:61]
	v_mfma_f32_16x16x32_bf16 v[50:53], v[182:185], v[190:193], v[50:53]
	v_mfma_f32_16x16x32_bf16 v[50:53], v[186:189], v[194:197], v[50:53]
	v_mfma_f32_16x16x32_bf16 v[54:57], v[174:177], v[190:193], v[54:57]
	v_mfma_f32_16x16x32_bf16 v[54:57], v[178:181], v[194:197], v[54:57]
	v_mfma_f32_16x16x32_bf16 v[38:41], v[174:177], v[198:201], v[38:41]
	v_mfma_f32_16x16x32_bf16 v[38:41], v[178:181], v[202:205], v[38:41]
	v_mfma_f32_16x16x32_bf16 v[34:37], v[182:185], v[198:201], v[34:37]
	v_mfma_f32_16x16x32_bf16 v[34:37], v[186:189], v[202:205], v[34:37]
	v_mfma_f32_16x16x32_bf16 v[42:45], v[154:157], v[198:201], v[42:45]
	v_mfma_f32_16x16x32_bf16 v[42:45], v[170:173], v[202:205], v[42:45]
	v_mfma_f32_16x16x32_bf16 v[46:49], v[132:135], v[198:201], v[46:49]
	v_mfma_f32_16x16x32_bf16 v[46:49], v[142:145], v[202:205], v[46:49]
	v_mfma_f32_16x16x32_bf16 v[30:33], v[132:135], v[228:231], v[30:33]
	v_mfma_f32_16x16x32_bf16 v[30:33], v[142:145], v[232:235], v[30:33]
	v_mfma_f32_16x16x32_bf16 v[26:29], v[154:157], v[228:231], v[26:29]
	v_mfma_f32_16x16x32_bf16 v[26:29], v[170:173], v[232:235], v[26:29]
	v_mfma_f32_16x16x32_bf16 v[18:21], v[182:185], v[228:231], v[18:21]
	v_mfma_f32_16x16x32_bf16 v[18:21], v[186:189], v[232:235], v[18:21]
	v_mfma_f32_16x16x32_bf16 v[22:25], v[174:177], v[228:231], v[22:25]
	v_mfma_f32_16x16x32_bf16 v[22:25], v[178:181], v[232:235], v[22:25]
	v_mfma_f32_16x16x32_bf16 v[6:9], v[174:177], v[236:239], v[6:9]
	v_mfma_f32_16x16x32_bf16 v[6:9], v[178:181], v[240:243], v[6:9]
	v_mfma_f32_16x16x32_bf16 v[2:5], v[182:185], v[236:239], v[2:5]
	v_mfma_f32_16x16x32_bf16 v[2:5], v[186:189], v[240:243], v[2:5]
	v_mfma_f32_16x16x32_bf16 v[10:13], v[154:157], v[236:239], v[10:13]
	v_mfma_f32_16x16x32_bf16 v[10:13], v[170:173], v[240:243], v[10:13]
	v_mfma_f32_16x16x32_bf16 v[14:17], v[132:135], v[236:239], v[14:17]
	v_mfma_f32_16x16x32_bf16 v[14:17], v[142:145], v[240:243], v[14:17]
	s_barrier
	s_setprio 0
	s_add_i32 s22, s22, 2
	s_addk_i32 s13, 0x100
	s_addk_i32 s21, 0x100
	s_cmp_gt_u32 s22, 29
.LBB0_1589:
	v_add_u32_e32 v170, 0x10000, v140
	v_add_u32_e32 v186, 0x14000, v140
	ds_read_b128 v[132:135], v170
	ds_read_b128 v[142:145], v170 offset:1024
	ds_read_b128 v[154:157], v170 offset:2048
	ds_read_b128 v[170:173], v170 offset:3072
	ds_read_b128 v[174:177], v186
	ds_read_b128 v[178:181], v186 offset:1024
	ds_read_b128 v[182:185], v186 offset:2048
	ds_read_b128 v[186:189], v186 offset:3072
	s_add_i32 s23, s13, 0xfff80080
	s_cmp_eq_u32 s22, 28
	s_cselect_b32 s27, s8, s23
	s_cselect_b32 s26, s9, s21
	s_or_b32 s23, s27, 0x80
	s_mov_b32 m0, s70
	ds_read_b128 v[190:193], v141
	ds_read_b128 v[194:197], v141 offset:1024
	ds_read_b128 v[198:201], v141 offset:2048
	ds_read_b128 v[202:205], v141 offset:3072
	ds_read_b128 v[228:231], v141 offset:4096
	ds_read_b128 v[232:235], v141 offset:5120
	ds_read_b128 v[236:239], v141 offset:6144
	ds_read_b128 v[240:243], v141 offset:7168
	buffer_load_dwordx4 v136, s[60:63], s13 offen lds
	s_mov_b32 m0, s72
	s_nop 0
	buffer_load_dwordx4 v138, s[60:63], s13 offen lds
	s_waitcnt vmcnt(8)
	s_waitcnt lgkmcnt(0)
	s_setprio 1
	s_barrier
	v_mfma_f32_16x16x32_bf16 v[126:129], v[132:135], v[190:193], v[126:129]
	v_mfma_f32_16x16x32_bf16 v[126:129], v[142:145], v[194:197], v[126:129]
	v_mfma_f32_16x16x32_bf16 v[106:109], v[154:157], v[190:193], v[106:109]
	v_mfma_f32_16x16x32_bf16 v[106:109], v[170:173], v[194:197], v[106:109]
	v_mfma_f32_16x16x32_bf16 v[110:113], v[182:185], v[190:193], v[110:113]
	v_mfma_f32_16x16x32_bf16 v[110:113], v[186:189], v[194:197], v[110:113]
	v_mfma_f32_16x16x32_bf16 v[122:125], v[174:177], v[190:193], v[122:125]
	v_mfma_f32_16x16x32_bf16 v[122:125], v[178:181], v[194:197], v[122:125]
	v_mfma_f32_16x16x32_bf16 v[102:105], v[174:177], v[198:201], v[102:105]
	v_mfma_f32_16x16x32_bf16 v[102:105], v[178:181], v[202:205], v[102:105]
	v_mfma_f32_16x16x32_bf16 v[98:101], v[182:185], v[198:201], v[98:101]
	v_mfma_f32_16x16x32_bf16 v[98:101], v[186:189], v[202:205], v[98:101]
	v_mfma_f32_16x16x32_bf16 v[114:117], v[154:157], v[198:201], v[114:117]
	v_mfma_f32_16x16x32_bf16 v[114:117], v[170:173], v[202:205], v[114:117]
	v_mfma_f32_16x16x32_bf16 v[118:121], v[132:135], v[198:201], v[118:121]
	v_mfma_f32_16x16x32_bf16 v[118:121], v[142:145], v[202:205], v[118:121]
	v_mfma_f32_16x16x32_bf16 v[94:97], v[132:135], v[228:231], v[94:97]
	v_mfma_f32_16x16x32_bf16 v[94:97], v[142:145], v[232:235], v[94:97]
	v_mfma_f32_16x16x32_bf16 v[90:93], v[154:157], v[228:231], v[90:93]
	v_mfma_f32_16x16x32_bf16 v[90:93], v[170:173], v[232:235], v[90:93]
	v_mfma_f32_16x16x32_bf16 v[82:85], v[182:185], v[228:231], v[82:85]
	v_mfma_f32_16x16x32_bf16 v[82:85], v[186:189], v[232:235], v[82:85]
	v_mfma_f32_16x16x32_bf16 v[86:89], v[174:177], v[228:231], v[86:89]
	v_mfma_f32_16x16x32_bf16 v[86:89], v[178:181], v[232:235], v[86:89]
	v_mfma_f32_16x16x32_bf16 v[70:73], v[174:177], v[236:239], v[70:73]
	v_mfma_f32_16x16x32_bf16 v[70:73], v[178:181], v[240:243], v[70:73]
	v_mfma_f32_16x16x32_bf16 v[66:69], v[182:185], v[236:239], v[66:69]
	v_mfma_f32_16x16x32_bf16 v[66:69], v[186:189], v[240:243], v[66:69]
	v_mfma_f32_16x16x32_bf16 v[74:77], v[154:157], v[236:239], v[74:77]
	v_mfma_f32_16x16x32_bf16 v[74:77], v[170:173], v[240:243], v[74:77]
	v_mfma_f32_16x16x32_bf16 v[78:81], v[132:135], v[236:239], v[78:81]
	v_mfma_f32_16x16x32_bf16 v[78:81], v[142:145], v[240:243], v[78:81]
	s_barrier
	s_setprio 0
	s_mov_b32 s46, s62
	s_mov_b32 s47, s63
	s_mov_b32 m0, s15
	ds_read_b128 v[190:193], v141 offset:16384
	buffer_load_dwordx4 v137, s[44:47], s26 offen lds
	s_add_i32 s49, s26, 0x80000
	s_mov_b32 m0, s16
	ds_read_b128 v[194:197], v141 offset:17408
	buffer_load_dwordx4 v139, s[44:47], s26 offen lds
	s_mov_b32 m0, s18
	ds_read_b128 v[198:201], v141 offset:18432
	buffer_load_dwordx4 v137, s[44:47], s49 offen lds
	s_mov_b32 m0, s19
	ds_read_b128 v[202:205], v141 offset:19456
	buffer_load_dwordx4 v139, s[44:47], s49 offen lds
	s_mov_b32 m0, s14
	ds_read_b128 v[228:231], v141 offset:20480
	buffer_load_dwordx4 v136, s[60:63], s27 offen lds
	s_mov_b32 m0, s24
	ds_read_b128 v[232:235], v141 offset:21504
	buffer_load_dwordx4 v138, s[60:63], s27 offen lds
	ds_read_b128 v[236:239], v141 offset:22528
	ds_read_b128 v[240:243], v141 offset:23552
	s_waitcnt vmcnt(8)
	s_waitcnt lgkmcnt(0)
	s_setprio 1
	s_barrier
	v_mfma_f32_16x16x32_bf16 v[62:65], v[132:135], v[190:193], v[62:65]
	v_mfma_f32_16x16x32_bf16 v[62:65], v[142:145], v[194:197], v[62:65]
	v_mfma_f32_16x16x32_bf16 v[58:61], v[154:157], v[190:193], v[58:61]
	v_mfma_f32_16x16x32_bf16 v[58:61], v[170:173], v[194:197], v[58:61]
	v_mfma_f32_16x16x32_bf16 v[50:53], v[182:185], v[190:193], v[50:53]
	v_mfma_f32_16x16x32_bf16 v[50:53], v[186:189], v[194:197], v[50:53]
	v_mfma_f32_16x16x32_bf16 v[54:57], v[174:177], v[190:193], v[54:57]
	v_mfma_f32_16x16x32_bf16 v[54:57], v[178:181], v[194:197], v[54:57]
	v_mfma_f32_16x16x32_bf16 v[38:41], v[174:177], v[198:201], v[38:41]
	v_mfma_f32_16x16x32_bf16 v[38:41], v[178:181], v[202:205], v[38:41]
	v_mfma_f32_16x16x32_bf16 v[34:37], v[182:185], v[198:201], v[34:37]
	v_mfma_f32_16x16x32_bf16 v[34:37], v[186:189], v[202:205], v[34:37]
	v_mfma_f32_16x16x32_bf16 v[42:45], v[154:157], v[198:201], v[42:45]
	v_mfma_f32_16x16x32_bf16 v[42:45], v[170:173], v[202:205], v[42:45]
	v_mfma_f32_16x16x32_bf16 v[46:49], v[132:135], v[198:201], v[46:49]
	v_mfma_f32_16x16x32_bf16 v[46:49], v[142:145], v[202:205], v[46:49]
	v_mfma_f32_16x16x32_bf16 v[30:33], v[132:135], v[228:231], v[30:33]
	v_mfma_f32_16x16x32_bf16 v[30:33], v[142:145], v[232:235], v[30:33]
	v_mfma_f32_16x16x32_bf16 v[26:29], v[154:157], v[228:231], v[26:29]
	v_mfma_f32_16x16x32_bf16 v[26:29], v[170:173], v[232:235], v[26:29]
	v_mfma_f32_16x16x32_bf16 v[18:21], v[182:185], v[228:231], v[18:21]
	v_mfma_f32_16x16x32_bf16 v[18:21], v[186:189], v[232:235], v[18:21]
	v_mfma_f32_16x16x32_bf16 v[22:25], v[174:177], v[228:231], v[22:25]
	v_mfma_f32_16x16x32_bf16 v[22:25], v[178:181], v[232:235], v[22:25]
	v_mfma_f32_16x16x32_bf16 v[6:9], v[174:177], v[236:239], v[6:9]
	v_mfma_f32_16x16x32_bf16 v[6:9], v[178:181], v[240:243], v[6:9]
	v_mfma_f32_16x16x32_bf16 v[2:5], v[182:185], v[236:239], v[2:5]
	v_mfma_f32_16x16x32_bf16 v[2:5], v[186:189], v[240:243], v[2:5]
	v_mfma_f32_16x16x32_bf16 v[10:13], v[154:157], v[236:239], v[10:13]
	v_mfma_f32_16x16x32_bf16 v[10:13], v[170:173], v[240:243], v[10:13]
	v_mfma_f32_16x16x32_bf16 v[14:17], v[132:135], v[236:239], v[14:17]
	v_mfma_f32_16x16x32_bf16 v[14:17], v[142:145], v[240:243], v[14:17]
	s_barrier
	s_setprio 0
	v_add_u32_e32 v170, 0x18000, v140
	v_add_u32_e32 v186, 0x1c000, v140
	ds_read_b128 v[132:135], v170
	ds_read_b128 v[142:145], v170 offset:1024
	ds_read_b128 v[154:157], v170 offset:2048
	ds_read_b128 v[170:173], v170 offset:3072
	ds_read_b128 v[174:177], v186
	ds_read_b128 v[178:181], v186 offset:1024
	ds_read_b128 v[182:185], v186 offset:2048
	ds_read_b128 v[186:189], v186 offset:3072
	s_add_i32 s27, s27, 0x80000
	s_mov_b32 m0, s25
	ds_read_b128 v[190:193], v141 offset:32768
	ds_read_b128 v[194:197], v141 offset:33792
	ds_read_b128 v[198:201], v141 offset:34816
	ds_read_b128 v[202:205], v141 offset:35840
	ds_read_b128 v[228:231], v141 offset:36864
	ds_read_b128 v[232:235], v141 offset:37888
	ds_read_b128 v[236:239], v141 offset:38912
	ds_read_b128 v[240:243], v141 offset:39936
	buffer_load_dwordx4 v136, s[60:63], s27 offen lds
	s_mov_b32 m0, s30
	s_nop 0
	buffer_load_dwordx4 v138, s[60:63], s27 offen lds
	s_waitcnt vmcnt(8)
	s_waitcnt lgkmcnt(0)
	s_setprio 1
	s_barrier
	v_mfma_f32_16x16x32_bf16 v[126:129], v[132:135], v[190:193], v[126:129]
	v_mfma_f32_16x16x32_bf16 v[126:129], v[142:145], v[194:197], v[126:129]
	v_mfma_f32_16x16x32_bf16 v[106:109], v[154:157], v[190:193], v[106:109]
	v_mfma_f32_16x16x32_bf16 v[106:109], v[170:173], v[194:197], v[106:109]
	v_mfma_f32_16x16x32_bf16 v[110:113], v[182:185], v[190:193], v[110:113]
	v_mfma_f32_16x16x32_bf16 v[110:113], v[186:189], v[194:197], v[110:113]
	v_mfma_f32_16x16x32_bf16 v[122:125], v[174:177], v[190:193], v[122:125]
	v_mfma_f32_16x16x32_bf16 v[122:125], v[178:181], v[194:197], v[122:125]
	v_mfma_f32_16x16x32_bf16 v[102:105], v[174:177], v[198:201], v[102:105]
	v_mfma_f32_16x16x32_bf16 v[102:105], v[178:181], v[202:205], v[102:105]
	v_mfma_f32_16x16x32_bf16 v[98:101], v[182:185], v[198:201], v[98:101]
	v_mfma_f32_16x16x32_bf16 v[98:101], v[186:189], v[202:205], v[98:101]
	v_mfma_f32_16x16x32_bf16 v[114:117], v[154:157], v[198:201], v[114:117]
	v_mfma_f32_16x16x32_bf16 v[114:117], v[170:173], v[202:205], v[114:117]
	v_mfma_f32_16x16x32_bf16 v[118:121], v[132:135], v[198:201], v[118:121]
	v_mfma_f32_16x16x32_bf16 v[118:121], v[142:145], v[202:205], v[118:121]
	v_mfma_f32_16x16x32_bf16 v[94:97], v[132:135], v[228:231], v[94:97]
	v_mfma_f32_16x16x32_bf16 v[94:97], v[142:145], v[232:235], v[94:97]
	v_mfma_f32_16x16x32_bf16 v[90:93], v[154:157], v[228:231], v[90:93]
	v_mfma_f32_16x16x32_bf16 v[90:93], v[170:173], v[232:235], v[90:93]
	v_mfma_f32_16x16x32_bf16 v[82:85], v[182:185], v[228:231], v[82:85]
	v_mfma_f32_16x16x32_bf16 v[82:85], v[186:189], v[232:235], v[82:85]
	v_mfma_f32_16x16x32_bf16 v[86:89], v[174:177], v[228:231], v[86:89]
	v_mfma_f32_16x16x32_bf16 v[86:89], v[178:181], v[232:235], v[86:89]
	v_mfma_f32_16x16x32_bf16 v[70:73], v[174:177], v[236:239], v[70:73]
	v_mfma_f32_16x16x32_bf16 v[70:73], v[178:181], v[240:243], v[70:73]
	v_mfma_f32_16x16x32_bf16 v[66:69], v[182:185], v[236:239], v[66:69]
	v_mfma_f32_16x16x32_bf16 v[66:69], v[186:189], v[240:243], v[66:69]
	v_mfma_f32_16x16x32_bf16 v[74:77], v[154:157], v[236:239], v[74:77]
	v_mfma_f32_16x16x32_bf16 v[74:77], v[170:173], v[240:243], v[74:77]
	v_mfma_f32_16x16x32_bf16 v[78:81], v[132:135], v[236:239], v[78:81]
	v_mfma_f32_16x16x32_bf16 v[78:81], v[142:145], v[240:243], v[78:81]
	s_barrier
	s_setprio 0
	s_or_b32 s27, s26, 0x80
	s_mov_b32 m0, s36
	ds_read_b128 v[190:193], v141 offset:49152
	buffer_load_dwordx4 v137, s[44:47], s27 offen lds
	s_add_i32 s26, s26, 0x80080
	s_mov_b32 m0, s37
	ds_read_b128 v[194:197], v141 offset:50176
	buffer_load_dwordx4 v139, s[44:47], s27 offen lds
	s_mov_b32 m0, s68
	ds_read_b128 v[198:201], v141 offset:51200
	buffer_load_dwordx4 v137, s[44:47], s26 offen lds
	s_mov_b32 m0, s69
	ds_read_b128 v[202:205], v141 offset:52224
	buffer_load_dwordx4 v139, s[44:47], s26 offen lds
	s_mov_b32 m0, s66
	ds_read_b128 v[228:231], v141 offset:53248
	buffer_load_dwordx4 v136, s[60:63], s23 offen lds
	s_mov_b32 m0, s67
	ds_read_b128 v[232:235], v141 offset:54272
	buffer_load_dwordx4 v138, s[60:63], s23 offen lds
	ds_read_b128 v[236:239], v141 offset:55296
	ds_read_b128 v[240:243], v141 offset:56320
	s_waitcnt vmcnt(8)
	s_waitcnt lgkmcnt(0)
	s_setprio 1
	s_barrier
	v_mfma_f32_16x16x32_bf16 v[62:65], v[132:135], v[190:193], v[62:65]
	v_mfma_f32_16x16x32_bf16 v[62:65], v[142:145], v[194:197], v[62:65]
	v_mfma_f32_16x16x32_bf16 v[58:61], v[154:157], v[190:193], v[58:61]
	v_mfma_f32_16x16x32_bf16 v[58:61], v[170:173], v[194:197], v[58:61]
	v_mfma_f32_16x16x32_bf16 v[50:53], v[182:185], v[190:193], v[50:53]
	v_mfma_f32_16x16x32_bf16 v[50:53], v[186:189], v[194:197], v[50:53]
	v_mfma_f32_16x16x32_bf16 v[54:57], v[174:177], v[190:193], v[54:57]
	v_mfma_f32_16x16x32_bf16 v[54:57], v[178:181], v[194:197], v[54:57]
	v_mfma_f32_16x16x32_bf16 v[38:41], v[174:177], v[198:201], v[38:41]
	v_mfma_f32_16x16x32_bf16 v[38:41], v[178:181], v[202:205], v[38:41]
	v_mfma_f32_16x16x32_bf16 v[34:37], v[182:185], v[198:201], v[34:37]
	v_mfma_f32_16x16x32_bf16 v[34:37], v[186:189], v[202:205], v[34:37]
	v_mfma_f32_16x16x32_bf16 v[42:45], v[154:157], v[198:201], v[42:45]
	v_mfma_f32_16x16x32_bf16 v[42:45], v[170:173], v[202:205], v[42:45]
	v_mfma_f32_16x16x32_bf16 v[46:49], v[132:135], v[198:201], v[46:49]
	v_mfma_f32_16x16x32_bf16 v[46:49], v[142:145], v[202:205], v[46:49]
	v_mfma_f32_16x16x32_bf16 v[30:33], v[132:135], v[228:231], v[30:33]
	v_mfma_f32_16x16x32_bf16 v[30:33], v[142:145], v[232:235], v[30:33]
	v_mfma_f32_16x16x32_bf16 v[26:29], v[154:157], v[228:231], v[26:29]
	v_mfma_f32_16x16x32_bf16 v[26:29], v[170:173], v[232:235], v[26:29]
	v_mfma_f32_16x16x32_bf16 v[18:21], v[182:185], v[228:231], v[18:21]
	v_mfma_f32_16x16x32_bf16 v[18:21], v[186:189], v[232:235], v[18:21]
	v_mfma_f32_16x16x32_bf16 v[22:25], v[174:177], v[228:231], v[22:25]
	v_mfma_f32_16x16x32_bf16 v[22:25], v[178:181], v[232:235], v[22:25]
	v_mfma_f32_16x16x32_bf16 v[6:9], v[174:177], v[236:239], v[6:9]
	v_mfma_f32_16x16x32_bf16 v[6:9], v[178:181], v[240:243], v[6:9]
	v_mfma_f32_16x16x32_bf16 v[2:5], v[182:185], v[236:239], v[2:5]
	v_mfma_f32_16x16x32_bf16 v[2:5], v[186:189], v[240:243], v[2:5]
	v_mfma_f32_16x16x32_bf16 v[10:13], v[154:157], v[236:239], v[10:13]
	v_mfma_f32_16x16x32_bf16 v[10:13], v[170:173], v[240:243], v[10:13]
	v_mfma_f32_16x16x32_bf16 v[14:17], v[132:135], v[236:239], v[14:17]
	v_mfma_f32_16x16x32_bf16 v[14:17], v[142:145], v[240:243], v[14:17]
	s_barrier
	s_setprio 0
	s_add_i32 s22, s22, 2
	s_addk_i32 s13, 0x100
	s_addk_i32 s21, 0x100
	s_cmp_gt_u32 s22, 29
	s_cbranch_scc0 .LBB0_1589
	s_and_b64 vcc, exec, s[64:65]
	s_cbranch_vccz .LBB0_1592
	s_barrier

.LBB0_1879:
	s_lshl_b32 s18, s91, 20
	s_and_b64 s[8:9], s[48:49], exec
	s_cselect_b32 s8, s18, s95
	s_lshl_b32 s19, s92, 20
	s_and_b64 s[42:43], s[48:49], exec
	s_cselect_b32 s9, s19, s94
	s_add_i32 vcc_lo, s95, 0x80080
	s_add_i32 vcc_hi, s94, 0x100
	s_mov_b32 s94, -2
	v_add_u32_e32 v139, 0x10000, v136
	ds_read_b128 v[140:143], v139
	ds_read_b128 v[154:157], v139 offset:1024
	ds_read_b128 v[170:173], v139 offset:2048
	ds_read_b128 v[174:177], v139 offset:3072
	v_add_u32_e32 v139, 0x14000, v136
	ds_read_b128 v[178:181], v139
	ds_read_b128 v[182:185], v139 offset:1024
	ds_read_b128 v[186:189], v139 offset:2048
	ds_read_b128 v[190:193], v139 offset:3072
	s_add_i32 s42, vcc_lo, 0xfff80080
	s_cmp_eq_u32 s94, 28
	s_cselect_b32 s52, s8, s42
	s_cselect_b32 s96, s9, vcc_hi
	s_or_b32 s95, s52, 0x80
	s_mov_b32 m0, s72
	ds_read_b128 v[194:197], v137
	ds_read_b128 v[198:201], v137 offset:1024
	ds_read_b128 v[202:205], v137 offset:2048
	ds_read_b128 v[228:231], v137 offset:3072
	ds_read_b128 v[232:235], v137 offset:4096
	ds_read_b128 v[236:239], v137 offset:5120
	ds_read_b128 v[240:243], v137 offset:6144
	ds_read_b128 v[244:247], v137 offset:7168
	buffer_load_dwordx4 v132, s[60:63], vcc_lo offen lds
	s_mov_b32 m0, s47
	s_nop 0
	buffer_load_dwordx4 v134, s[60:63], vcc_lo offen lds
	s_waitcnt vmcnt(8)
	s_waitcnt lgkmcnt(0)
	s_setprio 1
	s_barrier
	v_mfma_f32_16x16x32_bf16 v[114:117], v[140:143], v[194:197], 0
	v_mfma_f32_16x16x32_bf16 v[114:117], v[154:157], v[198:201], v[114:117]
	v_mfma_f32_16x16x32_bf16 v[110:113], v[170:173], v[194:197], 0
	v_mfma_f32_16x16x32_bf16 v[110:113], v[174:177], v[198:201], v[110:113]
	v_mfma_f32_16x16x32_bf16 v[122:125], v[186:189], v[194:197], 0
	v_mfma_f32_16x16x32_bf16 v[122:125], v[190:193], v[198:201], v[122:125]
	v_mfma_f32_16x16x32_bf16 v[126:129], v[178:181], v[194:197], 0
	v_mfma_f32_16x16x32_bf16 v[126:129], v[182:185], v[198:201], v[126:129]
	v_mfma_f32_16x16x32_bf16 v[118:121], v[178:181], v[202:205], 0
	v_mfma_f32_16x16x32_bf16 v[118:121], v[182:185], v[228:231], v[118:121]
	v_mfma_f32_16x16x32_bf16 v[98:101], v[186:189], v[202:205], 0
	v_mfma_f32_16x16x32_bf16 v[98:101], v[190:193], v[228:231], v[98:101]
	v_mfma_f32_16x16x32_bf16 v[102:105], v[170:173], v[202:205], 0
	v_mfma_f32_16x16x32_bf16 v[102:105], v[174:177], v[228:231], v[102:105]
	v_mfma_f32_16x16x32_bf16 v[106:109], v[140:143], v[202:205], 0
	v_mfma_f32_16x16x32_bf16 v[106:109], v[154:157], v[228:231], v[106:109]
	v_mfma_f32_16x16x32_bf16 v[94:97], v[140:143], v[232:235], 0
	v_mfma_f32_16x16x32_bf16 v[94:97], v[154:157], v[236:239], v[94:97]
	v_mfma_f32_16x16x32_bf16 v[86:89], v[170:173], v[232:235], 0
	v_mfma_f32_16x16x32_bf16 v[86:89], v[174:177], v[236:239], v[86:89]
	v_mfma_f32_16x16x32_bf16 v[82:85], v[186:189], v[232:235], 0
	v_mfma_f32_16x16x32_bf16 v[82:85], v[190:193], v[236:239], v[82:85]
	v_mfma_f32_16x16x32_bf16 v[90:93], v[178:181], v[232:235], 0
	v_mfma_f32_16x16x32_bf16 v[90:93], v[182:185], v[236:239], v[90:93]
	v_mfma_f32_16x16x32_bf16 v[74:77], v[178:181], v[240:243], 0
	v_mfma_f32_16x16x32_bf16 v[74:77], v[182:185], v[244:247], v[74:77]
	v_mfma_f32_16x16x32_bf16 v[66:69], v[186:189], v[240:243], 0
	v_mfma_f32_16x16x32_bf16 v[66:69], v[190:193], v[244:247], v[66:69]
	v_mfma_f32_16x16x32_bf16 v[70:73], v[170:173], v[240:243], 0
	v_mfma_f32_16x16x32_bf16 v[70:73], v[174:177], v[244:247], v[70:73]
	v_mfma_f32_16x16x32_bf16 v[78:81], v[140:143], v[240:243], 0
	v_mfma_f32_16x16x32_bf16 v[78:81], v[154:157], v[244:247], v[78:81]
	s_barrier
	s_setprio 0
	s_mov_b32 s42, s62
	s_mov_b32 s43, s63
	s_mov_b32 m0, s13
	ds_read_b128 v[194:197], v137 offset:16384
	buffer_load_dwordx4 v133, s[40:43], s96 offen lds
	s_add_i32 s53, s96, 0x80000
	s_mov_b32 m0, s14
	ds_read_b128 v[198:201], v137 offset:17408
	buffer_load_dwordx4 v135, s[40:43], s96 offen lds
	s_mov_b32 m0, s15
	ds_read_b128 v[202:205], v137 offset:18432
	buffer_load_dwordx4 v133, s[40:43], s53 offen lds
	s_mov_b32 m0, s16
	ds_read_b128 v[228:231], v137 offset:19456
	buffer_load_dwordx4 v135, s[40:43], s53 offen lds
	s_mov_b32 m0, s2
	ds_read_b128 v[232:235], v137 offset:20480
	buffer_load_dwordx4 v132, s[60:63], s52 offen lds
	s_mov_b32 m0, s21
	ds_read_b128 v[236:239], v137 offset:21504
	buffer_load_dwordx4 v134, s[60:63], s52 offen lds
	ds_read_b128 v[240:243], v137 offset:22528
	ds_read_b128 v[244:247], v137 offset:23552
	s_waitcnt vmcnt(8)
	s_waitcnt lgkmcnt(0)
	s_setprio 1
	s_barrier
	v_mfma_f32_16x16x32_bf16 v[62:65], v[140:143], v[194:197], 0
	v_mfma_f32_16x16x32_bf16 v[62:65], v[154:157], v[198:201], v[62:65]
	v_mfma_f32_16x16x32_bf16 v[54:57], v[170:173], v[194:197], 0
	v_mfma_f32_16x16x32_bf16 v[54:57], v[174:177], v[198:201], v[54:57]
	v_mfma_f32_16x16x32_bf16 v[50:53], v[186:189], v[194:197], 0
	v_mfma_f32_16x16x32_bf16 v[50:53], v[190:193], v[198:201], v[50:53]
	v_mfma_f32_16x16x32_bf16 v[58:61], v[178:181], v[194:197], 0
	v_mfma_f32_16x16x32_bf16 v[58:61], v[182:185], v[198:201], v[58:61]
	v_mfma_f32_16x16x32_bf16 v[42:45], v[178:181], v[202:205], 0
	v_mfma_f32_16x16x32_bf16 v[42:45], v[182:185], v[228:231], v[42:45]
	v_mfma_f32_16x16x32_bf16 v[34:37], v[186:189], v[202:205], 0
	v_mfma_f32_16x16x32_bf16 v[34:37], v[190:193], v[228:231], v[34:37]
	v_mfma_f32_16x16x32_bf16 v[38:41], v[170:173], v[202:205], 0
	v_mfma_f32_16x16x32_bf16 v[38:41], v[174:177], v[228:231], v[38:41]
	v_mfma_f32_16x16x32_bf16 v[46:49], v[140:143], v[202:205], 0
	v_mfma_f32_16x16x32_bf16 v[46:49], v[154:157], v[228:231], v[46:49]
	v_mfma_f32_16x16x32_bf16 v[30:33], v[140:143], v[232:235], 0
	v_mfma_f32_16x16x32_bf16 v[30:33], v[154:157], v[236:239], v[30:33]
	v_mfma_f32_16x16x32_bf16 v[22:25], v[170:173], v[232:235], 0
	v_mfma_f32_16x16x32_bf16 v[22:25], v[174:177], v[236:239], v[22:25]
	v_mfma_f32_16x16x32_bf16 v[18:21], v[186:189], v[232:235], 0
	v_mfma_f32_16x16x32_bf16 v[18:21], v[190:193], v[236:239], v[18:21]
	v_mfma_f32_16x16x32_bf16 v[26:29], v[178:181], v[232:235], 0
	v_mfma_f32_16x16x32_bf16 v[26:29], v[182:185], v[236:239], v[26:29]
	v_mfma_f32_16x16x32_bf16 v[10:13], v[178:181], v[240:243], 0
	v_mfma_f32_16x16x32_bf16 v[10:13], v[182:185], v[244:247], v[10:13]
	v_mfma_f32_16x16x32_bf16 v[2:5], v[186:189], v[240:243], 0
	v_mfma_f32_16x16x32_bf16 v[2:5], v[190:193], v[244:247], v[2:5]
	v_mfma_f32_16x16x32_bf16 v[6:9], v[170:173], v[240:243], 0
	v_mfma_f32_16x16x32_bf16 v[6:9], v[174:177], v[244:247], v[6:9]
	v_mfma_f32_16x16x32_bf16 v[14:17], v[140:143], v[240:243], 0
	v_mfma_f32_16x16x32_bf16 v[14:17], v[154:157], v[244:247], v[14:17]
	s_barrier
	s_setprio 0
	v_add_u32_e32 v139, 0x18000, v136
	ds_read_b128 v[140:143], v139
	ds_read_b128 v[154:157], v139 offset:1024
	ds_read_b128 v[170:173], v139 offset:2048
	ds_read_b128 v[174:177], v139 offset:3072
	v_add_u32_e32 v139, 0x1c000, v136
	ds_read_b128 v[178:181], v139
	ds_read_b128 v[182:185], v139 offset:1024
	ds_read_b128 v[186:189], v139 offset:2048
	ds_read_b128 v[190:193], v139 offset:3072
	s_add_i32 s52, s52, 0x80000
	s_mov_b32 m0, s23
	ds_read_b128 v[194:197], v137 offset:32768
	ds_read_b128 v[198:201], v137 offset:33792
	ds_read_b128 v[202:205], v137 offset:34816
	ds_read_b128 v[228:231], v137 offset:35840
	ds_read_b128 v[232:235], v137 offset:36864
	ds_read_b128 v[236:239], v137 offset:37888
	ds_read_b128 v[240:243], v137 offset:38912
	ds_read_b128 v[244:247], v137 offset:39936
	buffer_load_dwordx4 v132, s[60:63], s52 offen lds
	s_mov_b32 m0, s24
	s_nop 0
	buffer_load_dwordx4 v134, s[60:63], s52 offen lds
	s_waitcnt vmcnt(8)
	s_waitcnt lgkmcnt(0)
	s_setprio 1
	s_barrier
	v_mfma_f32_16x16x32_bf16 v[114:117], v[140:143], v[194:197], v[114:117]
	v_mfma_f32_16x16x32_bf16 v[114:117], v[154:157], v[198:201], v[114:117]
	v_mfma_f32_16x16x32_bf16 v[110:113], v[170:173], v[194:197], v[110:113]
	v_mfma_f32_16x16x32_bf16 v[110:113], v[174:177], v[198:201], v[110:113]
	v_mfma_f32_16x16x32_bf16 v[122:125], v[186:189], v[194:197], v[122:125]
	v_mfma_f32_16x16x32_bf16 v[122:125], v[190:193], v[198:201], v[122:125]
	v_mfma_f32_16x16x32_bf16 v[126:129], v[178:181], v[194:197], v[126:129]
	v_mfma_f32_16x16x32_bf16 v[126:129], v[182:185], v[198:201], v[126:129]
	v_mfma_f32_16x16x32_bf16 v[118:121], v[178:181], v[202:205], v[118:121]
	v_mfma_f32_16x16x32_bf16 v[118:121], v[182:185], v[228:231], v[118:121]
	v_mfma_f32_16x16x32_bf16 v[98:101], v[186:189], v[202:205], v[98:101]
	v_mfma_f32_16x16x32_bf16 v[98:101], v[190:193], v[228:231], v[98:101]
	v_mfma_f32_16x16x32_bf16 v[102:105], v[170:173], v[202:205], v[102:105]
	v_mfma_f32_16x16x32_bf16 v[102:105], v[174:177], v[228:231], v[102:105]
	v_mfma_f32_16x16x32_bf16 v[106:109], v[140:143], v[202:205], v[106:109]
	v_mfma_f32_16x16x32_bf16 v[106:109], v[154:157], v[228:231], v[106:109]
	v_mfma_f32_16x16x32_bf16 v[94:97], v[140:143], v[232:235], v[94:97]
	v_mfma_f32_16x16x32_bf16 v[94:97], v[154:157], v[236:239], v[94:97]
	v_mfma_f32_16x16x32_bf16 v[86:89], v[170:173], v[232:235], v[86:89]
	v_mfma_f32_16x16x32_bf16 v[86:89], v[174:177], v[236:239], v[86:89]
	v_mfma_f32_16x16x32_bf16 v[82:85], v[186:189], v[232:235], v[82:85]
	v_mfma_f32_16x16x32_bf16 v[82:85], v[190:193], v[236:239], v[82:85]
	v_mfma_f32_16x16x32_bf16 v[90:93], v[178:181], v[232:235], v[90:93]
	v_mfma_f32_16x16x32_bf16 v[90:93], v[182:185], v[236:239], v[90:93]
	v_mfma_f32_16x16x32_bf16 v[74:77], v[178:181], v[240:243], v[74:77]
	v_mfma_f32_16x16x32_bf16 v[74:77], v[182:185], v[244:247], v[74:77]
	v_mfma_f32_16x16x32_bf16 v[66:69], v[186:189], v[240:243], v[66:69]
	v_mfma_f32_16x16x32_bf16 v[66:69], v[190:193], v[244:247], v[66:69]
	v_mfma_f32_16x16x32_bf16 v[70:73], v[170:173], v[240:243], v[70:73]
	v_mfma_f32_16x16x32_bf16 v[70:73], v[174:177], v[244:247], v[70:73]
	v_mfma_f32_16x16x32_bf16 v[78:81], v[140:143], v[240:243], v[78:81]
	v_mfma_f32_16x16x32_bf16 v[78:81], v[154:157], v[244:247], v[78:81]
	s_barrier
	s_setprio 0
	s_or_b32 s52, s96, 0x80
	s_mov_b32 m0, s31
	ds_read_b128 v[194:197], v137 offset:49152
	buffer_load_dwordx4 v133, s[40:43], s52 offen lds
	s_add_i32 s96, s96, 0x80080
	s_mov_b32 m0, s33
	ds_read_b128 v[198:201], v137 offset:50176
	buffer_load_dwordx4 v135, s[40:43], s52 offen lds
	s_mov_b32 m0, s36
	ds_read_b128 v[202:205], v137 offset:51200
	buffer_load_dwordx4 v133, s[40:43], s96 offen lds
	s_mov_b32 m0, s37
	ds_read_b128 v[228:231], v137 offset:52224
	buffer_load_dwordx4 v135, s[40:43], s96 offen lds
	s_mov_b32 m0, s34
	ds_read_b128 v[232:235], v137 offset:53248
	buffer_load_dwordx4 v132, s[60:63], s95 offen lds
	s_mov_b32 m0, s35
	ds_read_b128 v[236:239], v137 offset:54272
	buffer_load_dwordx4 v134, s[60:63], s95 offen lds
	ds_read_b128 v[240:243], v137 offset:55296
	ds_read_b128 v[244:247], v137 offset:56320
	s_waitcnt vmcnt(8)
	s_waitcnt lgkmcnt(0)
	s_setprio 1
	s_barrier
	v_mfma_f32_16x16x32_bf16 v[62:65], v[140:143], v[194:197], v[62:65]
	v_mfma_f32_16x16x32_bf16 v[62:65], v[154:157], v[198:201], v[62:65]
	v_mfma_f32_16x16x32_bf16 v[54:57], v[170:173], v[194:197], v[54:57]
	v_mfma_f32_16x16x32_bf16 v[54:57], v[174:177], v[198:201], v[54:57]
	v_mfma_f32_16x16x32_bf16 v[50:53], v[186:189], v[194:197], v[50:53]
	v_mfma_f32_16x16x32_bf16 v[50:53], v[190:193], v[198:201], v[50:53]
	v_mfma_f32_16x16x32_bf16 v[58:61], v[178:181], v[194:197], v[58:61]
	v_mfma_f32_16x16x32_bf16 v[58:61], v[182:185], v[198:201], v[58:61]
	v_mfma_f32_16x16x32_bf16 v[42:45], v[178:181], v[202:205], v[42:45]
	v_mfma_f32_16x16x32_bf16 v[42:45], v[182:185], v[228:231], v[42:45]
	v_mfma_f32_16x16x32_bf16 v[34:37], v[186:189], v[202:205], v[34:37]
	v_mfma_f32_16x16x32_bf16 v[34:37], v[190:193], v[228:231], v[34:37]
	v_mfma_f32_16x16x32_bf16 v[38:41], v[170:173], v[202:205], v[38:41]
	v_mfma_f32_16x16x32_bf16 v[38:41], v[174:177], v[228:231], v[38:41]
	v_mfma_f32_16x16x32_bf16 v[46:49], v[140:143], v[202:205], v[46:49]
	v_mfma_f32_16x16x32_bf16 v[46:49], v[154:157], v[228:231], v[46:49]
	v_mfma_f32_16x16x32_bf16 v[30:33], v[140:143], v[232:235], v[30:33]
	v_mfma_f32_16x16x32_bf16 v[30:33], v[154:157], v[236:239], v[30:33]
	v_mfma_f32_16x16x32_bf16 v[22:25], v[170:173], v[232:235], v[22:25]
	v_mfma_f32_16x16x32_bf16 v[22:25], v[174:177], v[236:239], v[22:25]
	v_mfma_f32_16x16x32_bf16 v[18:21], v[186:189], v[232:235], v[18:21]
	v_mfma_f32_16x16x32_bf16 v[18:21], v[190:193], v[236:239], v[18:21]
	v_mfma_f32_16x16x32_bf16 v[26:29], v[178:181], v[232:235], v[26:29]
	v_mfma_f32_16x16x32_bf16 v[26:29], v[182:185], v[236:239], v[26:29]
	v_mfma_f32_16x16x32_bf16 v[10:13], v[178:181], v[240:243], v[10:13]
	v_mfma_f32_16x16x32_bf16 v[10:13], v[182:185], v[244:247], v[10:13]
	v_mfma_f32_16x16x32_bf16 v[2:5], v[186:189], v[240:243], v[2:5]
	v_mfma_f32_16x16x32_bf16 v[2:5], v[190:193], v[244:247], v[2:5]
	v_mfma_f32_16x16x32_bf16 v[6:9], v[170:173], v[240:243], v[6:9]
	v_mfma_f32_16x16x32_bf16 v[6:9], v[174:177], v[244:247], v[6:9]
	v_mfma_f32_16x16x32_bf16 v[14:17], v[140:143], v[240:243], v[14:17]
	v_mfma_f32_16x16x32_bf16 v[14:17], v[154:157], v[244:247], v[14:17]
	s_barrier
	s_setprio 0
	s_add_i32 s94, s94, 2
	s_addk_i32 vcc_lo, 0x100
	s_addk_i32 vcc_hi, 0x100
	s_cmp_gt_u32 s94, 29
.LBB0_1880:
	v_add_u32_e32 v139, 0x10000, v136
	ds_read_b128 v[140:143], v139
	ds_read_b128 v[154:157], v139 offset:1024
	ds_read_b128 v[170:173], v139 offset:2048
	ds_read_b128 v[174:177], v139 offset:3072
	v_add_u32_e32 v139, 0x14000, v136
	ds_read_b128 v[178:181], v139
	ds_read_b128 v[182:185], v139 offset:1024
	ds_read_b128 v[186:189], v139 offset:2048
	ds_read_b128 v[190:193], v139 offset:3072
	s_add_i32 s42, vcc_lo, 0xfff80080
	s_cmp_eq_u32 s94, 28
	s_cselect_b32 s52, s8, s42
	s_cselect_b32 s96, s9, vcc_hi
	s_or_b32 s95, s52, 0x80
	s_mov_b32 m0, s72
	ds_read_b128 v[194:197], v137
	ds_read_b128 v[198:201], v137 offset:1024
	ds_read_b128 v[202:205], v137 offset:2048
	ds_read_b128 v[228:231], v137 offset:3072
	ds_read_b128 v[232:235], v137 offset:4096
	ds_read_b128 v[236:239], v137 offset:5120
	ds_read_b128 v[240:243], v137 offset:6144
	ds_read_b128 v[244:247], v137 offset:7168
	buffer_load_dwordx4 v132, s[60:63], vcc_lo offen lds
	s_mov_b32 m0, s47
	s_nop 0
	buffer_load_dwordx4 v134, s[60:63], vcc_lo offen lds
	s_waitcnt vmcnt(8)
	s_waitcnt lgkmcnt(0)
	s_setprio 1
	s_barrier
	v_mfma_f32_16x16x32_bf16 v[114:117], v[140:143], v[194:197], v[114:117]
	v_mfma_f32_16x16x32_bf16 v[114:117], v[154:157], v[198:201], v[114:117]
	v_mfma_f32_16x16x32_bf16 v[110:113], v[170:173], v[194:197], v[110:113]
	v_mfma_f32_16x16x32_bf16 v[110:113], v[174:177], v[198:201], v[110:113]
	v_mfma_f32_16x16x32_bf16 v[122:125], v[186:189], v[194:197], v[122:125]
	v_mfma_f32_16x16x32_bf16 v[122:125], v[190:193], v[198:201], v[122:125]
	v_mfma_f32_16x16x32_bf16 v[126:129], v[178:181], v[194:197], v[126:129]
	v_mfma_f32_16x16x32_bf16 v[126:129], v[182:185], v[198:201], v[126:129]
	v_mfma_f32_16x16x32_bf16 v[118:121], v[178:181], v[202:205], v[118:121]
	v_mfma_f32_16x16x32_bf16 v[118:121], v[182:185], v[228:231], v[118:121]
	v_mfma_f32_16x16x32_bf16 v[98:101], v[186:189], v[202:205], v[98:101]
	v_mfma_f32_16x16x32_bf16 v[98:101], v[190:193], v[228:231], v[98:101]
	v_mfma_f32_16x16x32_bf16 v[102:105], v[170:173], v[202:205], v[102:105]
	v_mfma_f32_16x16x32_bf16 v[102:105], v[174:177], v[228:231], v[102:105]
	v_mfma_f32_16x16x32_bf16 v[106:109], v[140:143], v[202:205], v[106:109]
	v_mfma_f32_16x16x32_bf16 v[106:109], v[154:157], v[228:231], v[106:109]
	v_mfma_f32_16x16x32_bf16 v[94:97], v[140:143], v[232:235], v[94:97]
	v_mfma_f32_16x16x32_bf16 v[94:97], v[154:157], v[236:239], v[94:97]
	v_mfma_f32_16x16x32_bf16 v[86:89], v[170:173], v[232:235], v[86:89]
	v_mfma_f32_16x16x32_bf16 v[86:89], v[174:177], v[236:239], v[86:89]
	v_mfma_f32_16x16x32_bf16 v[82:85], v[186:189], v[232:235], v[82:85]
	v_mfma_f32_16x16x32_bf16 v[82:85], v[190:193], v[236:239], v[82:85]
	v_mfma_f32_16x16x32_bf16 v[90:93], v[178:181], v[232:235], v[90:93]
	v_mfma_f32_16x16x32_bf16 v[90:93], v[182:185], v[236:239], v[90:93]
	v_mfma_f32_16x16x32_bf16 v[74:77], v[178:181], v[240:243], v[74:77]
	v_mfma_f32_16x16x32_bf16 v[74:77], v[182:185], v[244:247], v[74:77]
	v_mfma_f32_16x16x32_bf16 v[66:69], v[186:189], v[240:243], v[66:69]
	v_mfma_f32_16x16x32_bf16 v[66:69], v[190:193], v[244:247], v[66:69]
	v_mfma_f32_16x16x32_bf16 v[70:73], v[170:173], v[240:243], v[70:73]
	v_mfma_f32_16x16x32_bf16 v[70:73], v[174:177], v[244:247], v[70:73]
	v_mfma_f32_16x16x32_bf16 v[78:81], v[140:143], v[240:243], v[78:81]
	v_mfma_f32_16x16x32_bf16 v[78:81], v[154:157], v[244:247], v[78:81]
	s_barrier
	s_setprio 0
	s_mov_b32 s42, s62
	s_mov_b32 s43, s63
	s_mov_b32 m0, s13
	ds_read_b128 v[194:197], v137 offset:16384
	buffer_load_dwordx4 v133, s[40:43], s96 offen lds
	s_add_i32 s53, s96, 0x80000
	s_mov_b32 m0, s14
	ds_read_b128 v[198:201], v137 offset:17408
	buffer_load_dwordx4 v135, s[40:43], s96 offen lds
	s_mov_b32 m0, s15
	ds_read_b128 v[202:205], v137 offset:18432
	buffer_load_dwordx4 v133, s[40:43], s53 offen lds
	s_mov_b32 m0, s16
	ds_read_b128 v[228:231], v137 offset:19456
	buffer_load_dwordx4 v135, s[40:43], s53 offen lds
	s_mov_b32 m0, s2
	ds_read_b128 v[232:235], v137 offset:20480
	buffer_load_dwordx4 v132, s[60:63], s52 offen lds
	s_mov_b32 m0, s21
	ds_read_b128 v[236:239], v137 offset:21504
	buffer_load_dwordx4 v134, s[60:63], s52 offen lds
	ds_read_b128 v[240:243], v137 offset:22528
	ds_read_b128 v[244:247], v137 offset:23552
	s_waitcnt vmcnt(8)
	s_waitcnt lgkmcnt(0)
	s_setprio 1
	s_barrier
	v_mfma_f32_16x16x32_bf16 v[62:65], v[140:143], v[194:197], v[62:65]
	v_mfma_f32_16x16x32_bf16 v[62:65], v[154:157], v[198:201], v[62:65]
	v_mfma_f32_16x16x32_bf16 v[54:57], v[170:173], v[194:197], v[54:57]
	v_mfma_f32_16x16x32_bf16 v[54:57], v[174:177], v[198:201], v[54:57]
	v_mfma_f32_16x16x32_bf16 v[50:53], v[186:189], v[194:197], v[50:53]
	v_mfma_f32_16x16x32_bf16 v[50:53], v[190:193], v[198:201], v[50:53]
	v_mfma_f32_16x16x32_bf16 v[58:61], v[178:181], v[194:197], v[58:61]
	v_mfma_f32_16x16x32_bf16 v[58:61], v[182:185], v[198:201], v[58:61]
	v_mfma_f32_16x16x32_bf16 v[42:45], v[178:181], v[202:205], v[42:45]
	v_mfma_f32_16x16x32_bf16 v[42:45], v[182:185], v[228:231], v[42:45]
	v_mfma_f32_16x16x32_bf16 v[34:37], v[186:189], v[202:205], v[34:37]
	v_mfma_f32_16x16x32_bf16 v[34:37], v[190:193], v[228:231], v[34:37]
	v_mfma_f32_16x16x32_bf16 v[38:41], v[170:173], v[202:205], v[38:41]
	v_mfma_f32_16x16x32_bf16 v[38:41], v[174:177], v[228:231], v[38:41]
	v_mfma_f32_16x16x32_bf16 v[46:49], v[140:143], v[202:205], v[46:49]
	v_mfma_f32_16x16x32_bf16 v[46:49], v[154:157], v[228:231], v[46:49]
	v_mfma_f32_16x16x32_bf16 v[30:33], v[140:143], v[232:235], v[30:33]
	v_mfma_f32_16x16x32_bf16 v[30:33], v[154:157], v[236:239], v[30:33]
	v_mfma_f32_16x16x32_bf16 v[22:25], v[170:173], v[232:235], v[22:25]
	v_mfma_f32_16x16x32_bf16 v[22:25], v[174:177], v[236:239], v[22:25]
	v_mfma_f32_16x16x32_bf16 v[18:21], v[186:189], v[232:235], v[18:21]
	v_mfma_f32_16x16x32_bf16 v[18:21], v[190:193], v[236:239], v[18:21]
	v_mfma_f32_16x16x32_bf16 v[26:29], v[178:181], v[232:235], v[26:29]
	v_mfma_f32_16x16x32_bf16 v[26:29], v[182:185], v[236:239], v[26:29]
	v_mfma_f32_16x16x32_bf16 v[10:13], v[178:181], v[240:243], v[10:13]
	v_mfma_f32_16x16x32_bf16 v[10:13], v[182:185], v[244:247], v[10:13]
	v_mfma_f32_16x16x32_bf16 v[2:5], v[186:189], v[240:243], v[2:5]
	v_mfma_f32_16x16x32_bf16 v[2:5], v[190:193], v[244:247], v[2:5]
	v_mfma_f32_16x16x32_bf16 v[6:9], v[170:173], v[240:243], v[6:9]
	v_mfma_f32_16x16x32_bf16 v[6:9], v[174:177], v[244:247], v[6:9]
	v_mfma_f32_16x16x32_bf16 v[14:17], v[140:143], v[240:243], v[14:17]
	v_mfma_f32_16x16x32_bf16 v[14:17], v[154:157], v[244:247], v[14:17]
	s_barrier
	s_setprio 0
	v_add_u32_e32 v139, 0x18000, v136
	ds_read_b128 v[140:143], v139
	ds_read_b128 v[154:157], v139 offset:1024
	ds_read_b128 v[170:173], v139 offset:2048
	ds_read_b128 v[174:177], v139 offset:3072
	v_add_u32_e32 v139, 0x1c000, v136
	ds_read_b128 v[178:181], v139
	ds_read_b128 v[182:185], v139 offset:1024
	ds_read_b128 v[186:189], v139 offset:2048
	ds_read_b128 v[190:193], v139 offset:3072
	s_add_i32 s52, s52, 0x80000
	s_mov_b32 m0, s23
	ds_read_b128 v[194:197], v137 offset:32768
	ds_read_b128 v[198:201], v137 offset:33792
	ds_read_b128 v[202:205], v137 offset:34816
	ds_read_b128 v[228:231], v137 offset:35840
	ds_read_b128 v[232:235], v137 offset:36864
	ds_read_b128 v[236:239], v137 offset:37888
	ds_read_b128 v[240:243], v137 offset:38912
	ds_read_b128 v[244:247], v137 offset:39936
	buffer_load_dwordx4 v132, s[60:63], s52 offen lds
	s_mov_b32 m0, s24
	s_nop 0
	buffer_load_dwordx4 v134, s[60:63], s52 offen lds
	s_waitcnt vmcnt(8)
	s_waitcnt lgkmcnt(0)
	s_setprio 1
	s_barrier
	v_mfma_f32_16x16x32_bf16 v[114:117], v[140:143], v[194:197], v[114:117]
	v_mfma_f32_16x16x32_bf16 v[114:117], v[154:157], v[198:201], v[114:117]
	v_mfma_f32_16x16x32_bf16 v[110:113], v[170:173], v[194:197], v[110:113]
	v_mfma_f32_16x16x32_bf16 v[110:113], v[174:177], v[198:201], v[110:113]
	v_mfma_f32_16x16x32_bf16 v[122:125], v[186:189], v[194:197], v[122:125]
	v_mfma_f32_16x16x32_bf16 v[122:125], v[190:193], v[198:201], v[122:125]
	v_mfma_f32_16x16x32_bf16 v[126:129], v[178:181], v[194:197], v[126:129]
	v_mfma_f32_16x16x32_bf16 v[126:129], v[182:185], v[198:201], v[126:129]
	v_mfma_f32_16x16x32_bf16 v[118:121], v[178:181], v[202:205], v[118:121]
	v_mfma_f32_16x16x32_bf16 v[118:121], v[182:185], v[228:231], v[118:121]
	v_mfma_f32_16x16x32_bf16 v[98:101], v[186:189], v[202:205], v[98:101]
	v_mfma_f32_16x16x32_bf16 v[98:101], v[190:193], v[228:231], v[98:101]
	v_mfma_f32_16x16x32_bf16 v[102:105], v[170:173], v[202:205], v[102:105]
	v_mfma_f32_16x16x32_bf16 v[102:105], v[174:177], v[228:231], v[102:105]
	v_mfma_f32_16x16x32_bf16 v[106:109], v[140:143], v[202:205], v[106:109]
	v_mfma_f32_16x16x32_bf16 v[106:109], v[154:157], v[228:231], v[106:109]
	v_mfma_f32_16x16x32_bf16 v[94:97], v[140:143], v[232:235], v[94:97]
	v_mfma_f32_16x16x32_bf16 v[94:97], v[154:157], v[236:239], v[94:97]
	v_mfma_f32_16x16x32_bf16 v[86:89], v[170:173], v[232:235], v[86:89]
	v_mfma_f32_16x16x32_bf16 v[86:89], v[174:177], v[236:239], v[86:89]
	v_mfma_f32_16x16x32_bf16 v[82:85], v[186:189], v[232:235], v[82:85]
	v_mfma_f32_16x16x32_bf16 v[82:85], v[190:193], v[236:239], v[82:85]
	v_mfma_f32_16x16x32_bf16 v[90:93], v[178:181], v[232:235], v[90:93]
	v_mfma_f32_16x16x32_bf16 v[90:93], v[182:185], v[236:239], v[90:93]
	v_mfma_f32_16x16x32_bf16 v[74:77], v[178:181], v[240:243], v[74:77]
	v_mfma_f32_16x16x32_bf16 v[74:77], v[182:185], v[244:247], v[74:77]
	v_mfma_f32_16x16x32_bf16 v[66:69], v[186:189], v[240:243], v[66:69]
	v_mfma_f32_16x16x32_bf16 v[66:69], v[190:193], v[244:247], v[66:69]
	v_mfma_f32_16x16x32_bf16 v[70:73], v[170:173], v[240:243], v[70:73]
	v_mfma_f32_16x16x32_bf16 v[70:73], v[174:177], v[244:247], v[70:73]
	v_mfma_f32_16x16x32_bf16 v[78:81], v[140:143], v[240:243], v[78:81]
	v_mfma_f32_16x16x32_bf16 v[78:81], v[154:157], v[244:247], v[78:81]
	s_barrier
	s_setprio 0
	s_or_b32 s52, s96, 0x80
	s_mov_b32 m0, s31
	ds_read_b128 v[194:197], v137 offset:49152
	buffer_load_dwordx4 v133, s[40:43], s52 offen lds
	s_add_i32 s96, s96, 0x80080
	s_mov_b32 m0, s33
	ds_read_b128 v[198:201], v137 offset:50176
	buffer_load_dwordx4 v135, s[40:43], s52 offen lds
	s_mov_b32 m0, s36
	ds_read_b128 v[202:205], v137 offset:51200
	buffer_load_dwordx4 v133, s[40:43], s96 offen lds
	s_mov_b32 m0, s37
	ds_read_b128 v[228:231], v137 offset:52224
	buffer_load_dwordx4 v135, s[40:43], s96 offen lds
	s_mov_b32 m0, s34
	ds_read_b128 v[232:235], v137 offset:53248
	buffer_load_dwordx4 v132, s[60:63], s95 offen lds
	s_mov_b32 m0, s35
	ds_read_b128 v[236:239], v137 offset:54272
	buffer_load_dwordx4 v134, s[60:63], s95 offen lds
	ds_read_b128 v[240:243], v137 offset:55296
	ds_read_b128 v[244:247], v137 offset:56320
	s_waitcnt vmcnt(8)
	s_waitcnt lgkmcnt(0)
	s_setprio 1
	s_barrier
	v_mfma_f32_16x16x32_bf16 v[62:65], v[140:143], v[194:197], v[62:65]
	v_mfma_f32_16x16x32_bf16 v[62:65], v[154:157], v[198:201], v[62:65]
	v_mfma_f32_16x16x32_bf16 v[54:57], v[170:173], v[194:197], v[54:57]
	v_mfma_f32_16x16x32_bf16 v[54:57], v[174:177], v[198:201], v[54:57]
	v_mfma_f32_16x16x32_bf16 v[50:53], v[186:189], v[194:197], v[50:53]
	v_mfma_f32_16x16x32_bf16 v[50:53], v[190:193], v[198:201], v[50:53]
	v_mfma_f32_16x16x32_bf16 v[58:61], v[178:181], v[194:197], v[58:61]
	v_mfma_f32_16x16x32_bf16 v[58:61], v[182:185], v[198:201], v[58:61]
	v_mfma_f32_16x16x32_bf16 v[42:45], v[178:181], v[202:205], v[42:45]
	v_mfma_f32_16x16x32_bf16 v[42:45], v[182:185], v[228:231], v[42:45]
	v_mfma_f32_16x16x32_bf16 v[34:37], v[186:189], v[202:205], v[34:37]
	v_mfma_f32_16x16x32_bf16 v[34:37], v[190:193], v[228:231], v[34:37]
	v_mfma_f32_16x16x32_bf16 v[38:41], v[170:173], v[202:205], v[38:41]
	v_mfma_f32_16x16x32_bf16 v[38:41], v[174:177], v[228:231], v[38:41]
	v_mfma_f32_16x16x32_bf16 v[46:49], v[140:143], v[202:205], v[46:49]
	v_mfma_f32_16x16x32_bf16 v[46:49], v[154:157], v[228:231], v[46:49]
	v_mfma_f32_16x16x32_bf16 v[30:33], v[140:143], v[232:235], v[30:33]
	v_mfma_f32_16x16x32_bf16 v[30:33], v[154:157], v[236:239], v[30:33]
	v_mfma_f32_16x16x32_bf16 v[22:25], v[170:173], v[232:235], v[22:25]
	v_mfma_f32_16x16x32_bf16 v[22:25], v[174:177], v[236:239], v[22:25]
	v_mfma_f32_16x16x32_bf16 v[18:21], v[186:189], v[232:235], v[18:21]
	v_mfma_f32_16x16x32_bf16 v[18:21], v[190:193], v[236:239], v[18:21]
	v_mfma_f32_16x16x32_bf16 v[26:29], v[178:181], v[232:235], v[26:29]
	v_mfma_f32_16x16x32_bf16 v[26:29], v[182:185], v[236:239], v[26:29]
	v_mfma_f32_16x16x32_bf16 v[10:13], v[178:181], v[240:243], v[10:13]
	v_mfma_f32_16x16x32_bf16 v[10:13], v[182:185], v[244:247], v[10:13]
	v_mfma_f32_16x16x32_bf16 v[2:5], v[186:189], v[240:243], v[2:5]
	v_mfma_f32_16x16x32_bf16 v[2:5], v[190:193], v[244:247], v[2:5]
	v_mfma_f32_16x16x32_bf16 v[6:9], v[170:173], v[240:243], v[6:9]
	v_mfma_f32_16x16x32_bf16 v[6:9], v[174:177], v[244:247], v[6:9]
	v_mfma_f32_16x16x32_bf16 v[14:17], v[140:143], v[240:243], v[14:17]
	v_mfma_f32_16x16x32_bf16 v[14:17], v[154:157], v[244:247], v[14:17]
	s_barrier
	s_setprio 0
	s_add_i32 s94, s94, 2
	s_addk_i32 vcc_lo, 0x100
	s_addk_i32 vcc_hi, 0x100
	s_cmp_gt_u32 s94, 29
	s_cbranch_scc0 .LBB0_1880
	s_and_b64 vcc, exec, s[64:65]
	s_cbranch_vccz .LBB0_1883
	s_barrier

.LBB0_2155:
	s_mul_i32 s49, s48, 0x2c0000
	s_and_b64 s[8:9], s[42:43], exec
	s_mul_i32 s23, s15, 0x2c0000
	s_cselect_b32 s8, s49, s21
	s_cselect_b32 s9, s23, s13
	s_addk_i32 s13, 0x100
	s_add_i32 s21, s21, 0xc000
	s_mov_b32 s22, -2
	s_waitcnt lgkmcnt(0)
	v_add_u32_e32 v170, 0x10000, v140
	v_add_u32_e32 v186, 0x14000, v140
	ds_read_b128 v[132:135], v170
	ds_read_b128 v[142:145], v170 offset:1024
	ds_read_b128 v[154:157], v170 offset:2048
	ds_read_b128 v[170:173], v170 offset:3072
	ds_read_b128 v[174:177], v186
	ds_read_b128 v[178:181], v186 offset:1024
	ds_read_b128 v[182:185], v186 offset:2048
	ds_read_b128 v[186:189], v186 offset:3072
	s_add_i32 s26, s21, 0x4000
	s_cmpk_eq_i32 s22, 0x54
	s_cselect_b32 s52, s8, s26
	s_cselect_b32 s27, s9, s13
	s_or_b32 s26, s52, 0x8000
	s_mov_b32 m0, s84
	ds_read_b128 v[190:193], v141
	ds_read_b128 v[194:197], v141 offset:1024
	ds_read_b128 v[198:201], v141 offset:2048
	ds_read_b128 v[202:205], v141 offset:3072
	ds_read_b128 v[228:231], v141 offset:4096
	ds_read_b128 v[232:235], v141 offset:5120
	ds_read_b128 v[236:239], v141 offset:6144
	ds_read_b128 v[240:243], v141 offset:7168
	buffer_load_dwordx4 v136, s[60:63], s21 offen lds
	s_mov_b32 m0, s16
	s_nop 0
	buffer_load_dwordx4 v138, s[60:63], s21 offen lds
	s_waitcnt vmcnt(8)
	s_waitcnt lgkmcnt(0)
	s_setprio 1
	s_barrier
	v_mfma_f32_16x16x32_bf16 v[126:129], v[132:135], v[190:193], 0
	v_mfma_f32_16x16x32_bf16 v[126:129], v[142:145], v[194:197], v[126:129]
	v_mfma_f32_16x16x32_bf16 v[106:109], v[154:157], v[190:193], 0
	v_mfma_f32_16x16x32_bf16 v[106:109], v[170:173], v[194:197], v[106:109]
	v_mfma_f32_16x16x32_bf16 v[110:113], v[182:185], v[190:193], 0
	v_mfma_f32_16x16x32_bf16 v[110:113], v[186:189], v[194:197], v[110:113]
	v_mfma_f32_16x16x32_bf16 v[122:125], v[174:177], v[190:193], 0
	v_mfma_f32_16x16x32_bf16 v[122:125], v[178:181], v[194:197], v[122:125]
	v_mfma_f32_16x16x32_bf16 v[102:105], v[174:177], v[198:201], 0
	v_mfma_f32_16x16x32_bf16 v[102:105], v[178:181], v[202:205], v[102:105]
	v_mfma_f32_16x16x32_bf16 v[98:101], v[182:185], v[198:201], 0
	v_mfma_f32_16x16x32_bf16 v[98:101], v[186:189], v[202:205], v[98:101]
	v_mfma_f32_16x16x32_bf16 v[114:117], v[154:157], v[198:201], 0
	v_mfma_f32_16x16x32_bf16 v[114:117], v[170:173], v[202:205], v[114:117]
	v_mfma_f32_16x16x32_bf16 v[118:121], v[132:135], v[198:201], 0
	v_mfma_f32_16x16x32_bf16 v[118:121], v[142:145], v[202:205], v[118:121]
	v_mfma_f32_16x16x32_bf16 v[94:97], v[132:135], v[228:231], 0
	v_mfma_f32_16x16x32_bf16 v[94:97], v[142:145], v[232:235], v[94:97]
	v_mfma_f32_16x16x32_bf16 v[90:93], v[154:157], v[228:231], 0
	v_mfma_f32_16x16x32_bf16 v[90:93], v[170:173], v[232:235], v[90:93]
	v_mfma_f32_16x16x32_bf16 v[82:85], v[182:185], v[228:231], 0
	v_mfma_f32_16x16x32_bf16 v[82:85], v[186:189], v[232:235], v[82:85]
	v_mfma_f32_16x16x32_bf16 v[86:89], v[174:177], v[228:231], 0
	v_mfma_f32_16x16x32_bf16 v[86:89], v[178:181], v[232:235], v[86:89]
	v_mfma_f32_16x16x32_bf16 v[70:73], v[174:177], v[236:239], 0
	v_mfma_f32_16x16x32_bf16 v[70:73], v[178:181], v[240:243], v[70:73]
	v_mfma_f32_16x16x32_bf16 v[66:69], v[182:185], v[236:239], 0
	v_mfma_f32_16x16x32_bf16 v[66:69], v[186:189], v[240:243], v[66:69]
	v_mfma_f32_16x16x32_bf16 v[74:77], v[154:157], v[236:239], 0
	v_mfma_f32_16x16x32_bf16 v[74:77], v[170:173], v[240:243], v[74:77]
	v_mfma_f32_16x16x32_bf16 v[78:81], v[132:135], v[236:239], 0
	v_mfma_f32_16x16x32_bf16 v[78:81], v[142:145], v[240:243], v[78:81]
	s_barrier
	s_setprio 0
	s_mov_b32 s46, s62
	s_mov_b32 s47, s63
	s_mov_b32 m0, s18
	ds_read_b128 v[190:193], v141 offset:16384
	buffer_load_dwordx4 v137, s[44:47], s27 offen lds
	s_add_i32 s53, s27, 0x160000
	s_mov_b32 m0, s19
	ds_read_b128 v[194:197], v141 offset:17408
	buffer_load_dwordx4 v139, s[44:47], s27 offen lds
	s_mov_b32 m0, s24
	ds_read_b128 v[198:201], v141 offset:18432
	buffer_load_dwordx4 v137, s[44:47], s53 offen lds
	s_mov_b32 m0, s25
	ds_read_b128 v[202:205], v141 offset:19456
	buffer_load_dwordx4 v139, s[44:47], s53 offen lds
	s_mov_b32 m0, s14
	ds_read_b128 v[228:231], v141 offset:20480
	buffer_load_dwordx4 v136, s[60:63], s52 offen lds
	s_mov_b32 m0, s30
	ds_read_b128 v[232:235], v141 offset:21504
	buffer_load_dwordx4 v138, s[60:63], s52 offen lds
	ds_read_b128 v[236:239], v141 offset:22528
	ds_read_b128 v[240:243], v141 offset:23552
	s_waitcnt vmcnt(8)
	s_waitcnt lgkmcnt(0)
	s_setprio 1
	s_barrier
	v_mfma_f32_16x16x32_bf16 v[62:65], v[132:135], v[190:193], 0
	v_mfma_f32_16x16x32_bf16 v[62:65], v[142:145], v[194:197], v[62:65]
	v_mfma_f32_16x16x32_bf16 v[58:61], v[154:157], v[190:193], 0
	v_mfma_f32_16x16x32_bf16 v[58:61], v[170:173], v[194:197], v[58:61]
	v_mfma_f32_16x16x32_bf16 v[50:53], v[182:185], v[190:193], 0
	v_mfma_f32_16x16x32_bf16 v[50:53], v[186:189], v[194:197], v[50:53]
	v_mfma_f32_16x16x32_bf16 v[54:57], v[174:177], v[190:193], 0
	v_mfma_f32_16x16x32_bf16 v[54:57], v[178:181], v[194:197], v[54:57]
	v_mfma_f32_16x16x32_bf16 v[38:41], v[174:177], v[198:201], 0
	v_mfma_f32_16x16x32_bf16 v[38:41], v[178:181], v[202:205], v[38:41]
	v_mfma_f32_16x16x32_bf16 v[34:37], v[182:185], v[198:201], 0
	v_mfma_f32_16x16x32_bf16 v[34:37], v[186:189], v[202:205], v[34:37]
	v_mfma_f32_16x16x32_bf16 v[42:45], v[154:157], v[198:201], 0
	v_mfma_f32_16x16x32_bf16 v[42:45], v[170:173], v[202:205], v[42:45]
	v_mfma_f32_16x16x32_bf16 v[46:49], v[132:135], v[198:201], 0
	v_mfma_f32_16x16x32_bf16 v[46:49], v[142:145], v[202:205], v[46:49]
	v_mfma_f32_16x16x32_bf16 v[30:33], v[132:135], v[228:231], 0
	v_mfma_f32_16x16x32_bf16 v[30:33], v[142:145], v[232:235], v[30:33]
	v_mfma_f32_16x16x32_bf16 v[26:29], v[154:157], v[228:231], 0
	v_mfma_f32_16x16x32_bf16 v[26:29], v[170:173], v[232:235], v[26:29]
	v_mfma_f32_16x16x32_bf16 v[18:21], v[182:185], v[228:231], 0
	v_mfma_f32_16x16x32_bf16 v[18:21], v[186:189], v[232:235], v[18:21]
	v_mfma_f32_16x16x32_bf16 v[22:25], v[174:177], v[228:231], 0
	v_mfma_f32_16x16x32_bf16 v[22:25], v[178:181], v[232:235], v[22:25]
	v_mfma_f32_16x16x32_bf16 v[6:9], v[174:177], v[236:239], 0
	v_mfma_f32_16x16x32_bf16 v[6:9], v[178:181], v[240:243], v[6:9]
	v_mfma_f32_16x16x32_bf16 v[2:5], v[182:185], v[236:239], 0
	v_mfma_f32_16x16x32_bf16 v[2:5], v[186:189], v[240:243], v[2:5]
	v_mfma_f32_16x16x32_bf16 v[10:13], v[154:157], v[236:239], 0
	v_mfma_f32_16x16x32_bf16 v[10:13], v[170:173], v[240:243], v[10:13]
	v_mfma_f32_16x16x32_bf16 v[14:17], v[132:135], v[236:239], 0
	v_mfma_f32_16x16x32_bf16 v[14:17], v[142:145], v[240:243], v[14:17]
	s_barrier
	s_setprio 0
	v_add_u32_e32 v170, 0x18000, v140
	v_add_u32_e32 v186, 0x1c000, v140
	ds_read_b128 v[132:135], v170
	ds_read_b128 v[142:145], v170 offset:1024
	ds_read_b128 v[154:157], v170 offset:2048
	ds_read_b128 v[170:173], v170 offset:3072
	ds_read_b128 v[174:177], v186
	ds_read_b128 v[178:181], v186 offset:1024
	ds_read_b128 v[182:185], v186 offset:2048
	ds_read_b128 v[186:189], v186 offset:3072
	s_bitset1_b32 s52, 14
	s_mov_b32 m0, s31
	ds_read_b128 v[190:193], v141 offset:32768
	ds_read_b128 v[194:197], v141 offset:33792
	ds_read_b128 v[198:201], v141 offset:34816
	ds_read_b128 v[202:205], v141 offset:35840
	ds_read_b128 v[228:231], v141 offset:36864
	ds_read_b128 v[232:235], v141 offset:37888
	ds_read_b128 v[236:239], v141 offset:38912
	ds_read_b128 v[240:243], v141 offset:39936
	buffer_load_dwordx4 v136, s[60:63], s52 offen lds
	s_mov_b32 m0, s33
	s_nop 0
	buffer_load_dwordx4 v138, s[60:63], s52 offen lds
	s_waitcnt vmcnt(8)
	s_waitcnt lgkmcnt(0)
	s_setprio 1
	s_barrier
	v_mfma_f32_16x16x32_bf16 v[126:129], v[132:135], v[190:193], v[126:129]
	v_mfma_f32_16x16x32_bf16 v[126:129], v[142:145], v[194:197], v[126:129]
	v_mfma_f32_16x16x32_bf16 v[106:109], v[154:157], v[190:193], v[106:109]
	v_mfma_f32_16x16x32_bf16 v[106:109], v[170:173], v[194:197], v[106:109]
	v_mfma_f32_16x16x32_bf16 v[110:113], v[182:185], v[190:193], v[110:113]
	v_mfma_f32_16x16x32_bf16 v[110:113], v[186:189], v[194:197], v[110:113]
	v_mfma_f32_16x16x32_bf16 v[122:125], v[174:177], v[190:193], v[122:125]
	v_mfma_f32_16x16x32_bf16 v[122:125], v[178:181], v[194:197], v[122:125]
	v_mfma_f32_16x16x32_bf16 v[102:105], v[174:177], v[198:201], v[102:105]
	v_mfma_f32_16x16x32_bf16 v[102:105], v[178:181], v[202:205], v[102:105]
	v_mfma_f32_16x16x32_bf16 v[98:101], v[182:185], v[198:201], v[98:101]
	v_mfma_f32_16x16x32_bf16 v[98:101], v[186:189], v[202:205], v[98:101]
	v_mfma_f32_16x16x32_bf16 v[114:117], v[154:157], v[198:201], v[114:117]
	v_mfma_f32_16x16x32_bf16 v[114:117], v[170:173], v[202:205], v[114:117]
	v_mfma_f32_16x16x32_bf16 v[118:121], v[132:135], v[198:201], v[118:121]
	v_mfma_f32_16x16x32_bf16 v[118:121], v[142:145], v[202:205], v[118:121]
	v_mfma_f32_16x16x32_bf16 v[94:97], v[132:135], v[228:231], v[94:97]
	v_mfma_f32_16x16x32_bf16 v[94:97], v[142:145], v[232:235], v[94:97]
	v_mfma_f32_16x16x32_bf16 v[90:93], v[154:157], v[228:231], v[90:93]
	v_mfma_f32_16x16x32_bf16 v[90:93], v[170:173], v[232:235], v[90:93]
	v_mfma_f32_16x16x32_bf16 v[82:85], v[182:185], v[228:231], v[82:85]
	v_mfma_f32_16x16x32_bf16 v[82:85], v[186:189], v[232:235], v[82:85]
	v_mfma_f32_16x16x32_bf16 v[86:89], v[174:177], v[228:231], v[86:89]
	v_mfma_f32_16x16x32_bf16 v[86:89], v[178:181], v[232:235], v[86:89]
	v_mfma_f32_16x16x32_bf16 v[70:73], v[174:177], v[236:239], v[70:73]
	v_mfma_f32_16x16x32_bf16 v[70:73], v[178:181], v[240:243], v[70:73]
	v_mfma_f32_16x16x32_bf16 v[66:69], v[182:185], v[236:239], v[66:69]
	v_mfma_f32_16x16x32_bf16 v[66:69], v[186:189], v[240:243], v[66:69]
	v_mfma_f32_16x16x32_bf16 v[74:77], v[154:157], v[236:239], v[74:77]
	v_mfma_f32_16x16x32_bf16 v[74:77], v[170:173], v[240:243], v[74:77]
	v_mfma_f32_16x16x32_bf16 v[78:81], v[132:135], v[236:239], v[78:81]
	v_mfma_f32_16x16x32_bf16 v[78:81], v[142:145], v[240:243], v[78:81]
	s_barrier
	s_setprio 0
	s_or_b32 s52, s27, 0x80
	s_mov_b32 m0, s68
	ds_read_b128 v[190:193], v141 offset:49152
	buffer_load_dwordx4 v137, s[44:47], s52 offen lds
	s_add_i32 s27, s27, 0x160080
	s_mov_b32 m0, s69
	ds_read_b128 v[194:197], v141 offset:50176
	buffer_load_dwordx4 v139, s[44:47], s52 offen lds
	s_mov_b32 m0, s72
	ds_read_b128 v[198:201], v141 offset:51200
	buffer_load_dwordx4 v137, s[44:47], s27 offen lds
	s_mov_b32 m0, s73
	ds_read_b128 v[202:205], v141 offset:52224
	buffer_load_dwordx4 v139, s[44:47], s27 offen lds
	s_mov_b32 m0, s70
	ds_read_b128 v[228:231], v141 offset:53248
	buffer_load_dwordx4 v136, s[60:63], s26 offen lds
	s_mov_b32 m0, s71
	ds_read_b128 v[232:235], v141 offset:54272
	buffer_load_dwordx4 v138, s[60:63], s26 offen lds
	ds_read_b128 v[236:239], v141 offset:55296
	ds_read_b128 v[240:243], v141 offset:56320
	s_waitcnt vmcnt(8)
	s_waitcnt lgkmcnt(0)
	s_setprio 1
	s_barrier
	v_mfma_f32_16x16x32_bf16 v[62:65], v[132:135], v[190:193], v[62:65]
	v_mfma_f32_16x16x32_bf16 v[62:65], v[142:145], v[194:197], v[62:65]
	v_mfma_f32_16x16x32_bf16 v[58:61], v[154:157], v[190:193], v[58:61]
	v_mfma_f32_16x16x32_bf16 v[58:61], v[170:173], v[194:197], v[58:61]
	v_mfma_f32_16x16x32_bf16 v[50:53], v[182:185], v[190:193], v[50:53]
	v_mfma_f32_16x16x32_bf16 v[50:53], v[186:189], v[194:197], v[50:53]
	v_mfma_f32_16x16x32_bf16 v[54:57], v[174:177], v[190:193], v[54:57]
	v_mfma_f32_16x16x32_bf16 v[54:57], v[178:181], v[194:197], v[54:57]
	v_mfma_f32_16x16x32_bf16 v[38:41], v[174:177], v[198:201], v[38:41]
	v_mfma_f32_16x16x32_bf16 v[38:41], v[178:181], v[202:205], v[38:41]
	v_mfma_f32_16x16x32_bf16 v[34:37], v[182:185], v[198:201], v[34:37]
	v_mfma_f32_16x16x32_bf16 v[34:37], v[186:189], v[202:205], v[34:37]
	v_mfma_f32_16x16x32_bf16 v[42:45], v[154:157], v[198:201], v[42:45]
	v_mfma_f32_16x16x32_bf16 v[42:45], v[170:173], v[202:205], v[42:45]
	v_mfma_f32_16x16x32_bf16 v[46:49], v[132:135], v[198:201], v[46:49]
	v_mfma_f32_16x16x32_bf16 v[46:49], v[142:145], v[202:205], v[46:49]
	v_mfma_f32_16x16x32_bf16 v[30:33], v[132:135], v[228:231], v[30:33]
	v_mfma_f32_16x16x32_bf16 v[30:33], v[142:145], v[232:235], v[30:33]
	v_mfma_f32_16x16x32_bf16 v[26:29], v[154:157], v[228:231], v[26:29]
	v_mfma_f32_16x16x32_bf16 v[26:29], v[170:173], v[232:235], v[26:29]
	v_mfma_f32_16x16x32_bf16 v[18:21], v[182:185], v[228:231], v[18:21]
	v_mfma_f32_16x16x32_bf16 v[18:21], v[186:189], v[232:235], v[18:21]
	v_mfma_f32_16x16x32_bf16 v[22:25], v[174:177], v[228:231], v[22:25]
	v_mfma_f32_16x16x32_bf16 v[22:25], v[178:181], v[232:235], v[22:25]
	v_mfma_f32_16x16x32_bf16 v[6:9], v[174:177], v[236:239], v[6:9]
	v_mfma_f32_16x16x32_bf16 v[6:9], v[178:181], v[240:243], v[6:9]
	v_mfma_f32_16x16x32_bf16 v[2:5], v[182:185], v[236:239], v[2:5]
	v_mfma_f32_16x16x32_bf16 v[2:5], v[186:189], v[240:243], v[2:5]
	v_mfma_f32_16x16x32_bf16 v[10:13], v[154:157], v[236:239], v[10:13]
	v_mfma_f32_16x16x32_bf16 v[10:13], v[170:173], v[240:243], v[10:13]
	v_mfma_f32_16x16x32_bf16 v[14:17], v[132:135], v[236:239], v[14:17]
	v_mfma_f32_16x16x32_bf16 v[14:17], v[142:145], v[240:243], v[14:17]
	s_barrier
	s_setprio 0
	s_addk_i32 s13, 0x100
	s_add_i32 s22, s22, 2
	s_add_i32 s21, s21, 0x10000
	s_cmpk_gt_u32 s22, 0x55
.LBB0_2156:
	v_add_u32_e32 v170, 0x10000, v140
	v_add_u32_e32 v186, 0x14000, v140
	ds_read_b128 v[132:135], v170
	ds_read_b128 v[142:145], v170 offset:1024
	ds_read_b128 v[154:157], v170 offset:2048
	ds_read_b128 v[170:173], v170 offset:3072
	ds_read_b128 v[174:177], v186
	ds_read_b128 v[178:181], v186 offset:1024
	ds_read_b128 v[182:185], v186 offset:2048
	ds_read_b128 v[186:189], v186 offset:3072
	s_add_i32 s26, s21, 0x4000
	s_cmpk_eq_i32 s22, 0x54
	s_cselect_b32 s52, s8, s26
	s_cselect_b32 s27, s9, s13
	s_or_b32 s26, s52, 0x8000
	s_mov_b32 m0, s84
	ds_read_b128 v[190:193], v141
	ds_read_b128 v[194:197], v141 offset:1024
	ds_read_b128 v[198:201], v141 offset:2048
	ds_read_b128 v[202:205], v141 offset:3072
	ds_read_b128 v[228:231], v141 offset:4096
	ds_read_b128 v[232:235], v141 offset:5120
	ds_read_b128 v[236:239], v141 offset:6144
	ds_read_b128 v[240:243], v141 offset:7168
	buffer_load_dwordx4 v136, s[60:63], s21 offen lds
	s_mov_b32 m0, s16
	s_nop 0
	buffer_load_dwordx4 v138, s[60:63], s21 offen lds
	s_waitcnt vmcnt(8)
	s_waitcnt lgkmcnt(0)
	s_setprio 1
	s_barrier
	v_mfma_f32_16x16x32_bf16 v[126:129], v[132:135], v[190:193], v[126:129]
	v_mfma_f32_16x16x32_bf16 v[126:129], v[142:145], v[194:197], v[126:129]
	v_mfma_f32_16x16x32_bf16 v[106:109], v[154:157], v[190:193], v[106:109]
	v_mfma_f32_16x16x32_bf16 v[106:109], v[170:173], v[194:197], v[106:109]
	v_mfma_f32_16x16x32_bf16 v[110:113], v[182:185], v[190:193], v[110:113]
	v_mfma_f32_16x16x32_bf16 v[110:113], v[186:189], v[194:197], v[110:113]
	v_mfma_f32_16x16x32_bf16 v[122:125], v[174:177], v[190:193], v[122:125]
	v_mfma_f32_16x16x32_bf16 v[122:125], v[178:181], v[194:197], v[122:125]
	v_mfma_f32_16x16x32_bf16 v[102:105], v[174:177], v[198:201], v[102:105]
	v_mfma_f32_16x16x32_bf16 v[102:105], v[178:181], v[202:205], v[102:105]
	v_mfma_f32_16x16x32_bf16 v[98:101], v[182:185], v[198:201], v[98:101]
	v_mfma_f32_16x16x32_bf16 v[98:101], v[186:189], v[202:205], v[98:101]
	v_mfma_f32_16x16x32_bf16 v[114:117], v[154:157], v[198:201], v[114:117]
	v_mfma_f32_16x16x32_bf16 v[114:117], v[170:173], v[202:205], v[114:117]
	v_mfma_f32_16x16x32_bf16 v[118:121], v[132:135], v[198:201], v[118:121]
	v_mfma_f32_16x16x32_bf16 v[118:121], v[142:145], v[202:205], v[118:121]
	v_mfma_f32_16x16x32_bf16 v[94:97], v[132:135], v[228:231], v[94:97]
	v_mfma_f32_16x16x32_bf16 v[94:97], v[142:145], v[232:235], v[94:97]
	v_mfma_f32_16x16x32_bf16 v[90:93], v[154:157], v[228:231], v[90:93]
	v_mfma_f32_16x16x32_bf16 v[90:93], v[170:173], v[232:235], v[90:93]
	v_mfma_f32_16x16x32_bf16 v[82:85], v[182:185], v[228:231], v[82:85]
	v_mfma_f32_16x16x32_bf16 v[82:85], v[186:189], v[232:235], v[82:85]
	v_mfma_f32_16x16x32_bf16 v[86:89], v[174:177], v[228:231], v[86:89]
	v_mfma_f32_16x16x32_bf16 v[86:89], v[178:181], v[232:235], v[86:89]
	v_mfma_f32_16x16x32_bf16 v[70:73], v[174:177], v[236:239], v[70:73]
	v_mfma_f32_16x16x32_bf16 v[70:73], v[178:181], v[240:243], v[70:73]
	v_mfma_f32_16x16x32_bf16 v[66:69], v[182:185], v[236:239], v[66:69]
	v_mfma_f32_16x16x32_bf16 v[66:69], v[186:189], v[240:243], v[66:69]
	v_mfma_f32_16x16x32_bf16 v[74:77], v[154:157], v[236:239], v[74:77]
	v_mfma_f32_16x16x32_bf16 v[74:77], v[170:173], v[240:243], v[74:77]
	v_mfma_f32_16x16x32_bf16 v[78:81], v[132:135], v[236:239], v[78:81]
	v_mfma_f32_16x16x32_bf16 v[78:81], v[142:145], v[240:243], v[78:81]
	s_barrier
	s_setprio 0
	s_mov_b32 s46, s62
	s_mov_b32 s47, s63
	s_mov_b32 m0, s18
	ds_read_b128 v[190:193], v141 offset:16384
	buffer_load_dwordx4 v137, s[44:47], s27 offen lds
	s_add_i32 s53, s27, 0x160000
	s_mov_b32 m0, s19
	ds_read_b128 v[194:197], v141 offset:17408
	buffer_load_dwordx4 v139, s[44:47], s27 offen lds
	s_mov_b32 m0, s24
	ds_read_b128 v[198:201], v141 offset:18432
	buffer_load_dwordx4 v137, s[44:47], s53 offen lds
	s_mov_b32 m0, s25
	ds_read_b128 v[202:205], v141 offset:19456
	buffer_load_dwordx4 v139, s[44:47], s53 offen lds
	s_mov_b32 m0, s14
	ds_read_b128 v[228:231], v141 offset:20480
	buffer_load_dwordx4 v136, s[60:63], s52 offen lds
	s_mov_b32 m0, s30
	ds_read_b128 v[232:235], v141 offset:21504
	buffer_load_dwordx4 v138, s[60:63], s52 offen lds
	ds_read_b128 v[236:239], v141 offset:22528
	ds_read_b128 v[240:243], v141 offset:23552
	s_waitcnt vmcnt(8)
	s_waitcnt lgkmcnt(0)
	s_setprio 1
	s_barrier
	v_mfma_f32_16x16x32_bf16 v[62:65], v[132:135], v[190:193], v[62:65]
	v_mfma_f32_16x16x32_bf16 v[62:65], v[142:145], v[194:197], v[62:65]
	v_mfma_f32_16x16x32_bf16 v[58:61], v[154:157], v[190:193], v[58:61]
	v_mfma_f32_16x16x32_bf16 v[58:61], v[170:173], v[194:197], v[58:61]
	v_mfma_f32_16x16x32_bf16 v[50:53], v[182:185], v[190:193], v[50:53]
	v_mfma_f32_16x16x32_bf16 v[50:53], v[186:189], v[194:197], v[50:53]
	v_mfma_f32_16x16x32_bf16 v[54:57], v[174:177], v[190:193], v[54:57]
	v_mfma_f32_16x16x32_bf16 v[54:57], v[178:181], v[194:197], v[54:57]
	v_mfma_f32_16x16x32_bf16 v[38:41], v[174:177], v[198:201], v[38:41]
	v_mfma_f32_16x16x32_bf16 v[38:41], v[178:181], v[202:205], v[38:41]
	v_mfma_f32_16x16x32_bf16 v[34:37], v[182:185], v[198:201], v[34:37]
	v_mfma_f32_16x16x32_bf16 v[34:37], v[186:189], v[202:205], v[34:37]
	v_mfma_f32_16x16x32_bf16 v[42:45], v[154:157], v[198:201], v[42:45]
	v_mfma_f32_16x16x32_bf16 v[42:45], v[170:173], v[202:205], v[42:45]
	v_mfma_f32_16x16x32_bf16 v[46:49], v[132:135], v[198:201], v[46:49]
	v_mfma_f32_16x16x32_bf16 v[46:49], v[142:145], v[202:205], v[46:49]
	v_mfma_f32_16x16x32_bf16 v[30:33], v[132:135], v[228:231], v[30:33]
	v_mfma_f32_16x16x32_bf16 v[30:33], v[142:145], v[232:235], v[30:33]
	v_mfma_f32_16x16x32_bf16 v[26:29], v[154:157], v[228:231], v[26:29]
	v_mfma_f32_16x16x32_bf16 v[26:29], v[170:173], v[232:235], v[26:29]
	v_mfma_f32_16x16x32_bf16 v[18:21], v[182:185], v[228:231], v[18:21]
	v_mfma_f32_16x16x32_bf16 v[18:21], v[186:189], v[232:235], v[18:21]
	v_mfma_f32_16x16x32_bf16 v[22:25], v[174:177], v[228:231], v[22:25]
	v_mfma_f32_16x16x32_bf16 v[22:25], v[178:181], v[232:235], v[22:25]
	v_mfma_f32_16x16x32_bf16 v[6:9], v[174:177], v[236:239], v[6:9]
	v_mfma_f32_16x16x32_bf16 v[6:9], v[178:181], v[240:243], v[6:9]
	v_mfma_f32_16x16x32_bf16 v[2:5], v[182:185], v[236:239], v[2:5]
	v_mfma_f32_16x16x32_bf16 v[2:5], v[186:189], v[240:243], v[2:5]
	v_mfma_f32_16x16x32_bf16 v[10:13], v[154:157], v[236:239], v[10:13]
	v_mfma_f32_16x16x32_bf16 v[10:13], v[170:173], v[240:243], v[10:13]
	v_mfma_f32_16x16x32_bf16 v[14:17], v[132:135], v[236:239], v[14:17]
	v_mfma_f32_16x16x32_bf16 v[14:17], v[142:145], v[240:243], v[14:17]
	s_barrier
	s_setprio 0
	v_add_u32_e32 v170, 0x18000, v140
	v_add_u32_e32 v186, 0x1c000, v140
	ds_read_b128 v[132:135], v170
	ds_read_b128 v[142:145], v170 offset:1024
	ds_read_b128 v[154:157], v170 offset:2048
	ds_read_b128 v[170:173], v170 offset:3072
	ds_read_b128 v[174:177], v186
	ds_read_b128 v[178:181], v186 offset:1024
	ds_read_b128 v[182:185], v186 offset:2048
	ds_read_b128 v[186:189], v186 offset:3072
	s_bitset1_b32 s52, 14
	s_mov_b32 m0, s31
	ds_read_b128 v[190:193], v141 offset:32768
	ds_read_b128 v[194:197], v141 offset:33792
	ds_read_b128 v[198:201], v141 offset:34816
	ds_read_b128 v[202:205], v141 offset:35840
	ds_read_b128 v[228:231], v141 offset:36864
	ds_read_b128 v[232:235], v141 offset:37888
	ds_read_b128 v[236:239], v141 offset:38912
	ds_read_b128 v[240:243], v141 offset:39936
	buffer_load_dwordx4 v136, s[60:63], s52 offen lds
	s_mov_b32 m0, s33
	s_nop 0
	buffer_load_dwordx4 v138, s[60:63], s52 offen lds
	s_waitcnt vmcnt(8)
	s_waitcnt lgkmcnt(0)
	s_setprio 1
	s_barrier
	v_mfma_f32_16x16x32_bf16 v[126:129], v[132:135], v[190:193], v[126:129]
	v_mfma_f32_16x16x32_bf16 v[126:129], v[142:145], v[194:197], v[126:129]
	v_mfma_f32_16x16x32_bf16 v[106:109], v[154:157], v[190:193], v[106:109]
	v_mfma_f32_16x16x32_bf16 v[106:109], v[170:173], v[194:197], v[106:109]
	v_mfma_f32_16x16x32_bf16 v[110:113], v[182:185], v[190:193], v[110:113]
	v_mfma_f32_16x16x32_bf16 v[110:113], v[186:189], v[194:197], v[110:113]
	v_mfma_f32_16x16x32_bf16 v[122:125], v[174:177], v[190:193], v[122:125]
	v_mfma_f32_16x16x32_bf16 v[122:125], v[178:181], v[194:197], v[122:125]
	v_mfma_f32_16x16x32_bf16 v[102:105], v[174:177], v[198:201], v[102:105]
	v_mfma_f32_16x16x32_bf16 v[102:105], v[178:181], v[202:205], v[102:105]
	v_mfma_f32_16x16x32_bf16 v[98:101], v[182:185], v[198:201], v[98:101]
	v_mfma_f32_16x16x32_bf16 v[98:101], v[186:189], v[202:205], v[98:101]
	v_mfma_f32_16x16x32_bf16 v[114:117], v[154:157], v[198:201], v[114:117]
	v_mfma_f32_16x16x32_bf16 v[114:117], v[170:173], v[202:205], v[114:117]
	v_mfma_f32_16x16x32_bf16 v[118:121], v[132:135], v[198:201], v[118:121]
	v_mfma_f32_16x16x32_bf16 v[118:121], v[142:145], v[202:205], v[118:121]
	v_mfma_f32_16x16x32_bf16 v[94:97], v[132:135], v[228:231], v[94:97]
	v_mfma_f32_16x16x32_bf16 v[94:97], v[142:145], v[232:235], v[94:97]
	v_mfma_f32_16x16x32_bf16 v[90:93], v[154:157], v[228:231], v[90:93]
	v_mfma_f32_16x16x32_bf16 v[90:93], v[170:173], v[232:235], v[90:93]
	v_mfma_f32_16x16x32_bf16 v[82:85], v[182:185], v[228:231], v[82:85]
	v_mfma_f32_16x16x32_bf16 v[82:85], v[186:189], v[232:235], v[82:85]
	v_mfma_f32_16x16x32_bf16 v[86:89], v[174:177], v[228:231], v[86:89]
	v_mfma_f32_16x16x32_bf16 v[86:89], v[178:181], v[232:235], v[86:89]
	v_mfma_f32_16x16x32_bf16 v[70:73], v[174:177], v[236:239], v[70:73]
	v_mfma_f32_16x16x32_bf16 v[70:73], v[178:181], v[240:243], v[70:73]
	v_mfma_f32_16x16x32_bf16 v[66:69], v[182:185], v[236:239], v[66:69]
	v_mfma_f32_16x16x32_bf16 v[66:69], v[186:189], v[240:243], v[66:69]
	v_mfma_f32_16x16x32_bf16 v[74:77], v[154:157], v[236:239], v[74:77]
	v_mfma_f32_16x16x32_bf16 v[74:77], v[170:173], v[240:243], v[74:77]
	v_mfma_f32_16x16x32_bf16 v[78:81], v[132:135], v[236:239], v[78:81]
	v_mfma_f32_16x16x32_bf16 v[78:81], v[142:145], v[240:243], v[78:81]
	s_barrier
	s_setprio 0
	s_or_b32 s52, s27, 0x80
	s_mov_b32 m0, s68
	ds_read_b128 v[190:193], v141 offset:49152
	buffer_load_dwordx4 v137, s[44:47], s52 offen lds
	s_add_i32 s27, s27, 0x160080
	s_mov_b32 m0, s69
	ds_read_b128 v[194:197], v141 offset:50176
	buffer_load_dwordx4 v139, s[44:47], s52 offen lds
	s_mov_b32 m0, s72
	ds_read_b128 v[198:201], v141 offset:51200
	buffer_load_dwordx4 v137, s[44:47], s27 offen lds
	s_mov_b32 m0, s73
	ds_read_b128 v[202:205], v141 offset:52224
	buffer_load_dwordx4 v139, s[44:47], s27 offen lds
	s_mov_b32 m0, s70
	ds_read_b128 v[228:231], v141 offset:53248
	buffer_load_dwordx4 v136, s[60:63], s26 offen lds
	s_mov_b32 m0, s71
	ds_read_b128 v[232:235], v141 offset:54272
	buffer_load_dwordx4 v138, s[60:63], s26 offen lds
	ds_read_b128 v[236:239], v141 offset:55296
	ds_read_b128 v[240:243], v141 offset:56320
	s_waitcnt vmcnt(8)
	s_waitcnt lgkmcnt(0)
	s_setprio 1
	s_barrier
	v_mfma_f32_16x16x32_bf16 v[62:65], v[132:135], v[190:193], v[62:65]
	v_mfma_f32_16x16x32_bf16 v[62:65], v[142:145], v[194:197], v[62:65]
	v_mfma_f32_16x16x32_bf16 v[58:61], v[154:157], v[190:193], v[58:61]
	v_mfma_f32_16x16x32_bf16 v[58:61], v[170:173], v[194:197], v[58:61]
	v_mfma_f32_16x16x32_bf16 v[50:53], v[182:185], v[190:193], v[50:53]
	v_mfma_f32_16x16x32_bf16 v[50:53], v[186:189], v[194:197], v[50:53]
	v_mfma_f32_16x16x32_bf16 v[54:57], v[174:177], v[190:193], v[54:57]
	v_mfma_f32_16x16x32_bf16 v[54:57], v[178:181], v[194:197], v[54:57]
	v_mfma_f32_16x16x32_bf16 v[38:41], v[174:177], v[198:201], v[38:41]
	v_mfma_f32_16x16x32_bf16 v[38:41], v[178:181], v[202:205], v[38:41]
	v_mfma_f32_16x16x32_bf16 v[34:37], v[182:185], v[198:201], v[34:37]
	v_mfma_f32_16x16x32_bf16 v[34:37], v[186:189], v[202:205], v[34:37]
	v_mfma_f32_16x16x32_bf16 v[42:45], v[154:157], v[198:201], v[42:45]
	v_mfma_f32_16x16x32_bf16 v[42:45], v[170:173], v[202:205], v[42:45]
	v_mfma_f32_16x16x32_bf16 v[46:49], v[132:135], v[198:201], v[46:49]
	v_mfma_f32_16x16x32_bf16 v[46:49], v[142:145], v[202:205], v[46:49]
	v_mfma_f32_16x16x32_bf16 v[30:33], v[132:135], v[228:231], v[30:33]
	v_mfma_f32_16x16x32_bf16 v[30:33], v[142:145], v[232:235], v[30:33]
	v_mfma_f32_16x16x32_bf16 v[26:29], v[154:157], v[228:231], v[26:29]
	v_mfma_f32_16x16x32_bf16 v[26:29], v[170:173], v[232:235], v[26:29]
	v_mfma_f32_16x16x32_bf16 v[18:21], v[182:185], v[228:231], v[18:21]
	v_mfma_f32_16x16x32_bf16 v[18:21], v[186:189], v[232:235], v[18:21]
	v_mfma_f32_16x16x32_bf16 v[22:25], v[174:177], v[228:231], v[22:25]
	v_mfma_f32_16x16x32_bf16 v[22:25], v[178:181], v[232:235], v[22:25]
	v_mfma_f32_16x16x32_bf16 v[6:9], v[174:177], v[236:239], v[6:9]
	v_mfma_f32_16x16x32_bf16 v[6:9], v[178:181], v[240:243], v[6:9]
	v_mfma_f32_16x16x32_bf16 v[2:5], v[182:185], v[236:239], v[2:5]
	v_mfma_f32_16x16x32_bf16 v[2:5], v[186:189], v[240:243], v[2:5]
	v_mfma_f32_16x16x32_bf16 v[10:13], v[154:157], v[236:239], v[10:13]
	v_mfma_f32_16x16x32_bf16 v[10:13], v[170:173], v[240:243], v[10:13]
	v_mfma_f32_16x16x32_bf16 v[14:17], v[132:135], v[236:239], v[14:17]
	v_mfma_f32_16x16x32_bf16 v[14:17], v[142:145], v[240:243], v[14:17]
	s_barrier
	s_setprio 0
	s_addk_i32 s13, 0x100
	s_add_i32 s22, s22, 2
	s_add_i32 s21, s21, 0x10000
	s_cmpk_gt_u32 s22, 0x55
	s_cbranch_scc0 .LBB0_2156
	s_and_b64 vcc, exec, s[66:67]
	s_cbranch_vccz .LBB0_2159
	s_barrier

.LBB0_2173:
	v_mov_b32_e32 v125, 0
	s_mul_i32 s69, s68, s12
	s_mul_i32 s70, s67, s12
	s_andn2_b64 vcc, exec, s[34:35]
	v_mov_b32_e32 v124, v125
	v_mov_b32_e32 v123, v125
	v_mov_b32_e32 v122, v125
	v_mov_b32_e32 v129, v125
	v_mov_b32_e32 v128, v125
	v_mov_b32_e32 v127, v125
	v_mov_b32_e32 v126, v125
	v_mov_b32_e32 v113, v125
	v_mov_b32_e32 v112, v125
	v_mov_b32_e32 v111, v125
	v_mov_b32_e32 v110, v125
	v_mov_b32_e32 v109, v125
	v_mov_b32_e32 v108, v125
	v_mov_b32_e32 v107, v125
	v_mov_b32_e32 v106, v125
	v_mov_b32_e32 v97, v125
	v_mov_b32_e32 v96, v125
	v_mov_b32_e32 v95, v125
	v_mov_b32_e32 v94, v125
	v_mov_b32_e32 v93, v125
	v_mov_b32_e32 v92, v125
	v_mov_b32_e32 v91, v125
	v_mov_b32_e32 v90, v125
	v_mov_b32_e32 v81, v125
	v_mov_b32_e32 v80, v125
	v_mov_b32_e32 v79, v125
	v_mov_b32_e32 v78, v125
	v_mov_b32_e32 v77, v125
	v_mov_b32_e32 v76, v125
	v_mov_b32_e32 v75, v125
	v_mov_b32_e32 v74, v125
	v_mov_b32_e32 v121, v125
	v_mov_b32_e32 v120, v125
	v_mov_b32_e32 v119, v125
	v_mov_b32_e32 v118, v125
	v_mov_b32_e32 v117, v125
	v_mov_b32_e32 v116, v125
	v_mov_b32_e32 v115, v125
	v_mov_b32_e32 v114, v125
	v_mov_b32_e32 v105, v125
	v_mov_b32_e32 v104, v125
	v_mov_b32_e32 v103, v125
	v_mov_b32_e32 v102, v125
	v_mov_b32_e32 v101, v125
	v_mov_b32_e32 v100, v125
	v_mov_b32_e32 v99, v125
	v_mov_b32_e32 v98, v125
	v_mov_b32_e32 v89, v125
	v_mov_b32_e32 v88, v125
	v_mov_b32_e32 v87, v125
	v_mov_b32_e32 v86, v125
	v_mov_b32_e32 v85, v125
	v_mov_b32_e32 v84, v125
	v_mov_b32_e32 v83, v125
	v_mov_b32_e32 v82, v125
	v_mov_b32_e32 v73, v125
	v_mov_b32_e32 v72, v125
	v_mov_b32_e32 v71, v125
	v_mov_b32_e32 v70, v125
	v_mov_b32_e32 v69, v125
	v_mov_b32_e32 v68, v125
	v_mov_b32_e32 v67, v125
	v_mov_b32_e32 v66, v125
	v_mov_b32_e32 v65, v125
	v_mov_b32_e32 v64, v125
	v_mov_b32_e32 v63, v125
	v_mov_b32_e32 v62, v125
	v_mov_b32_e32 v61, v125
	v_mov_b32_e32 v60, v125
	v_mov_b32_e32 v59, v125
	v_mov_b32_e32 v58, v125
	v_mov_b32_e32 v49, v125
	v_mov_b32_e32 v48, v125
	v_mov_b32_e32 v47, v125
	v_mov_b32_e32 v46, v125
	v_mov_b32_e32 v45, v125
	v_mov_b32_e32 v44, v125
	v_mov_b32_e32 v43, v125
	v_mov_b32_e32 v42, v125
	v_mov_b32_e32 v33, v125
	v_mov_b32_e32 v32, v125
	v_mov_b32_e32 v31, v125
	v_mov_b32_e32 v30, v125
	v_mov_b32_e32 v29, v125
	v_mov_b32_e32 v28, v125
	v_mov_b32_e32 v27, v125
	v_mov_b32_e32 v26, v125
	v_mov_b32_e32 v17, v125
	v_mov_b32_e32 v16, v125
	v_mov_b32_e32 v15, v125
	v_mov_b32_e32 v14, v125
	v_mov_b32_e32 v13, v125
	v_mov_b32_e32 v12, v125
	v_mov_b32_e32 v11, v125
	v_mov_b32_e32 v10, v125
	v_mov_b32_e32 v57, v125
	v_mov_b32_e32 v56, v125
	v_mov_b32_e32 v55, v125
	v_mov_b32_e32 v54, v125
	v_mov_b32_e32 v53, v125
	v_mov_b32_e32 v52, v125
	v_mov_b32_e32 v51, v125
	v_mov_b32_e32 v50, v125
	v_mov_b32_e32 v41, v125
	v_mov_b32_e32 v40, v125
	v_mov_b32_e32 v39, v125
	v_mov_b32_e32 v38, v125
	v_mov_b32_e32 v37, v125
	v_mov_b32_e32 v36, v125
	v_mov_b32_e32 v35, v125
	v_mov_b32_e32 v34, v125
	v_mov_b32_e32 v25, v125
	v_mov_b32_e32 v24, v125
	v_mov_b32_e32 v23, v125
	v_mov_b32_e32 v22, v125
	v_mov_b32_e32 v21, v125
	v_mov_b32_e32 v20, v125
	v_mov_b32_e32 v19, v125
	v_mov_b32_e32 v18, v125
	v_mov_b32_e32 v9, v125
	v_mov_b32_e32 v8, v125
	v_mov_b32_e32 v7, v125
	v_mov_b32_e32 v6, v125
	v_mov_b32_e32 v5, v125
	v_mov_b32_e32 v4, v125
	v_mov_b32_e32 v3, v125
	v_mov_b32_e32 v2, v125
	s_cbranch_vccnz .LBB0_2177
	s_and_b64 s[8:9], s[40:41], exec
	s_cselect_b32 s8, s69, s73
	s_cselect_b32 s9, s70, s82
	s_addk_i32 s73, 0x80
	s_addk_i32 s82, 0x100
	s_mov_b32 s83, 0
	v_add_u32_e32 v144, 0x10000, v134
	ds_read_b128 v[136:139], v144
	ds_read_b128 v[140:143], v144 offset:1024
	ds_read_b128 v[154:157], v144 offset:2048
	ds_read_b128 v[170:173], v144 offset:3072
	v_add_u32_e32 v144, 0x14000, v134
	ds_read_b128 v[174:177], v144
	ds_read_b128 v[178:181], v144 offset:1024
	ds_read_b128 v[182:185], v144 offset:2048
	ds_read_b128 v[186:189], v144 offset:3072
	s_add_i32 s46, s73, 0x80
	s_cmp_eq_u32 s49, s83
	s_cselect_b32 s52, s8, s46
	s_cselect_b32 s85, s9, s82
	s_add_i32 s84, s52, 0x80
	s_add_i32 s46, s2, s73
	s_mov_b32 m0, s64
	ds_read_b128 v[190:193], v135
	ds_read_b128 v[194:197], v135 offset:1024
	ds_read_b128 v[198:201], v135 offset:2048
	ds_read_b128 v[202:205], v135 offset:3072
	ds_read_b128 v[228:231], v135 offset:4096
	ds_read_b128 v[232:235], v135 offset:5120
	ds_read_b128 v[236:239], v135 offset:6144
	ds_read_b128 v[240:243], v135 offset:7168
	buffer_load_dwordx4 v130, s[60:63], s46 offen lds
	s_mov_b32 m0, s65
	s_nop 0
	buffer_load_dwordx4 v132, s[60:63], s46 offen lds
	s_waitcnt vmcnt(8)
	s_waitcnt lgkmcnt(0)
	s_setprio 1
	s_barrier
	v_mfma_f32_16x16x32_bf16 v[122:125], v[136:139], v[190:193], 0
	v_mfma_f32_16x16x32_bf16 v[122:125], v[140:143], v[194:197], v[122:125]
	v_mfma_f32_16x16x32_bf16 v[126:129], v[154:157], v[190:193], 0
	v_mfma_f32_16x16x32_bf16 v[126:129], v[170:173], v[194:197], v[126:129]
	v_mfma_f32_16x16x32_bf16 v[114:117], v[182:185], v[190:193], 0
	v_mfma_f32_16x16x32_bf16 v[114:117], v[186:189], v[194:197], v[114:117]
	v_mfma_f32_16x16x32_bf16 v[118:121], v[174:177], v[190:193], 0
	v_mfma_f32_16x16x32_bf16 v[118:121], v[178:181], v[194:197], v[118:121]
	v_mfma_f32_16x16x32_bf16 v[102:105], v[174:177], v[198:201], 0
	v_mfma_f32_16x16x32_bf16 v[102:105], v[178:181], v[202:205], v[102:105]
	v_mfma_f32_16x16x32_bf16 v[98:101], v[182:185], v[198:201], 0
	v_mfma_f32_16x16x32_bf16 v[98:101], v[186:189], v[202:205], v[98:101]
	v_mfma_f32_16x16x32_bf16 v[106:109], v[154:157], v[198:201], 0
	v_mfma_f32_16x16x32_bf16 v[106:109], v[170:173], v[202:205], v[106:109]
	v_mfma_f32_16x16x32_bf16 v[110:113], v[136:139], v[198:201], 0
	v_mfma_f32_16x16x32_bf16 v[110:113], v[140:143], v[202:205], v[110:113]
	v_mfma_f32_16x16x32_bf16 v[94:97], v[136:139], v[228:231], 0
	v_mfma_f32_16x16x32_bf16 v[94:97], v[140:143], v[232:235], v[94:97]
	v_mfma_f32_16x16x32_bf16 v[90:93], v[154:157], v[228:231], 0
	v_mfma_f32_16x16x32_bf16 v[90:93], v[170:173], v[232:235], v[90:93]
	v_mfma_f32_16x16x32_bf16 v[82:85], v[182:185], v[228:231], 0
	v_mfma_f32_16x16x32_bf16 v[82:85], v[186:189], v[232:235], v[82:85]
	v_mfma_f32_16x16x32_bf16 v[86:89], v[174:177], v[228:231], 0
	v_mfma_f32_16x16x32_bf16 v[86:89], v[178:181], v[232:235], v[86:89]
	v_mfma_f32_16x16x32_bf16 v[70:73], v[174:177], v[236:239], 0
	v_mfma_f32_16x16x32_bf16 v[70:73], v[178:181], v[240:243], v[70:73]
	v_mfma_f32_16x16x32_bf16 v[66:69], v[182:185], v[236:239], 0
	v_mfma_f32_16x16x32_bf16 v[66:69], v[186:189], v[240:243], v[66:69]
	v_mfma_f32_16x16x32_bf16 v[74:77], v[154:157], v[236:239], 0
	v_mfma_f32_16x16x32_bf16 v[74:77], v[170:173], v[240:243], v[74:77]
	v_mfma_f32_16x16x32_bf16 v[78:81], v[136:139], v[236:239], 0
	v_mfma_f32_16x16x32_bf16 v[78:81], v[140:143], v[240:243], v[78:81]
	s_barrier
	s_setprio 0
	s_mov_b32 s46, s62
	s_mov_b32 s47, s63
	s_mov_b32 m0, s14
	ds_read_b128 v[190:193], v135 offset:16384
	buffer_load_dwordx4 v131, s[44:47], s85 offen lds
	s_add_i32 s53, s85, s2
	s_mov_b32 m0, s15
	ds_read_b128 v[194:197], v135 offset:17408
	buffer_load_dwordx4 v133, s[44:47], s85 offen lds
	s_mov_b32 m0, s16
	ds_read_b128 v[198:201], v135 offset:18432
	buffer_load_dwordx4 v131, s[44:47], s53 offen lds
	s_mov_b32 m0, s18
	ds_read_b128 v[202:205], v135 offset:19456
	buffer_load_dwordx4 v133, s[44:47], s53 offen lds
	s_mov_b32 m0, s13
	ds_read_b128 v[228:231], v135 offset:20480
	buffer_load_dwordx4 v130, s[60:63], s52 offen lds
	s_mov_b32 m0, s19
	ds_read_b128 v[232:235], v135 offset:21504
	buffer_load_dwordx4 v132, s[60:63], s52 offen lds
	ds_read_b128 v[236:239], v135 offset:22528
	ds_read_b128 v[240:243], v135 offset:23552
	s_waitcnt vmcnt(8)
	s_waitcnt lgkmcnt(0)
	s_setprio 1
	s_barrier
	v_mfma_f32_16x16x32_bf16 v[62:65], v[136:139], v[190:193], 0
	v_mfma_f32_16x16x32_bf16 v[62:65], v[140:143], v[194:197], v[62:65]
	v_mfma_f32_16x16x32_bf16 v[58:61], v[154:157], v[190:193], 0
	v_mfma_f32_16x16x32_bf16 v[58:61], v[170:173], v[194:197], v[58:61]
	v_mfma_f32_16x16x32_bf16 v[50:53], v[182:185], v[190:193], 0
	v_mfma_f32_16x16x32_bf16 v[50:53], v[186:189], v[194:197], v[50:53]
	v_mfma_f32_16x16x32_bf16 v[54:57], v[174:177], v[190:193], 0
	v_mfma_f32_16x16x32_bf16 v[54:57], v[178:181], v[194:197], v[54:57]
	v_mfma_f32_16x16x32_bf16 v[38:41], v[174:177], v[198:201], 0
	v_mfma_f32_16x16x32_bf16 v[38:41], v[178:181], v[202:205], v[38:41]
	v_mfma_f32_16x16x32_bf16 v[34:37], v[182:185], v[198:201], 0
	v_mfma_f32_16x16x32_bf16 v[34:37], v[186:189], v[202:205], v[34:37]
	v_mfma_f32_16x16x32_bf16 v[42:45], v[154:157], v[198:201], 0
	v_mfma_f32_16x16x32_bf16 v[42:45], v[170:173], v[202:205], v[42:45]
	v_mfma_f32_16x16x32_bf16 v[46:49], v[136:139], v[198:201], 0
	v_mfma_f32_16x16x32_bf16 v[46:49], v[140:143], v[202:205], v[46:49]
	v_mfma_f32_16x16x32_bf16 v[30:33], v[136:139], v[228:231], 0
	v_mfma_f32_16x16x32_bf16 v[30:33], v[140:143], v[232:235], v[30:33]
	v_mfma_f32_16x16x32_bf16 v[26:29], v[154:157], v[228:231], 0
	v_mfma_f32_16x16x32_bf16 v[26:29], v[170:173], v[232:235], v[26:29]
	v_mfma_f32_16x16x32_bf16 v[18:21], v[182:185], v[228:231], 0
	v_mfma_f32_16x16x32_bf16 v[18:21], v[186:189], v[232:235], v[18:21]
	v_mfma_f32_16x16x32_bf16 v[22:25], v[174:177], v[228:231], 0
	v_mfma_f32_16x16x32_bf16 v[22:25], v[178:181], v[232:235], v[22:25]
	v_mfma_f32_16x16x32_bf16 v[6:9], v[174:177], v[236:239], 0
	v_mfma_f32_16x16x32_bf16 v[6:9], v[178:181], v[240:243], v[6:9]
	v_mfma_f32_16x16x32_bf16 v[2:5], v[182:185], v[236:239], 0
	v_mfma_f32_16x16x32_bf16 v[2:5], v[186:189], v[240:243], v[2:5]
	v_mfma_f32_16x16x32_bf16 v[10:13], v[154:157], v[236:239], 0
	v_mfma_f32_16x16x32_bf16 v[10:13], v[170:173], v[240:243], v[10:13]
	v_mfma_f32_16x16x32_bf16 v[14:17], v[136:139], v[236:239], 0
	v_mfma_f32_16x16x32_bf16 v[14:17], v[140:143], v[240:243], v[14:17]
	s_barrier
	s_setprio 0
	v_add_u32_e32 v144, 0x18000, v134
	ds_read_b128 v[136:139], v144
	ds_read_b128 v[140:143], v144 offset:1024
	ds_read_b128 v[154:157], v144 offset:2048
	ds_read_b128 v[170:173], v144 offset:3072
	v_add_u32_e32 v144, 0x1c000, v134
	ds_read_b128 v[174:177], v144
	ds_read_b128 v[178:181], v144 offset:1024
	ds_read_b128 v[182:185], v144 offset:2048
	ds_read_b128 v[186:189], v144 offset:3072
	s_add_i32 s52, s52, s2
	s_mov_b32 m0, s21
	ds_read_b128 v[190:193], v135 offset:32768
	ds_read_b128 v[194:197], v135 offset:33792
	ds_read_b128 v[198:201], v135 offset:34816
	ds_read_b128 v[202:205], v135 offset:35840
	ds_read_b128 v[228:231], v135 offset:36864
	ds_read_b128 v[232:235], v135 offset:37888
	ds_read_b128 v[236:239], v135 offset:38912
	ds_read_b128 v[240:243], v135 offset:39936
	buffer_load_dwordx4 v130, s[60:63], s52 offen lds
	s_mov_b32 m0, s22
	s_nop 0
	buffer_load_dwordx4 v132, s[60:63], s52 offen lds
	s_waitcnt vmcnt(8)
	s_waitcnt lgkmcnt(0)
	s_setprio 1
	s_barrier
	v_mfma_f32_16x16x32_bf16 v[122:125], v[136:139], v[190:193], v[122:125]
	v_mfma_f32_16x16x32_bf16 v[122:125], v[140:143], v[194:197], v[122:125]
	v_mfma_f32_16x16x32_bf16 v[126:129], v[154:157], v[190:193], v[126:129]
	v_mfma_f32_16x16x32_bf16 v[126:129], v[170:173], v[194:197], v[126:129]
	v_mfma_f32_16x16x32_bf16 v[114:117], v[182:185], v[190:193], v[114:117]
	v_mfma_f32_16x16x32_bf16 v[114:117], v[186:189], v[194:197], v[114:117]
	v_mfma_f32_16x16x32_bf16 v[118:121], v[174:177], v[190:193], v[118:121]
	v_mfma_f32_16x16x32_bf16 v[118:121], v[178:181], v[194:197], v[118:121]
	v_mfma_f32_16x16x32_bf16 v[102:105], v[174:177], v[198:201], v[102:105]
	v_mfma_f32_16x16x32_bf16 v[102:105], v[178:181], v[202:205], v[102:105]
	v_mfma_f32_16x16x32_bf16 v[98:101], v[182:185], v[198:201], v[98:101]
	v_mfma_f32_16x16x32_bf16 v[98:101], v[186:189], v[202:205], v[98:101]
	v_mfma_f32_16x16x32_bf16 v[106:109], v[154:157], v[198:201], v[106:109]
	v_mfma_f32_16x16x32_bf16 v[106:109], v[170:173], v[202:205], v[106:109]
	v_mfma_f32_16x16x32_bf16 v[110:113], v[136:139], v[198:201], v[110:113]
	v_mfma_f32_16x16x32_bf16 v[110:113], v[140:143], v[202:205], v[110:113]
	v_mfma_f32_16x16x32_bf16 v[94:97], v[136:139], v[228:231], v[94:97]
	v_mfma_f32_16x16x32_bf16 v[94:97], v[140:143], v[232:235], v[94:97]
	v_mfma_f32_16x16x32_bf16 v[90:93], v[154:157], v[228:231], v[90:93]
	v_mfma_f32_16x16x32_bf16 v[90:93], v[170:173], v[232:235], v[90:93]
	v_mfma_f32_16x16x32_bf16 v[82:85], v[182:185], v[228:231], v[82:85]
	v_mfma_f32_16x16x32_bf16 v[82:85], v[186:189], v[232:235], v[82:85]
	v_mfma_f32_16x16x32_bf16 v[86:89], v[174:177], v[228:231], v[86:89]
	v_mfma_f32_16x16x32_bf16 v[86:89], v[178:181], v[232:235], v[86:89]
	v_mfma_f32_16x16x32_bf16 v[70:73], v[174:177], v[236:239], v[70:73]
	v_mfma_f32_16x16x32_bf16 v[70:73], v[178:181], v[240:243], v[70:73]
	v_mfma_f32_16x16x32_bf16 v[66:69], v[182:185], v[236:239], v[66:69]
	v_mfma_f32_16x16x32_bf16 v[66:69], v[186:189], v[240:243], v[66:69]
	v_mfma_f32_16x16x32_bf16 v[74:77], v[154:157], v[236:239], v[74:77]
	v_mfma_f32_16x16x32_bf16 v[74:77], v[170:173], v[240:243], v[74:77]
	v_mfma_f32_16x16x32_bf16 v[78:81], v[136:139], v[236:239], v[78:81]
	v_mfma_f32_16x16x32_bf16 v[78:81], v[140:143], v[240:243], v[78:81]
	s_barrier
	s_setprio 0
	s_add_i32 s52, s85, 0x80
	s_mov_b32 m0, s33
	ds_read_b128 v[190:193], v135 offset:49152
	buffer_load_dwordx4 v131, s[44:47], s52 offen lds
	s_mov_b32 m0, s36
	ds_read_b128 v[194:197], v135 offset:50176
	buffer_load_dwordx4 v133, s[44:47], s52 offen lds
	s_add_i32 s52, s52, s2
	s_mov_b32 m0, s43
	ds_read_b128 v[198:201], v135 offset:51200
	buffer_load_dwordx4 v131, s[44:47], s52 offen lds
	s_mov_b32 m0, s48
	ds_read_b128 v[202:205], v135 offset:52224
	buffer_load_dwordx4 v133, s[44:47], s52 offen lds
	s_mov_b32 m0, s37
	ds_read_b128 v[228:231], v135 offset:53248
	buffer_load_dwordx4 v130, s[60:63], s84 offen lds
	s_mov_b32 m0, s42
	ds_read_b128 v[232:235], v135 offset:54272
	buffer_load_dwordx4 v132, s[60:63], s84 offen lds
	ds_read_b128 v[236:239], v135 offset:55296
	ds_read_b128 v[240:243], v135 offset:56320
	s_waitcnt vmcnt(8)
	s_waitcnt lgkmcnt(0)
	s_setprio 1
	s_barrier
	v_mfma_f32_16x16x32_bf16 v[62:65], v[136:139], v[190:193], v[62:65]
	v_mfma_f32_16x16x32_bf16 v[62:65], v[140:143], v[194:197], v[62:65]
	v_mfma_f32_16x16x32_bf16 v[58:61], v[154:157], v[190:193], v[58:61]
	v_mfma_f32_16x16x32_bf16 v[58:61], v[170:173], v[194:197], v[58:61]
	v_mfma_f32_16x16x32_bf16 v[50:53], v[182:185], v[190:193], v[50:53]
	v_mfma_f32_16x16x32_bf16 v[50:53], v[186:189], v[194:197], v[50:53]
	v_mfma_f32_16x16x32_bf16 v[54:57], v[174:177], v[190:193], v[54:57]
	v_mfma_f32_16x16x32_bf16 v[54:57], v[178:181], v[194:197], v[54:57]
	v_mfma_f32_16x16x32_bf16 v[38:41], v[174:177], v[198:201], v[38:41]
	v_mfma_f32_16x16x32_bf16 v[38:41], v[178:181], v[202:205], v[38:41]
	v_mfma_f32_16x16x32_bf16 v[34:37], v[182:185], v[198:201], v[34:37]
	v_mfma_f32_16x16x32_bf16 v[34:37], v[186:189], v[202:205], v[34:37]
	v_mfma_f32_16x16x32_bf16 v[42:45], v[154:157], v[198:201], v[42:45]
	v_mfma_f32_16x16x32_bf16 v[42:45], v[170:173], v[202:205], v[42:45]
	v_mfma_f32_16x16x32_bf16 v[46:49], v[136:139], v[198:201], v[46:49]
	v_mfma_f32_16x16x32_bf16 v[46:49], v[140:143], v[202:205], v[46:49]
	v_mfma_f32_16x16x32_bf16 v[30:33], v[136:139], v[228:231], v[30:33]
	v_mfma_f32_16x16x32_bf16 v[30:33], v[140:143], v[232:235], v[30:33]
	v_mfma_f32_16x16x32_bf16 v[26:29], v[154:157], v[228:231], v[26:29]
	v_mfma_f32_16x16x32_bf16 v[26:29], v[170:173], v[232:235], v[26:29]
	v_mfma_f32_16x16x32_bf16 v[18:21], v[182:185], v[228:231], v[18:21]
	v_mfma_f32_16x16x32_bf16 v[18:21], v[186:189], v[232:235], v[18:21]
	v_mfma_f32_16x16x32_bf16 v[22:25], v[174:177], v[228:231], v[22:25]
	v_mfma_f32_16x16x32_bf16 v[22:25], v[178:181], v[232:235], v[22:25]
	v_mfma_f32_16x16x32_bf16 v[6:9], v[174:177], v[236:239], v[6:9]
	v_mfma_f32_16x16x32_bf16 v[6:9], v[178:181], v[240:243], v[6:9]
	v_mfma_f32_16x16x32_bf16 v[2:5], v[182:185], v[236:239], v[2:5]
	v_mfma_f32_16x16x32_bf16 v[2:5], v[186:189], v[240:243], v[2:5]
	v_mfma_f32_16x16x32_bf16 v[10:13], v[154:157], v[236:239], v[10:13]
	v_mfma_f32_16x16x32_bf16 v[10:13], v[170:173], v[240:243], v[10:13]
	v_mfma_f32_16x16x32_bf16 v[14:17], v[136:139], v[236:239], v[14:17]
	v_mfma_f32_16x16x32_bf16 v[14:17], v[140:143], v[240:243], v[14:17]
	s_barrier
	s_setprio 0
	s_add_i32 s83, s83, 2
	s_addk_i32 s73, 0x100
	s_addk_i32 s82, 0x100
	s_cmp_ge_i32 s83, s23
.LBB0_2175:
	v_add_u32_e32 v144, 0x10000, v134
	ds_read_b128 v[136:139], v144
	ds_read_b128 v[140:143], v144 offset:1024
	ds_read_b128 v[154:157], v144 offset:2048
	ds_read_b128 v[170:173], v144 offset:3072
	v_add_u32_e32 v144, 0x14000, v134
	ds_read_b128 v[174:177], v144
	ds_read_b128 v[178:181], v144 offset:1024
	ds_read_b128 v[182:185], v144 offset:2048
	ds_read_b128 v[186:189], v144 offset:3072
	s_add_i32 s46, s73, 0x80
	s_cmp_eq_u32 s49, s83
	s_cselect_b32 s52, s8, s46
	s_cselect_b32 s85, s9, s82
	s_add_i32 s84, s52, 0x80
	s_add_i32 s46, s2, s73
	s_mov_b32 m0, s64
	ds_read_b128 v[190:193], v135
	ds_read_b128 v[194:197], v135 offset:1024
	ds_read_b128 v[198:201], v135 offset:2048
	ds_read_b128 v[202:205], v135 offset:3072
	ds_read_b128 v[228:231], v135 offset:4096
	ds_read_b128 v[232:235], v135 offset:5120
	ds_read_b128 v[236:239], v135 offset:6144
	ds_read_b128 v[240:243], v135 offset:7168
	buffer_load_dwordx4 v130, s[60:63], s46 offen lds
	s_mov_b32 m0, s65
	s_nop 0
	buffer_load_dwordx4 v132, s[60:63], s46 offen lds
	s_waitcnt vmcnt(8)
	s_waitcnt lgkmcnt(0)
	s_setprio 1
	s_barrier
	v_mfma_f32_16x16x32_bf16 v[122:125], v[136:139], v[190:193], v[122:125]
	v_mfma_f32_16x16x32_bf16 v[122:125], v[140:143], v[194:197], v[122:125]
	v_mfma_f32_16x16x32_bf16 v[126:129], v[154:157], v[190:193], v[126:129]
	v_mfma_f32_16x16x32_bf16 v[126:129], v[170:173], v[194:197], v[126:129]
	v_mfma_f32_16x16x32_bf16 v[114:117], v[182:185], v[190:193], v[114:117]
	v_mfma_f32_16x16x32_bf16 v[114:117], v[186:189], v[194:197], v[114:117]
	v_mfma_f32_16x16x32_bf16 v[118:121], v[174:177], v[190:193], v[118:121]
	v_mfma_f32_16x16x32_bf16 v[118:121], v[178:181], v[194:197], v[118:121]
	v_mfma_f32_16x16x32_bf16 v[102:105], v[174:177], v[198:201], v[102:105]
	v_mfma_f32_16x16x32_bf16 v[102:105], v[178:181], v[202:205], v[102:105]
	v_mfma_f32_16x16x32_bf16 v[98:101], v[182:185], v[198:201], v[98:101]
	v_mfma_f32_16x16x32_bf16 v[98:101], v[186:189], v[202:205], v[98:101]
	v_mfma_f32_16x16x32_bf16 v[106:109], v[154:157], v[198:201], v[106:109]
	v_mfma_f32_16x16x32_bf16 v[106:109], v[170:173], v[202:205], v[106:109]
	v_mfma_f32_16x16x32_bf16 v[110:113], v[136:139], v[198:201], v[110:113]
	v_mfma_f32_16x16x32_bf16 v[110:113], v[140:143], v[202:205], v[110:113]
	v_mfma_f32_16x16x32_bf16 v[94:97], v[136:139], v[228:231], v[94:97]
	v_mfma_f32_16x16x32_bf16 v[94:97], v[140:143], v[232:235], v[94:97]
	v_mfma_f32_16x16x32_bf16 v[90:93], v[154:157], v[228:231], v[90:93]
	v_mfma_f32_16x16x32_bf16 v[90:93], v[170:173], v[232:235], v[90:93]
	v_mfma_f32_16x16x32_bf16 v[82:85], v[182:185], v[228:231], v[82:85]
	v_mfma_f32_16x16x32_bf16 v[82:85], v[186:189], v[232:235], v[82:85]
	v_mfma_f32_16x16x32_bf16 v[86:89], v[174:177], v[228:231], v[86:89]
	v_mfma_f32_16x16x32_bf16 v[86:89], v[178:181], v[232:235], v[86:89]
	v_mfma_f32_16x16x32_bf16 v[70:73], v[174:177], v[236:239], v[70:73]
	v_mfma_f32_16x16x32_bf16 v[70:73], v[178:181], v[240:243], v[70:73]
	v_mfma_f32_16x16x32_bf16 v[66:69], v[182:185], v[236:239], v[66:69]
	v_mfma_f32_16x16x32_bf16 v[66:69], v[186:189], v[240:243], v[66:69]
	v_mfma_f32_16x16x32_bf16 v[74:77], v[154:157], v[236:239], v[74:77]
	v_mfma_f32_16x16x32_bf16 v[74:77], v[170:173], v[240:243], v[74:77]
	v_mfma_f32_16x16x32_bf16 v[78:81], v[136:139], v[236:239], v[78:81]
	v_mfma_f32_16x16x32_bf16 v[78:81], v[140:143], v[240:243], v[78:81]
	s_barrier
	s_setprio 0
	s_mov_b32 s46, s62
	s_mov_b32 s47, s63
	s_mov_b32 m0, s14
	ds_read_b128 v[190:193], v135 offset:16384
	buffer_load_dwordx4 v131, s[44:47], s85 offen lds
	s_add_i32 s53, s85, s2
	s_mov_b32 m0, s15
	ds_read_b128 v[194:197], v135 offset:17408
	buffer_load_dwordx4 v133, s[44:47], s85 offen lds
	s_mov_b32 m0, s16
	ds_read_b128 v[198:201], v135 offset:18432
	buffer_load_dwordx4 v131, s[44:47], s53 offen lds
	s_mov_b32 m0, s18
	ds_read_b128 v[202:205], v135 offset:19456
	buffer_load_dwordx4 v133, s[44:47], s53 offen lds
	s_mov_b32 m0, s13
	ds_read_b128 v[228:231], v135 offset:20480
	buffer_load_dwordx4 v130, s[60:63], s52 offen lds
	s_mov_b32 m0, s19
	ds_read_b128 v[232:235], v135 offset:21504
	buffer_load_dwordx4 v132, s[60:63], s52 offen lds
	ds_read_b128 v[236:239], v135 offset:22528
	ds_read_b128 v[240:243], v135 offset:23552
	s_waitcnt vmcnt(8)
	s_waitcnt lgkmcnt(0)
	s_setprio 1
	s_barrier
	v_mfma_f32_16x16x32_bf16 v[62:65], v[136:139], v[190:193], v[62:65]
	v_mfma_f32_16x16x32_bf16 v[62:65], v[140:143], v[194:197], v[62:65]
	v_mfma_f32_16x16x32_bf16 v[58:61], v[154:157], v[190:193], v[58:61]
	v_mfma_f32_16x16x32_bf16 v[58:61], v[170:173], v[194:197], v[58:61]
	v_mfma_f32_16x16x32_bf16 v[50:53], v[182:185], v[190:193], v[50:53]
	v_mfma_f32_16x16x32_bf16 v[50:53], v[186:189], v[194:197], v[50:53]
	v_mfma_f32_16x16x32_bf16 v[54:57], v[174:177], v[190:193], v[54:57]
	v_mfma_f32_16x16x32_bf16 v[54:57], v[178:181], v[194:197], v[54:57]
	v_mfma_f32_16x16x32_bf16 v[38:41], v[174:177], v[198:201], v[38:41]
	v_mfma_f32_16x16x32_bf16 v[38:41], v[178:181], v[202:205], v[38:41]
	v_mfma_f32_16x16x32_bf16 v[34:37], v[182:185], v[198:201], v[34:37]
	v_mfma_f32_16x16x32_bf16 v[34:37], v[186:189], v[202:205], v[34:37]
	v_mfma_f32_16x16x32_bf16 v[42:45], v[154:157], v[198:201], v[42:45]
	v_mfma_f32_16x16x32_bf16 v[42:45], v[170:173], v[202:205], v[42:45]
	v_mfma_f32_16x16x32_bf16 v[46:49], v[136:139], v[198:201], v[46:49]
	v_mfma_f32_16x16x32_bf16 v[46:49], v[140:143], v[202:205], v[46:49]
	v_mfma_f32_16x16x32_bf16 v[30:33], v[136:139], v[228:231], v[30:33]
	v_mfma_f32_16x16x32_bf16 v[30:33], v[140:143], v[232:235], v[30:33]
	v_mfma_f32_16x16x32_bf16 v[26:29], v[154:157], v[228:231], v[26:29]
	v_mfma_f32_16x16x32_bf16 v[26:29], v[170:173], v[232:235], v[26:29]
	v_mfma_f32_16x16x32_bf16 v[18:21], v[182:185], v[228:231], v[18:21]
	v_mfma_f32_16x16x32_bf16 v[18:21], v[186:189], v[232:235], v[18:21]
	v_mfma_f32_16x16x32_bf16 v[22:25], v[174:177], v[228:231], v[22:25]
	v_mfma_f32_16x16x32_bf16 v[22:25], v[178:181], v[232:235], v[22:25]
	v_mfma_f32_16x16x32_bf16 v[6:9], v[174:177], v[236:239], v[6:9]
	v_mfma_f32_16x16x32_bf16 v[6:9], v[178:181], v[240:243], v[6:9]
	v_mfma_f32_16x16x32_bf16 v[2:5], v[182:185], v[236:239], v[2:5]
	v_mfma_f32_16x16x32_bf16 v[2:5], v[186:189], v[240:243], v[2:5]
	v_mfma_f32_16x16x32_bf16 v[10:13], v[154:157], v[236:239], v[10:13]
	v_mfma_f32_16x16x32_bf16 v[10:13], v[170:173], v[240:243], v[10:13]
	v_mfma_f32_16x16x32_bf16 v[14:17], v[136:139], v[236:239], v[14:17]
	v_mfma_f32_16x16x32_bf16 v[14:17], v[140:143], v[240:243], v[14:17]
	s_barrier
	s_setprio 0
	v_add_u32_e32 v144, 0x18000, v134
	ds_read_b128 v[136:139], v144
	ds_read_b128 v[140:143], v144 offset:1024
	ds_read_b128 v[154:157], v144 offset:2048
	ds_read_b128 v[170:173], v144 offset:3072
	v_add_u32_e32 v144, 0x1c000, v134
	ds_read_b128 v[174:177], v144
	ds_read_b128 v[178:181], v144 offset:1024
	ds_read_b128 v[182:185], v144 offset:2048
	ds_read_b128 v[186:189], v144 offset:3072
	s_add_i32 s52, s52, s2
	s_mov_b32 m0, s21
	ds_read_b128 v[190:193], v135 offset:32768
	ds_read_b128 v[194:197], v135 offset:33792
	ds_read_b128 v[198:201], v135 offset:34816
	ds_read_b128 v[202:205], v135 offset:35840
	ds_read_b128 v[228:231], v135 offset:36864
	ds_read_b128 v[232:235], v135 offset:37888
	ds_read_b128 v[236:239], v135 offset:38912
	ds_read_b128 v[240:243], v135 offset:39936
	buffer_load_dwordx4 v130, s[60:63], s52 offen lds
	s_mov_b32 m0, s22
	s_nop 0
	buffer_load_dwordx4 v132, s[60:63], s52 offen lds
	s_waitcnt vmcnt(8)
	s_waitcnt lgkmcnt(0)
	s_setprio 1
	s_barrier
	v_mfma_f32_16x16x32_bf16 v[122:125], v[136:139], v[190:193], v[122:125]
	v_mfma_f32_16x16x32_bf16 v[122:125], v[140:143], v[194:197], v[122:125]
	v_mfma_f32_16x16x32_bf16 v[126:129], v[154:157], v[190:193], v[126:129]
	v_mfma_f32_16x16x32_bf16 v[126:129], v[170:173], v[194:197], v[126:129]
	v_mfma_f32_16x16x32_bf16 v[114:117], v[182:185], v[190:193], v[114:117]
	v_mfma_f32_16x16x32_bf16 v[114:117], v[186:189], v[194:197], v[114:117]
	v_mfma_f32_16x16x32_bf16 v[118:121], v[174:177], v[190:193], v[118:121]
	v_mfma_f32_16x16x32_bf16 v[118:121], v[178:181], v[194:197], v[118:121]
	v_mfma_f32_16x16x32_bf16 v[102:105], v[174:177], v[198:201], v[102:105]
	v_mfma_f32_16x16x32_bf16 v[102:105], v[178:181], v[202:205], v[102:105]
	v_mfma_f32_16x16x32_bf16 v[98:101], v[182:185], v[198:201], v[98:101]
	v_mfma_f32_16x16x32_bf16 v[98:101], v[186:189], v[202:205], v[98:101]
	v_mfma_f32_16x16x32_bf16 v[106:109], v[154:157], v[198:201], v[106:109]
	v_mfma_f32_16x16x32_bf16 v[106:109], v[170:173], v[202:205], v[106:109]
	v_mfma_f32_16x16x32_bf16 v[110:113], v[136:139], v[198:201], v[110:113]
	v_mfma_f32_16x16x32_bf16 v[110:113], v[140:143], v[202:205], v[110:113]
	v_mfma_f32_16x16x32_bf16 v[94:97], v[136:139], v[228:231], v[94:97]
	v_mfma_f32_16x16x32_bf16 v[94:97], v[140:143], v[232:235], v[94:97]
	v_mfma_f32_16x16x32_bf16 v[90:93], v[154:157], v[228:231], v[90:93]
	v_mfma_f32_16x16x32_bf16 v[90:93], v[170:173], v[232:235], v[90:93]
	v_mfma_f32_16x16x32_bf16 v[82:85], v[182:185], v[228:231], v[82:85]
	v_mfma_f32_16x16x32_bf16 v[82:85], v[186:189], v[232:235], v[82:85]
	v_mfma_f32_16x16x32_bf16 v[86:89], v[174:177], v[228:231], v[86:89]
	v_mfma_f32_16x16x32_bf16 v[86:89], v[178:181], v[232:235], v[86:89]
	v_mfma_f32_16x16x32_bf16 v[70:73], v[174:177], v[236:239], v[70:73]
	v_mfma_f32_16x16x32_bf16 v[70:73], v[178:181], v[240:243], v[70:73]
	v_mfma_f32_16x16x32_bf16 v[66:69], v[182:185], v[236:239], v[66:69]
	v_mfma_f32_16x16x32_bf16 v[66:69], v[186:189], v[240:243], v[66:69]
	v_mfma_f32_16x16x32_bf16 v[74:77], v[154:157], v[236:239], v[74:77]
	v_mfma_f32_16x16x32_bf16 v[74:77], v[170:173], v[240:243], v[74:77]
	v_mfma_f32_16x16x32_bf16 v[78:81], v[136:139], v[236:239], v[78:81]
	v_mfma_f32_16x16x32_bf16 v[78:81], v[140:143], v[240:243], v[78:81]
	s_barrier
	s_setprio 0
	s_add_i32 s52, s85, 0x80
	s_mov_b32 m0, s33
	ds_read_b128 v[190:193], v135 offset:49152
	buffer_load_dwordx4 v131, s[44:47], s52 offen lds
	s_mov_b32 m0, s36
	ds_read_b128 v[194:197], v135 offset:50176
	buffer_load_dwordx4 v133, s[44:47], s52 offen lds
	s_add_i32 s52, s52, s2
	s_mov_b32 m0, s43
	ds_read_b128 v[198:201], v135 offset:51200
	buffer_load_dwordx4 v131, s[44:47], s52 offen lds
	s_mov_b32 m0, s48
	ds_read_b128 v[202:205], v135 offset:52224
	buffer_load_dwordx4 v133, s[44:47], s52 offen lds
	s_mov_b32 m0, s37
	ds_read_b128 v[228:231], v135 offset:53248
	buffer_load_dwordx4 v130, s[60:63], s84 offen lds
	s_mov_b32 m0, s42
	ds_read_b128 v[232:235], v135 offset:54272
	buffer_load_dwordx4 v132, s[60:63], s84 offen lds
	ds_read_b128 v[236:239], v135 offset:55296
	ds_read_b128 v[240:243], v135 offset:56320
	s_waitcnt vmcnt(8)
	s_waitcnt lgkmcnt(0)
	s_setprio 1
	s_barrier
	v_mfma_f32_16x16x32_bf16 v[62:65], v[136:139], v[190:193], v[62:65]
	v_mfma_f32_16x16x32_bf16 v[62:65], v[140:143], v[194:197], v[62:65]
	v_mfma_f32_16x16x32_bf16 v[58:61], v[154:157], v[190:193], v[58:61]
	v_mfma_f32_16x16x32_bf16 v[58:61], v[170:173], v[194:197], v[58:61]
	v_mfma_f32_16x16x32_bf16 v[50:53], v[182:185], v[190:193], v[50:53]
	v_mfma_f32_16x16x32_bf16 v[50:53], v[186:189], v[194:197], v[50:53]
	v_mfma_f32_16x16x32_bf16 v[54:57], v[174:177], v[190:193], v[54:57]
	v_mfma_f32_16x16x32_bf16 v[54:57], v[178:181], v[194:197], v[54:57]
	v_mfma_f32_16x16x32_bf16 v[38:41], v[174:177], v[198:201], v[38:41]
	v_mfma_f32_16x16x32_bf16 v[38:41], v[178:181], v[202:205], v[38:41]
	v_mfma_f32_16x16x32_bf16 v[34:37], v[182:185], v[198:201], v[34:37]
	v_mfma_f32_16x16x32_bf16 v[34:37], v[186:189], v[202:205], v[34:37]
	v_mfma_f32_16x16x32_bf16 v[42:45], v[154:157], v[198:201], v[42:45]
	v_mfma_f32_16x16x32_bf16 v[42:45], v[170:173], v[202:205], v[42:45]
	v_mfma_f32_16x16x32_bf16 v[46:49], v[136:139], v[198:201], v[46:49]
	v_mfma_f32_16x16x32_bf16 v[46:49], v[140:143], v[202:205], v[46:49]
	v_mfma_f32_16x16x32_bf16 v[30:33], v[136:139], v[228:231], v[30:33]
	v_mfma_f32_16x16x32_bf16 v[30:33], v[140:143], v[232:235], v[30:33]
	v_mfma_f32_16x16x32_bf16 v[26:29], v[154:157], v[228:231], v[26:29]
	v_mfma_f32_16x16x32_bf16 v[26:29], v[170:173], v[232:235], v[26:29]
	v_mfma_f32_16x16x32_bf16 v[18:21], v[182:185], v[228:231], v[18:21]
	v_mfma_f32_16x16x32_bf16 v[18:21], v[186:189], v[232:235], v[18:21]
	v_mfma_f32_16x16x32_bf16 v[22:25], v[174:177], v[228:231], v[22:25]
	v_mfma_f32_16x16x32_bf16 v[22:25], v[178:181], v[232:235], v[22:25]
	v_mfma_f32_16x16x32_bf16 v[6:9], v[174:177], v[236:239], v[6:9]
	v_mfma_f32_16x16x32_bf16 v[6:9], v[178:181], v[240:243], v[6:9]
	v_mfma_f32_16x16x32_bf16 v[2:5], v[182:185], v[236:239], v[2:5]
	v_mfma_f32_16x16x32_bf16 v[2:5], v[186:189], v[240:243], v[2:5]
	v_mfma_f32_16x16x32_bf16 v[10:13], v[154:157], v[236:239], v[10:13]
	v_mfma_f32_16x16x32_bf16 v[10:13], v[170:173], v[240:243], v[10:13]
	v_mfma_f32_16x16x32_bf16 v[14:17], v[136:139], v[236:239], v[14:17]
	v_mfma_f32_16x16x32_bf16 v[14:17], v[140:143], v[240:243], v[14:17]
	s_barrier
	s_setprio 0
	s_add_i32 s83, s83, 2
	s_addk_i32 s73, 0x100
	s_addk_i32 s82, 0x100
	s_cmp_ge_i32 s83, s23
	s_cbranch_scc0 .LBB0_2175
	v_readlane_b32 s83, v252, 30

.LBB0_2449:
	s_lshl_b32 s73, s72, 20
	s_and_b64 s[8:9], s[40:41], exec
	s_cselect_b32 s8, s73, s13
	s_lshl_b32 s84, s71, 20
	s_and_b64 s[24:25], s[40:41], exec
	s_cselect_b32 s9, s84, s21
	s_add_i32 s13, s13, 0x80080
	s_addk_i32 s21, 0x100
	s_mov_b32 s22, -2
	s_waitcnt lgkmcnt(0)
	v_add_u32_e32 v142, 0x10000, v188
	v_add_u32_e32 v182, 0x14000, v188
	ds_read_b128 v[130:133], v142
	ds_read_b128 v[134:137], v142 offset:1024
	ds_read_b128 v[138:141], v142 offset:2048
	ds_read_b128 v[142:145], v142 offset:3072
	ds_read_b128 v[154:157], v182
	ds_read_b128 v[174:177], v182 offset:1024
	ds_read_b128 v[178:181], v182 offset:2048
	ds_read_b128 v[190:193], v182 offset:3072
	s_add_i32 s24, s13, 0xfff80080
	s_cmp_eq_u32 s22, 28
	s_cselect_b32 s52, s8, s24
	s_cselect_b32 s25, s9, s21
	s_or_b32 s24, s52, 0x80
	s_mov_b32 m0, s68
	ds_read_b128 v[194:197], v189
	ds_read_b128 v[198:201], v189 offset:1024
	ds_read_b128 v[202:205], v189 offset:2048
	ds_read_b128 v[228:231], v189 offset:3072
	ds_read_b128 v[232:235], v189 offset:4096
	ds_read_b128 v[236:239], v189 offset:5120
	ds_read_b128 v[240:243], v189 offset:6144
	ds_read_b128 v[244:247], v189 offset:7168
	buffer_load_dwordx4 v184, s[60:63], s13 offen lds
	s_mov_b32 m0, s70
	s_nop 0
	buffer_load_dwordx4 v186, s[60:63], s13 offen lds
	s_waitcnt vmcnt(8)
	s_waitcnt lgkmcnt(0)
	s_setprio 1
	s_barrier
	v_mfma_f32_16x16x32_bf16 v[126:129], v[130:133], v[194:197], 0
	v_mfma_f32_16x16x32_bf16 v[126:129], v[134:137], v[198:201], v[126:129]
	v_mfma_f32_16x16x32_bf16 v[122:125], v[138:141], v[194:197], 0
	v_mfma_f32_16x16x32_bf16 v[122:125], v[142:145], v[198:201], v[122:125]
	v_mfma_f32_16x16x32_bf16 v[114:117], v[178:181], v[194:197], 0
	v_mfma_f32_16x16x32_bf16 v[114:117], v[190:193], v[198:201], v[114:117]
	v_mfma_f32_16x16x32_bf16 v[118:121], v[154:157], v[194:197], 0
	v_mfma_f32_16x16x32_bf16 v[118:121], v[174:177], v[198:201], v[118:121]
	v_mfma_f32_16x16x32_bf16 v[102:105], v[154:157], v[202:205], 0
	v_mfma_f32_16x16x32_bf16 v[102:105], v[174:177], v[228:231], v[102:105]
	v_mfma_f32_16x16x32_bf16 v[98:101], v[178:181], v[202:205], 0
	v_mfma_f32_16x16x32_bf16 v[98:101], v[190:193], v[228:231], v[98:101]
	v_mfma_f32_16x16x32_bf16 v[106:109], v[138:141], v[202:205], 0
	v_mfma_f32_16x16x32_bf16 v[106:109], v[142:145], v[228:231], v[106:109]
	v_mfma_f32_16x16x32_bf16 v[110:113], v[130:133], v[202:205], 0
	v_mfma_f32_16x16x32_bf16 v[110:113], v[134:137], v[228:231], v[110:113]
	v_mfma_f32_16x16x32_bf16 v[94:97], v[130:133], v[232:235], 0
	v_mfma_f32_16x16x32_bf16 v[94:97], v[134:137], v[236:239], v[94:97]
	v_mfma_f32_16x16x32_bf16 v[90:93], v[138:141], v[232:235], 0
	v_mfma_f32_16x16x32_bf16 v[90:93], v[142:145], v[236:239], v[90:93]
	v_mfma_f32_16x16x32_bf16 v[82:85], v[178:181], v[232:235], 0
	v_mfma_f32_16x16x32_bf16 v[82:85], v[190:193], v[236:239], v[82:85]
	v_mfma_f32_16x16x32_bf16 v[86:89], v[154:157], v[232:235], 0
	v_mfma_f32_16x16x32_bf16 v[86:89], v[174:177], v[236:239], v[86:89]
	v_mfma_f32_16x16x32_bf16 v[70:73], v[154:157], v[240:243], 0
	v_mfma_f32_16x16x32_bf16 v[70:73], v[174:177], v[244:247], v[70:73]
	v_mfma_f32_16x16x32_bf16 v[66:69], v[178:181], v[240:243], 0
	v_mfma_f32_16x16x32_bf16 v[66:69], v[190:193], v[244:247], v[66:69]
	v_mfma_f32_16x16x32_bf16 v[74:77], v[138:141], v[240:243], 0
	v_mfma_f32_16x16x32_bf16 v[74:77], v[142:145], v[244:247], v[74:77]
	v_mfma_f32_16x16x32_bf16 v[78:81], v[130:133], v[240:243], 0
	v_mfma_f32_16x16x32_bf16 v[78:81], v[134:137], v[244:247], v[78:81]
	s_barrier
	s_setprio 0
	s_mov_b32 s46, s62
	s_mov_b32 s47, s63
	s_mov_b32 m0, s16
	ds_read_b128 v[194:197], v189 offset:16384
	buffer_load_dwordx4 v185, s[44:47], s25 offen lds
	s_add_i32 s53, s25, 0x80000
	s_mov_b32 m0, s18
	ds_read_b128 v[198:201], v189 offset:17408
	buffer_load_dwordx4 v187, s[44:47], s25 offen lds
	s_mov_b32 m0, s19
	ds_read_b128 v[202:205], v189 offset:18432
	buffer_load_dwordx4 v185, s[44:47], s53 offen lds
	s_mov_b32 m0, s23
	ds_read_b128 v[228:231], v189 offset:19456
	buffer_load_dwordx4 v187, s[44:47], s53 offen lds
	s_mov_b32 m0, s15
	ds_read_b128 v[232:235], v189 offset:20480
	buffer_load_dwordx4 v184, s[60:63], s52 offen lds
	s_mov_b32 m0, s26
	ds_read_b128 v[236:239], v189 offset:21504
	buffer_load_dwordx4 v186, s[60:63], s52 offen lds
	ds_read_b128 v[240:243], v189 offset:22528
	ds_read_b128 v[244:247], v189 offset:23552
	s_waitcnt vmcnt(8)
	s_waitcnt lgkmcnt(0)
	s_setprio 1
	s_barrier
	v_mfma_f32_16x16x32_bf16 v[62:65], v[130:133], v[194:197], 0
	v_mfma_f32_16x16x32_bf16 v[62:65], v[134:137], v[198:201], v[62:65]
	v_mfma_f32_16x16x32_bf16 v[58:61], v[138:141], v[194:197], 0
	v_mfma_f32_16x16x32_bf16 v[58:61], v[142:145], v[198:201], v[58:61]
	v_mfma_f32_16x16x32_bf16 v[50:53], v[178:181], v[194:197], 0
	v_mfma_f32_16x16x32_bf16 v[50:53], v[190:193], v[198:201], v[50:53]
	v_mfma_f32_16x16x32_bf16 v[54:57], v[154:157], v[194:197], 0
	v_mfma_f32_16x16x32_bf16 v[54:57], v[174:177], v[198:201], v[54:57]
	v_mfma_f32_16x16x32_bf16 v[38:41], v[154:157], v[202:205], 0
	v_mfma_f32_16x16x32_bf16 v[38:41], v[174:177], v[228:231], v[38:41]
	v_mfma_f32_16x16x32_bf16 v[34:37], v[178:181], v[202:205], 0
	v_mfma_f32_16x16x32_bf16 v[34:37], v[190:193], v[228:231], v[34:37]
	v_mfma_f32_16x16x32_bf16 v[42:45], v[138:141], v[202:205], 0
	v_mfma_f32_16x16x32_bf16 v[42:45], v[142:145], v[228:231], v[42:45]
	v_mfma_f32_16x16x32_bf16 v[46:49], v[130:133], v[202:205], 0
	v_mfma_f32_16x16x32_bf16 v[46:49], v[134:137], v[228:231], v[46:49]
	v_mfma_f32_16x16x32_bf16 v[30:33], v[130:133], v[232:235], 0
	v_mfma_f32_16x16x32_bf16 v[30:33], v[134:137], v[236:239], v[30:33]
	v_mfma_f32_16x16x32_bf16 v[26:29], v[138:141], v[232:235], 0
	v_mfma_f32_16x16x32_bf16 v[26:29], v[142:145], v[236:239], v[26:29]
	v_mfma_f32_16x16x32_bf16 v[18:21], v[178:181], v[232:235], 0
	v_mfma_f32_16x16x32_bf16 v[18:21], v[190:193], v[236:239], v[18:21]
	v_mfma_f32_16x16x32_bf16 v[22:25], v[154:157], v[232:235], 0
	v_mfma_f32_16x16x32_bf16 v[22:25], v[174:177], v[236:239], v[22:25]
	v_mfma_f32_16x16x32_bf16 v[6:9], v[154:157], v[240:243], 0
	v_mfma_f32_16x16x32_bf16 v[6:9], v[174:177], v[244:247], v[6:9]
	v_mfma_f32_16x16x32_bf16 v[2:5], v[178:181], v[240:243], 0
	v_mfma_f32_16x16x32_bf16 v[2:5], v[190:193], v[244:247], v[2:5]
	v_mfma_f32_16x16x32_bf16 v[10:13], v[138:141], v[240:243], 0
	v_mfma_f32_16x16x32_bf16 v[10:13], v[142:145], v[244:247], v[10:13]
	v_mfma_f32_16x16x32_bf16 v[14:17], v[130:133], v[240:243], 0
	v_mfma_f32_16x16x32_bf16 v[14:17], v[134:137], v[244:247], v[14:17]
	s_barrier
	s_setprio 0
	v_add_u32_e32 v142, 0x18000, v188
	v_add_u32_e32 v182, 0x1c000, v188
	ds_read_b128 v[130:133], v142
	ds_read_b128 v[134:137], v142 offset:1024
	ds_read_b128 v[138:141], v142 offset:2048
	ds_read_b128 v[142:145], v142 offset:3072
	ds_read_b128 v[154:157], v182
	ds_read_b128 v[174:177], v182 offset:1024
	ds_read_b128 v[178:181], v182 offset:2048
	ds_read_b128 v[190:193], v182 offset:3072
	s_add_i32 s52, s52, 0x80000
	s_mov_b32 m0, s27
	ds_read_b128 v[194:197], v189 offset:32768
	ds_read_b128 v[198:201], v189 offset:33792
	ds_read_b128 v[202:205], v189 offset:34816
	ds_read_b128 v[228:231], v189 offset:35840
	ds_read_b128 v[232:235], v189 offset:36864
	ds_read_b128 v[236:239], v189 offset:37888
	ds_read_b128 v[240:243], v189 offset:38912
	ds_read_b128 v[244:247], v189 offset:39936
	buffer_load_dwordx4 v184, s[60:63], s52 offen lds
	s_mov_b32 m0, s30
	s_nop 0
	buffer_load_dwordx4 v186, s[60:63], s52 offen lds
	s_waitcnt vmcnt(8)
	s_waitcnt lgkmcnt(0)
	s_setprio 1
	s_barrier
	v_mfma_f32_16x16x32_bf16 v[126:129], v[130:133], v[194:197], v[126:129]
	v_mfma_f32_16x16x32_bf16 v[126:129], v[134:137], v[198:201], v[126:129]
	v_mfma_f32_16x16x32_bf16 v[122:125], v[138:141], v[194:197], v[122:125]
	v_mfma_f32_16x16x32_bf16 v[122:125], v[142:145], v[198:201], v[122:125]
	v_mfma_f32_16x16x32_bf16 v[114:117], v[178:181], v[194:197], v[114:117]
	v_mfma_f32_16x16x32_bf16 v[114:117], v[190:193], v[198:201], v[114:117]
	v_mfma_f32_16x16x32_bf16 v[118:121], v[154:157], v[194:197], v[118:121]
	v_mfma_f32_16x16x32_bf16 v[118:121], v[174:177], v[198:201], v[118:121]
	v_mfma_f32_16x16x32_bf16 v[102:105], v[154:157], v[202:205], v[102:105]
	v_mfma_f32_16x16x32_bf16 v[102:105], v[174:177], v[228:231], v[102:105]
	v_mfma_f32_16x16x32_bf16 v[98:101], v[178:181], v[202:205], v[98:101]
	v_mfma_f32_16x16x32_bf16 v[98:101], v[190:193], v[228:231], v[98:101]
	v_mfma_f32_16x16x32_bf16 v[106:109], v[138:141], v[202:205], v[106:109]
	v_mfma_f32_16x16x32_bf16 v[106:109], v[142:145], v[228:231], v[106:109]
	v_mfma_f32_16x16x32_bf16 v[110:113], v[130:133], v[202:205], v[110:113]
	v_mfma_f32_16x16x32_bf16 v[110:113], v[134:137], v[228:231], v[110:113]
	v_mfma_f32_16x16x32_bf16 v[94:97], v[130:133], v[232:235], v[94:97]
	v_mfma_f32_16x16x32_bf16 v[94:97], v[134:137], v[236:239], v[94:97]
	v_mfma_f32_16x16x32_bf16 v[90:93], v[138:141], v[232:235], v[90:93]
	v_mfma_f32_16x16x32_bf16 v[90:93], v[142:145], v[236:239], v[90:93]
	v_mfma_f32_16x16x32_bf16 v[82:85], v[178:181], v[232:235], v[82:85]
	v_mfma_f32_16x16x32_bf16 v[82:85], v[190:193], v[236:239], v[82:85]
	v_mfma_f32_16x16x32_bf16 v[86:89], v[154:157], v[232:235], v[86:89]
	v_mfma_f32_16x16x32_bf16 v[86:89], v[174:177], v[236:239], v[86:89]
	v_mfma_f32_16x16x32_bf16 v[70:73], v[154:157], v[240:243], v[70:73]
	v_mfma_f32_16x16x32_bf16 v[70:73], v[174:177], v[244:247], v[70:73]
	v_mfma_f32_16x16x32_bf16 v[66:69], v[178:181], v[240:243], v[66:69]
	v_mfma_f32_16x16x32_bf16 v[66:69], v[190:193], v[244:247], v[66:69]
	v_mfma_f32_16x16x32_bf16 v[74:77], v[138:141], v[240:243], v[74:77]
	v_mfma_f32_16x16x32_bf16 v[74:77], v[142:145], v[244:247], v[74:77]
	v_mfma_f32_16x16x32_bf16 v[78:81], v[130:133], v[240:243], v[78:81]
	v_mfma_f32_16x16x32_bf16 v[78:81], v[134:137], v[244:247], v[78:81]
	s_barrier
	s_setprio 0
	s_or_b32 s52, s25, 0x80
	s_mov_b32 m0, s36
	ds_read_b128 v[194:197], v189 offset:49152
	buffer_load_dwordx4 v185, s[44:47], s52 offen lds
	s_add_i32 s25, s25, 0x80080
	s_mov_b32 m0, s37
	ds_read_b128 v[198:201], v189 offset:50176
	buffer_load_dwordx4 v187, s[44:47], s52 offen lds
	s_mov_b32 m0, s66
	ds_read_b128 v[202:205], v189 offset:51200
	buffer_load_dwordx4 v185, s[44:47], s25 offen lds
	s_mov_b32 m0, s67
	ds_read_b128 v[228:231], v189 offset:52224
	buffer_load_dwordx4 v187, s[44:47], s25 offen lds
	s_mov_b32 m0, s48
	ds_read_b128 v[232:235], v189 offset:53248
	buffer_load_dwordx4 v184, s[60:63], s24 offen lds
	s_mov_b32 m0, s49
	ds_read_b128 v[236:239], v189 offset:54272
	buffer_load_dwordx4 v186, s[60:63], s24 offen lds
	ds_read_b128 v[240:243], v189 offset:55296
	ds_read_b128 v[244:247], v189 offset:56320
	s_waitcnt vmcnt(8)
	s_waitcnt lgkmcnt(0)
	s_setprio 1
	s_barrier
	v_mfma_f32_16x16x32_bf16 v[62:65], v[130:133], v[194:197], v[62:65]
	v_mfma_f32_16x16x32_bf16 v[62:65], v[134:137], v[198:201], v[62:65]
	v_mfma_f32_16x16x32_bf16 v[58:61], v[138:141], v[194:197], v[58:61]
	v_mfma_f32_16x16x32_bf16 v[58:61], v[142:145], v[198:201], v[58:61]
	v_mfma_f32_16x16x32_bf16 v[50:53], v[178:181], v[194:197], v[50:53]
	v_mfma_f32_16x16x32_bf16 v[50:53], v[190:193], v[198:201], v[50:53]
	v_mfma_f32_16x16x32_bf16 v[54:57], v[154:157], v[194:197], v[54:57]
	v_mfma_f32_16x16x32_bf16 v[54:57], v[174:177], v[198:201], v[54:57]
	v_mfma_f32_16x16x32_bf16 v[38:41], v[154:157], v[202:205], v[38:41]
	v_mfma_f32_16x16x32_bf16 v[38:41], v[174:177], v[228:231], v[38:41]
	v_mfma_f32_16x16x32_bf16 v[34:37], v[178:181], v[202:205], v[34:37]
	v_mfma_f32_16x16x32_bf16 v[34:37], v[190:193], v[228:231], v[34:37]
	v_mfma_f32_16x16x32_bf16 v[42:45], v[138:141], v[202:205], v[42:45]
	v_mfma_f32_16x16x32_bf16 v[42:45], v[142:145], v[228:231], v[42:45]
	v_mfma_f32_16x16x32_bf16 v[46:49], v[130:133], v[202:205], v[46:49]
	v_mfma_f32_16x16x32_bf16 v[46:49], v[134:137], v[228:231], v[46:49]
	v_mfma_f32_16x16x32_bf16 v[30:33], v[130:133], v[232:235], v[30:33]
	v_mfma_f32_16x16x32_bf16 v[30:33], v[134:137], v[236:239], v[30:33]
	v_mfma_f32_16x16x32_bf16 v[26:29], v[138:141], v[232:235], v[26:29]
	v_mfma_f32_16x16x32_bf16 v[26:29], v[142:145], v[236:239], v[26:29]
	v_mfma_f32_16x16x32_bf16 v[18:21], v[178:181], v[232:235], v[18:21]
	v_mfma_f32_16x16x32_bf16 v[18:21], v[190:193], v[236:239], v[18:21]
	v_mfma_f32_16x16x32_bf16 v[22:25], v[154:157], v[232:235], v[22:25]
	v_mfma_f32_16x16x32_bf16 v[22:25], v[174:177], v[236:239], v[22:25]
	v_mfma_f32_16x16x32_bf16 v[6:9], v[154:157], v[240:243], v[6:9]
	v_mfma_f32_16x16x32_bf16 v[6:9], v[174:177], v[244:247], v[6:9]
	v_mfma_f32_16x16x32_bf16 v[2:5], v[178:181], v[240:243], v[2:5]
	v_mfma_f32_16x16x32_bf16 v[2:5], v[190:193], v[244:247], v[2:5]
	v_mfma_f32_16x16x32_bf16 v[10:13], v[138:141], v[240:243], v[10:13]
	v_mfma_f32_16x16x32_bf16 v[10:13], v[142:145], v[244:247], v[10:13]
	v_mfma_f32_16x16x32_bf16 v[14:17], v[130:133], v[240:243], v[14:17]
	v_mfma_f32_16x16x32_bf16 v[14:17], v[134:137], v[244:247], v[14:17]
	s_barrier
	s_setprio 0
	s_add_i32 s22, s22, 2
	s_addk_i32 s13, 0x100
	s_addk_i32 s21, 0x100
	s_cmp_gt_u32 s22, 29
.LBB0_2450:
	v_add_u32_e32 v142, 0x10000, v188
	v_add_u32_e32 v182, 0x14000, v188
	ds_read_b128 v[130:133], v142
	ds_read_b128 v[134:137], v142 offset:1024
	ds_read_b128 v[138:141], v142 offset:2048
	ds_read_b128 v[142:145], v142 offset:3072
	ds_read_b128 v[154:157], v182
	ds_read_b128 v[174:177], v182 offset:1024
	ds_read_b128 v[178:181], v182 offset:2048
	ds_read_b128 v[190:193], v182 offset:3072
	s_add_i32 s24, s13, 0xfff80080
	s_cmp_eq_u32 s22, 28
	s_cselect_b32 s52, s8, s24
	s_cselect_b32 s25, s9, s21
	s_or_b32 s24, s52, 0x80
	s_mov_b32 m0, s68
	ds_read_b128 v[194:197], v189
	ds_read_b128 v[198:201], v189 offset:1024
	ds_read_b128 v[202:205], v189 offset:2048
	ds_read_b128 v[228:231], v189 offset:3072
	ds_read_b128 v[232:235], v189 offset:4096
	ds_read_b128 v[236:239], v189 offset:5120
	ds_read_b128 v[240:243], v189 offset:6144
	ds_read_b128 v[244:247], v189 offset:7168
	buffer_load_dwordx4 v184, s[60:63], s13 offen lds
	s_mov_b32 m0, s70
	s_nop 0
	buffer_load_dwordx4 v186, s[60:63], s13 offen lds
	s_waitcnt vmcnt(8)
	s_waitcnt lgkmcnt(0)
	s_setprio 1
	s_barrier
	v_mfma_f32_16x16x32_bf16 v[126:129], v[130:133], v[194:197], v[126:129]
	v_mfma_f32_16x16x32_bf16 v[126:129], v[134:137], v[198:201], v[126:129]
	v_mfma_f32_16x16x32_bf16 v[122:125], v[138:141], v[194:197], v[122:125]
	v_mfma_f32_16x16x32_bf16 v[122:125], v[142:145], v[198:201], v[122:125]
	v_mfma_f32_16x16x32_bf16 v[114:117], v[178:181], v[194:197], v[114:117]
	v_mfma_f32_16x16x32_bf16 v[114:117], v[190:193], v[198:201], v[114:117]
	v_mfma_f32_16x16x32_bf16 v[118:121], v[154:157], v[194:197], v[118:121]
	v_mfma_f32_16x16x32_bf16 v[118:121], v[174:177], v[198:201], v[118:121]
	v_mfma_f32_16x16x32_bf16 v[102:105], v[154:157], v[202:205], v[102:105]
	v_mfma_f32_16x16x32_bf16 v[102:105], v[174:177], v[228:231], v[102:105]
	v_mfma_f32_16x16x32_bf16 v[98:101], v[178:181], v[202:205], v[98:101]
	v_mfma_f32_16x16x32_bf16 v[98:101], v[190:193], v[228:231], v[98:101]
	v_mfma_f32_16x16x32_bf16 v[106:109], v[138:141], v[202:205], v[106:109]
	v_mfma_f32_16x16x32_bf16 v[106:109], v[142:145], v[228:231], v[106:109]
	v_mfma_f32_16x16x32_bf16 v[110:113], v[130:133], v[202:205], v[110:113]
	v_mfma_f32_16x16x32_bf16 v[110:113], v[134:137], v[228:231], v[110:113]
	v_mfma_f32_16x16x32_bf16 v[94:97], v[130:133], v[232:235], v[94:97]
	v_mfma_f32_16x16x32_bf16 v[94:97], v[134:137], v[236:239], v[94:97]
	v_mfma_f32_16x16x32_bf16 v[90:93], v[138:141], v[232:235], v[90:93]
	v_mfma_f32_16x16x32_bf16 v[90:93], v[142:145], v[236:239], v[90:93]
	v_mfma_f32_16x16x32_bf16 v[82:85], v[178:181], v[232:235], v[82:85]
	v_mfma_f32_16x16x32_bf16 v[82:85], v[190:193], v[236:239], v[82:85]
	v_mfma_f32_16x16x32_bf16 v[86:89], v[154:157], v[232:235], v[86:89]
	v_mfma_f32_16x16x32_bf16 v[86:89], v[174:177], v[236:239], v[86:89]
	v_mfma_f32_16x16x32_bf16 v[70:73], v[154:157], v[240:243], v[70:73]
	v_mfma_f32_16x16x32_bf16 v[70:73], v[174:177], v[244:247], v[70:73]
	v_mfma_f32_16x16x32_bf16 v[66:69], v[178:181], v[240:243], v[66:69]
	v_mfma_f32_16x16x32_bf16 v[66:69], v[190:193], v[244:247], v[66:69]
	v_mfma_f32_16x16x32_bf16 v[74:77], v[138:141], v[240:243], v[74:77]
	v_mfma_f32_16x16x32_bf16 v[74:77], v[142:145], v[244:247], v[74:77]
	v_mfma_f32_16x16x32_bf16 v[78:81], v[130:133], v[240:243], v[78:81]
	v_mfma_f32_16x16x32_bf16 v[78:81], v[134:137], v[244:247], v[78:81]
	s_barrier
	s_setprio 0
	s_mov_b32 s46, s62
	s_mov_b32 s47, s63
	s_mov_b32 m0, s16
	ds_read_b128 v[194:197], v189 offset:16384
	buffer_load_dwordx4 v185, s[44:47], s25 offen lds
	s_add_i32 s53, s25, 0x80000
	s_mov_b32 m0, s18
	ds_read_b128 v[198:201], v189 offset:17408
	buffer_load_dwordx4 v187, s[44:47], s25 offen lds
	s_mov_b32 m0, s19
	ds_read_b128 v[202:205], v189 offset:18432
	buffer_load_dwordx4 v185, s[44:47], s53 offen lds
	s_mov_b32 m0, s23
	ds_read_b128 v[228:231], v189 offset:19456
	buffer_load_dwordx4 v187, s[44:47], s53 offen lds
	s_mov_b32 m0, s15
	ds_read_b128 v[232:235], v189 offset:20480
	buffer_load_dwordx4 v184, s[60:63], s52 offen lds
	s_mov_b32 m0, s26
	ds_read_b128 v[236:239], v189 offset:21504
	buffer_load_dwordx4 v186, s[60:63], s52 offen lds
	ds_read_b128 v[240:243], v189 offset:22528
	ds_read_b128 v[244:247], v189 offset:23552
	s_waitcnt vmcnt(8)
	s_waitcnt lgkmcnt(0)
	s_setprio 1
	s_barrier
	v_mfma_f32_16x16x32_bf16 v[62:65], v[130:133], v[194:197], v[62:65]
	v_mfma_f32_16x16x32_bf16 v[62:65], v[134:137], v[198:201], v[62:65]
	v_mfma_f32_16x16x32_bf16 v[58:61], v[138:141], v[194:197], v[58:61]
	v_mfma_f32_16x16x32_bf16 v[58:61], v[142:145], v[198:201], v[58:61]
	v_mfma_f32_16x16x32_bf16 v[50:53], v[178:181], v[194:197], v[50:53]
	v_mfma_f32_16x16x32_bf16 v[50:53], v[190:193], v[198:201], v[50:53]
	v_mfma_f32_16x16x32_bf16 v[54:57], v[154:157], v[194:197], v[54:57]
	v_mfma_f32_16x16x32_bf16 v[54:57], v[174:177], v[198:201], v[54:57]
	v_mfma_f32_16x16x32_bf16 v[38:41], v[154:157], v[202:205], v[38:41]
	v_mfma_f32_16x16x32_bf16 v[38:41], v[174:177], v[228:231], v[38:41]
	v_mfma_f32_16x16x32_bf16 v[34:37], v[178:181], v[202:205], v[34:37]
	v_mfma_f32_16x16x32_bf16 v[34:37], v[190:193], v[228:231], v[34:37]
	v_mfma_f32_16x16x32_bf16 v[42:45], v[138:141], v[202:205], v[42:45]
	v_mfma_f32_16x16x32_bf16 v[42:45], v[142:145], v[228:231], v[42:45]
	v_mfma_f32_16x16x32_bf16 v[46:49], v[130:133], v[202:205], v[46:49]
	v_mfma_f32_16x16x32_bf16 v[46:49], v[134:137], v[228:231], v[46:49]
	v_mfma_f32_16x16x32_bf16 v[30:33], v[130:133], v[232:235], v[30:33]
	v_mfma_f32_16x16x32_bf16 v[30:33], v[134:137], v[236:239], v[30:33]
	v_mfma_f32_16x16x32_bf16 v[26:29], v[138:141], v[232:235], v[26:29]
	v_mfma_f32_16x16x32_bf16 v[26:29], v[142:145], v[236:239], v[26:29]
	v_mfma_f32_16x16x32_bf16 v[18:21], v[178:181], v[232:235], v[18:21]
	v_mfma_f32_16x16x32_bf16 v[18:21], v[190:193], v[236:239], v[18:21]
	v_mfma_f32_16x16x32_bf16 v[22:25], v[154:157], v[232:235], v[22:25]
	v_mfma_f32_16x16x32_bf16 v[22:25], v[174:177], v[236:239], v[22:25]
	v_mfma_f32_16x16x32_bf16 v[6:9], v[154:157], v[240:243], v[6:9]
	v_mfma_f32_16x16x32_bf16 v[6:9], v[174:177], v[244:247], v[6:9]
	v_mfma_f32_16x16x32_bf16 v[2:5], v[178:181], v[240:243], v[2:5]
	v_mfma_f32_16x16x32_bf16 v[2:5], v[190:193], v[244:247], v[2:5]
	v_mfma_f32_16x16x32_bf16 v[10:13], v[138:141], v[240:243], v[10:13]
	v_mfma_f32_16x16x32_bf16 v[10:13], v[142:145], v[244:247], v[10:13]
	v_mfma_f32_16x16x32_bf16 v[14:17], v[130:133], v[240:243], v[14:17]
	v_mfma_f32_16x16x32_bf16 v[14:17], v[134:137], v[244:247], v[14:17]
	s_barrier
	s_setprio 0
	v_add_u32_e32 v142, 0x18000, v188
	v_add_u32_e32 v182, 0x1c000, v188
	ds_read_b128 v[130:133], v142
	ds_read_b128 v[134:137], v142 offset:1024
	ds_read_b128 v[138:141], v142 offset:2048
	ds_read_b128 v[142:145], v142 offset:3072
	ds_read_b128 v[154:157], v182
	ds_read_b128 v[174:177], v182 offset:1024
	ds_read_b128 v[178:181], v182 offset:2048
	ds_read_b128 v[190:193], v182 offset:3072
	s_add_i32 s52, s52, 0x80000
	s_mov_b32 m0, s27
	ds_read_b128 v[194:197], v189 offset:32768
	ds_read_b128 v[198:201], v189 offset:33792
	ds_read_b128 v[202:205], v189 offset:34816
	ds_read_b128 v[228:231], v189 offset:35840
	ds_read_b128 v[232:235], v189 offset:36864
	ds_read_b128 v[236:239], v189 offset:37888
	ds_read_b128 v[240:243], v189 offset:38912
	ds_read_b128 v[244:247], v189 offset:39936
	buffer_load_dwordx4 v184, s[60:63], s52 offen lds
	s_mov_b32 m0, s30
	s_nop 0
	buffer_load_dwordx4 v186, s[60:63], s52 offen lds
	s_waitcnt vmcnt(8)
	s_waitcnt lgkmcnt(0)
	s_setprio 1
	s_barrier
	v_mfma_f32_16x16x32_bf16 v[126:129], v[130:133], v[194:197], v[126:129]
	v_mfma_f32_16x16x32_bf16 v[126:129], v[134:137], v[198:201], v[126:129]
	v_mfma_f32_16x16x32_bf16 v[122:125], v[138:141], v[194:197], v[122:125]
	v_mfma_f32_16x16x32_bf16 v[122:125], v[142:145], v[198:201], v[122:125]
	v_mfma_f32_16x16x32_bf16 v[114:117], v[178:181], v[194:197], v[114:117]
	v_mfma_f32_16x16x32_bf16 v[114:117], v[190:193], v[198:201], v[114:117]
	v_mfma_f32_16x16x32_bf16 v[118:121], v[154:157], v[194:197], v[118:121]
	v_mfma_f32_16x16x32_bf16 v[118:121], v[174:177], v[198:201], v[118:121]
	v_mfma_f32_16x16x32_bf16 v[102:105], v[154:157], v[202:205], v[102:105]
	v_mfma_f32_16x16x32_bf16 v[102:105], v[174:177], v[228:231], v[102:105]
	v_mfma_f32_16x16x32_bf16 v[98:101], v[178:181], v[202:205], v[98:101]
	v_mfma_f32_16x16x32_bf16 v[98:101], v[190:193], v[228:231], v[98:101]
	v_mfma_f32_16x16x32_bf16 v[106:109], v[138:141], v[202:205], v[106:109]
	v_mfma_f32_16x16x32_bf16 v[106:109], v[142:145], v[228:231], v[106:109]
	v_mfma_f32_16x16x32_bf16 v[110:113], v[130:133], v[202:205], v[110:113]
	v_mfma_f32_16x16x32_bf16 v[110:113], v[134:137], v[228:231], v[110:113]
	v_mfma_f32_16x16x32_bf16 v[94:97], v[130:133], v[232:235], v[94:97]
	v_mfma_f32_16x16x32_bf16 v[94:97], v[134:137], v[236:239], v[94:97]
	v_mfma_f32_16x16x32_bf16 v[90:93], v[138:141], v[232:235], v[90:93]
	v_mfma_f32_16x16x32_bf16 v[90:93], v[142:145], v[236:239], v[90:93]
	v_mfma_f32_16x16x32_bf16 v[82:85], v[178:181], v[232:235], v[82:85]
	v_mfma_f32_16x16x32_bf16 v[82:85], v[190:193], v[236:239], v[82:85]
	v_mfma_f32_16x16x32_bf16 v[86:89], v[154:157], v[232:235], v[86:89]
	v_mfma_f32_16x16x32_bf16 v[86:89], v[174:177], v[236:239], v[86:89]
	v_mfma_f32_16x16x32_bf16 v[70:73], v[154:157], v[240:243], v[70:73]
	v_mfma_f32_16x16x32_bf16 v[70:73], v[174:177], v[244:247], v[70:73]
	v_mfma_f32_16x16x32_bf16 v[66:69], v[178:181], v[240:243], v[66:69]
	v_mfma_f32_16x16x32_bf16 v[66:69], v[190:193], v[244:247], v[66:69]
	v_mfma_f32_16x16x32_bf16 v[74:77], v[138:141], v[240:243], v[74:77]
	v_mfma_f32_16x16x32_bf16 v[74:77], v[142:145], v[244:247], v[74:77]
	v_mfma_f32_16x16x32_bf16 v[78:81], v[130:133], v[240:243], v[78:81]
	v_mfma_f32_16x16x32_bf16 v[78:81], v[134:137], v[244:247], v[78:81]
	s_barrier
	s_setprio 0
	s_or_b32 s52, s25, 0x80
	s_mov_b32 m0, s36
	ds_read_b128 v[194:197], v189 offset:49152
	buffer_load_dwordx4 v185, s[44:47], s52 offen lds
	s_add_i32 s25, s25, 0x80080
	s_mov_b32 m0, s37
	ds_read_b128 v[198:201], v189 offset:50176
	buffer_load_dwordx4 v187, s[44:47], s52 offen lds
	s_mov_b32 m0, s66
	ds_read_b128 v[202:205], v189 offset:51200
	buffer_load_dwordx4 v185, s[44:47], s25 offen lds
	s_mov_b32 m0, s67
	ds_read_b128 v[228:231], v189 offset:52224
	buffer_load_dwordx4 v187, s[44:47], s25 offen lds
	s_mov_b32 m0, s48
	ds_read_b128 v[232:235], v189 offset:53248
	buffer_load_dwordx4 v184, s[60:63], s24 offen lds
	s_mov_b32 m0, s49
	ds_read_b128 v[236:239], v189 offset:54272
	buffer_load_dwordx4 v186, s[60:63], s24 offen lds
	ds_read_b128 v[240:243], v189 offset:55296
	ds_read_b128 v[244:247], v189 offset:56320
	s_waitcnt vmcnt(8)
	s_waitcnt lgkmcnt(0)
	s_setprio 1
	s_barrier
	v_mfma_f32_16x16x32_bf16 v[62:65], v[130:133], v[194:197], v[62:65]
	v_mfma_f32_16x16x32_bf16 v[62:65], v[134:137], v[198:201], v[62:65]
	v_mfma_f32_16x16x32_bf16 v[58:61], v[138:141], v[194:197], v[58:61]
	v_mfma_f32_16x16x32_bf16 v[58:61], v[142:145], v[198:201], v[58:61]
	v_mfma_f32_16x16x32_bf16 v[50:53], v[178:181], v[194:197], v[50:53]
	v_mfma_f32_16x16x32_bf16 v[50:53], v[190:193], v[198:201], v[50:53]
	v_mfma_f32_16x16x32_bf16 v[54:57], v[154:157], v[194:197], v[54:57]
	v_mfma_f32_16x16x32_bf16 v[54:57], v[174:177], v[198:201], v[54:57]
	v_mfma_f32_16x16x32_bf16 v[38:41], v[154:157], v[202:205], v[38:41]
	v_mfma_f32_16x16x32_bf16 v[38:41], v[174:177], v[228:231], v[38:41]
	v_mfma_f32_16x16x32_bf16 v[34:37], v[178:181], v[202:205], v[34:37]
	v_mfma_f32_16x16x32_bf16 v[34:37], v[190:193], v[228:231], v[34:37]
	v_mfma_f32_16x16x32_bf16 v[42:45], v[138:141], v[202:205], v[42:45]
	v_mfma_f32_16x16x32_bf16 v[42:45], v[142:145], v[228:231], v[42:45]
	v_mfma_f32_16x16x32_bf16 v[46:49], v[130:133], v[202:205], v[46:49]
	v_mfma_f32_16x16x32_bf16 v[46:49], v[134:137], v[228:231], v[46:49]
	v_mfma_f32_16x16x32_bf16 v[30:33], v[130:133], v[232:235], v[30:33]
	v_mfma_f32_16x16x32_bf16 v[30:33], v[134:137], v[236:239], v[30:33]
	v_mfma_f32_16x16x32_bf16 v[26:29], v[138:141], v[232:235], v[26:29]
	v_mfma_f32_16x16x32_bf16 v[26:29], v[142:145], v[236:239], v[26:29]
	v_mfma_f32_16x16x32_bf16 v[18:21], v[178:181], v[232:235], v[18:21]
	v_mfma_f32_16x16x32_bf16 v[18:21], v[190:193], v[236:239], v[18:21]
	v_mfma_f32_16x16x32_bf16 v[22:25], v[154:157], v[232:235], v[22:25]
	v_mfma_f32_16x16x32_bf16 v[22:25], v[174:177], v[236:239], v[22:25]
	v_mfma_f32_16x16x32_bf16 v[6:9], v[154:157], v[240:243], v[6:9]
	v_mfma_f32_16x16x32_bf16 v[6:9], v[174:177], v[244:247], v[6:9]
	v_mfma_f32_16x16x32_bf16 v[2:5], v[178:181], v[240:243], v[2:5]
	v_mfma_f32_16x16x32_bf16 v[2:5], v[190:193], v[244:247], v[2:5]
	v_mfma_f32_16x16x32_bf16 v[10:13], v[138:141], v[240:243], v[10:13]
	v_mfma_f32_16x16x32_bf16 v[10:13], v[142:145], v[244:247], v[10:13]
	v_mfma_f32_16x16x32_bf16 v[14:17], v[130:133], v[240:243], v[14:17]
	v_mfma_f32_16x16x32_bf16 v[14:17], v[134:137], v[244:247], v[14:17]
	s_barrier
	s_setprio 0
	s_add_i32 s22, s22, 2
	s_addk_i32 s13, 0x100
	s_addk_i32 s21, 0x100
	s_cmp_gt_u32 s22, 29
	s_cbranch_scc0 .LBB0_2450
	s_and_b64 vcc, exec, s[64:65]
	s_cbranch_vccz .LBB0_2453
	s_barrier
